# wave reductions in LN/quant phases via DPP+permlane swaps instead of ds_bpermute; LN1 g/b staged in LDS; preheader vmcnt(0) removed
# speedup vs baseline: 1.0054x; 1.0054x over previous
; __device__ __forceinline__ float wave_sum(float v) {
; #pragma unroll
;     for (int o = 1; o < 64; o <<= 1) v += __shfl_xor(v, o);
;     return v;
; }
; __device__ __forceinline__ void ln_row_in(const float* src, const float* g, const float* b, bf16* dstb, signed char* dstq, float* rowinv, int lane) {
;     const f32x4* xr = (const f32x4*)src + lane;
;     f32x4 v[16]; float s = 0.f;
; #pragma unroll
;     for (int j = 0; j < 16; ++j) { v[j] = __builtin_nontemporal_load(xr + 64 * j); s += (v[j].x + v[j].y) + (v[j].z + v[j].w); }
;     const float mean = wave_sum(s) * (1.f / 4096.f); float s2 = 0.f;
.LBB0_21:
	v_lshlrev_b32_e32 v70, 4, v66
	v_lshl_add_u64 v[2:3], s[6:7], 0, v[70:71]
	global_load_dwordx4 v[58:61], v70, s[6:7] nt
	global_load_dwordx4 v[62:65], v70, s[6:7] offset:1024 nt
	global_load_dwordx4 v[54:57], v70, s[6:7] offset:2048 nt
	global_load_dwordx4 v[50:53], v70, s[6:7] offset:3072 nt
	v_add_co_u32_e32 v4, vcc, s39, v2
	s_waitcnt vmcnt(3)
	v_mov_b32_e32 v126, v59
	v_addc_co_u32_e32 v5, vcc, 0, v3, vcc
	global_load_dwordx4 v[46:49], v[4:5], off offset:-4096 nt
	v_add_co_u32_e32 v6, vcc, s25, v2
	v_mov_b32_e32 v127, v60
	s_nop 0
	v_addc_co_u32_e32 v7, vcc, 0, v3, vcc
	global_load_dwordx4 v[42:45], v[6:7], off offset:1024 nt
	global_load_dwordx4 v[38:41], v[6:7], off offset:2048 nt
	global_load_dwordx4 v[34:37], v[6:7], off offset:3072 nt
	global_load_dwordx4 v[30:33], v[4:5], off nt
	global_load_dwordx4 v[26:29], v[4:5], off offset:1024 nt
	global_load_dwordx4 v[22:25], v[4:5], off offset:2048 nt
	v_add_co_u32_e32 v6, vcc, s40, v2
	v_mov_b32_e32 v128, v58
	s_nop 0
	v_addc_co_u32_e32 v7, vcc, 0, v3, vcc
	global_load_dwordx4 v[18:21], v[4:5], off offset:3072 nt
	global_load_dwordx4 v[10:13], v[6:7], off nt
	global_load_dwordx4 v[14:17], v[6:7], off offset:1024 nt
	s_nop 0
	global_load_dwordx4 v[2:5], v[6:7], off offset:3072 nt
	s_nop 0
	global_load_dwordx4 v[6:9], v[6:7], off offset:2048 nt
	v_mov_b32_e32 v129, v61
	s_waitcnt vmcnt(14)
	v_mov_b32_e32 v130, v63
	v_mov_b32_e32 v131, v64
	v_mov_b32_e32 v132, v62
	v_mov_b32_e32 v133, v65
	v_pk_add_f32 v[126:127], v[126:127], v[128:129]
	v_pk_add_f32 v[128:129], v[130:131], v[132:133]
	v_add_f32_e32 v70, v126, v127
	v_pk_add_f32 v[126:127], v[128:129], v[128:129] op_sel:[0,1] op_sel_hi:[1,0]
	s_waitcnt vmcnt(13)
	v_add_f32_e32 v134, v54, v55
	s_waitcnt vmcnt(12)
	v_mov_b32_e32 v135, v52
	v_add_f32_e32 v136, v56, v57
	v_mov_b32_e32 v137, v53
	v_mov_b32_e32 v139, v50
	v_add_f32_e32 v138, 0, v70
	v_mov_b32_e32 v127, v51
	v_pk_add_f32 v[130:131], v[134:135], v[136:137]
	v_pk_add_f32 v[126:127], v[138:139], v[126:127]
	s_waitcnt vmcnt(11)
	v_mov_b32_e32 v132, v47
	v_mov_b32_e32 v133, v48
	v_mov_b32_e32 v134, v46
	v_mov_b32_e32 v135, v49
	v_pk_add_f32 v[128:129], v[132:133], v[134:135]
	v_pk_add_f32 v[126:127], v[126:127], v[130:131]
	v_pk_add_f32 v[128:129], v[128:129], v[128:129] op_sel:[0,1] op_sel_hi:[1,0]
	v_pk_add_f32 v[126:127], v[126:127], v[126:127] op_sel:[0,1] op_sel_hi:[1,0]
	s_waitcnt vmcnt(10)
	v_add_f32_e32 v136, v42, v43
	s_waitcnt vmcnt(9)
	v_mov_b32_e32 v137, v40
	v_add_f32_e32 v140, v44, v45
	v_mov_b32_e32 v141, v41
	v_mov_b32_e32 v129, v39
	v_mov_b32_e32 v127, v38
	s_waitcnt vmcnt(8)
	v_mov_b32_e32 v156, v35
	v_mov_b32_e32 v157, v36
	v_mov_b32_e32 v158, v34
	v_mov_b32_e32 v159, v37
	v_pk_add_f32 v[132:133], v[136:137], v[140:141]
	v_pk_add_f32 v[126:127], v[126:127], v[128:129]
	v_pk_add_f32 v[134:135], v[156:157], v[158:159]
	v_pk_add_f32 v[126:127], v[126:127], v[132:133]
	v_pk_add_f32 v[134:135], v[134:135], v[134:135] op_sel:[0,1] op_sel_hi:[1,0]
	v_pk_add_f32 v[126:127], v[126:127], v[126:127] op_sel:[0,1] op_sel_hi:[1,0]
	s_waitcnt vmcnt(7)
	v_add_f32_e32 v160, v30, v31
	s_waitcnt vmcnt(6)
	v_mov_b32_e32 v161, v28
	v_add_f32_e32 v162, v32, v33
	v_mov_b32_e32 v163, v29
	v_mov_b32_e32 v135, v27
	v_mov_b32_e32 v127, v26
	s_waitcnt vmcnt(5)
	v_mov_b32_e32 v164, v23
	v_mov_b32_e32 v165, v24
	v_mov_b32_e32 v166, v22
	v_mov_b32_e32 v167, v25
	v_pk_add_f32 v[136:137], v[160:161], v[162:163]
	v_pk_add_f32 v[126:127], v[126:127], v[134:135]
	v_pk_add_f32 v[140:141], v[164:165], v[166:167]
	v_pk_add_f32 v[126:127], v[126:127], v[136:137]
	v_pk_add_f32 v[138:139], v[140:141], v[140:141] op_sel:[0,1] op_sel_hi:[1,0]
	v_pk_add_f32 v[126:127], v[126:127], v[126:127] op_sel:[0,1] op_sel_hi:[1,0]
	s_waitcnt vmcnt(4)
	v_add_f32_e32 v168, v18, v19
	s_waitcnt vmcnt(3)
	v_mov_b32_e32 v169, v12
	v_add_f32_e32 v170, v20, v21
	v_mov_b32_e32 v171, v13
	v_mov_b32_e32 v139, v11
	v_mov_b32_e32 v127, v10
	v_pk_add_f32 v[156:157], v[168:169], v[170:171]
	v_pk_add_f32 v[126:127], v[126:127], v[138:139]
	s_waitcnt vmcnt(2)
	v_mov_b32_e32 v128, v15
	v_mov_b32_e32 v129, v16
	v_mov_b32_e32 v130, v14
	v_mov_b32_e32 v131, v17
	v_pk_add_f32 v[126:127], v[126:127], v[156:157]
	v_pk_add_f32 v[128:129], v[128:129], v[130:131]
	v_pk_add_f32 v[126:127], v[126:127], v[126:127] op_sel:[0,1] op_sel_hi:[1,0]
	v_pk_add_f32 v[128:129], v[128:129], v[128:129] op_sel:[0,1] op_sel_hi:[1,0]
	s_waitcnt vmcnt(1)
	v_mov_b32_e32 v127, v2
	v_mov_b32_e32 v129, v3
	v_pk_add_f32 v[126:127], v[126:127], v[128:129]
	s_waitcnt vmcnt(0)
	v_add_f32_e32 v128, v6, v7
	v_mov_b32_e32 v129, v4
	v_add_f32_e32 v130, v8, v9
	v_mov_b32_e32 v131, v5
	v_pk_add_f32 v[128:129], v[128:129], v[130:131]
	global_load_dwordx4 v[156:159], v[72:73], off
	global_load_dwordx4 v[160:163], v[74:75], off
	v_pk_add_f32 v[126:127], v[126:127], v[128:129]
	v_lshlrev_b32_e32 v164, 3, v66
	v_add_f32_e32 v70, v126, v127
	s_nop 1
	v_mov_b32_dpp v126, v70 quad_perm:[1,0,3,2] row_mask:0xf bank_mask:0xf
	s_waitcnt lgkmcnt(0)
	v_add_f32_e32 v70, v70, v126
	s_nop 1
	v_mov_b32_dpp v126, v70 quad_perm:[2,3,0,1] row_mask:0xf bank_mask:0xf
	s_waitcnt lgkmcnt(0)
	v_add_f32_e32 v70, v70, v126
	s_nop 1
	v_mov_b32_dpp v126, v70 row_half_mirror row_mask:0xf bank_mask:0xf
	s_waitcnt lgkmcnt(0)
	v_add_f32_e32 v70, v70, v126
	s_nop 1
	v_mov_b32_dpp v126, v70 row_mirror row_mask:0xf bank_mask:0xf
	s_waitcnt lgkmcnt(0)
	v_add_f32_e32 v70, v70, v126
	v_mov_b32_e32 v126, v70
	s_nop 1
	v_permlane16_swap_b32_e32 v126, v70
	s_waitcnt lgkmcnt(0)
	v_add_f32_e32 v70, v70, v126
	v_mov_b32_e32 v126, v70
	s_nop 1
	v_permlane32_swap_b32_e32 v126, v70
	s_waitcnt lgkmcnt(0)
; __device__ __forceinline__ void ln_row_in(const float* src, const float* g, const float* b, bf16* dstb, signed char* dstq, float* rowinv, int lane) {
;     ...
;     const float mean = wave_sum(s) * (1.f / 4096.f); float s2 = 0.f;
; #pragma unroll
;     for (int j = 0; j < 16; ++j) { v[j] = v[j] - mean; s2 += (v[j].x * v[j].x + v[j].y * v[j].y) + (v[j].z * v[j].z + v[j].w * v[j].w); }
;     const float rstd = 1.f / sqrtf(wave_sum(s2) * (1.f / 4096.f) + 1e-5f);
	v_add_f32_e32 v70, v70, v126
	v_fmamk_f32 v141, v70, 0xb9800000, v59
	v_fmamk_f32 v140, v70, 0xb9800000, v58
	v_fmamk_f32 v61, v70, 0xb9800000, v61
	v_fmac_f32_e32 v60, 0xb9800000, v70
	v_fmamk_f32 v135, v70, 0xb9800000, v63
	v_fmamk_f32 v134, v70, 0xb9800000, v62
	v_fmamk_f32 v65, v70, 0xb9800000, v65
	v_fmac_f32_e32 v64, 0xb9800000, v70
	v_pk_mul_f32 v[58:59], v[60:61], v[60:61]
	v_pk_mul_f32 v[62:63], v[140:141], v[140:141]
	v_fmamk_f32 v136, v70, 0xb9800000, v54
	v_pk_mul_f32 v[126:127], v[64:65], v[64:65]
	v_pk_mul_f32 v[128:129], v[134:135], v[134:135]
	v_pk_mov_b32 v[130:131], v[62:63], v[58:59] op_sel:[1,0]
	v_mov_b32_e32 v63, v59
	v_fmamk_f32 v137, v70, 0xb9800000, v55
	v_mul_f32_e32 v54, v136, v136
	v_pk_add_f32 v[58:59], v[130:131], v[62:63]
	v_pk_mov_b32 v[62:63], v[128:129], v[126:127] op_sel:[1,0]
	v_mov_b32_e32 v129, v127
	v_fmac_f32_e32 v56, 0xb9800000, v70
	v_pk_fma_f32 v[54:55], v[136:137], v[136:137], v[54:55] op_sel_hi:[1,1,0]
	v_pk_add_f32 v[62:63], v[62:63], v[128:129]
	v_fmamk_f32 v57, v70, 0xb9800000, v57
	v_mul_f32_e32 v54, v56, v56
	v_pk_fma_f32 v[126:127], v[56:57], v[56:57], v[54:55] op_sel_hi:[1,1,0]
	v_fmamk_f32 v51, v70, 0xb9800000, v51
	v_fmac_f32_e32 v50, 0xb9800000, v70
	v_pk_add_f32 v[58:59], v[58:59], v[58:59] op_sel_hi:[0,1]
	v_pk_add_f32 v[62:63], v[62:63], v[62:63] op_sel_hi:[0,1]
	v_fmamk_f32 v139, v70, 0xb9800000, v53
	v_fmamk_f32 v138, v70, 0xb9800000, v52
	v_mul_f32_e32 v54, v50, v50
	v_mul_f32_e32 v126, v51, v51
	v_mul_f32_e32 v58, v138, v138
	v_mul_f32_e32 v62, v139, v139
	v_pk_add_f32 v[54:55], v[54:55], v[126:127]
	v_pk_add_f32 v[52:53], v[58:59], v[62:63]
	v_fmamk_f32 v133, v70, 0xb9800000, v47
	v_fmamk_f32 v132, v70, 0xb9800000, v46
	v_fmamk_f32 v49, v70, 0xb9800000, v49
	v_fmac_f32_e32 v48, 0xb9800000, v70
	v_pk_add_f32 v[52:53], v[54:55], v[52:53]
	v_pk_mul_f32 v[46:47], v[48:49], v[48:49]
	v_pk_mul_f32 v[54:55], v[132:133], v[132:133]
	v_fmamk_f32 v42, v70, 0xb9800000, v42
	v_pk_mov_b32 v[58:59], v[54:55], v[46:47] op_sel:[1,0]
	v_mov_b32_e32 v55, v47
	v_pk_add_f32 v[46:47], v[58:59], v[54:55]
	v_fmamk_f32 v43, v70, 0xb9800000, v43
	v_mul_f32_e32 v54, v42, v42
	v_fmac_f32_e32 v44, 0xb9800000, v70
	v_pk_fma_f32 v[54:55], v[42:43], v[42:43], v[54:55] op_sel_hi:[1,1,0]
	v_fmamk_f32 v45, v70, 0xb9800000, v45
	v_mul_f32_e32 v54, v44, v44
	v_pk_add_f32 v[52:53], v[52:53], v[52:53] op_sel_hi:[0,1]
	v_pk_add_f32 v[46:47], v[46:47], v[46:47] op_sel_hi:[0,1]
	v_fmamk_f32 v131, v70, 0xb9800000, v41
	v_fmamk_f32 v130, v70, 0xb9800000, v40
	v_pk_fma_f32 v[58:59], v[44:45], v[44:45], v[54:55] op_sel_hi:[1,1,0]
	v_fmamk_f32 v39, v70, 0xb9800000, v39
	v_fmac_f32_e32 v38, 0xb9800000, v70
	v_mul_f32_e32 v46, v130, v130
	v_mul_f32_e32 v52, v131, v131
	v_fmamk_f32 v127, v70, 0xb9800000, v35
	v_fmamk_f32 v126, v70, 0xb9800000, v34
	v_fmamk_f32 v37, v70, 0xb9800000, v37
	v_fmac_f32_e32 v36, 0xb9800000, v70
	v_fmamk_f32 v62, v70, 0xb9800000, v30
	v_mul_f32_e32 v54, v38, v38
	v_mul_f32_e32 v58, v39, v39
	v_pk_add_f32 v[40:41], v[46:47], v[52:53]
	v_pk_mul_f32 v[34:35], v[36:37], v[36:37]
	v_pk_mul_f32 v[46:47], v[126:127], v[126:127]
	v_fmamk_f32 v63, v70, 0xb9800000, v31
	v_mul_f32_e32 v30, v62, v62
	v_pk_add_f32 v[54:55], v[54:55], v[58:59]
	v_pk_mov_b32 v[52:53], v[46:47], v[34:35] op_sel:[1,0]
	v_mov_b32_e32 v47, v35
	v_fmac_f32_e32 v32, 0xb9800000, v70
	v_pk_fma_f32 v[30:31], v[62:63], v[62:63], v[30:31] op_sel_hi:[1,1,0]
	v_pk_add_f32 v[40:41], v[54:55], v[40:41]
	v_pk_add_f32 v[34:35], v[52:53], v[46:47]
	v_fmamk_f32 v33, v70, 0xb9800000, v33
	v_mul_f32_e32 v30, v32, v32
	v_pk_fma_f32 v[46:47], v[32:33], v[32:33], v[30:31] op_sel_hi:[1,1,0]
	v_fmamk_f32 v27, v70, 0xb9800000, v27
	v_fmac_f32_e32 v26, 0xb9800000, v70
	v_pk_add_f32 v[40:41], v[40:41], v[40:41] op_sel_hi:[0,1]
	v_pk_add_f32 v[34:35], v[34:35], v[34:35] op_sel_hi:[0,1]
	v_fmamk_f32 v129, v70, 0xb9800000, v29
	v_fmamk_f32 v128, v70, 0xb9800000, v28
	v_mul_f32_e32 v30, v26, v26
	v_mul_f32_e32 v46, v27, v27
	v_mul_f32_e32 v34, v128, v128
	v_mul_f32_e32 v40, v129, v129
	v_pk_add_f32 v[30:31], v[30:31], v[46:47]
	v_pk_add_f32 v[28:29], v[34:35], v[40:41]
	v_fmamk_f32 v59, v70, 0xb9800000, v23
	v_fmamk_f32 v58, v70, 0xb9800000, v22
	v_fmamk_f32 v25, v70, 0xb9800000, v25
	v_fmac_f32_e32 v24, 0xb9800000, v70
	v_fmamk_f32 v52, v70, 0xb9800000, v18
	v_pk_add_f32 v[28:29], v[30:31], v[28:29]
	v_pk_mul_f32 v[22:23], v[24:25], v[24:25]
	v_pk_mul_f32 v[30:31], v[58:59], v[58:59]
	v_fmamk_f32 v53, v70, 0xb9800000, v19
	v_mul_f32_e32 v18, v52, v52
	v_pk_mov_b32 v[34:35], v[30:31], v[22:23] op_sel:[1,0]
	v_mov_b32_e32 v31, v23
	v_fmac_f32_e32 v20, 0xb9800000, v70
	v_pk_fma_f32 v[18:19], v[52:53], v[52:53], v[18:19] op_sel_hi:[1,1,0]
	v_pk_add_f32 v[22:23], v[34:35], v[30:31]
	v_fmamk_f32 v21, v70, 0xb9800000, v21
	v_mul_f32_e32 v18, v20, v20
	v_pk_fma_f32 v[30:31], v[20:21], v[20:21], v[18:19] op_sel_hi:[1,1,0]
	v_fmamk_f32 v11, v70, 0xb9800000, v11
	v_fmac_f32_e32 v10, 0xb9800000, v70
	v_pk_add_f32 v[28:29], v[28:29], v[28:29] op_sel_hi:[0,1]
	v_pk_add_f32 v[22:23], v[22:23], v[22:23] op_sel_hi:[0,1]
	v_fmamk_f32 v55, v70, 0xb9800000, v13
	v_fmamk_f32 v54, v70, 0xb9800000, v12
	v_mul_f32_e32 v18, v10, v10
	v_mul_f32_e32 v30, v11, v11
	v_mul_f32_e32 v22, v54, v54
	v_mul_f32_e32 v28, v55, v55
	v_pk_add_f32 v[18:19], v[18:19], v[30:31]
	v_pk_add_f32 v[12:13], v[22:23], v[28:29]
	v_fmamk_f32 v47, v70, 0xb9800000, v15
	v_fmamk_f32 v46, v70, 0xb9800000, v14
	v_fmamk_f32 v17, v70, 0xb9800000, v17
	v_fmac_f32_e32 v16, 0xb9800000, v70
	v_pk_add_f32 v[12:13], v[18:19], v[12:13]
	v_pk_mul_f32 v[14:15], v[16:17], v[16:17]
	v_pk_mul_f32 v[18:19], v[46:47], v[46:47]
	v_fmac_f32_e32 v8, 0xb9800000, v70
	v_pk_mov_b32 v[22:23], v[18:19], v[14:15] op_sel:[1,0]
	v_fmamk_f32 v14, v70, 0xb9800000, v6
	v_mov_b32_e32 v19, v15
	v_fmamk_f32 v15, v70, 0xb9800000, v7
	v_mul_f32_e32 v6, v14, v14
	v_pk_fma_f32 v[6:7], v[14:15], v[14:15], v[6:7] op_sel_hi:[1,1,0]
	v_pk_add_f32 v[18:19], v[22:23], v[18:19]
	v_fmamk_f32 v9, v70, 0xb9800000, v9
	v_mul_f32_e32 v6, v8, v8
	v_pk_fma_f32 v[22:23], v[8:9], v[8:9], v[6:7] op_sel_hi:[1,1,0]
	v_fmamk_f32 v3, v70, 0xb9800000, v3
	v_fmac_f32_e32 v2, 0xb9800000, v70
	v_fmamk_f32 v29, v70, 0xb9800000, v5
	v_fmamk_f32 v28, v70, 0xb9800000, v4
	v_pk_add_f32 v[4:5], v[12:13], v[12:13] op_sel_hi:[0,1]
	v_pk_add_f32 v[12:13], v[18:19], v[18:19] op_sel_hi:[0,1]
	v_mul_f32_e32 v6, v2, v2
	v_mul_f32_e32 v22, v3, v3
	v_mul_f32_e32 v12, v28, v28
	v_mul_f32_e32 v4, v29, v29
	v_pk_add_f32 v[6:7], v[6:7], v[22:23]
	v_pk_add_f32 v[4:5], v[12:13], v[4:5]
	s_nop 0
	v_pk_add_f32 v[4:5], v[6:7], v[4:5]
	s_nop 0
	v_add_f32_e32 v4, v4, v5
	s_nop 1
	v_mov_b32_dpp v5, v4 quad_perm:[1,0,3,2] row_mask:0xf bank_mask:0xf
	s_waitcnt lgkmcnt(0)
; __device__ __forceinline__ unsigned pkh(float a, float b) { const f2v_t f = {a, b}; const h2v_t h = __builtin_convertvector(f, h2v_t); return __builtin_bit_cast(unsigned, h); }
; __device__ __forceinline__ void ln_row_in(const float* src, const float* g, const float* b, bf16* dstb, signed char* dstq, float* rowinv, int lane) {
;     ...
;     const float rstd = 1.f / sqrtf(wave_sum(s2) * (1.f / 4096.f) + 1e-5f);
; #pragma unroll
;     for (int j = 0; j < 16; ++j) {
;         const f32x4 gg = ((const f32x4*)g)[64 * j + lane], bb = ((const f32x4*)b)[64 * j + lane];
;         v[j] = v[j] * rstd * gg + bb;
;         v2u w; w.x = pg8::pkh(v[j].x, v[j].y); w.y = pg8::pkh(v[j].z, v[j].w); ((v2u*)dstb)[64 * j + lane] = w;
;     }
	v_add_f32_e32 v4, v4, v5
	s_nop 1
	v_mov_b32_dpp v5, v4 quad_perm:[2,3,0,1] row_mask:0xf bank_mask:0xf
	s_waitcnt lgkmcnt(0)
	v_add_f32_e32 v4, v4, v5
	s_nop 1
	v_mov_b32_dpp v5, v4 row_half_mirror row_mask:0xf bank_mask:0xf
	s_waitcnt lgkmcnt(0)
	v_add_f32_e32 v4, v4, v5
	s_nop 1
	v_mov_b32_dpp v5, v4 row_mirror row_mask:0xf bank_mask:0xf
	s_waitcnt lgkmcnt(0)
	v_add_f32_e32 v4, v4, v5
	v_mov_b32_e32 v5, v4
	s_nop 1
	v_permlane16_swap_b32_e32 v5, v4
	s_waitcnt lgkmcnt(0)
	v_add_f32_e32 v4, v4, v5
	v_mov_b32_e32 v5, v4
	s_nop 1
	v_permlane32_swap_b32_e32 v5, v4
	s_waitcnt lgkmcnt(0)
	v_add_f32_e32 v4, v4, v5
	v_fmamk_f32 v4, v4, 0x39800000, v69
	v_mul_f32_e32 v5, 0x4f800000, v4
	v_cmp_gt_f32_e32 vcc, s41, v4
	s_nop 1
	v_cndmask_b32_e32 v4, v4, v5, vcc
	v_sqrt_f32_e32 v5, v4
	s_nop 0
	v_add_u32_e32 v6, -1, v5
	v_fma_f32 v7, -v6, v5, v4
	v_cmp_ge_f32_e64 s[6:7], 0, v7
	v_add_u32_e32 v7, 1, v5
	s_nop 0
	v_cndmask_b32_e64 v6, v5, v6, s[6:7]
	v_fma_f32 v5, -v7, v5, v4
	v_cmp_lt_f32_e64 s[6:7], 0, v5
	s_nop 1
	v_cndmask_b32_e64 v5, v6, v7, s[6:7]
	v_mul_f32_e32 v6, 0x37800000, v5
	v_cndmask_b32_e32 v5, v5, v6, vcc
	v_cmp_class_f32_e32 vcc, v4, v155
	s_nop 1
	v_cndmask_b32_e32 v4, v5, v4, vcc
	v_div_scale_f32 v5, s[6:7], v4, v4, 1.0
	v_rcp_f32_e32 v6, v5
	s_lshl_b64 s[6:7], s[8:9], 13
	s_add_u32 s6, s3, s6
	s_addc_u32 s7, s24, s7
	v_fma_f32 v7, -v5, v6, 1.0
	v_fmac_f32_e32 v6, v7, v6
	v_div_scale_f32 v7, vcc, 1.0, v4, 1.0
	v_mul_f32_e32 v12, v7, v6
	v_fma_f32 v13, -v5, v12, v7
	v_fmac_f32_e32 v12, v13, v6
	v_fma_f32 v5, -v5, v12, v7
	v_div_fmas_f32 v5, v5, v6, v12
	v_div_fixup_f32 v70, v5, v4, 1.0
	v_pk_mul_f32 v[4:5], v[60:61], v[70:71] op_sel_hi:[1,0]
	v_pk_mul_f32 v[6:7], v[140:141], v[70:71] op_sel_hi:[1,0]
	s_waitcnt vmcnt(0)
	v_pk_fma_f32 v[4:5], v[158:159], v[4:5], v[162:163]
	v_pk_fma_f32 v[18:19], v[156:157], v[6:7], v[160:161]
	v_cvt_pk_f16_f32 v7, v4, v5
	v_cvt_pk_f16_f32 v6, v18, v19
	global_store_dwordx2 v164, v[6:7], s[6:7]
	global_load_dwordx4 v[156:159], v[72:73], off offset:1024
	global_load_dwordx4 v[160:163], v[74:75], off offset:1024
	v_pk_mul_f32 v[6:7], v[64:65], v[70:71] op_sel_hi:[1,0]
	v_pk_mul_f32 v[12:13], v[134:135], v[70:71] op_sel_hi:[1,0]
	v_pk_mul_f32 v[22:23], v[136:137], v[70:71] op_sel_hi:[1,0]
	v_pk_mul_f32 v[30:31], v[50:51], v[70:71] op_sel_hi:[1,0]
	v_pk_mul_f32 v[44:45], v[44:45], v[70:71] op_sel_hi:[1,0]
	v_pk_mul_f32 v[36:37], v[36:37], v[70:71] op_sel_hi:[1,0]
	v_pk_mul_f32 v[32:33], v[32:33], v[70:71] op_sel_hi:[1,0]
	v_pk_mul_f32 v[62:63], v[62:63], v[70:71] op_sel_hi:[1,0]
	v_pk_mul_f32 v[24:25], v[24:25], v[70:71] op_sel_hi:[1,0]
	v_pk_mul_f32 v[58:59], v[58:59], v[70:71] op_sel_hi:[1,0]
	v_pk_mul_f32 v[20:21], v[20:21], v[70:71] op_sel_hi:[1,0]
	v_pk_mul_f32 v[52:53], v[52:53], v[70:71] op_sel_hi:[1,0]
	v_pk_mul_f32 v[16:17], v[16:17], v[70:71] op_sel_hi:[1,0]
	v_pk_mul_f32 v[46:47], v[46:47], v[70:71] op_sel_hi:[1,0]
	v_pk_mul_f32 v[8:9], v[8:9], v[70:71] op_sel_hi:[1,0]
	v_pk_mul_f32 v[14:15], v[14:15], v[70:71] op_sel_hi:[1,0]
	s_waitcnt vmcnt(0)
	v_pk_fma_f32 v[6:7], v[158:159], v[6:7], v[162:163]
	v_pk_fma_f32 v[34:35], v[156:157], v[12:13], v[160:161]
	v_cvt_pk_f16_f32 v13, v6, v7
	v_cvt_pk_f16_f32 v12, v34, v35
	global_store_dwordx2 v164, v[12:13], s[6:7] offset:512
	global_load_dwordx4 v[156:159], v[72:73], off offset:2048
	global_load_dwordx4 v[160:163], v[74:75], off offset:2048
	v_pk_mul_f32 v[12:13], v[56:57], v[70:71] op_sel_hi:[1,0]
	s_waitcnt vmcnt(0)
	v_pk_fma_f32 v[40:41], v[156:157], v[22:23], v[160:161]
	v_pk_fma_f32 v[12:13], v[158:159], v[12:13], v[162:163]
	v_cvt_pk_f16_f32 v22, v40, v41
	v_cvt_pk_f16_f32 v23, v12, v13
	global_store_dwordx2 v164, v[22:23], s[6:7] offset:1024
	global_load_dwordx4 v[134:137], v[72:73], off offset:3072
	global_load_dwordx4 v[156:159], v[74:75], off offset:3072
	v_pk_mul_f32 v[22:23], v[138:139], v[70:71] op_sel_hi:[1,0]
	s_waitcnt vmcnt(0)
	v_pk_fma_f32 v[50:51], v[134:135], v[30:31], v[156:157]
	v_pk_fma_f32 v[22:23], v[136:137], v[22:23], v[158:159]
	v_cvt_pk_f16_f32 v30, v50, v51
	v_cvt_pk_f16_f32 v31, v22, v23
	global_store_dwordx2 v164, v[30:31], s[6:7] offset:1536
	global_load_dwordx4 v[134:137], v[108:109], off
	global_load_dwordx4 v[138:141], v[110:111], off
	v_pk_mul_f32 v[30:31], v[48:49], v[70:71] op_sel_hi:[1,0]
	v_pk_mul_f32 v[48:49], v[132:133], v[70:71] op_sel_hi:[1,0]
	s_waitcnt vmcnt(0)
	v_pk_fma_f32 v[30:31], v[136:137], v[30:31], v[140:141]
	v_pk_fma_f32 v[48:49], v[134:135], v[48:49], v[138:139]
	v_cvt_pk_f16_f32 v57, v30, v31
	v_cvt_pk_f16_f32 v56, v48, v49
	global_store_dwordx2 v164, v[56:57], s[6:7] offset:2048
	global_load_dwordx4 v[132:135], v[112:113], off
	global_load_dwordx4 v[136:139], v[114:115], off
	v_pk_mul_f32 v[56:57], v[42:43], v[70:71] op_sel_hi:[1,0]
	s_waitcnt vmcnt(0)
	v_pk_fma_f32 v[42:43], v[134:135], v[44:45], v[138:139]
	v_pk_fma_f32 v[44:45], v[132:133], v[56:57], v[136:137]
	v_cvt_pk_f16_f32 v57, v42, v43
	v_cvt_pk_f16_f32 v56, v44, v45
	global_store_dwordx2 v164, v[56:57], s[6:7] offset:2560
	global_load_dwordx4 v[132:135], v[116:117], off
	global_load_dwordx4 v[136:139], v[118:119], off
	v_pk_mul_f32 v[56:57], v[38:39], v[70:71] op_sel_hi:[1,0]
	v_pk_mul_f32 v[38:39], v[130:131], v[70:71] op_sel_hi:[1,0]
	s_waitcnt vmcnt(0)
	v_pk_fma_f32 v[56:57], v[132:133], v[56:57], v[136:137]
	v_pk_fma_f32 v[38:39], v[134:135], v[38:39], v[138:139]
	v_cvt_pk_f16_f32 v60, v56, v57
	v_cvt_pk_f16_f32 v61, v38, v39
	global_store_dwordx2 v164, v[60:61], s[6:7] offset:3072
	global_load_dwordx4 v[130:133], v[76:77], off
	global_load_dwordx4 v[134:137], v[78:79], off
	v_pk_mul_f32 v[60:61], v[126:127], v[70:71] op_sel_hi:[1,0]
	s_waitcnt vmcnt(0)
; __device__ __forceinline__ unsigned pkh(float a, float b) { const f2v_t f = {a, b}; const h2v_t h = __builtin_convertvector(f, h2v_t); return __builtin_bit_cast(unsigned, h); }
; template <bool PAIR> __device__ __forceinline__ void row_quant(const f32x4 (&v)[16], signed char* dstq, float* rowinv, int lane) {
;     float mx = 0.f;
; #pragma unroll
;     for (int j = 0; j < 16; ++j) mx = fmaxf(fmaxf(mx, fmaxf(fabsf(v[j].x), fabsf(v[j].y))), fmaxf(fabsf(v[j].z), fabsf(v[j].w)));
; #pragma unroll
;     for (int o = 1; o < 64; o <<= 1) mx = fmaxf(mx, __shfl_xor(mx, o));
;     mx = fmaxf(mx, 1e-20f);
;     const float sc = 127.0f / mx;
;     if (lane == 0) *rowinv = mx * (1.0f / 127.0f);
;     unsigned w[16];
; #pragma unroll
;     for (int j = 0; j < 16; ++j) w[j] = ((unsigned)(int)rintf(v[j].x * sc) & 0xffu) | (((unsigned)(int)rintf(v[j].y * sc) & 0xffu) << 8) | (((unsigned)(int)rintf(v[j].z * sc) & 0xffu) << 16) | (((unsigned)(int)rintf(v[j].w * sc) & 0xffu) << 24);
;     if (PAIR) {
; #pragma unroll
;         for (int j = 0; j < 8; ++j) ((v2u*)dstq)[64 * j + lane] = (v2u){w[2 * j], w[2 * j + 1]};
;     } else {
; #pragma unroll
;         for (int j = 0; j < 16; ++j) ((unsigned*)dstq)[64 * j + lane] = w[j];
;     }
; }
; __device__ __forceinline__ void ln_row_in(const float* src, const float* g, const float* b, bf16* dstb, signed char* dstq, float* rowinv, int lane) {
;     ...
;     for (int j = 0; j < 16; ++j) {
;         const f32x4 gg = ((const f32x4*)g)[64 * j + lane], bb = ((const f32x4*)b)[64 * j + lane];
;         v[j] = v[j] * rstd * gg + bb;
;         v2u w; w.x = pg8::pkh(v[j].x, v[j].y); w.y = pg8::pkh(v[j].z, v[j].w); ((v2u*)dstb)[64 * j + lane] = w;
;     }
	v_pk_fma_f32 v[36:37], v[132:133], v[36:37], v[136:137]
	v_pk_fma_f32 v[60:61], v[130:131], v[60:61], v[134:135]
	v_cvt_pk_f16_f32 v65, v36, v37
	v_cvt_pk_f16_f32 v64, v60, v61
	global_store_dwordx2 v164, v[64:65], s[6:7] offset:3584
	global_load_dwordx4 v[130:133], v[80:81], off
	global_load_dwordx4 v[134:137], v[82:83], off
	s_waitcnt vmcnt(0)
	v_pk_fma_f32 v[32:33], v[132:133], v[32:33], v[136:137]
	v_pk_fma_f32 v[62:63], v[130:131], v[62:63], v[134:135]
	v_cvt_pk_f16_f32 v65, v32, v33
	v_cvt_pk_f16_f32 v64, v62, v63
	global_store_dwordx2 v67, v[64:65], s[6:7]
	global_load_dwordx4 v[130:133], v[84:85], off
	global_load_dwordx4 v[134:137], v[86:87], off
	v_pk_mul_f32 v[64:65], v[26:27], v[70:71] op_sel_hi:[1,0]
	v_pk_mul_f32 v[26:27], v[128:129], v[70:71] op_sel_hi:[1,0]
	s_waitcnt vmcnt(0)
	v_pk_fma_f32 v[64:65], v[130:131], v[64:65], v[134:135]
	v_pk_fma_f32 v[26:27], v[132:133], v[26:27], v[136:137]
	v_cvt_pk_f16_f32 v126, v64, v65
	v_cvt_pk_f16_f32 v127, v26, v27
	global_store_dwordx2 v142, v[126:127], s[6:7]
	global_load_dwordx4 v[126:129], v[88:89], off
	s_nop 0
	global_load_dwordx4 v[130:133], v[90:91], off
	v_pk_mul_f32 v[134:135], v[10:11], v[70:71] op_sel_hi:[1,0]
	v_pk_mul_f32 v[10:11], v[54:55], v[70:71] op_sel_hi:[1,0]
	s_waitcnt vmcnt(0)
	v_pk_fma_f32 v[24:25], v[128:129], v[24:25], v[132:133]
	v_pk_fma_f32 v[58:59], v[126:127], v[58:59], v[130:131]
	v_cvt_pk_f16_f32 v127, v24, v25
	v_cvt_pk_f16_f32 v126, v58, v59
	global_store_dwordx2 v143, v[126:127], s[6:7]
	global_load_dwordx4 v[126:129], v[92:93], off
	s_nop 0
	global_load_dwordx4 v[130:133], v[94:95], off
	s_waitcnt vmcnt(0)
	v_pk_fma_f32 v[20:21], v[20:21], v[128:129], v[132:133]
	v_pk_fma_f32 v[52:53], v[52:53], v[126:127], v[130:131]
	v_cvt_pk_f16_f32 v127, v20, v21
	v_cvt_pk_f16_f32 v126, v52, v53
	global_store_dwordx2 v144, v[126:127], s[6:7]
	global_load_dwordx4 v[126:129], v[96:97], off
	s_nop 0
	global_load_dwordx4 v[130:133], v[98:99], off
	s_waitcnt vmcnt(0)
	v_pk_fma_f32 v[10:11], v[10:11], v[128:129], v[132:133]
	v_pk_fma_f32 v[54:55], v[134:135], v[126:127], v[130:131]
	v_cvt_pk_f16_f32 v127, v10, v11
	v_cvt_pk_f16_f32 v126, v54, v55
	global_store_dwordx2 v145, v[126:127], s[6:7]
	global_load_dwordx4 v[126:129], v[100:101], off
	s_nop 0
	global_load_dwordx4 v[130:133], v[102:103], off
	v_pk_mul_f32 v[134:135], v[2:3], v[70:71] op_sel_hi:[1,0]
	v_pk_mul_f32 v[2:3], v[28:29], v[70:71] op_sel_hi:[1,0]
	v_max_f32_e64 v28, |v18|, |v19|
	v_max_f32_e64 v29, |v4|, |v5|
	v_max3_f32 v28, v28, 0, v29
	v_max_f32_e64 v29, |v34|, |v35|
	v_max_f32_e64 v70, |v6|, |v7|
	v_max3_f32 v28, v28, v29, v70
	v_max_f32_e64 v29, |v40|, |v41|
	v_max_f32_e64 v70, |v12|, |v13|
	v_max3_f32 v28, v28, v29, v70
	v_max_f32_e64 v29, |v50|, |v51|
	v_max_f32_e64 v70, |v22|, |v23|
	v_max3_f32 v28, v28, v29, v70
	v_max_f32_e64 v29, |v48|, |v49|
	v_max_f32_e64 v70, |v30|, |v31|
	v_max3_f32 v28, v28, v29, v70
	v_max_f32_e64 v29, |v44|, |v45|
	v_max_f32_e64 v70, |v42|, |v43|
	v_max3_f32 v28, v28, v29, v70
	v_max_f32_e64 v29, |v56|, |v57|
	v_max_f32_e64 v70, |v38|, |v39|
	v_max3_f32 v28, v28, v29, v70
	v_max_f32_e64 v29, |v60|, |v61|
	v_max_f32_e64 v70, |v36|, |v37|
	v_max3_f32 v28, v28, v29, v70
	v_max_f32_e64 v29, |v62|, |v63|
	v_max_f32_e64 v70, |v32|, |v33|
	v_max3_f32 v28, v28, v29, v70
	v_max_f32_e64 v29, |v64|, |v65|
	v_max_f32_e64 v70, |v26|, |v27|
	v_max3_f32 v28, v28, v29, v70
	v_max_f32_e64 v29, |v58|, |v59|
	v_max_f32_e64 v70, |v24|, |v25|
	v_max3_f32 v28, v28, v29, v70
	v_max_f32_e64 v29, |v52|, |v53|
	v_max_f32_e64 v70, |v20|, |v21|
	v_max3_f32 v28, v28, v29, v70
	v_max_f32_e64 v29, |v54|, |v55|
	v_max_f32_e64 v70, |v10|, |v11|
	v_max3_f32 v28, v28, v29, v70
	s_waitcnt vmcnt(0)
	v_pk_fma_f32 v[16:17], v[16:17], v[128:129], v[132:133]
	v_pk_fma_f32 v[46:47], v[46:47], v[126:127], v[130:131]
	v_cvt_pk_f16_f32 v127, v16, v17
	v_cvt_pk_f16_f32 v126, v46, v47
	global_store_dwordx2 v146, v[126:127], s[6:7]
	global_load_dwordx4 v[126:129], v[104:105], off
	s_nop 0
	global_load_dwordx4 v[130:133], v[106:107], off
	v_max_f32_e64 v29, |v46|, |v47|
	v_max_f32_e64 v70, |v16|, |v17|
	v_max3_f32 v28, v28, v29, v70
	s_waitcnt vmcnt(0)
	v_pk_fma_f32 v[8:9], v[8:9], v[128:129], v[132:133]
	v_pk_fma_f32 v[14:15], v[14:15], v[126:127], v[130:131]
	v_cvt_pk_f16_f32 v127, v8, v9
	v_cvt_pk_f16_f32 v126, v14, v15
	global_store_dwordx2 v147, v[126:127], s[6:7]
	global_load_dwordx4 v[126:129], v[122:123], off
	s_nop 0
	global_load_dwordx4 v[130:133], v[124:125], off
	v_max_f32_e64 v29, |v14|, |v15|
	v_max_f32_e64 v70, |v8|, |v9|
	v_max3_f32 v70, v28, v29, v70
	s_waitcnt vmcnt(0)
	v_pk_fma_f32 v[2:3], v[2:3], v[128:129], v[132:133]
	v_pk_fma_f32 v[28:29], v[134:135], v[126:127], v[130:131]
	v_max_f32_e64 v127, |v2|, |v3|
	v_max_f32_e64 v126, |v28|, |v29|
	v_max3_f32 v70, v70, v126, v127
	s_nop 1
	v_mov_b32_dpp v126, v70 quad_perm:[1,0,3,2] row_mask:0xf bank_mask:0xf
	v_cvt_pk_f16_f32 v127, v2, v3
	s_waitcnt lgkmcnt(0)
	v_max_f32_e32 v126, v126, v126
	v_max_f32_e32 v70, v70, v126
	s_nop 1
	v_mov_b32_dpp v126, v70 quad_perm:[2,3,0,1] row_mask:0xf bank_mask:0xf
	s_waitcnt lgkmcnt(0)
	v_max_f32_e32 v126, v126, v126
	v_max_f32_e32 v70, v70, v126
	s_nop 1
	v_mov_b32_dpp v126, v70 row_half_mirror row_mask:0xf bank_mask:0xf
	s_waitcnt lgkmcnt(0)
	v_max_f32_e32 v126, v126, v126
	v_max_f32_e32 v70, v70, v126
	s_nop 1
	v_mov_b32_dpp v126, v70 row_mirror row_mask:0xf bank_mask:0xf
	s_waitcnt lgkmcnt(0)
	v_max_f32_e32 v126, v126, v126
	v_max_f32_e32 v70, v70, v126
	v_mov_b32_e32 v126, v70
	s_nop 1
	v_permlane16_swap_b32_e32 v126, v70
	s_waitcnt lgkmcnt(0)
	v_max_f32_e32 v126, v126, v126
	v_max_f32_e32 v70, v70, v126
	v_mov_b32_e32 v128, v70
	s_nop 1
	v_permlane32_swap_b32_e32 v128, v70
	v_cvt_pk_f16_f32 v126, v28, v29
	global_store_dwordx2 v148, v[126:127], s[6:7]
	s_waitcnt lgkmcnt(0)
	v_max3_f32 v70, v70, v128, s42
	s_and_saveexec_b64 s[6:7], s[4:5]
	s_cbranch_execz .LBB0_16
	s_lshl_b64 s[10:11], s[8:9], 2
	s_add_u32 s10, s33, s10
	v_mul_f32_e32 v126, 0x3c010204, v70
	s_addc_u32 s11, s38, s11
	global_store_dword v71, v126, s[10:11]
	s_branch .LBB0_16

; __device__ __forceinline__ int row_perm(int m) { const int j = m >> 11, r = m & 2047; return (11 - 3 * (j & 3) - (j >> 2)) * 2048 + r; }
; __device__ __forceinline__ kaptr ka_fresh() { kaptr p = (kaptr)__builtin_amdgcn_kernarg_segment_ptr(); asm volatile("" : "+s"(p)); return p; }
; #define KA_IN(ka, i) (*(const float* const __attribute__((address_space(4)))*)((ka) + 8 * (i)))
; #define KA_WS(ka) (*(unsigned char* const __attribute__((address_space(4)))*)((ka) + 216))
; #define PHASE_IDS() int vcu = vcu0, G = G0; asm volatile("" : "+s"(vcu), "+s"(G)); const int ngw = G * NWAVES; (void)ngw; int tid = tid0; asm volatile("" : "+v"(tid)); const int lane = tid & 63, wave = __builtin_amdgcn_readfirstlane(tid >> 6), gw = vcu * NWAVES + wave; (void)lane; (void)gw
; __device__ __forceinline__ void ln_row_qb(const v4u (&src)[8], const float* g, const float* b, signed char* dstq, float* rowinv, float* stat, int lane) {
;     ...
;     for (int j = 0; j < 16; ++j) {
;         const int q = 2 * (64 * (j >> 1) + lane) + (j & 1);
;         const f32x4 gg = ((const f32x4*)g)[q], bb = ((const f32x4*)b)[q];
;         v[j] = v[j] * rstd * gg + bb;
; __global__ void __launch_bounds__(NT, 2) fwd_kernel(Args args_unused) {
;     ...
;         if (IN(P + 5)) {
;             PHASE_IDS(); kaptr ka = ka_fresh(); unsigned char* ws = KA_WS(ka);
;             for (int m0 = gw; m0 < MTOK; m0 += 2 * ngw) { const int mA = row_perm(m0), mB = row_perm(m0 + ngw < MTOK ? m0 + ngw : m0); const bool hasB = m0 + ngw < MTOK;
;                 v4u rawA[8], rawB[8]; ln_fetch_b(WSP(const bf16, WS_XR) + (size_t)mA * DM, rawA, lane); ln_fetch_b(WSP(const bf16, WS_XR) + (size_t)mB * DM, rawB, lane);
;                 { const int m = mA; ln_row_qb(rawA, KA_IN(ka, 20) + l * DM, KA_IN(ka, 21) + l * DM, WSP(signed char, WS_XB) + (size_t)m * DM, WSP(float, WS_ROWINV) + m, WSP(float, WS_STATS) + 2 * m, lane); }
;                 if (hasB) { const int m = mB; ln_row_qb(rawB, KA_IN(ka, 20) + l * DM, KA_IN(ka, 21) + l * DM, WSP(signed char, WS_XB) + (size_t)m * DM, WSP(float, WS_ROWINV) + m, WSP(float, WS_STATS) + 2 * m, lane); } }
.LBB0_977:
	v_readlane_b32 s4, v252, 6
	v_readlane_b32 s6, v252, 8
	v_readlane_b32 s7, v252, 9
	s_mov_b64 s[10:11], s[6:7]
	s_cmp_le_i32 s10, s3
	s_cselect_b64 s[6:7], -1, 0
	s_cmp_lt_i32 s3, s11
	s_cselect_b64 s[8:9], -1, 0
	s_and_b64 s[10:11], s[6:7], s[8:9]
	s_andn2_b64 vcc, exec, s[10:11]
	v_readlane_b32 s5, v252, 7
	s_cbranch_vccnz .LBB0_991
	v_readlane_b32 s3, v252, 5
	v_readlane_b32 s8, v252, 4
	v_mov_b32_e32 v1, v0
	s_lshl_b32 s3, s3, 3
	v_readfirstlane_b32 s6, v1
	s_ashr_i32 s6, s6, 6
	s_add_i32 s3, s6, s3
	v_readlane_b32 s6, v252, 0
	v_readlane_b32 s7, v252, 1
	s_cmpk_gt_i32 s3, 0x5fff
	s_cbranch_scc1 .LBB0_991
	s_load_dwordx2 s[14:15], s[6:7], 0xd8
	s_load_dwordx4 s[28:31], s[6:7], 0xa0
	v_and_b32_e32 v4, 63, v1
	v_lshlrev_b32_e32 v182, 4, v4
	s_mov_b64 s[4:5], 0x96a00000
	s_waitcnt lgkmcnt(0)
	v_lshl_add_u64 v[2:3], s[14:15], 0, v[182:183]
	v_and_b32_e32 v1, 64, v223
	v_lshl_add_u64 v[66:67], v[2:3], 0, s[4:5]
	v_add_u32_e32 v2, 64, v1
	v_xor_b32_e32 v1, 1, v223
	v_cmp_lt_i32_e32 vcc, v1, v2
	v_xor_b32_e32 v3, 2, v223
	v_readlane_b32 s4, v251, 10
	v_cndmask_b32_e32 v1, v223, v1, vcc
	v_cmp_lt_i32_e32 vcc, v3, v2
	v_readlane_b32 s5, v251, 11
	s_lshl_b32 s26, s8, 3
	v_cndmask_b32_e32 v3, v223, v3, vcc
	v_lshlrev_b32_e32 v152, 2, v3
	v_xor_b32_e32 v3, 4, v223
	v_cmp_lt_i32_e32 vcc, v3, v2
	s_lshl_b64 s[6:7], s[4:5], 2
	s_add_u32 s16, s28, s6
	v_cndmask_b32_e32 v3, v223, v3, vcc
	v_lshlrev_b32_e32 v153, 2, v3
	v_xor_b32_e32 v3, 8, v223
	v_cmp_lt_i32_e32 vcc, v3, v2
	s_addc_u32 s17, s29, s7
	s_add_u32 s30, s30, s6
	v_cndmask_b32_e32 v3, v223, v3, vcc
	v_lshlrev_b32_e32 v154, 2, v3
	v_xor_b32_e32 v3, 16, v223
	v_cmp_lt_i32_e32 vcc, v3, v2
	v_lshlrev_b32_e32 v182, 5, v4
	s_addc_u32 s31, s31, s7
	v_cndmask_b32_e32 v3, v223, v3, vcc
	v_lshlrev_b32_e32 v155, 2, v3
	v_xor_b32_e32 v3, 32, v223
	v_cmp_lt_i32_e32 vcc, v3, v2
	s_add_u32 s27, s14, 0xe00000
	v_lshl_add_u64 v[68:69], s[16:17], 0, v[182:183]
	v_cndmask_b32_e32 v2, v223, v3, vcc
	v_lshlrev_b32_e32 v156, 2, v2
	v_or_b32_e32 v2, 0x800, v182
	v_mov_b32_e32 v3, v183
	v_lshl_add_u64 v[72:73], s[16:17], 0, v[2:3]
	v_lshl_add_u64 v[74:75], s[30:31], 0, v[2:3]
	v_or_b32_e32 v2, 0x1000, v182
	v_lshl_add_u64 v[76:77], s[16:17], 0, v[2:3]
	v_lshl_add_u64 v[78:79], s[30:31], 0, v[2:3]
	v_or_b32_e32 v2, 0x1800, v182
	v_lshl_add_u64 v[80:81], s[16:17], 0, v[2:3]
	v_lshl_add_u64 v[82:83], s[30:31], 0, v[2:3]
	v_or_b32_e32 v2, 0x2000, v182
	v_lshl_add_u64 v[84:85], s[16:17], 0, v[2:3]
	v_lshl_add_u64 v[86:87], s[30:31], 0, v[2:3]
	v_or_b32_e32 v2, 0x2800, v182
	v_lshl_add_u64 v[70:71], s[30:31], 0, v[182:183]
	v_lshl_add_u64 v[88:89], s[16:17], 0, v[2:3]
	v_lshl_add_u64 v[90:91], s[30:31], 0, v[2:3]
	v_or_b32_e32 v2, 0x3000, v182
	v_or_b32_e32 v182, 0x3800, v182
	s_addc_u32 s28, s15, 0
	v_lshl_add_u64 v[96:97], s[16:17], 0, v[182:183]
	v_lshl_add_u64 v[98:99], s[30:31], 0, v[182:183]
	v_lshlrev_b32_e32 v182, 3, v4
	s_add_u32 s29, s14, 0xe40000
	v_lshl_add_u64 v[92:93], s[16:17], 0, v[2:3]
	v_lshl_add_u64 v[94:95], s[30:31], 0, v[2:3]
	v_lshl_add_u64 v[2:3], s[14:15], 0, v[182:183]
	s_mov_b64 s[4:5], 0x1000000
	s_addc_u32 s42, s15, 0
	v_lshlrev_b32_e32 v1, 2, v1
	v_cmp_eq_u32_e64 s[6:7], 0, v4
	s_lshl_b32 s43, s8, 4
	v_lshl_add_u64 v[100:101], v[2:3], 0, s[4:5]
	v_lshlrev_b32_e32 v162, 4, v0
	v_add_u32_e32 v163, 0x2000, v162
	global_load_dwordx4 v[164:167], v162, s[16:17]
	global_load_dwordx4 v[168:171], v163, s[16:17]
	global_load_dwordx4 v[172:175], v162, s[30:31]
	global_load_dwordx4 v[176:179], v163, s[30:31]
	v_and_b32_e32 v181, 63, v0
	v_lshlrev_b32_e32 v181, 5, v181
	v_add_u32_e32 v181, 0x12000, v181
	v_add_u32_e32 v180, 0x12000, v162
	s_waitcnt vmcnt(0)
	ds_write_b128 v180, v[164:167]
	ds_write_b128 v180, v[168:171] offset:8192
	ds_write_b128 v180, v[172:175] offset:16384
	ds_write_b128 v180, v[176:179] offset:24576
	s_waitcnt lgkmcnt(0)
	s_barrier
	s_branch .LBB0_982

; __device__ __forceinline__ f32x4 h4lo(const u32x4 w) { return (f32x4){hlo(w.x), hhi(w.x), hlo(w.y), hhi(w.y)}; }
; __device__ __forceinline__ f32x4 h4hi(const u32x4 w) { return (f32x4){hlo(w.z), hhi(w.z), hlo(w.w), hhi(w.w)}; }
; __device__ __forceinline__ int row_perm(int m) { const int j = m >> 11, r = m & 2047; return (11 - 3 * (j & 3) - (j >> 2)) * 2048 + r; }
; __device__ __forceinline__ void ln_fetch_b(const bf16* src, v4u (&raw)[8], int lane) {
;     const v4u* xr = (const v4u*)src + lane;
; #pragma unroll
;     for (int j = 0; j < 8; ++j) raw[j] = xr[64 * j];
; }
; __device__ __forceinline__ void ln_load_b(const v4u (&raw)[8], f32x4 (&v)[16], float& mean, float& rstd, int lane) {
;     float s = 0.f;
; #pragma unroll
;     for (int j = 0; j < 8; ++j) { const v4u w = raw[j]; v[2 * j] = pg8::h4lo(w); v[2 * j + 1] = pg8::h4hi(w);
;         s += ((v[2 * j].x + v[2 * j].y) + (v[2 * j].z + v[2 * j].w)) + ((v[2 * j + 1].x + v[2 * j + 1].y) + (v[2 * j + 1].z + v[2 * j + 1].w)); }
;     mean = wave_sum(s) * (1.f / 4096.f); float s2 = 0.f;
; __global__ void __launch_bounds__(NT, 2) fwd_kernel(Args args_unused) {
;     ...
;             for (int m0 = gw; m0 < MTOK; m0 += 2 * ngw) { const int mA = row_perm(m0), mB = row_perm(m0 + ngw < MTOK ? m0 + ngw : m0); const bool hasB = m0 + ngw < MTOK;
;                 v4u rawA[8], rawB[8]; ln_fetch_b(WSP(const bf16, WS_XR) + (size_t)mA * DM, rawA, lane); ln_fetch_b(WSP(const bf16, WS_XR) + (size_t)mB * DM, rawB, lane);
.LBB0_982:
	s_bfe_u32 s9, s3, 0x2000b
	s_mul_i32 s9, s9, 0x1ffffd
	s_ashr_i32 s14, s3, 13
	s_sub_i32 s9, s9, s14
	s_and_b32 s8, s3, 0x7ff
	s_lshl_b32 s9, s9, 11
	s_or_b32 s8, s9, s8
	s_add_i32 s36, s8, 0x5800
	s_add_i32 s14, s26, s3
	s_cmpk_lt_i32 s14, 0x6000
	s_cselect_b64 s[16:17], -1, 0
	s_and_b64 s[8:9], s[16:17], exec
	s_cselect_b32 s8, s14, s3
	s_ashr_i32 s37, s36, 31
	s_lshl_b64 s[14:15], s[36:37], 13
	v_lshl_add_u64 v[2:3], v[66:67], 0, s[14:15]
	global_load_dwordx4 v[62:65], v[2:3], off
	global_load_dwordx4 v[58:61], v[2:3], off offset:1024
	global_load_dwordx4 v[54:57], v[2:3], off offset:2048
	global_load_dwordx4 v[50:53], v[2:3], off offset:3072
	v_add_co_u32_e32 v2, vcc, s25, v2
	v_mov_b32_e32 v4, v183
	s_nop 0
	v_addc_co_u32_e32 v3, vcc, 0, v3, vcc
	global_load_dwordx4 v[42:45], v[2:3], off
	global_load_dwordx4 v[38:41], v[2:3], off offset:1024
	global_load_dwordx4 v[34:37], v[2:3], off offset:2048
	global_load_dwordx4 v[46:49], v[2:3], off offset:3072
	s_bfe_u32 s14, s8, 0x2000b
	s_and_b32 s9, s8, 0x7ff
	s_mul_i32 s14, s14, 0x1ffffd
	s_ashr_i32 s8, s8, 13
	s_sub_i32 s8, s14, s8
	s_lshl_b32 s8, s8, 11
	s_or_b32 s8, s8, s9
	s_add_i32 s14, s8, 0x5800
	s_ashr_i32 s15, s14, 31
	s_lshl_b64 s[8:9], s[14:15], 13
	s_waitcnt vmcnt(0)
	v_cvt_f32_f16_e32 v2, v62
	v_cvt_f32_f16_sdwa v6, v62 dst_sel:DWORD dst_unused:UNUSED_PAD src0_sel:WORD_1
	v_cvt_f32_f16_e32 v8, v63
	v_cvt_f32_f16_sdwa v10, v63 dst_sel:DWORD dst_unused:UNUSED_PAD src0_sel:WORD_1
	v_cvt_f32_f16_e32 v3, v64
	v_cvt_f32_f16_sdwa v7, v64 dst_sel:DWORD dst_unused:UNUSED_PAD src0_sel:WORD_1
	v_cvt_f32_f16_e32 v9, v65
	v_cvt_f32_f16_sdwa v11, v65 dst_sel:DWORD dst_unused:UNUSED_PAD src0_sel:WORD_1
	v_cvt_f32_f16_e32 v12, v58
	v_cvt_f32_f16_sdwa v14, v58 dst_sel:DWORD dst_unused:UNUSED_PAD src0_sel:WORD_1
	v_cvt_f32_f16_e32 v13, v59
	v_cvt_f32_f16_sdwa v15, v59 dst_sel:DWORD dst_unused:UNUSED_PAD src0_sel:WORD_1
	v_cvt_f32_f16_e32 v16, v60
	v_cvt_f32_f16_sdwa v18, v60 dst_sel:DWORD dst_unused:UNUSED_PAD src0_sel:WORD_1
	v_cvt_f32_f16_e32 v17, v61
	v_cvt_f32_f16_sdwa v19, v61 dst_sel:DWORD dst_unused:UNUSED_PAD src0_sel:WORD_1
	v_pk_add_f32 v[2:3], v[2:3], v[6:7]
	v_pk_add_f32 v[6:7], v[8:9], v[10:11]
	v_pk_add_f32 v[8:9], v[12:13], v[14:15]
	v_pk_add_f32 v[10:11], v[16:17], v[18:19]
	v_pk_add_f32 v[2:3], v[2:3], v[6:7]
	v_cvt_f32_f16_e32 v20, v54
	v_cvt_f32_f16_sdwa v22, v54 dst_sel:DWORD dst_unused:UNUSED_PAD src0_sel:WORD_1
	v_cvt_f32_f16_e32 v24, v55
	v_cvt_f32_f16_sdwa v26, v55 dst_sel:DWORD dst_unused:UNUSED_PAD src0_sel:WORD_1
	v_cvt_f32_f16_e32 v112, v56
	v_cvt_f32_f16_sdwa v113, v56 dst_sel:DWORD dst_unused:UNUSED_PAD src0_sel:WORD_1
	v_cvt_f32_f16_e32 v114, v57
	v_cvt_f32_f16_sdwa v115, v57 dst_sel:DWORD dst_unused:UNUSED_PAD src0_sel:WORD_1
	v_pk_add_f32 v[6:7], v[8:9], v[8:9] op_sel:[0,1] op_sel_hi:[1,0]
	v_pk_add_f32 v[8:9], v[10:11], v[10:11] op_sel:[0,1] op_sel_hi:[1,0]
	v_pk_add_f32 v[2:3], v[2:3], v[2:3] op_sel:[0,1] op_sel_hi:[1,0]
	v_cvt_f32_f16_sdwa v5, v50 dst_sel:DWORD dst_unused:UNUSED_PAD src0_sel:WORD_1
	v_cvt_f32_f16_e32 v21, v52
	v_cvt_f32_f16_sdwa v23, v52 dst_sel:DWORD dst_unused:UNUSED_PAD src0_sel:WORD_1
	v_cvt_f32_f16_e32 v25, v53
	v_cvt_f32_f16_sdwa v27, v53 dst_sel:DWORD dst_unused:UNUSED_PAD src0_sel:WORD_1
	v_cvt_f32_f16_e32 v7, v51
	v_cvt_f32_f16_sdwa v9, v51 dst_sel:DWORD dst_unused:UNUSED_PAD src0_sel:WORD_1
	v_cvt_f32_f16_e32 v3, v50
	v_add_f32_e32 v20, v22, v20
	v_add_f32_e32 v22, v26, v24
	v_add_f32_e32 v24, v113, v112
	v_add_f32_e32 v26, v115, v114
	v_pk_add_f32 v[10:11], v[20:21], v[22:23]
	v_pk_add_f32 v[12:13], v[24:25], v[26:27]
	v_pk_add_f32 v[6:7], v[6:7], v[8:9]
	v_pk_add_f32 v[2:3], v[2:3], v[4:5]
	v_cvt_f32_f16_e32 v28, v42
	v_cvt_f32_f16_sdwa v30, v42 dst_sel:DWORD dst_unused:UNUSED_PAD src0_sel:WORD_1
	v_cvt_f32_f16_e32 v32, v43
	v_cvt_f32_f16_sdwa v102, v43 dst_sel:DWORD dst_unused:UNUSED_PAD src0_sel:WORD_1
	v_cvt_f32_f16_e32 v29, v44
	v_cvt_f32_f16_sdwa v31, v44 dst_sel:DWORD dst_unused:UNUSED_PAD src0_sel:WORD_1
	v_cvt_f32_f16_e32 v33, v45
	v_cvt_f32_f16_sdwa v103, v45 dst_sel:DWORD dst_unused:UNUSED_PAD src0_sel:WORD_1
	v_pk_add_f32 v[10:11], v[10:11], v[12:13]
	v_pk_add_f32 v[2:3], v[2:3], v[6:7]
	v_cvt_f32_f16_e32 v104, v38
	v_cvt_f32_f16_sdwa v106, v38 dst_sel:DWORD dst_unused:UNUSED_PAD src0_sel:WORD_1
	v_cvt_f32_f16_e32 v105, v39
	v_cvt_f32_f16_sdwa v107, v39 dst_sel:DWORD dst_unused:UNUSED_PAD src0_sel:WORD_1
	v_cvt_f32_f16_e32 v108, v40
	v_cvt_f32_f16_sdwa v110, v40 dst_sel:DWORD dst_unused:UNUSED_PAD src0_sel:WORD_1
	v_cvt_f32_f16_e32 v109, v41
	v_cvt_f32_f16_sdwa v111, v41 dst_sel:DWORD dst_unused:UNUSED_PAD src0_sel:WORD_1
	v_pk_add_f32 v[2:3], v[2:3], v[10:11]
	v_cvt_f32_f16_sdwa v5, v35 dst_sel:DWORD dst_unused:UNUSED_PAD src0_sel:WORD_1
	v_pk_add_f32 v[2:3], v[2:3], v[2:3] op_sel:[0,1] op_sel_hi:[1,0]
	v_cvt_f32_f16_e32 v7, v36
	v_cvt_f32_f16_e32 v3, v35
	v_cvt_f32_f16_sdwa v8, v36 dst_sel:DWORD dst_unused:UNUSED_PAD src0_sel:WORD_1
	v_cvt_f32_f16_e32 v9, v37
	v_cvt_f32_f16_sdwa v10, v37 dst_sel:DWORD dst_unused:UNUSED_PAD src0_sel:WORD_1
	v_pk_add_f32 v[14:15], v[28:29], v[30:31]
	v_pk_add_f32 v[16:17], v[32:33], v[102:103]
	v_pk_add_f32 v[18:19], v[104:105], v[106:107]
	v_pk_add_f32 v[20:21], v[108:109], v[110:111]
	v_pk_add_f32 v[12:13], v[14:15], v[16:17]
	v_cvt_f32_f16_e32 v116, v34
	v_cvt_f32_f16_sdwa v117, v34 dst_sel:DWORD dst_unused:UNUSED_PAD src0_sel:WORD_1
	v_pk_add_f32 v[14:15], v[18:19], v[18:19] op_sel:[0,1] op_sel_hi:[1,0]
	v_pk_add_f32 v[16:17], v[20:21], v[20:21] op_sel:[0,1] op_sel_hi:[1,0]
	v_pk_add_f32 v[12:13], v[12:13], v[12:13] op_sel:[0,1] op_sel_hi:[1,0]
	v_add_f32_e32 v6, v5, v3
	v_add_f32_e32 v8, v8, v7
	v_add_f32_e32 v10, v10, v9
	v_cvt_f32_f16_e32 v3, v46
	v_cvt_f32_f16_sdwa v13, v46 dst_sel:DWORD dst_unused:UNUSED_PAD src0_sel:WORD_1
	v_cvt_f32_f16_e32 v15, v47
	v_cvt_f32_f16_sdwa v17, v47 dst_sel:DWORD dst_unused:UNUSED_PAD src0_sel:WORD_1
	v_cvt_f32_f16_e32 v5, v48
	v_cvt_f32_f16_sdwa v7, v48 dst_sel:DWORD dst_unused:UNUSED_PAD src0_sel:WORD_1
	v_cvt_f32_f16_e32 v9, v49
	v_cvt_f32_f16_sdwa v11, v49 dst_sel:DWORD dst_unused:UNUSED_PAD src0_sel:WORD_1
	v_add_f32_e32 v4, v117, v116
	v_pk_add_f32 v[2:3], v[2:3], v[12:13]
	v_pk_add_f32 v[12:13], v[14:15], v[16:17]
	v_pk_add_f32 v[4:5], v[4:5], v[6:7]
	v_pk_add_f32 v[6:7], v[8:9], v[10:11]
	v_pk_add_f32 v[2:3], v[2:3], v[12:13]
	v_pk_add_f32 v[4:5], v[4:5], v[6:7]
	s_nop 0
	v_pk_add_f32 v[2:3], v[2:3], v[4:5]
	s_nop 0
	v_add_f32_e32 v2, v2, v3
	s_nop 1
	v_mov_b32_dpp v3, v2 quad_perm:[1,0,3,2] row_mask:0xf bank_mask:0xf
	s_waitcnt lgkmcnt(0)
; __device__ __forceinline__ f32x4 h4lo(const u32x4 w) { return (f32x4){hlo(w.x), hhi(w.x), hlo(w.y), hhi(w.y)}; }
; __device__ __forceinline__ f32x4 h4hi(const u32x4 w) { return (f32x4){hlo(w.z), hhi(w.z), hlo(w.w), hhi(w.w)}; }
; __device__ __forceinline__ void ln_load_b(const v4u (&raw)[8], f32x4 (&v)[16], float& mean, float& rstd, int lane) {
;     float s = 0.f;
; #pragma unroll
;     for (int j = 0; j < 8; ++j) { const v4u w = raw[j]; v[2 * j] = pg8::h4lo(w); v[2 * j + 1] = pg8::h4hi(w);
;         s += ((v[2 * j].x + v[2 * j].y) + (v[2 * j].z + v[2 * j].w)) + ((v[2 * j + 1].x + v[2 * j + 1].y) + (v[2 * j + 1].z + v[2 * j + 1].w)); }
;     mean = wave_sum(s) * (1.f / 4096.f); float s2 = 0.f;
; #pragma unroll
;     for (int j = 0; j < 16; ++j) { v[j] = v[j] - mean; s2 += (v[j].x * v[j].x + v[j].y * v[j].y) + (v[j].z * v[j].z + v[j].w * v[j].w); }
;     rstd = 1.f / sqrtf(wave_sum(s2) * (1.f / 4096.f) + 1e-5f);
; }
	v_add_f32_e32 v2, v2, v3
	s_nop 1
	v_mov_b32_dpp v3, v2 quad_perm:[2,3,0,1] row_mask:0xf bank_mask:0xf
	s_waitcnt lgkmcnt(0)
	v_add_f32_e32 v4, v2, v3
	s_nop 1
	v_mov_b32_dpp v5, v4 row_half_mirror row_mask:0xf bank_mask:0xf
	v_lshl_add_u64 v[2:3], v[66:67], 0, s[8:9]
	global_load_dwordx4 v[30:33], v[2:3], off
	global_load_dwordx4 v[26:29], v[2:3], off offset:1024
	global_load_dwordx4 v[22:25], v[2:3], off offset:2048
	global_load_dwordx4 v[18:21], v[2:3], off offset:3072
	v_add_co_u32_e32 v2, vcc, s25, v2
	s_waitcnt lgkmcnt(0)
	v_add_f32_e32 v4, v4, v5
	s_nop 1
	v_mov_b32_dpp v5, v4 row_mirror row_mask:0xf bank_mask:0xf
	v_addc_co_u32_e32 v3, vcc, 0, v3, vcc
	s_waitcnt lgkmcnt(0)
	v_add_f32_e32 v4, v4, v5
	v_mov_b32_e32 v5, v4
	s_nop 1
	v_permlane16_swap_b32_e32 v5, v4
	s_waitcnt lgkmcnt(0)
	v_add_f32_e32 v102, v4, v5
	v_mov_b32_e32 v103, v102
	s_nop 1
	v_permlane32_swap_b32_e32 v103, v102
	global_load_dwordx4 v[14:17], v[2:3], off
	global_load_dwordx4 v[10:13], v[2:3], off offset:1024
	global_load_dwordx4 v[6:9], v[2:3], off offset:2048
	s_nop 0
	global_load_dwordx4 v[2:5], v[2:3], off offset:3072
	s_waitcnt lgkmcnt(0)
	v_add_f32_e32 v146, v102, v103
	v_fma_mix_f32 v103, v146, s87, v63 op_sel:[0,0,1] op_sel_hi:[0,0,1]
	v_fma_mix_f32 v109, v146, s87, v62 op_sel:[0,0,1] op_sel_hi:[0,0,1]
	v_fma_mix_f32 v102, v146, s87, v63 op_sel_hi:[0,0,1]
	v_fma_mix_f32 v108, v146, s87, v62 op_sel_hi:[0,0,1]
	v_mul_f32_e32 v62, v109, v109
	v_mul_f32_e32 v63, v103, v103
	v_fmac_f32_e32 v62, v108, v108
	v_fmac_f32_e32 v63, v102, v102
	v_fma_mix_f32 v111, v146, s87, v65 op_sel:[0,0,1] op_sel_hi:[0,0,1]
	v_fma_mix_f32 v145, v146, s87, v64 op_sel:[0,0,1] op_sel_hi:[0,0,1]
	v_fma_mix_f32 v105, v146, s87, v59 op_sel:[0,0,1] op_sel_hi:[0,0,1]
	v_fma_mix_f32 v107, v146, s87, v58 op_sel:[0,0,1] op_sel_hi:[0,0,1]
	v_add_f32_e32 v62, v62, v63
	v_fma_mix_f32 v110, v146, s87, v65 op_sel_hi:[0,0,1]
	v_fma_mix_f32 v144, v146, s87, v64 op_sel_hi:[0,0,1]
	v_mul_f32_e32 v63, v145, v145
	v_mul_f32_e32 v64, v111, v111
	v_fma_mix_f32 v104, v146, s87, v59 op_sel_hi:[0,0,1]
	v_fma_mix_f32 v106, v146, s87, v58 op_sel_hi:[0,0,1]
	v_mul_f32_e32 v58, v107, v107
	v_mul_f32_e32 v59, v105, v105
	v_fmac_f32_e32 v63, v144, v144
	v_fmac_f32_e32 v64, v110, v110
	v_fmac_f32_e32 v58, v106, v106
	v_fmac_f32_e32 v59, v104, v104
	v_fma_mix_f32 v117, v146, s87, v61 op_sel:[0,0,1] op_sel_hi:[0,0,1]
	v_fma_mix_f32 v119, v146, s87, v60 op_sel:[0,0,1] op_sel_hi:[0,0,1]
	v_fma_mix_f32 v113, v146, s87, v55 op_sel:[0,0,1] op_sel_hi:[0,0,1]
	v_fma_mix_f32 v115, v146, s87, v54 op_sel:[0,0,1] op_sel_hi:[0,0,1]
	v_add_f32_e32 v63, v63, v64
	v_add_f32_e32 v58, v58, v59
	v_fma_mix_f32 v116, v146, s87, v61 op_sel_hi:[0,0,1]
	v_fma_mix_f32 v118, v146, s87, v60 op_sel_hi:[0,0,1]
	v_mul_f32_e32 v59, v119, v119
	v_mul_f32_e32 v60, v117, v117
	v_fma_mix_f32 v112, v146, s87, v55 op_sel_hi:[0,0,1]
	v_fma_mix_f32 v114, v146, s87, v54 op_sel_hi:[0,0,1]
	v_mul_f32_e32 v54, v115, v115
	v_mul_f32_e32 v55, v113, v113
	v_add_f32_e32 v62, v62, v63
	v_fmac_f32_e32 v59, v118, v118
	v_fmac_f32_e32 v60, v116, v116
	v_fmac_f32_e32 v54, v114, v114
	v_fmac_f32_e32 v55, v112, v112
	v_fma_mix_f32 v125, v146, s87, v57 op_sel:[0,0,1] op_sel_hi:[0,0,1]
	v_fma_mix_f32 v127, v146, s87, v56 op_sel:[0,0,1] op_sel_hi:[0,0,1]
	v_fma_mix_f32 v121, v146, s87, v51 op_sel:[0,0,1] op_sel_hi:[0,0,1]
	v_fma_mix_f32 v123, v146, s87, v50 op_sel:[0,0,1] op_sel_hi:[0,0,1]
	v_add_f32_e32 v58, v58, v62
	v_add_f32_e32 v59, v59, v60
	v_add_f32_e32 v54, v54, v55
	v_fma_mix_f32 v124, v146, s87, v57 op_sel_hi:[0,0,1]
	v_fma_mix_f32 v126, v146, s87, v56 op_sel_hi:[0,0,1]
	v_mul_f32_e32 v55, v127, v127
	v_mul_f32_e32 v56, v125, v125
	v_fma_mix_f32 v120, v146, s87, v51 op_sel_hi:[0,0,1]
	v_fma_mix_f32 v122, v146, s87, v50 op_sel_hi:[0,0,1]
	v_mul_f32_e32 v50, v123, v123
	v_mul_f32_e32 v51, v121, v121
	v_add_f32_e32 v58, v59, v58
	v_fmac_f32_e32 v55, v126, v126
	v_fmac_f32_e32 v56, v124, v124
	v_fmac_f32_e32 v50, v122, v122
	v_fmac_f32_e32 v51, v120, v120
	v_fma_mix_f32 v133, v146, s87, v53 op_sel:[0,0,1] op_sel_hi:[0,0,1]
	v_fma_mix_f32 v135, v146, s87, v52 op_sel:[0,0,1] op_sel_hi:[0,0,1]
	v_fma_mix_f32 v129, v146, s87, v43 op_sel:[0,0,1] op_sel_hi:[0,0,1]
	v_fma_mix_f32 v131, v146, s87, v42 op_sel:[0,0,1] op_sel_hi:[0,0,1]
	v_add_f32_e32 v54, v54, v58
	v_add_f32_e32 v55, v55, v56
	v_add_f32_e32 v50, v50, v51
	v_fma_mix_f32 v132, v146, s87, v53 op_sel_hi:[0,0,1]
	v_fma_mix_f32 v134, v146, s87, v52 op_sel_hi:[0,0,1]
	v_mul_f32_e32 v51, v135, v135
	v_mul_f32_e32 v52, v133, v133
	v_fma_mix_f32 v128, v146, s87, v43 op_sel_hi:[0,0,1]
	v_fma_mix_f32 v130, v146, s87, v42 op_sel_hi:[0,0,1]
	v_mul_f32_e32 v42, v131, v131
	v_mul_f32_e32 v43, v129, v129
	v_add_f32_e32 v54, v55, v54
	v_fmac_f32_e32 v51, v134, v134
	v_fmac_f32_e32 v52, v132, v132
	v_fmac_f32_e32 v42, v130, v130
	v_fmac_f32_e32 v43, v128, v128
	v_fma_mix_f32 v141, v146, s87, v45 op_sel:[0,0,1] op_sel_hi:[0,0,1]
	v_fma_mix_f32 v143, v146, s87, v44 op_sel:[0,0,1] op_sel_hi:[0,0,1]
	v_add_f32_e32 v50, v50, v54
	v_add_f32_e32 v51, v51, v52
	v_add_f32_e32 v42, v42, v43
	v_fma_mix_f32 v140, v146, s87, v45 op_sel_hi:[0,0,1]
	v_fma_mix_f32 v142, v146, s87, v44 op_sel_hi:[0,0,1]
	v_mul_f32_e32 v43, v143, v143
	v_mul_f32_e32 v44, v141, v141
	v_add_f32_e32 v50, v51, v50
	v_fmac_f32_e32 v43, v142, v142
	v_fmac_f32_e32 v44, v140, v140
	v_add_f32_e32 v42, v42, v50
	v_add_f32_e32 v43, v43, v44
	v_add_f32_e32 v50, v43, v42
	v_fma_mix_f32 v43, v146, s87, v39 op_sel:[0,0,1] op_sel_hi:[0,0,1]
	v_fma_mix_f32 v45, v146, s87, v38 op_sel:[0,0,1] op_sel_hi:[0,0,1]
	v_fma_mix_f32 v42, v146, s87, v39 op_sel_hi:[0,0,1]
; __device__ __forceinline__ void ln_load_b(const v4u (&raw)[8], f32x4 (&v)[16], float& mean, float& rstd, int lane) {
;     ...
;     mean = wave_sum(s) * (1.f / 4096.f); float s2 = 0.f;
; #pragma unroll
;     for (int j = 0; j < 16; ++j) { v[j] = v[j] - mean; s2 += (v[j].x * v[j].x + v[j].y * v[j].y) + (v[j].z * v[j].z + v[j].w * v[j].w); }
;     rstd = 1.f / sqrtf(wave_sum(s2) * (1.f / 4096.f) + 1e-5f);
; }
; __device__ __forceinline__ void ln_row_qb(const v4u (&src)[8], const float* g, const float* b, signed char* dstq, float* rowinv, float* stat, int lane) {
;     f32x4 v[16]; float mean, rstd; ln_load_b(src, v, mean, rstd, lane);
;     if (lane == 0) { stat[0] = mean; stat[1] = rstd; }
	v_fma_mix_f32 v44, v146, s87, v38 op_sel_hi:[0,0,1]
	v_mul_f32_e32 v38, v45, v45
	v_mul_f32_e32 v39, v43, v43
	v_fmac_f32_e32 v38, v44, v44
	v_fmac_f32_e32 v39, v42, v42
	v_fma_mix_f32 v137, v146, s87, v41 op_sel:[0,0,1] op_sel_hi:[0,0,1]
	v_fma_mix_f32 v139, v146, s87, v40 op_sel:[0,0,1] op_sel_hi:[0,0,1]
	v_add_f32_e32 v38, v38, v39
	v_fma_mix_f32 v136, v146, s87, v41 op_sel_hi:[0,0,1]
	v_fma_mix_f32 v138, v146, s87, v40 op_sel_hi:[0,0,1]
	v_mul_f32_e32 v39, v139, v139
	v_mul_f32_e32 v40, v137, v137
	v_fmac_f32_e32 v39, v138, v138
	v_fmac_f32_e32 v40, v136, v136
	v_add_f32_e32 v38, v38, v50
	v_add_f32_e32 v39, v39, v40
	v_add_f32_e32 v40, v39, v38
	v_fma_mix_f32 v39, v146, s87, v35 op_sel:[0,0,1] op_sel_hi:[0,0,1]
	v_fma_mix_f32 v38, v146, s87, v35 op_sel_hi:[0,0,1]
	v_fma_mix_f32 v35, v146, s87, v34 op_sel:[0,0,1] op_sel_hi:[0,0,1]
	v_fma_mix_f32 v34, v146, s87, v34 op_sel_hi:[0,0,1]
	v_mul_f32_e32 v41, v35, v35
	v_mul_f32_e32 v50, v39, v39
	v_fmac_f32_e32 v41, v34, v34
	v_fmac_f32_e32 v50, v38, v38
	v_add_f32_e32 v41, v41, v50
	v_add_f32_e32 v50, v41, v40
	v_fma_mix_f32 v41, v146, s87, v37 op_sel:[0,0,1] op_sel_hi:[0,0,1]
	v_fma_mix_f32 v40, v146, s87, v37 op_sel_hi:[0,0,1]
	v_fma_mix_f32 v37, v146, s87, v36 op_sel:[0,0,1] op_sel_hi:[0,0,1]
	v_fma_mix_f32 v36, v146, s87, v36 op_sel_hi:[0,0,1]
	v_mul_f32_e32 v51, v37, v37
	v_mul_f32_e32 v52, v41, v41
	v_fmac_f32_e32 v51, v36, v36
	v_fmac_f32_e32 v52, v40, v40
	v_fma_mix_f32 v53, v146, s87, v47 op_sel:[0,0,1] op_sel_hi:[0,0,1]
	v_fma_mix_f32 v57, v146, s87, v46 op_sel:[0,0,1] op_sel_hi:[0,0,1]
	v_add_f32_e32 v51, v51, v52
	v_fma_mix_f32 v52, v146, s87, v47 op_sel_hi:[0,0,1]
	v_fma_mix_f32 v56, v146, s87, v46 op_sel_hi:[0,0,1]
	v_mul_f32_e32 v46, v57, v57
	v_mul_f32_e32 v47, v53, v53
	v_fmac_f32_e32 v46, v56, v56
	v_fmac_f32_e32 v47, v52, v52
	v_add_f32_e32 v50, v51, v50
	v_add_f32_e32 v46, v46, v47
	v_fma_mix_f32 v51, v146, s87, v49 op_sel:[0,0,1] op_sel_hi:[0,0,1]
	v_fma_mix_f32 v55, v146, s87, v48 op_sel:[0,0,1] op_sel_hi:[0,0,1]
	v_add_f32_e32 v46, v46, v50
	v_fma_mix_f32 v50, v146, s87, v49 op_sel_hi:[0,0,1]
	v_fma_mix_f32 v54, v146, s87, v48 op_sel_hi:[0,0,1]
	v_mul_f32_e32 v47, v55, v55
	v_mul_f32_e32 v48, v51, v51
	v_fmac_f32_e32 v47, v54, v54
	v_fmac_f32_e32 v48, v50, v50
	v_add_f32_e32 v47, v47, v48
	v_add_f32_e32 v46, v47, v46
	s_nop 1
	v_mov_b32_dpp v47, v46 quad_perm:[1,0,3,2] row_mask:0xf bank_mask:0xf
	s_waitcnt lgkmcnt(0)
	v_add_f32_e32 v46, v46, v47
	s_nop 1
	v_mov_b32_dpp v47, v46 quad_perm:[2,3,0,1] row_mask:0xf bank_mask:0xf
	s_waitcnt lgkmcnt(0)
	v_add_f32_e32 v46, v46, v47
	s_nop 1
	v_mov_b32_dpp v47, v46 row_half_mirror row_mask:0xf bank_mask:0xf
	s_waitcnt lgkmcnt(0)
	v_add_f32_e32 v46, v46, v47
	s_nop 1
	v_mov_b32_dpp v47, v46 row_mirror row_mask:0xf bank_mask:0xf
	s_waitcnt lgkmcnt(0)
	v_add_f32_e32 v46, v46, v47
	v_mov_b32_e32 v47, v46
	s_nop 1
	v_permlane16_swap_b32_e32 v47, v46
	s_waitcnt lgkmcnt(0)
	v_add_f32_e32 v46, v46, v47
	v_mov_b32_e32 v47, v46
	s_nop 1
	v_permlane32_swap_b32_e32 v47, v46
	s_waitcnt lgkmcnt(0)
	v_add_f32_e32 v46, v46, v47
	v_fmamk_f32 v46, v46, 0x39800000, v216
	v_mul_f32_e32 v47, 0x4f800000, v46
	v_cmp_gt_f32_e32 vcc, s95, v46
	s_nop 1
	v_cndmask_b32_e32 v46, v46, v47, vcc
	v_sqrt_f32_e32 v47, v46
	s_nop 0
	v_add_u32_e32 v48, -1, v47
	v_fma_f32 v49, -v48, v47, v46
	v_cmp_ge_f32_e64 s[8:9], 0, v49
	v_add_u32_e32 v49, 1, v47
	s_nop 0
	v_cndmask_b32_e64 v48, v47, v48, s[8:9]
	v_fma_f32 v47, -v49, v47, v46
	v_cmp_lt_f32_e64 s[8:9], 0, v47
	s_nop 1
	v_cndmask_b32_e64 v47, v48, v49, s[8:9]
	v_mul_f32_e32 v48, 0x37800000, v47
	v_cndmask_b32_e32 v47, v47, v48, vcc
	v_cmp_class_f32_e32 vcc, v46, v215
	s_nop 1
	v_cndmask_b32_e32 v46, v47, v46, vcc
	v_div_scale_f32 v47, s[8:9], v46, v46, 1.0
	v_rcp_f32_e32 v48, v47
	s_nop 0
	v_fma_f32 v49, -v47, v48, 1.0
	v_fmac_f32_e32 v48, v49, v48
	v_div_scale_f32 v49, vcc, 1.0, v46, 1.0
	v_mul_f32_e32 v58, v49, v48
	v_fma_f32 v59, -v47, v58, v49
	v_fmac_f32_e32 v58, v59, v48
	v_fma_f32 v47, -v47, v58, v49
	v_div_fmas_f32 v47, v47, v48, v58
	v_div_fixup_f32 v62, v47, v46, 1.0
	s_and_saveexec_b64 s[8:9], s[6:7]
	s_cbranch_execz .LBB0_984
	s_lshl_b32 s30, s36, 1
	s_ashr_i32 s31, s30, 31
	s_lshl_b64 s[30:31], s[30:31], 2
	s_add_u32 s30, s29, s30
	v_mul_f32_e32 v46, 0x39800000, v146
	s_addc_u32 s31, s42, s31
	v_mov_b32_e32 v47, v62
	global_store_dwordx2 v183, v[46:47], s[30:31]
; __device__ __forceinline__ void ln_row_qb(const v4u (&src)[8], const float* g, const float* b, signed char* dstq, float* rowinv, float* stat, int lane) {
;     ...
;     float mx = 0.f;
; #pragma unroll
;     for (int j = 0; j < 16; ++j) {
;         const int q = 2 * (64 * (j >> 1) + lane) + (j & 1);
;         const f32x4 gg = ((const f32x4*)g)[q], bb = ((const f32x4*)b)[q];
;         v[j] = v[j] * rstd * gg + bb;
;         mx = fmaxf(fmaxf(mx, fmaxf(fabsf(v[j].x), fabsf(v[j].y))), fmaxf(fabsf(v[j].z), fabsf(v[j].w)));
;     }
.LBB0_984:
	s_or_b64 exec, exec, s[8:9]
	ds_read_b128 v[46:49], v181 offset:16
	ds_read_b128 v[58:61], v181
	ds_read_b128 v[146:149], v181 offset:16400
	ds_read_b128 v[158:161], v181 offset:16384
	v_pk_mul_f32 v[64:65], v[102:103], v[62:63] op_sel_hi:[1,0]
	v_pk_mul_f32 v[102:103], v[108:109], v[62:63] op_sel_hi:[1,0]
	s_waitcnt vmcnt(0) lgkmcnt(0)
	v_pk_fma_f32 v[64:65], v[64:65], v[60:61], v[160:161]
	v_pk_fma_f32 v[102:103], v[102:103], v[58:59], v[158:159]
	v_max_f32_e64 v59, |v64|, |v65|
	v_max_f32_e64 v58, |v102|, |v103|
	v_max3_f32 v63, v58, 0, v59
	v_pk_mul_f32 v[58:59], v[110:111], v[62:63] op_sel_hi:[1,0]
	v_pk_mul_f32 v[60:61], v[144:145], v[62:63] op_sel_hi:[1,0]
	v_pk_fma_f32 v[58:59], v[58:59], v[48:49], v[148:149]
	v_pk_fma_f32 v[60:61], v[60:61], v[46:47], v[146:147]
	v_max_f32_e64 v47, |v58|, |v59|
	v_max_f32_e64 v46, |v60|, |v61|
	v_max3_f32 v63, v63, v46, v47
	ds_read_b128 v[46:49], v181 offset:2064
	ds_read_b128 v[144:147], v181 offset:2048
	ds_read_b128 v[148:151], v181 offset:18448
	ds_read_b128 v[158:161], v181 offset:18432
	v_pk_mul_f32 v[104:105], v[104:105], v[62:63] op_sel_hi:[1,0]
	v_pk_mul_f32 v[106:107], v[106:107], v[62:63] op_sel_hi:[1,0]
	s_waitcnt lgkmcnt(0)
	v_pk_fma_f32 v[108:109], v[104:105], v[146:147], v[160:161]
	v_pk_fma_f32 v[110:111], v[106:107], v[144:145], v[158:159]
	v_max_f32_e64 v105, |v108|, |v109|
	v_max_f32_e64 v104, |v110|, |v111|
	v_max3_f32 v63, v63, v104, v105
	v_pk_mul_f32 v[104:105], v[116:117], v[62:63] op_sel_hi:[1,0]
	v_pk_mul_f32 v[106:107], v[118:119], v[62:63] op_sel_hi:[1,0]
	v_pk_fma_f32 v[104:105], v[104:105], v[48:49], v[150:151]
	v_pk_fma_f32 v[106:107], v[106:107], v[46:47], v[148:149]
	v_max_f32_e64 v47, |v104|, |v105|
	v_max_f32_e64 v46, |v106|, |v107|
	v_max3_f32 v63, v63, v46, v47
	ds_read_b128 v[46:49], v181 offset:4112
	ds_read_b128 v[144:147], v181 offset:4096
	ds_read_b128 v[148:151], v181 offset:20496
	ds_read_b128 v[158:161], v181 offset:20480
	v_pk_mul_f32 v[112:113], v[112:113], v[62:63] op_sel_hi:[1,0]
	v_pk_mul_f32 v[114:115], v[114:115], v[62:63] op_sel_hi:[1,0]
	s_waitcnt lgkmcnt(0)
	v_pk_fma_f32 v[116:117], v[112:113], v[146:147], v[160:161]
	v_pk_fma_f32 v[118:119], v[114:115], v[144:145], v[158:159]
	v_max_f32_e64 v113, |v116|, |v117|
	v_max_f32_e64 v112, |v118|, |v119|
	v_max3_f32 v63, v63, v112, v113
	v_pk_mul_f32 v[112:113], v[124:125], v[62:63] op_sel_hi:[1,0]
	v_pk_mul_f32 v[114:115], v[126:127], v[62:63] op_sel_hi:[1,0]
	v_pk_fma_f32 v[112:113], v[112:113], v[48:49], v[150:151]
	v_pk_fma_f32 v[114:115], v[114:115], v[46:47], v[148:149]
	v_max_f32_e64 v47, |v112|, |v113|
	v_max_f32_e64 v46, |v114|, |v115|
	v_max3_f32 v63, v63, v46, v47
	ds_read_b128 v[46:49], v181 offset:6160
	ds_read_b128 v[144:147], v181 offset:6144
	ds_read_b128 v[148:151], v181 offset:22544
	ds_read_b128 v[158:161], v181 offset:22528
	v_pk_mul_f32 v[120:121], v[120:121], v[62:63] op_sel_hi:[1,0]
	v_pk_mul_f32 v[122:123], v[122:123], v[62:63] op_sel_hi:[1,0]
	s_waitcnt lgkmcnt(0)
	v_pk_fma_f32 v[124:125], v[120:121], v[146:147], v[160:161]
	v_pk_fma_f32 v[126:127], v[122:123], v[144:145], v[158:159]
	v_max_f32_e64 v121, |v124|, |v125|
	v_max_f32_e64 v120, |v126|, |v127|
	v_max3_f32 v63, v63, v120, v121
	v_pk_mul_f32 v[120:121], v[132:133], v[62:63] op_sel_hi:[1,0]
	v_pk_mul_f32 v[122:123], v[134:135], v[62:63] op_sel_hi:[1,0]
	v_pk_fma_f32 v[120:121], v[120:121], v[48:49], v[150:151]
	v_pk_fma_f32 v[122:123], v[122:123], v[46:47], v[148:149]
	v_max_f32_e64 v47, |v120|, |v121|
	v_max_f32_e64 v46, |v122|, |v123|
	v_max3_f32 v63, v63, v46, v47
	ds_read_b128 v[46:49], v181 offset:8208
	ds_read_b128 v[144:147], v181 offset:8192
	ds_read_b128 v[148:151], v181 offset:24592
	ds_read_b128 v[158:161], v181 offset:24576
	v_pk_mul_f32 v[128:129], v[128:129], v[62:63] op_sel_hi:[1,0]
	v_pk_mul_f32 v[130:131], v[130:131], v[62:63] op_sel_hi:[1,0]
	s_waitcnt lgkmcnt(0)
	v_pk_fma_f32 v[132:133], v[128:129], v[146:147], v[160:161]
	v_pk_fma_f32 v[134:135], v[130:131], v[144:145], v[158:159]
	v_max_f32_e64 v129, |v132|, |v133|
	v_max_f32_e64 v128, |v134|, |v135|
	v_max3_f32 v63, v63, v128, v129
	v_pk_mul_f32 v[128:129], v[140:141], v[62:63] op_sel_hi:[1,0]
	v_pk_mul_f32 v[130:131], v[142:143], v[62:63] op_sel_hi:[1,0]
	v_pk_fma_f32 v[128:129], v[128:129], v[48:49], v[150:151]
	v_pk_fma_f32 v[130:131], v[130:131], v[46:47], v[148:149]
	v_max_f32_e64 v47, |v128|, |v129|
	v_max_f32_e64 v46, |v130|, |v131|
	v_max3_f32 v63, v63, v46, v47
	ds_read_b128 v[46:49], v181 offset:10256
	ds_read_b128 v[142:145], v181 offset:10240
	ds_read_b128 v[146:149], v181 offset:26640
	ds_read_b128 v[158:161], v181 offset:26624
	v_pk_mul_f32 v[42:43], v[42:43], v[62:63] op_sel_hi:[1,0]
	v_pk_mul_f32 v[44:45], v[44:45], v[62:63] op_sel_hi:[1,0]
	s_waitcnt lgkmcnt(0)
	v_pk_fma_f32 v[140:141], v[42:43], v[144:145], v[160:161]
	v_pk_fma_f32 v[142:143], v[44:45], v[142:143], v[158:159]
	v_max_f32_e64 v43, |v140|, |v141|
	v_max_f32_e64 v42, |v142|, |v143|
	v_max3_f32 v63, v63, v42, v43
	v_pk_mul_f32 v[42:43], v[136:137], v[62:63] op_sel_hi:[1,0]
	v_pk_mul_f32 v[44:45], v[138:139], v[62:63] op_sel_hi:[1,0]
	v_pk_fma_f32 v[136:137], v[42:43], v[48:49], v[148:149]
	v_pk_fma_f32 v[138:139], v[44:45], v[46:47], v[146:147]
	v_max_f32_e64 v43, |v136|, |v137|
	v_max_f32_e64 v42, |v138|, |v139|
	v_max3_f32 v63, v63, v42, v43
	ds_read_b128 v[42:45], v181 offset:12304
	ds_read_b128 v[46:49], v181 offset:12288
	ds_read_b128 v[158:161], v181 offset:28688
	ds_read_b128 v[144:147], v181 offset:28672
	v_pk_mul_f32 v[38:39], v[38:39], v[62:63] op_sel_hi:[1,0]
	v_pk_mul_f32 v[34:35], v[34:35], v[62:63] op_sel_hi:[1,0]
	v_pk_mul_f32 v[36:37], v[36:37], v[62:63] op_sel_hi:[1,0]
	s_waitcnt lgkmcnt(0)
; __device__ __forceinline__ void ln_row_qb(const v4u (&src)[8], const float* g, const float* b, signed char* dstq, float* rowinv, float* stat, int lane) {
;     ...
;     for (int j = 0; j < 16; ++j) {
;         const int q = 2 * (64 * (j >> 1) + lane) + (j & 1);
;         const f32x4 gg = ((const f32x4*)g)[q], bb = ((const f32x4*)b)[q];
;         v[j] = v[j] * rstd * gg + bb;
;         mx = fmaxf(fmaxf(mx, fmaxf(fabsf(v[j].x), fabsf(v[j].y))), fmaxf(fabsf(v[j].z), fabsf(v[j].w)));
;     }
; #pragma unroll
;     for (int o = 1; o < 64; o <<= 1) mx = fmaxf(mx, __shfl_xor(mx, o));
;     mx = fmaxf(mx, 1e-20f);
;     const float sc = 127.0f / mx;
;     if (lane == 0) *rowinv = mx * (1.0f / 127.0f);
; #pragma unroll
;     for (int j = 0; j < 8; ++j) { v2u w;
;         w.x = ((unsigned)(int)rintf(v[2 * j].x * sc) & 0xffu) | (((unsigned)(int)rintf(v[2 * j].y * sc) & 0xffu) << 8) | (((unsigned)(int)rintf(v[2 * j].z * sc) & 0xffu) << 16) | (((unsigned)(int)rintf(v[2 * j].w * sc) & 0xffu) << 24);
;         w.y = ((unsigned)(int)rintf(v[2 * j + 1].x * sc) & 0xffu) | (((unsigned)(int)rintf(v[2 * j + 1].y * sc) & 0xffu) << 8) | (((unsigned)(int)rintf(v[2 * j + 1].z * sc) & 0xffu) << 16) | (((unsigned)(int)rintf(v[2 * j + 1].w * sc) & 0xffu) << 24);
;         ((v2u*)dstq)[64 * j + lane] = w; }
	v_pk_fma_f32 v[148:149], v[38:39], v[48:49], v[146:147]
	v_pk_fma_f32 v[150:151], v[34:35], v[46:47], v[144:145]
	v_max_f32_e64 v35, |v148|, |v149|
	v_max_f32_e64 v34, |v150|, |v151|
	v_max3_f32 v38, v63, v34, v35
	v_pk_mul_f32 v[34:35], v[40:41], v[62:63] op_sel_hi:[1,0]
	v_pk_fma_f32 v[146:147], v[36:37], v[42:43], v[158:159]
	v_pk_fma_f32 v[144:145], v[34:35], v[44:45], v[160:161]
	v_max_f32_e64 v34, |v146|, |v147|
	v_max_f32_e64 v35, |v144|, |v145|
	v_max3_f32 v63, v38, v34, v35
	ds_read_b128 v[34:37], v181 offset:14352
	ds_read_b128 v[42:45], v181 offset:14336
	ds_read_b128 v[38:41], v181 offset:30736
	ds_read_b128 v[46:49], v181 offset:30720
	v_pk_mul_f32 v[52:53], v[52:53], v[62:63] op_sel_hi:[1,0]
	v_pk_mul_f32 v[56:57], v[56:57], v[62:63] op_sel_hi:[1,0]
	s_waitcnt lgkmcnt(0)
	v_pk_fma_f32 v[44:45], v[52:53], v[44:45], v[48:49]
	v_pk_fma_f32 v[42:43], v[56:57], v[42:43], v[46:47]
	v_max_f32_e64 v47, |v44|, |v45|
	v_max_f32_e64 v46, |v42|, |v43|
	v_max3_f32 v52, v63, v46, v47
	v_pk_mul_f32 v[46:47], v[50:51], v[62:63] op_sel_hi:[1,0]
	v_pk_mul_f32 v[48:49], v[54:55], v[62:63] op_sel_hi:[1,0]
	v_pk_fma_f32 v[36:37], v[46:47], v[36:37], v[40:41]
	v_pk_fma_f32 v[34:35], v[48:49], v[34:35], v[38:39]
	v_max_f32_e64 v39, |v36|, |v37|
	v_max_f32_e64 v38, |v34|, |v35|
	v_max3_f32 v38, v52, v38, v39
	s_nop 1
	v_mov_b32_dpp v39, v38 quad_perm:[1,0,3,2] row_mask:0xf bank_mask:0xf
	s_waitcnt lgkmcnt(0)
	v_max_f32_e32 v39, v39, v39
	v_max_f32_e32 v38, v38, v39
	s_nop 1
	v_mov_b32_dpp v39, v38 quad_perm:[2,3,0,1] row_mask:0xf bank_mask:0xf
	s_waitcnt lgkmcnt(0)
	v_max_f32_e32 v39, v39, v39
	v_max_f32_e32 v38, v38, v39
	s_nop 1
	v_mov_b32_dpp v39, v38 row_half_mirror row_mask:0xf bank_mask:0xf
	s_waitcnt lgkmcnt(0)
	v_max_f32_e32 v39, v39, v39
	v_max_f32_e32 v38, v38, v39
	s_nop 1
	v_mov_b32_dpp v39, v38 row_mirror row_mask:0xf bank_mask:0xf
	s_waitcnt lgkmcnt(0)
	v_max_f32_e32 v39, v39, v39
	v_max_f32_e32 v38, v38, v39
	v_mov_b32_e32 v39, v38
	s_nop 1
	v_permlane16_swap_b32_e32 v39, v38
	s_waitcnt lgkmcnt(0)
	v_max_f32_e32 v39, v39, v39
	v_max_f32_e32 v38, v38, v39
	v_mov_b32_e32 v39, v38
	s_nop 1
	v_permlane32_swap_b32_e32 v39, v38
	s_waitcnt lgkmcnt(0)
	v_max3_f32 v38, v38, v39, s50
	s_and_saveexec_b64 s[8:9], s[6:7]
	s_cbranch_execz .LBB0_986
	s_lshl_b64 s[30:31], s[36:37], 2
	s_add_u32 s30, s27, s30
	s_addc_u32 s31, s28, s31
	v_mul_f32_e32 v39, 0x3c010204, v38
	global_store_dword v183, v39, s[30:31]
.LBB0_986:
	s_or_b64 exec, exec, s[8:9]
	v_div_scale_f32 v39, s[8:9], v38, v38, s41
	v_rcp_f32_e32 v40, v39
	s_lshl_b64 s[8:9], s[36:37], 12
	v_fma_f32 v41, -v39, v40, 1.0
	v_fmac_f32_e32 v40, v41, v40
	v_div_scale_f32 v41, vcc, s41, v38, s41
	v_mul_f32_e32 v46, v41, v40
	v_fma_f32 v47, -v39, v46, v41
	v_fmac_f32_e32 v46, v47, v40
	v_fma_f32 v39, -v39, v46, v41
	v_div_fmas_f32 v39, v39, v40, v46
	v_div_fixup_f32 v46, v39, v38, s41
	v_mul_f32_e32 v39, v103, v46
	v_mul_f32_e32 v38, v102, v46
	v_rndne_f32_e32 v39, v39
	v_mul_f32_e32 v40, v64, v46
	v_mul_f32_e32 v41, v65, v46
	v_rndne_f32_e32 v38, v38
	v_cvt_i32_f32_e32 v39, v39
	v_rndne_f32_e32 v40, v40
	v_rndne_f32_e32 v41, v41
	v_cvt_i32_f32_e32 v38, v38
	v_cvt_i32_f32_sdwa v40, v40 dst_sel:WORD_1 dst_unused:UNUSED_PAD src0_sel:DWORD
	v_cvt_i32_f32_e32 v41, v41
	v_lshlrev_b32_e32 v39, 8, v39
	v_and_b32_e32 v39, 0xff00, v39
	v_and_b32_e32 v40, 0xff0000, v40
	v_perm_b32 v38, v41, v38, s88
	v_or3_b32 v40, v38, v39, v40
	v_mul_f32_e32 v39, v61, v46
	v_mul_f32_e32 v38, v60, v46
	v_rndne_f32_e32 v39, v39
	v_mul_f32_e32 v41, v58, v46
	v_mul_f32_e32 v47, v59, v46
	v_rndne_f32_e32 v38, v38
	v_cvt_i32_f32_e32 v39, v39
	v_rndne_f32_e32 v41, v41
	v_rndne_f32_e32 v47, v47
	v_cvt_i32_f32_e32 v38, v38
	v_cvt_i32_f32_sdwa v41, v41 dst_sel:WORD_1 dst_unused:UNUSED_PAD src0_sel:DWORD
	v_cvt_i32_f32_e32 v47, v47
	v_lshlrev_b32_e32 v39, 8, v39
	v_and_b32_e32 v39, 0xff00, v39
	v_and_b32_e32 v41, 0xff0000, v41
	v_perm_b32 v38, v47, v38, s88
	v_or3_b32 v41, v38, v39, v41
	v_lshl_add_u64 v[38:39], v[100:101], 0, s[8:9]
	global_store_dwordx2 v[38:39], v[40:41], off
	v_mul_f32_e32 v41, v111, v46
	v_mul_f32_e32 v40, v110, v46
	v_rndne_f32_e32 v41, v41
	v_mul_f32_e32 v47, v108, v46
	v_mul_f32_e32 v48, v109, v46
	v_rndne_f32_e32 v40, v40
	v_cvt_i32_f32_e32 v41, v41
	v_rndne_f32_e32 v47, v47
	v_rndne_f32_e32 v48, v48
	v_cvt_i32_f32_e32 v40, v40
	v_cvt_i32_f32_sdwa v47, v47 dst_sel:WORD_1 dst_unused:UNUSED_PAD src0_sel:DWORD
	v_cvt_i32_f32_e32 v48, v48
	v_lshlrev_b32_e32 v41, 8, v41
	v_and_b32_e32 v41, 0xff00, v41
	v_and_b32_e32 v47, 0xff0000, v47
	v_perm_b32 v40, v48, v40, s88
	v_or3_b32 v40, v40, v41, v47
	v_mul_f32_e32 v47, v107, v46
	v_mul_f32_e32 v41, v106, v46
	v_rndne_f32_e32 v47, v47
	v_mul_f32_e32 v48, v104, v46
	v_mul_f32_e32 v49, v105, v46
	v_rndne_f32_e32 v41, v41
	v_cvt_i32_f32_e32 v47, v47
	v_rndne_f32_e32 v48, v48
	v_rndne_f32_e32 v49, v49
	v_cvt_i32_f32_e32 v41, v41
	v_cvt_i32_f32_sdwa v48, v48 dst_sel:WORD_1 dst_unused:UNUSED_PAD src0_sel:DWORD
	v_cvt_i32_f32_e32 v49, v49
	v_lshlrev_b32_e32 v47, 8, v47
	v_and_b32_e32 v47, 0xff00, v47
	v_and_b32_e32 v48, 0xff0000, v48
	v_perm_b32 v41, v49, v41, s88
	v_or3_b32 v41, v41, v47, v48
	global_store_dwordx2 v[38:39], v[40:41], off offset:512
	v_mul_f32_e32 v41, v119, v46
	v_mul_f32_e32 v40, v118, v46
	v_rndne_f32_e32 v41, v41
	v_mul_f32_e32 v47, v116, v46
	v_mul_f32_e32 v48, v117, v46
	v_rndne_f32_e32 v40, v40
	v_cvt_i32_f32_e32 v41, v41
	v_rndne_f32_e32 v47, v47
	v_rndne_f32_e32 v48, v48
	v_cvt_i32_f32_e32 v40, v40
	v_cvt_i32_f32_sdwa v47, v47 dst_sel:WORD_1 dst_unused:UNUSED_PAD src0_sel:DWORD
	v_cvt_i32_f32_e32 v48, v48
	v_lshlrev_b32_e32 v41, 8, v41
; __device__ __forceinline__ void ln_row_qb(const v4u (&src)[8], const float* g, const float* b, signed char* dstq, float* rowinv, float* stat, int lane) {
;     ...
;     for (int j = 0; j < 8; ++j) { v2u w;
;         w.x = ((unsigned)(int)rintf(v[2 * j].x * sc) & 0xffu) | (((unsigned)(int)rintf(v[2 * j].y * sc) & 0xffu) << 8) | (((unsigned)(int)rintf(v[2 * j].z * sc) & 0xffu) << 16) | (((unsigned)(int)rintf(v[2 * j].w * sc) & 0xffu) << 24);
;         w.y = ((unsigned)(int)rintf(v[2 * j + 1].x * sc) & 0xffu) | (((unsigned)(int)rintf(v[2 * j + 1].y * sc) & 0xffu) << 8) | (((unsigned)(int)rintf(v[2 * j + 1].z * sc) & 0xffu) << 16) | (((unsigned)(int)rintf(v[2 * j + 1].w * sc) & 0xffu) << 24);
;         ((v2u*)dstq)[64 * j + lane] = w; }
	v_and_b32_e32 v41, 0xff00, v41
	v_and_b32_e32 v47, 0xff0000, v47
	v_perm_b32 v40, v48, v40, s88
	v_or3_b32 v40, v40, v41, v47
	v_mul_f32_e32 v47, v115, v46
	v_mul_f32_e32 v41, v114, v46
	v_rndne_f32_e32 v47, v47
	v_mul_f32_e32 v48, v112, v46
	v_mul_f32_e32 v49, v113, v46
	v_rndne_f32_e32 v41, v41
	v_cvt_i32_f32_e32 v47, v47
	v_rndne_f32_e32 v48, v48
	v_rndne_f32_e32 v49, v49
	v_cvt_i32_f32_e32 v41, v41
	v_cvt_i32_f32_sdwa v48, v48 dst_sel:WORD_1 dst_unused:UNUSED_PAD src0_sel:DWORD
	v_cvt_i32_f32_e32 v49, v49
	v_lshlrev_b32_e32 v47, 8, v47
	v_and_b32_e32 v47, 0xff00, v47
	v_and_b32_e32 v48, 0xff0000, v48
	v_perm_b32 v41, v49, v41, s88
	v_or3_b32 v41, v41, v47, v48
	global_store_dwordx2 v[38:39], v[40:41], off offset:1024
	v_mul_f32_e32 v41, v127, v46
	v_mul_f32_e32 v40, v126, v46
	v_rndne_f32_e32 v41, v41
	v_mul_f32_e32 v47, v124, v46
	v_mul_f32_e32 v48, v125, v46
	v_rndne_f32_e32 v40, v40
	v_cvt_i32_f32_e32 v41, v41
	v_rndne_f32_e32 v47, v47
	v_rndne_f32_e32 v48, v48
	v_cvt_i32_f32_e32 v40, v40
	v_cvt_i32_f32_sdwa v47, v47 dst_sel:WORD_1 dst_unused:UNUSED_PAD src0_sel:DWORD
	v_cvt_i32_f32_e32 v48, v48
	v_lshlrev_b32_e32 v41, 8, v41
	v_and_b32_e32 v41, 0xff00, v41
	v_and_b32_e32 v47, 0xff0000, v47
	v_perm_b32 v40, v48, v40, s88
	v_or3_b32 v40, v40, v41, v47
	v_mul_f32_e32 v47, v123, v46
	v_mul_f32_e32 v41, v122, v46
	v_rndne_f32_e32 v47, v47
	v_mul_f32_e32 v48, v120, v46
	v_mul_f32_e32 v49, v121, v46
	v_rndne_f32_e32 v41, v41
	v_cvt_i32_f32_e32 v47, v47
	v_rndne_f32_e32 v48, v48
	v_rndne_f32_e32 v49, v49
	v_cvt_i32_f32_e32 v41, v41
	v_cvt_i32_f32_sdwa v48, v48 dst_sel:WORD_1 dst_unused:UNUSED_PAD src0_sel:DWORD
	v_cvt_i32_f32_e32 v49, v49
	v_lshlrev_b32_e32 v47, 8, v47
	v_and_b32_e32 v47, 0xff00, v47
	v_and_b32_e32 v48, 0xff0000, v48
	v_perm_b32 v41, v49, v41, s88
	v_or3_b32 v41, v41, v47, v48
	global_store_dwordx2 v[38:39], v[40:41], off offset:1536
	v_mul_f32_e32 v41, v135, v46
	v_mul_f32_e32 v40, v134, v46
	v_rndne_f32_e32 v41, v41
	v_mul_f32_e32 v47, v132, v46
	v_mul_f32_e32 v48, v133, v46
	v_rndne_f32_e32 v40, v40
	v_cvt_i32_f32_e32 v41, v41
	v_rndne_f32_e32 v47, v47
	v_rndne_f32_e32 v48, v48
	v_cvt_i32_f32_e32 v40, v40
	v_cvt_i32_f32_sdwa v47, v47 dst_sel:WORD_1 dst_unused:UNUSED_PAD src0_sel:DWORD
	v_cvt_i32_f32_e32 v48, v48
	v_lshlrev_b32_e32 v41, 8, v41
	v_and_b32_e32 v41, 0xff00, v41
	v_and_b32_e32 v47, 0xff0000, v47
	v_perm_b32 v40, v48, v40, s88
	v_or3_b32 v40, v40, v41, v47
	v_mul_f32_e32 v47, v131, v46
	v_mul_f32_e32 v41, v130, v46
	v_rndne_f32_e32 v47, v47
	v_mul_f32_e32 v48, v128, v46
	v_mul_f32_e32 v49, v129, v46
	v_rndne_f32_e32 v41, v41
	v_cvt_i32_f32_e32 v47, v47
	v_rndne_f32_e32 v48, v48
	v_rndne_f32_e32 v49, v49
	v_cvt_i32_f32_e32 v41, v41
	v_cvt_i32_f32_sdwa v48, v48 dst_sel:WORD_1 dst_unused:UNUSED_PAD src0_sel:DWORD
	v_cvt_i32_f32_e32 v49, v49
	v_lshlrev_b32_e32 v47, 8, v47
	v_and_b32_e32 v47, 0xff00, v47
	v_and_b32_e32 v48, 0xff0000, v48
	v_perm_b32 v41, v49, v41, s88
	v_or3_b32 v41, v41, v47, v48
	global_store_dwordx2 v[38:39], v[40:41], off offset:2048
	v_mul_f32_e32 v41, v143, v46
	v_mul_f32_e32 v40, v142, v46
	v_rndne_f32_e32 v41, v41
	v_mul_f32_e32 v47, v140, v46
	v_mul_f32_e32 v48, v141, v46
	v_rndne_f32_e32 v40, v40
	v_cvt_i32_f32_e32 v41, v41
	v_rndne_f32_e32 v47, v47
	v_rndne_f32_e32 v48, v48
	v_cvt_i32_f32_e32 v40, v40
	v_cvt_i32_f32_sdwa v47, v47 dst_sel:WORD_1 dst_unused:UNUSED_PAD src0_sel:DWORD
	v_cvt_i32_f32_e32 v48, v48
	v_lshlrev_b32_e32 v41, 8, v41
	v_and_b32_e32 v41, 0xff00, v41
	v_and_b32_e32 v47, 0xff0000, v47
	v_perm_b32 v40, v48, v40, s88
	v_or3_b32 v40, v40, v41, v47
	v_mul_f32_e32 v47, v139, v46
	v_mul_f32_e32 v41, v138, v46
	v_rndne_f32_e32 v47, v47
	v_mul_f32_e32 v48, v136, v46
	v_mul_f32_e32 v49, v137, v46
	v_rndne_f32_e32 v41, v41
	v_cvt_i32_f32_e32 v47, v47
	v_rndne_f32_e32 v48, v48
	v_rndne_f32_e32 v49, v49
	v_cvt_i32_f32_e32 v41, v41
	v_cvt_i32_f32_sdwa v48, v48 dst_sel:WORD_1 dst_unused:UNUSED_PAD src0_sel:DWORD
	v_cvt_i32_f32_e32 v49, v49
	v_lshlrev_b32_e32 v47, 8, v47
	v_and_b32_e32 v47, 0xff00, v47
	v_and_b32_e32 v48, 0xff0000, v48
	v_perm_b32 v41, v49, v41, s88
	v_or3_b32 v41, v41, v47, v48
	global_store_dwordx2 v[38:39], v[40:41], off offset:2560
	v_mul_f32_e32 v41, v151, v46
	v_mul_f32_e32 v40, v150, v46
	v_rndne_f32_e32 v41, v41
	v_mul_f32_e32 v47, v148, v46
	v_mul_f32_e32 v48, v149, v46
	v_rndne_f32_e32 v40, v40
	v_cvt_i32_f32_e32 v41, v41
	v_rndne_f32_e32 v47, v47
	v_rndne_f32_e32 v48, v48
	v_cvt_i32_f32_e32 v40, v40
	v_cvt_i32_f32_sdwa v47, v47 dst_sel:WORD_1 dst_unused:UNUSED_PAD src0_sel:DWORD
	v_cvt_i32_f32_e32 v48, v48
	v_lshlrev_b32_e32 v41, 8, v41
	v_and_b32_e32 v41, 0xff00, v41
	v_and_b32_e32 v47, 0xff0000, v47
	v_perm_b32 v40, v48, v40, s88
	v_or3_b32 v40, v40, v41, v47
	v_mul_f32_e32 v47, v147, v46
	v_mul_f32_e32 v41, v146, v46
	v_rndne_f32_e32 v47, v47
	v_mul_f32_e32 v48, v144, v46
	v_mul_f32_e32 v49, v145, v46
	v_rndne_f32_e32 v41, v41
	v_cvt_i32_f32_e32 v47, v47
	v_rndne_f32_e32 v48, v48
	v_rndne_f32_e32 v49, v49
	v_cvt_i32_f32_e32 v41, v41
	v_cvt_i32_f32_sdwa v48, v48 dst_sel:WORD_1 dst_unused:UNUSED_PAD src0_sel:DWORD
	v_cvt_i32_f32_e32 v49, v49
	v_lshlrev_b32_e32 v47, 8, v47
	v_and_b32_e32 v47, 0xff00, v47
	v_and_b32_e32 v48, 0xff0000, v48
	v_perm_b32 v41, v49, v41, s88
	v_or3_b32 v41, v41, v47, v48
	global_store_dwordx2 v[38:39], v[40:41], off offset:3072
	v_mul_f32_e32 v41, v43, v46
	v_mul_f32_e32 v35, v35, v46
	v_mul_f32_e32 v40, v42, v46
	v_rndne_f32_e32 v41, v41
	v_mul_f32_e32 v42, v44, v46
	v_mul_f32_e32 v43, v45, v46
	v_mul_f32_e32 v34, v34, v46
	v_rndne_f32_e32 v35, v35
	v_mul_f32_e32 v36, v36, v46
	v_mul_f32_e32 v37, v37, v46
	v_rndne_f32_e32 v40, v40
	v_cvt_i32_f32_e32 v41, v41
	v_rndne_f32_e32 v42, v42
	v_rndne_f32_e32 v43, v43
	v_rndne_f32_e32 v34, v34
	v_cvt_i32_f32_e32 v35, v35
	v_rndne_f32_e32 v36, v36
	v_rndne_f32_e32 v37, v37
	v_cvt_i32_f32_e32 v40, v40
	v_cvt_i32_f32_sdwa v42, v42 dst_sel:WORD_1 dst_unused:UNUSED_PAD src0_sel:DWORD
	v_cvt_i32_f32_e32 v43, v43
	v_cvt_i32_f32_e32 v34, v34
	v_cvt_i32_f32_sdwa v36, v36 dst_sel:WORD_1 dst_unused:UNUSED_PAD src0_sel:DWORD
	v_cvt_i32_f32_e32 v37, v37
	v_lshlrev_b32_e32 v41, 8, v41
	v_lshlrev_b32_e32 v35, 8, v35
	v_and_b32_e32 v41, 0xff00, v41
	v_and_b32_e32 v42, 0xff0000, v42
	v_perm_b32 v40, v43, v40, s88
	v_and_b32_e32 v35, 0xff00, v35
	v_and_b32_e32 v36, 0xff0000, v36
	v_perm_b32 v34, v37, v34, s88
	v_or3_b32 v40, v40, v41, v42
	v_or3_b32 v41, v34, v35, v36
	s_andn2_b64 vcc, exec, s[16:17]
	global_store_dwordx2 v[38:39], v[40:41], off offset:3584
	s_cbranch_vccnz .LBB0_981
; __device__ __forceinline__ f32x4 h4lo(const u32x4 w) { return (f32x4){hlo(w.x), hhi(w.x), hlo(w.y), hhi(w.y)}; }
; __device__ __forceinline__ f32x4 h4hi(const u32x4 w) { return (f32x4){hlo(w.z), hhi(w.z), hlo(w.w), hhi(w.w)}; }
; __device__ __forceinline__ void ln_load_b(const v4u (&raw)[8], f32x4 (&v)[16], float& mean, float& rstd, int lane) {
;     float s = 0.f;
; #pragma unroll
;     for (int j = 0; j < 8; ++j) { const v4u w = raw[j]; v[2 * j] = pg8::h4lo(w); v[2 * j + 1] = pg8::h4hi(w);
;         s += ((v[2 * j].x + v[2 * j].y) + (v[2 * j].z + v[2 * j].w)) + ((v[2 * j + 1].x + v[2 * j + 1].y) + (v[2 * j + 1].z + v[2 * j + 1].w)); }
;     mean = wave_sum(s) * (1.f / 4096.f); float s2 = 0.f;
; #pragma unroll
;     for (int j = 0; j < 16; ++j) { v[j] = v[j] - mean; s2 += (v[j].x * v[j].x + v[j].y * v[j].y) + (v[j].z * v[j].z + v[j].w * v[j].w); }
;     rstd = 1.f / sqrtf(wave_sum(s2) * (1.f / 4096.f) + 1e-5f);
; }
	v_cvt_f32_f16_sdwa v34, v30 dst_sel:DWORD dst_unused:UNUSED_PAD src0_sel:WORD_1
	v_cvt_f32_f16_e32 v36, v30
	v_cvt_f32_f16_sdwa v38, v31 dst_sel:DWORD dst_unused:UNUSED_PAD src0_sel:WORD_1
	v_cvt_f32_f16_e32 v40, v31
	v_cvt_f32_f16_sdwa v35, v32 dst_sel:DWORD dst_unused:UNUSED_PAD src0_sel:WORD_1
	v_cvt_f32_f16_e32 v37, v32
	v_cvt_f32_f16_sdwa v39, v33 dst_sel:DWORD dst_unused:UNUSED_PAD src0_sel:WORD_1
	v_cvt_f32_f16_e32 v41, v33
	v_cvt_f32_f16_e32 v42, v28
	v_pk_add_f32 v[34:35], v[36:37], v[34:35]
	v_cvt_f32_f16_e32 v43, v29
	v_pk_add_f32 v[36:37], v[40:41], v[38:39]
	v_cvt_f32_f16_e32 v38, v26
	v_pk_add_f32 v[34:35], v[34:35], v[36:37]
	v_cvt_f32_f16_sdwa v36, v26 dst_sel:DWORD dst_unused:UNUSED_PAD src0_sel:WORD_1
	v_cvt_f32_f16_sdwa v37, v27 dst_sel:DWORD dst_unused:UNUSED_PAD src0_sel:WORD_1
	v_cvt_f32_f16_e32 v39, v27
	v_cvt_f32_f16_sdwa v40, v28 dst_sel:DWORD dst_unused:UNUSED_PAD src0_sel:WORD_1
	v_cvt_f32_f16_sdwa v41, v29 dst_sel:DWORD dst_unused:UNUSED_PAD src0_sel:WORD_1
	v_pk_add_f32 v[34:35], v[34:35], v[34:35] op_sel:[0,1] op_sel_hi:[1,0]
	v_pk_add_f32 v[36:37], v[38:39], v[36:37]
	v_cvt_f32_f16_sdwa v35, v22 dst_sel:DWORD dst_unused:UNUSED_PAD src0_sel:WORD_1
	v_pk_add_f32 v[38:39], v[42:43], v[40:41]
	v_pk_add_f32 v[36:37], v[36:37], v[36:37] op_sel:[0,1] op_sel_hi:[1,0]
	v_pk_add_f32 v[38:39], v[38:39], v[38:39] op_sel:[0,1] op_sel_hi:[1,0]
	v_cvt_f32_f16_e32 v37, v22
	v_cvt_f32_f16_sdwa v39, v23 dst_sel:DWORD dst_unused:UNUSED_PAD src0_sel:WORD_1
	v_cvt_f32_f16_e32 v41, v23
	v_cvt_f32_f16_sdwa v43, v24 dst_sel:DWORD dst_unused:UNUSED_PAD src0_sel:WORD_1
	v_cvt_f32_f16_e32 v44, v24
	v_cvt_f32_f16_sdwa v45, v25 dst_sel:DWORD dst_unused:UNUSED_PAD src0_sel:WORD_1
	v_cvt_f32_f16_e32 v46, v25
	v_add_f32_e32 v40, v35, v37
	v_add_f32_e32 v42, v39, v41
	v_cvt_f32_f16_sdwa v49, v18 dst_sel:DWORD dst_unused:UNUSED_PAD src0_sel:WORD_1
	v_cvt_f32_f16_e32 v35, v18
	v_cvt_f32_f16_sdwa v39, v19 dst_sel:DWORD dst_unused:UNUSED_PAD src0_sel:WORD_1
	v_cvt_f32_f16_e32 v37, v19
	v_add_f32_e32 v44, v43, v44
	v_add_f32_e32 v46, v45, v46
	v_cvt_f32_f16_sdwa v43, v20 dst_sel:DWORD dst_unused:UNUSED_PAD src0_sel:WORD_1
	v_cvt_f32_f16_e32 v41, v20
	v_cvt_f32_f16_sdwa v47, v21 dst_sel:DWORD dst_unused:UNUSED_PAD src0_sel:WORD_1
	v_cvt_f32_f16_e32 v45, v21
	v_mov_b32_e32 v48, v183
	v_pk_add_f32 v[34:35], v[34:35], v[48:49]
	v_pk_add_f32 v[36:37], v[36:37], v[38:39]
	v_pk_add_f32 v[38:39], v[44:45], v[46:47]
	v_pk_add_f32 v[34:35], v[34:35], v[36:37]
	v_pk_add_f32 v[36:37], v[40:41], v[42:43]
	v_cvt_f32_f16_e32 v40, v14
	v_pk_add_f32 v[36:37], v[36:37], v[38:39]
	v_cvt_f32_f16_sdwa v38, v14 dst_sel:DWORD dst_unused:UNUSED_PAD src0_sel:WORD_1
	v_cvt_f32_f16_sdwa v42, v15 dst_sel:DWORD dst_unused:UNUSED_PAD src0_sel:WORD_1
	v_cvt_f32_f16_e32 v44, v15
	v_cvt_f32_f16_sdwa v39, v16 dst_sel:DWORD dst_unused:UNUSED_PAD src0_sel:WORD_1
	v_cvt_f32_f16_e32 v41, v16
	v_cvt_f32_f16_sdwa v43, v17 dst_sel:DWORD dst_unused:UNUSED_PAD src0_sel:WORD_1
	v_cvt_f32_f16_e32 v45, v17
	v_pk_add_f32 v[34:35], v[34:35], v[36:37]
	v_pk_add_f32 v[36:37], v[40:41], v[38:39]
	v_cvt_f32_f16_e32 v40, v10
	v_pk_add_f32 v[38:39], v[44:45], v[42:43]
	v_cvt_f32_f16_e32 v41, v11
	v_pk_add_f32 v[36:37], v[36:37], v[38:39]
	v_cvt_f32_f16_sdwa v38, v10 dst_sel:DWORD dst_unused:UNUSED_PAD src0_sel:WORD_1
	v_cvt_f32_f16_sdwa v39, v11 dst_sel:DWORD dst_unused:UNUSED_PAD src0_sel:WORD_1
	v_cvt_f32_f16_sdwa v42, v12 dst_sel:DWORD dst_unused:UNUSED_PAD src0_sel:WORD_1
	v_cvt_f32_f16_e32 v44, v12
	v_cvt_f32_f16_sdwa v43, v13 dst_sel:DWORD dst_unused:UNUSED_PAD src0_sel:WORD_1
	v_cvt_f32_f16_e32 v45, v13
	v_pk_add_f32 v[38:39], v[40:41], v[38:39]
	v_pk_add_f32 v[34:35], v[34:35], v[34:35] op_sel:[0,1] op_sel_hi:[1,0]
	v_pk_add_f32 v[36:37], v[36:37], v[36:37] op_sel:[0,1] op_sel_hi:[1,0]
	v_pk_add_f32 v[40:41], v[44:45], v[42:43]
	v_pk_add_f32 v[38:39], v[38:39], v[38:39] op_sel:[0,1] op_sel_hi:[1,0]
	v_pk_add_f32 v[40:41], v[40:41], v[40:41] op_sel:[0,1] op_sel_hi:[1,0]
	v_cvt_f32_f16_sdwa v35, v6 dst_sel:DWORD dst_unused:UNUSED_PAD src0_sel:WORD_1
	v_cvt_f32_f16_e32 v37, v6
	v_cvt_f32_f16_sdwa v39, v7 dst_sel:DWORD dst_unused:UNUSED_PAD src0_sel:WORD_1
	v_cvt_f32_f16_e32 v41, v7
	v_cvt_f32_f16_sdwa v43, v8 dst_sel:DWORD dst_unused:UNUSED_PAD src0_sel:WORD_1
	v_cvt_f32_f16_e32 v45, v8
	v_cvt_f32_f16_sdwa v47, v9 dst_sel:DWORD dst_unused:UNUSED_PAD src0_sel:WORD_1
	v_cvt_f32_f16_e32 v48, v9
	v_add_f32_e32 v42, v35, v37
	v_add_f32_e32 v44, v39, v41
	v_cvt_f32_f16_sdwa v37, v2 dst_sel:DWORD dst_unused:UNUSED_PAD src0_sel:WORD_1
	v_cvt_f32_f16_e32 v35, v2
	v_cvt_f32_f16_sdwa v41, v3 dst_sel:DWORD dst_unused:UNUSED_PAD src0_sel:WORD_1
	v_cvt_f32_f16_e32 v39, v3
	v_add_f32_e32 v46, v43, v45
	v_add_f32_e32 v48, v47, v48
	v_cvt_f32_f16_sdwa v45, v4 dst_sel:DWORD dst_unused:UNUSED_PAD src0_sel:WORD_1
	v_cvt_f32_f16_e32 v43, v4
	v_cvt_f32_f16_sdwa v49, v5 dst_sel:DWORD dst_unused:UNUSED_PAD src0_sel:WORD_1
	v_cvt_f32_f16_e32 v47, v5
	v_pk_add_f32 v[34:35], v[34:35], v[36:37]
	v_pk_add_f32 v[36:37], v[38:39], v[40:41]
	v_pk_add_f32 v[38:39], v[46:47], v[48:49]
	v_pk_add_f32 v[34:35], v[34:35], v[36:37]
	v_pk_add_f32 v[36:37], v[42:43], v[44:45]
	s_nop 0
	v_pk_add_f32 v[36:37], v[36:37], v[38:39]
	s_nop 0
	v_pk_add_f32 v[34:35], v[34:35], v[36:37]
	s_nop 0
	v_add_f32_e32 v34, v34, v35
	s_nop 1
	v_mov_b32_dpp v35, v34 quad_perm:[1,0,3,2] row_mask:0xf bank_mask:0xf
	s_waitcnt lgkmcnt(0)
	v_add_f32_e32 v34, v34, v35
	s_nop 1
	v_mov_b32_dpp v35, v34 quad_perm:[2,3,0,1] row_mask:0xf bank_mask:0xf
	s_waitcnt lgkmcnt(0)
	v_add_f32_e32 v34, v34, v35
	s_nop 1
	v_mov_b32_dpp v35, v34 row_half_mirror row_mask:0xf bank_mask:0xf
	s_waitcnt lgkmcnt(0)
; __device__ __forceinline__ f32x4 h4lo(const u32x4 w) { return (f32x4){hlo(w.x), hhi(w.x), hlo(w.y), hhi(w.y)}; }
; __device__ __forceinline__ f32x4 h4hi(const u32x4 w) { return (f32x4){hlo(w.z), hhi(w.z), hlo(w.w), hhi(w.w)}; }
; __device__ __forceinline__ void ln_load_b(const v4u (&raw)[8], f32x4 (&v)[16], float& mean, float& rstd, int lane) {
;     ...
;     for (int j = 0; j < 8; ++j) { const v4u w = raw[j]; v[2 * j] = pg8::h4lo(w); v[2 * j + 1] = pg8::h4hi(w);
;         s += ((v[2 * j].x + v[2 * j].y) + (v[2 * j].z + v[2 * j].w)) + ((v[2 * j + 1].x + v[2 * j + 1].y) + (v[2 * j + 1].z + v[2 * j + 1].w)); }
;     mean = wave_sum(s) * (1.f / 4096.f); float s2 = 0.f;
; #pragma unroll
;     for (int j = 0; j < 16; ++j) { v[j] = v[j] - mean; s2 += (v[j].x * v[j].x + v[j].y * v[j].y) + (v[j].z * v[j].z + v[j].w * v[j].w); }
;     rstd = 1.f / sqrtf(wave_sum(s2) * (1.f / 4096.f) + 1e-5f);
	v_add_f32_e32 v34, v34, v35
	s_nop 1
	v_mov_b32_dpp v35, v34 row_mirror row_mask:0xf bank_mask:0xf
	s_waitcnt lgkmcnt(0)
	v_add_f32_e32 v34, v34, v35
	v_mov_b32_e32 v35, v34
	s_nop 1
	v_permlane16_swap_b32_e32 v35, v34
	s_waitcnt lgkmcnt(0)
	v_add_f32_e32 v34, v34, v35
	v_mov_b32_e32 v35, v34
	s_nop 1
	v_permlane32_swap_b32_e32 v35, v34
	s_waitcnt lgkmcnt(0)
	v_add_f32_e32 v114, v34, v35
	v_fma_mix_f32 v35, v114, s87, v31 op_sel:[0,0,1] op_sel_hi:[0,0,1]
	v_fma_mix_f32 v41, v114, s87, v30 op_sel:[0,0,1] op_sel_hi:[0,0,1]
	v_fma_mix_f32 v34, v114, s87, v31 op_sel_hi:[0,0,1]
	v_fma_mix_f32 v40, v114, s87, v30 op_sel_hi:[0,0,1]
	v_mul_f32_e32 v30, v41, v41
	v_mul_f32_e32 v31, v35, v35
	v_fmac_f32_e32 v30, v40, v40
	v_fmac_f32_e32 v31, v34, v34
	v_fma_mix_f32 v43, v114, s87, v33 op_sel:[0,0,1] op_sel_hi:[0,0,1]
	v_fma_mix_f32 v113, v114, s87, v32 op_sel:[0,0,1] op_sel_hi:[0,0,1]
	v_fma_mix_f32 v37, v114, s87, v27 op_sel:[0,0,1] op_sel_hi:[0,0,1]
	v_fma_mix_f32 v39, v114, s87, v26 op_sel:[0,0,1] op_sel_hi:[0,0,1]
	v_add_f32_e32 v30, v30, v31
	v_fma_mix_f32 v42, v114, s87, v33 op_sel_hi:[0,0,1]
	v_fma_mix_f32 v112, v114, s87, v32 op_sel_hi:[0,0,1]
	v_mul_f32_e32 v31, v113, v113
	v_mul_f32_e32 v32, v43, v43
	v_fma_mix_f32 v36, v114, s87, v27 op_sel_hi:[0,0,1]
	v_fma_mix_f32 v38, v114, s87, v26 op_sel_hi:[0,0,1]
	v_mul_f32_e32 v26, v39, v39
	v_mul_f32_e32 v27, v37, v37
	v_fmac_f32_e32 v31, v112, v112
	v_fmac_f32_e32 v32, v42, v42
	v_fmac_f32_e32 v26, v38, v38
	v_fmac_f32_e32 v27, v36, v36
	v_fma_mix_f32 v49, v114, s87, v29 op_sel:[0,0,1] op_sel_hi:[0,0,1]
	v_fma_mix_f32 v51, v114, s87, v28 op_sel:[0,0,1] op_sel_hi:[0,0,1]
	v_fma_mix_f32 v45, v114, s87, v23 op_sel:[0,0,1] op_sel_hi:[0,0,1]
	v_fma_mix_f32 v47, v114, s87, v22 op_sel:[0,0,1] op_sel_hi:[0,0,1]
	v_add_f32_e32 v31, v31, v32
	v_add_f32_e32 v26, v26, v27
	v_fma_mix_f32 v48, v114, s87, v29 op_sel_hi:[0,0,1]
	v_fma_mix_f32 v50, v114, s87, v28 op_sel_hi:[0,0,1]
	v_mul_f32_e32 v27, v51, v51
	v_mul_f32_e32 v28, v49, v49
	v_fma_mix_f32 v44, v114, s87, v23 op_sel_hi:[0,0,1]
	v_fma_mix_f32 v46, v114, s87, v22 op_sel_hi:[0,0,1]
	v_mul_f32_e32 v22, v47, v47
	v_mul_f32_e32 v23, v45, v45
	v_add_f32_e32 v30, v30, v31
	v_fmac_f32_e32 v27, v50, v50
	v_fmac_f32_e32 v28, v48, v48
	v_fmac_f32_e32 v22, v46, v46
	v_fmac_f32_e32 v23, v44, v44
	v_fma_mix_f32 v57, v114, s87, v25 op_sel:[0,0,1] op_sel_hi:[0,0,1]
	v_fma_mix_f32 v59, v114, s87, v24 op_sel:[0,0,1] op_sel_hi:[0,0,1]
	v_fma_mix_f32 v53, v114, s87, v19 op_sel:[0,0,1] op_sel_hi:[0,0,1]
	v_fma_mix_f32 v55, v114, s87, v18 op_sel:[0,0,1] op_sel_hi:[0,0,1]
	v_add_f32_e32 v26, v26, v30
	v_add_f32_e32 v27, v27, v28
	v_add_f32_e32 v22, v22, v23
	v_fma_mix_f32 v56, v114, s87, v25 op_sel_hi:[0,0,1]
	v_fma_mix_f32 v58, v114, s87, v24 op_sel_hi:[0,0,1]
	v_mul_f32_e32 v23, v59, v59
	v_mul_f32_e32 v24, v57, v57
	v_fma_mix_f32 v52, v114, s87, v19 op_sel_hi:[0,0,1]
	v_fma_mix_f32 v54, v114, s87, v18 op_sel_hi:[0,0,1]
	v_mul_f32_e32 v18, v55, v55
	v_mul_f32_e32 v19, v53, v53
	v_add_f32_e32 v26, v27, v26
	v_fmac_f32_e32 v23, v58, v58
	v_fmac_f32_e32 v24, v56, v56
	v_fmac_f32_e32 v18, v54, v54
	v_fmac_f32_e32 v19, v52, v52
	v_fma_mix_f32 v65, v114, s87, v21 op_sel:[0,0,1] op_sel_hi:[0,0,1]
	v_fma_mix_f32 v103, v114, s87, v20 op_sel:[0,0,1] op_sel_hi:[0,0,1]
	v_fma_mix_f32 v61, v114, s87, v15 op_sel:[0,0,1] op_sel_hi:[0,0,1]
	v_fma_mix_f32 v63, v114, s87, v14 op_sel:[0,0,1] op_sel_hi:[0,0,1]
	v_add_f32_e32 v22, v22, v26
	v_add_f32_e32 v23, v23, v24
	v_add_f32_e32 v18, v18, v19
	v_fma_mix_f32 v64, v114, s87, v21 op_sel_hi:[0,0,1]
	v_fma_mix_f32 v102, v114, s87, v20 op_sel_hi:[0,0,1]
	v_mul_f32_e32 v19, v103, v103
	v_mul_f32_e32 v20, v65, v65
	v_fma_mix_f32 v60, v114, s87, v15 op_sel_hi:[0,0,1]
	v_fma_mix_f32 v62, v114, s87, v14 op_sel_hi:[0,0,1]
	v_mul_f32_e32 v14, v63, v63
	v_mul_f32_e32 v15, v61, v61
	v_add_f32_e32 v22, v23, v22
	v_fmac_f32_e32 v19, v102, v102
	v_fmac_f32_e32 v20, v64, v64
	v_fmac_f32_e32 v14, v62, v62
	v_fmac_f32_e32 v15, v60, v60
	v_fma_mix_f32 v109, v114, s87, v17 op_sel:[0,0,1] op_sel_hi:[0,0,1]
	v_fma_mix_f32 v111, v114, s87, v16 op_sel:[0,0,1] op_sel_hi:[0,0,1]
	v_add_f32_e32 v18, v18, v22
	v_add_f32_e32 v19, v19, v20
	v_add_f32_e32 v14, v14, v15
	v_fma_mix_f32 v108, v114, s87, v17 op_sel_hi:[0,0,1]
	v_fma_mix_f32 v110, v114, s87, v16 op_sel_hi:[0,0,1]
	v_mul_f32_e32 v15, v111, v111
	v_mul_f32_e32 v16, v109, v109
	v_add_f32_e32 v18, v19, v18
	v_fmac_f32_e32 v15, v110, v110
	v_fmac_f32_e32 v16, v108, v108
	v_add_f32_e32 v14, v14, v18
	v_add_f32_e32 v15, v15, v16
	v_add_f32_e32 v18, v15, v14
	v_fma_mix_f32 v15, v114, s87, v11 op_sel:[0,0,1] op_sel_hi:[0,0,1]
	v_fma_mix_f32 v17, v114, s87, v10 op_sel:[0,0,1] op_sel_hi:[0,0,1]
	v_fma_mix_f32 v14, v114, s87, v11 op_sel_hi:[0,0,1]
	v_fma_mix_f32 v16, v114, s87, v10 op_sel_hi:[0,0,1]
	v_mul_f32_e32 v10, v17, v17
	v_mul_f32_e32 v11, v15, v15
	v_fmac_f32_e32 v10, v16, v16
	v_fmac_f32_e32 v11, v14, v14
	v_fma_mix_f32 v105, v114, s87, v13 op_sel:[0,0,1] op_sel_hi:[0,0,1]
	v_fma_mix_f32 v107, v114, s87, v12 op_sel:[0,0,1] op_sel_hi:[0,0,1]
	v_add_f32_e32 v10, v10, v11
	v_fma_mix_f32 v104, v114, s87, v13 op_sel_hi:[0,0,1]
	v_fma_mix_f32 v106, v114, s87, v12 op_sel_hi:[0,0,1]
	v_mul_f32_e32 v11, v107, v107
	v_mul_f32_e32 v12, v105, v105
	v_fmac_f32_e32 v11, v106, v106
	v_fmac_f32_e32 v12, v104, v104
	v_add_f32_e32 v10, v10, v18
	v_add_f32_e32 v11, v11, v12
	v_add_f32_e32 v12, v11, v10
	v_fma_mix_f32 v11, v114, s87, v7 op_sel:[0,0,1] op_sel_hi:[0,0,1]
	v_fma_mix_f32 v10, v114, s87, v7 op_sel_hi:[0,0,1]
	v_fma_mix_f32 v7, v114, s87, v6 op_sel:[0,0,1] op_sel_hi:[0,0,1]
	v_fma_mix_f32 v6, v114, s87, v6 op_sel_hi:[0,0,1]
; __device__ __forceinline__ void ln_load_b(const v4u (&raw)[8], f32x4 (&v)[16], float& mean, float& rstd, int lane) {
;     ...
;     mean = wave_sum(s) * (1.f / 4096.f); float s2 = 0.f;
; #pragma unroll
;     for (int j = 0; j < 16; ++j) { v[j] = v[j] - mean; s2 += (v[j].x * v[j].x + v[j].y * v[j].y) + (v[j].z * v[j].z + v[j].w * v[j].w); }
;     rstd = 1.f / sqrtf(wave_sum(s2) * (1.f / 4096.f) + 1e-5f);
; }
; __device__ __forceinline__ void ln_row_qb(const v4u (&src)[8], const float* g, const float* b, signed char* dstq, float* rowinv, float* stat, int lane) {
;     f32x4 v[16]; float mean, rstd; ln_load_b(src, v, mean, rstd, lane);
;     if (lane == 0) { stat[0] = mean; stat[1] = rstd; }
;     float mx = 0.f;
; #pragma unroll
;     for (int j = 0; j < 16; ++j) {
;         const int q = 2 * (64 * (j >> 1) + lane) + (j & 1);
;         const f32x4 gg = ((const f32x4*)g)[q], bb = ((const f32x4*)b)[q];
;         v[j] = v[j] * rstd * gg + bb;
;         mx = fmaxf(fmaxf(mx, fmaxf(fabsf(v[j].x), fabsf(v[j].y))), fmaxf(fabsf(v[j].z), fabsf(v[j].w)));
;     }
	v_mul_f32_e32 v13, v7, v7
	v_mul_f32_e32 v18, v11, v11
	v_fmac_f32_e32 v13, v6, v6
	v_fmac_f32_e32 v18, v10, v10
	v_add_f32_e32 v13, v13, v18
	v_add_f32_e32 v18, v13, v12
	v_fma_mix_f32 v13, v114, s87, v9 op_sel:[0,0,1] op_sel_hi:[0,0,1]
	v_fma_mix_f32 v12, v114, s87, v9 op_sel_hi:[0,0,1]
	v_fma_mix_f32 v9, v114, s87, v8 op_sel:[0,0,1] op_sel_hi:[0,0,1]
	v_fma_mix_f32 v8, v114, s87, v8 op_sel_hi:[0,0,1]
	v_mul_f32_e32 v19, v9, v9
	v_mul_f32_e32 v20, v13, v13
	v_fmac_f32_e32 v19, v8, v8
	v_fmac_f32_e32 v20, v12, v12
	v_fma_mix_f32 v21, v114, s87, v3 op_sel:[0,0,1] op_sel_hi:[0,0,1]
	v_fma_mix_f32 v25, v114, s87, v2 op_sel:[0,0,1] op_sel_hi:[0,0,1]
	v_add_f32_e32 v19, v19, v20
	v_fma_mix_f32 v20, v114, s87, v3 op_sel_hi:[0,0,1]
	v_fma_mix_f32 v24, v114, s87, v2 op_sel_hi:[0,0,1]
	v_mul_f32_e32 v2, v25, v25
	v_mul_f32_e32 v3, v21, v21
	v_fmac_f32_e32 v2, v24, v24
	v_fmac_f32_e32 v3, v20, v20
	v_add_f32_e32 v18, v19, v18
	v_add_f32_e32 v2, v2, v3
	v_fma_mix_f32 v19, v114, s87, v5 op_sel:[0,0,1] op_sel_hi:[0,0,1]
	v_fma_mix_f32 v23, v114, s87, v4 op_sel:[0,0,1] op_sel_hi:[0,0,1]
	v_add_f32_e32 v2, v2, v18
	v_fma_mix_f32 v18, v114, s87, v5 op_sel_hi:[0,0,1]
	v_fma_mix_f32 v22, v114, s87, v4 op_sel_hi:[0,0,1]
	v_mul_f32_e32 v3, v23, v23
	v_mul_f32_e32 v4, v19, v19
	v_fmac_f32_e32 v3, v22, v22
	v_fmac_f32_e32 v4, v18, v18
	v_add_f32_e32 v3, v3, v4
	v_add_f32_e32 v2, v3, v2
	s_nop 1
	v_mov_b32_dpp v3, v2 quad_perm:[1,0,3,2] row_mask:0xf bank_mask:0xf
	s_waitcnt lgkmcnt(0)
	v_add_f32_e32 v2, v2, v3
	s_nop 1
	v_mov_b32_dpp v3, v2 quad_perm:[2,3,0,1] row_mask:0xf bank_mask:0xf
	s_waitcnt lgkmcnt(0)
	v_add_f32_e32 v2, v2, v3
	s_nop 1
	v_mov_b32_dpp v3, v2 row_half_mirror row_mask:0xf bank_mask:0xf
	s_waitcnt lgkmcnt(0)
	v_add_f32_e32 v2, v2, v3
	s_nop 1
	v_mov_b32_dpp v3, v2 row_mirror row_mask:0xf bank_mask:0xf
	s_waitcnt lgkmcnt(0)
	v_add_f32_e32 v2, v2, v3
	v_mov_b32_e32 v3, v2
	s_nop 1
	v_permlane16_swap_b32_e32 v3, v2
	s_waitcnt lgkmcnt(0)
	v_add_f32_e32 v2, v2, v3
	v_mov_b32_e32 v3, v2
	s_nop 1
	v_permlane32_swap_b32_e32 v3, v2
	s_waitcnt lgkmcnt(0)
	v_add_f32_e32 v2, v2, v3
	v_fmamk_f32 v2, v2, 0x39800000, v216
	v_mul_f32_e32 v3, 0x4f800000, v2
	v_cmp_gt_f32_e32 vcc, s95, v2
	s_nop 1
	v_cndmask_b32_e32 v2, v2, v3, vcc
	v_sqrt_f32_e32 v3, v2
	s_nop 0
	v_add_u32_e32 v4, -1, v3
	v_fma_f32 v5, -v4, v3, v2
	v_cmp_ge_f32_e64 s[8:9], 0, v5
	v_add_u32_e32 v5, 1, v3
	s_nop 0
	v_cndmask_b32_e64 v4, v3, v4, s[8:9]
	v_fma_f32 v3, -v5, v3, v2
	v_cmp_lt_f32_e64 s[8:9], 0, v3
	s_nop 1
	v_cndmask_b32_e64 v3, v4, v5, s[8:9]
	v_mul_f32_e32 v4, 0x37800000, v3
	v_cndmask_b32_e32 v3, v3, v4, vcc
	v_cmp_class_f32_e32 vcc, v2, v215
	s_nop 1
	v_cndmask_b32_e32 v2, v3, v2, vcc
	v_div_scale_f32 v3, s[8:9], v2, v2, 1.0
	v_rcp_f32_e32 v4, v3
	s_nop 0
	v_fma_f32 v5, -v3, v4, 1.0
	v_fmac_f32_e32 v4, v5, v4
	v_div_scale_f32 v5, vcc, 1.0, v2, 1.0
	v_mul_f32_e32 v26, v5, v4
	v_fma_f32 v27, -v3, v26, v5
	v_fmac_f32_e32 v26, v27, v4
	v_fma_f32 v3, -v3, v26, v5
	v_div_fmas_f32 v3, v3, v4, v26
	v_div_fixup_f32 v30, v3, v2, 1.0
	s_and_saveexec_b64 s[8:9], s[6:7]
	s_cbranch_execz .LBB0_989
	s_lshl_b32 s16, s14, 1
	s_ashr_i32 s17, s16, 31
	s_lshl_b64 s[16:17], s[16:17], 2
	s_add_u32 s16, s29, s16
	v_mul_f32_e32 v2, 0x39800000, v114
	s_addc_u32 s17, s42, s17
	v_mov_b32_e32 v3, v30
	global_store_dwordx2 v183, v[2:3], s[16:17]
.LBB0_989:
	s_or_b64 exec, exec, s[8:9]
	ds_read_b128 v[2:5], v181 offset:16
	ds_read_b128 v[26:29], v181
	ds_read_b128 v[114:117], v181 offset:16400
	ds_read_b128 v[118:121], v181 offset:16384
	v_pk_mul_f32 v[32:33], v[34:35], v[30:31] op_sel_hi:[1,0]
	v_pk_mul_f32 v[34:35], v[40:41], v[30:31] op_sel_hi:[1,0]
	s_waitcnt vmcnt(0) lgkmcnt(0)
	v_pk_fma_f32 v[32:33], v[32:33], v[28:29], v[120:121]
	v_pk_fma_f32 v[34:35], v[34:35], v[26:27], v[118:119]
	v_max_f32_e64 v27, |v32|, |v33|
	v_max_f32_e64 v26, |v34|, |v35|
	v_max3_f32 v31, v26, 0, v27
	v_pk_mul_f32 v[26:27], v[42:43], v[30:31] op_sel_hi:[1,0]
	v_pk_mul_f32 v[28:29], v[112:113], v[30:31] op_sel_hi:[1,0]
	v_pk_fma_f32 v[26:27], v[26:27], v[4:5], v[116:117]
	v_pk_fma_f32 v[28:29], v[28:29], v[2:3], v[114:115]
	v_max_f32_e64 v3, |v26|, |v27|
	v_max_f32_e64 v2, |v28|, |v29|
	v_max3_f32 v31, v31, v2, v3
	ds_read_b128 v[2:5], v181 offset:2064
	ds_read_b128 v[112:115], v181 offset:2048
	ds_read_b128 v[116:119], v181 offset:18448
	ds_read_b128 v[120:123], v181 offset:18432
	v_pk_mul_f32 v[36:37], v[36:37], v[30:31] op_sel_hi:[1,0]
	v_pk_mul_f32 v[38:39], v[38:39], v[30:31] op_sel_hi:[1,0]
	s_waitcnt lgkmcnt(0)
	v_pk_fma_f32 v[40:41], v[36:37], v[114:115], v[122:123]
	v_pk_fma_f32 v[42:43], v[38:39], v[112:113], v[120:121]
	v_max_f32_e64 v37, |v40|, |v41|
	v_max_f32_e64 v36, |v42|, |v43|
	v_max3_f32 v31, v31, v36, v37
	v_pk_mul_f32 v[36:37], v[48:49], v[30:31] op_sel_hi:[1,0]
	v_pk_mul_f32 v[38:39], v[50:51], v[30:31] op_sel_hi:[1,0]
	v_pk_fma_f32 v[36:37], v[36:37], v[4:5], v[118:119]
	v_pk_fma_f32 v[38:39], v[38:39], v[2:3], v[116:117]
	v_max_f32_e64 v3, |v36|, |v37|
	v_max_f32_e64 v2, |v38|, |v39|
	v_max3_f32 v31, v31, v2, v3
	ds_read_b128 v[2:5], v181 offset:4112
	ds_read_b128 v[112:115], v181 offset:4096
	ds_read_b128 v[116:119], v181 offset:20496
	ds_read_b128 v[120:123], v181 offset:20480
	v_pk_mul_f32 v[44:45], v[44:45], v[30:31] op_sel_hi:[1,0]
	v_pk_mul_f32 v[46:47], v[46:47], v[30:31] op_sel_hi:[1,0]
	s_waitcnt lgkmcnt(0)
; __device__ __forceinline__ void ln_row_qb(const v4u (&src)[8], const float* g, const float* b, signed char* dstq, float* rowinv, float* stat, int lane) {
;     ...
;     float mx = 0.f;
; #pragma unroll
;     for (int j = 0; j < 16; ++j) {
;         const int q = 2 * (64 * (j >> 1) + lane) + (j & 1);
;         const f32x4 gg = ((const f32x4*)g)[q], bb = ((const f32x4*)b)[q];
;         v[j] = v[j] * rstd * gg + bb;
;         mx = fmaxf(fmaxf(mx, fmaxf(fabsf(v[j].x), fabsf(v[j].y))), fmaxf(fabsf(v[j].z), fabsf(v[j].w)));
;     }
; #pragma unroll
;     for (int o = 1; o < 64; o <<= 1) mx = fmaxf(mx, __shfl_xor(mx, o));
;     mx = fmaxf(mx, 1e-20f);
;     const float sc = 127.0f / mx;
;     if (lane == 0) *rowinv = mx * (1.0f / 127.0f);
	v_pk_fma_f32 v[48:49], v[44:45], v[114:115], v[122:123]
	v_pk_fma_f32 v[50:51], v[46:47], v[112:113], v[120:121]
	v_max_f32_e64 v45, |v48|, |v49|
	v_max_f32_e64 v44, |v50|, |v51|
	v_max3_f32 v31, v31, v44, v45
	v_pk_mul_f32 v[44:45], v[56:57], v[30:31] op_sel_hi:[1,0]
	v_pk_mul_f32 v[46:47], v[58:59], v[30:31] op_sel_hi:[1,0]
	v_pk_fma_f32 v[44:45], v[44:45], v[4:5], v[118:119]
	v_pk_fma_f32 v[46:47], v[46:47], v[2:3], v[116:117]
	v_max_f32_e64 v3, |v44|, |v45|
	v_max_f32_e64 v2, |v46|, |v47|
	v_max3_f32 v31, v31, v2, v3
	ds_read_b128 v[2:5], v181 offset:6160
	ds_read_b128 v[112:115], v181 offset:6144
	ds_read_b128 v[116:119], v181 offset:22544
	ds_read_b128 v[120:123], v181 offset:22528
	v_pk_mul_f32 v[52:53], v[52:53], v[30:31] op_sel_hi:[1,0]
	v_pk_mul_f32 v[54:55], v[54:55], v[30:31] op_sel_hi:[1,0]
	s_waitcnt lgkmcnt(0)
	v_pk_fma_f32 v[56:57], v[52:53], v[114:115], v[122:123]
	v_pk_fma_f32 v[58:59], v[54:55], v[112:113], v[120:121]
	v_max_f32_e64 v53, |v56|, |v57|
	v_max_f32_e64 v52, |v58|, |v59|
	v_max3_f32 v31, v31, v52, v53
	v_pk_mul_f32 v[52:53], v[64:65], v[30:31] op_sel_hi:[1,0]
	v_pk_mul_f32 v[54:55], v[102:103], v[30:31] op_sel_hi:[1,0]
	v_pk_fma_f32 v[52:53], v[52:53], v[4:5], v[118:119]
	v_pk_fma_f32 v[54:55], v[54:55], v[2:3], v[116:117]
	v_max_f32_e64 v3, |v52|, |v53|
	v_max_f32_e64 v2, |v54|, |v55|
	v_max3_f32 v31, v31, v2, v3
	ds_read_b128 v[2:5], v181 offset:8208
	ds_read_b128 v[112:115], v181 offset:8192
	ds_read_b128 v[116:119], v181 offset:24592
	ds_read_b128 v[120:123], v181 offset:24576
	v_pk_mul_f32 v[60:61], v[60:61], v[30:31] op_sel_hi:[1,0]
	v_pk_mul_f32 v[62:63], v[62:63], v[30:31] op_sel_hi:[1,0]
	s_waitcnt lgkmcnt(0)
	v_pk_fma_f32 v[64:65], v[60:61], v[114:115], v[122:123]
	v_pk_fma_f32 v[102:103], v[62:63], v[112:113], v[120:121]
	v_max_f32_e64 v61, |v64|, |v65|
	v_max_f32_e64 v60, |v102|, |v103|
	v_max3_f32 v31, v31, v60, v61
	v_pk_mul_f32 v[60:61], v[108:109], v[30:31] op_sel_hi:[1,0]
	v_pk_mul_f32 v[62:63], v[110:111], v[30:31] op_sel_hi:[1,0]
	v_pk_fma_f32 v[60:61], v[60:61], v[4:5], v[118:119]
	v_pk_fma_f32 v[62:63], v[62:63], v[2:3], v[116:117]
	v_max_f32_e64 v3, |v60|, |v61|
	v_max_f32_e64 v2, |v62|, |v63|
	v_max3_f32 v31, v31, v2, v3
	ds_read_b128 v[2:5], v181 offset:10256
	ds_read_b128 v[110:113], v181 offset:10240
	ds_read_b128 v[114:117], v181 offset:26640
	ds_read_b128 v[118:121], v181 offset:26624
	v_pk_mul_f32 v[14:15], v[14:15], v[30:31] op_sel_hi:[1,0]
	v_pk_mul_f32 v[16:17], v[16:17], v[30:31] op_sel_hi:[1,0]
	s_waitcnt lgkmcnt(0)
	v_pk_fma_f32 v[108:109], v[14:15], v[112:113], v[120:121]
	v_pk_fma_f32 v[110:111], v[16:17], v[110:111], v[118:119]
	v_max_f32_e64 v15, |v108|, |v109|
	v_max_f32_e64 v14, |v110|, |v111|
	v_max3_f32 v31, v31, v14, v15
	v_pk_mul_f32 v[14:15], v[104:105], v[30:31] op_sel_hi:[1,0]
	v_pk_mul_f32 v[16:17], v[106:107], v[30:31] op_sel_hi:[1,0]
	v_pk_fma_f32 v[104:105], v[14:15], v[4:5], v[116:117]
	v_pk_fma_f32 v[106:107], v[16:17], v[2:3], v[114:115]
	v_max_f32_e64 v3, |v104|, |v105|
	v_max_f32_e64 v2, |v106|, |v107|
	v_max3_f32 v31, v31, v2, v3
	ds_read_b128 v[2:5], v181 offset:12304
	ds_read_b128 v[14:17], v181 offset:12288
	ds_read_b128 v[120:123], v181 offset:28688
	ds_read_b128 v[112:115], v181 offset:28672
	v_pk_mul_f32 v[10:11], v[10:11], v[30:31] op_sel_hi:[1,0]
	v_pk_mul_f32 v[6:7], v[6:7], v[30:31] op_sel_hi:[1,0]
	v_pk_mul_f32 v[8:9], v[8:9], v[30:31] op_sel_hi:[1,0]
	s_waitcnt lgkmcnt(0)
	v_pk_fma_f32 v[116:117], v[10:11], v[16:17], v[114:115]
	v_pk_fma_f32 v[118:119], v[6:7], v[14:15], v[112:113]
	v_max_f32_e64 v7, |v116|, |v117|
	v_max_f32_e64 v6, |v118|, |v119|
	v_max3_f32 v10, v31, v6, v7
	v_pk_mul_f32 v[6:7], v[12:13], v[30:31] op_sel_hi:[1,0]
	v_pk_fma_f32 v[114:115], v[8:9], v[2:3], v[120:121]
	v_pk_fma_f32 v[112:113], v[6:7], v[4:5], v[122:123]
	v_max_f32_e64 v2, |v114|, |v115|
	v_max_f32_e64 v3, |v112|, |v113|
	v_max3_f32 v31, v10, v2, v3
	ds_read_b128 v[2:5], v181 offset:14352
	ds_read_b128 v[10:13], v181 offset:14336
	ds_read_b128 v[6:9], v181 offset:30736
	ds_read_b128 v[14:17], v181 offset:30720
	v_pk_mul_f32 v[20:21], v[20:21], v[30:31] op_sel_hi:[1,0]
	v_pk_mul_f32 v[24:25], v[24:25], v[30:31] op_sel_hi:[1,0]
	s_waitcnt lgkmcnt(0)
	v_pk_fma_f32 v[12:13], v[20:21], v[12:13], v[16:17]
	v_pk_fma_f32 v[10:11], v[24:25], v[10:11], v[14:15]
	v_max_f32_e64 v15, |v12|, |v13|
	v_max_f32_e64 v14, |v10|, |v11|
	v_max3_f32 v20, v31, v14, v15
	v_pk_mul_f32 v[14:15], v[18:19], v[30:31] op_sel_hi:[1,0]
	v_pk_mul_f32 v[16:17], v[22:23], v[30:31] op_sel_hi:[1,0]
	v_pk_fma_f32 v[4:5], v[14:15], v[4:5], v[8:9]
	v_pk_fma_f32 v[2:3], v[16:17], v[2:3], v[6:7]
	v_max_f32_e64 v7, |v4|, |v5|
	v_max_f32_e64 v6, |v2|, |v3|
	v_max3_f32 v6, v20, v6, v7
	s_nop 1
	v_mov_b32_dpp v7, v6 quad_perm:[1,0,3,2] row_mask:0xf bank_mask:0xf
	s_waitcnt lgkmcnt(0)
	v_max_f32_e32 v7, v7, v7
	v_max_f32_e32 v6, v6, v7
	s_nop 1
	v_mov_b32_dpp v7, v6 quad_perm:[2,3,0,1] row_mask:0xf bank_mask:0xf
	s_waitcnt lgkmcnt(0)
	v_max_f32_e32 v7, v7, v7
	v_max_f32_e32 v6, v6, v7
	s_nop 1
	v_mov_b32_dpp v7, v6 row_half_mirror row_mask:0xf bank_mask:0xf
	s_waitcnt lgkmcnt(0)
	v_max_f32_e32 v7, v7, v7
	v_max_f32_e32 v6, v6, v7
	s_nop 1
	v_mov_b32_dpp v7, v6 row_mirror row_mask:0xf bank_mask:0xf
	s_waitcnt lgkmcnt(0)
	v_max_f32_e32 v7, v7, v7
	v_max_f32_e32 v6, v6, v7
	v_mov_b32_e32 v7, v6
	s_nop 1
	v_permlane16_swap_b32_e32 v7, v6
	s_waitcnt lgkmcnt(0)
	v_max_f32_e32 v7, v7, v7
	v_max_f32_e32 v6, v6, v7
	v_mov_b32_e32 v7, v6
	s_nop 1
	v_permlane32_swap_b32_e32 v7, v6
	s_waitcnt lgkmcnt(0)
	v_max3_f32 v6, v6, v7, s50
	s_and_saveexec_b64 s[8:9], s[6:7]
	s_cbranch_execz .LBB0_980
	s_lshl_b64 s[16:17], s[14:15], 2
	s_add_u32 s16, s27, s16
	s_addc_u32 s17, s28, s17
	v_mul_f32_e32 v7, 0x3c010204, v6
	global_store_dword v183, v7, s[16:17]
	s_branch .LBB0_980

; __device__ __forceinline__ void quant_row_h(const bf16* src, signed char* dst, float* rowinv, int lane) {
;     v4u x[22]; float mx = 0.f;
; #pragma unroll
;     for (int i = 0; i < 22; ++i) { const int id = lane + 64 * i; x[i] = id < 1376 ? __builtin_nontemporal_load((const v4u*)src + id) : (v4u){0u, 0u, 0u, 0u};
;         mx = fmaxf(mx, fmaxf(fmaxf(fmaxf(fabsf(bflo(x[i].x)), fabsf(bfhi(x[i].x))), fmaxf(fabsf(bflo(x[i].y)), fabsf(bfhi(x[i].y)))), fmaxf(fmaxf(fabsf(bflo(x[i].z)), fabsf(bfhi(x[i].z))), fmaxf(fabsf(bflo(x[i].w)), fabsf(bfhi(x[i].w)))))); }
.LBB0_1126:
	s_or_b64 exec, exec, s[36:37]
	s_waitcnt vmcnt(0)
	v_lshlrev_b32_e32 v238, 16, v86
	v_and_b32_e32 v237, 0xffff0000, v86
	v_lshlrev_b32_e32 v232, 16, v89
	v_and_b32_e32 v231, 0xffff0000, v89
	v_max_f32_e64 v86, |v237|, |v237|
	v_max_f32_e64 v127, |v238|, |v238|
	v_lshlrev_b32_e32 v236, 16, v87
	v_and_b32_e32 v235, 0xffff0000, v87
	v_lshlrev_b32_e32 v234, 16, v88
	v_and_b32_e32 v233, 0xffff0000, v88
	v_max_f32_e64 v88, |v231|, |v231|
	v_max_f32_e64 v89, |v232|, |v232|
	v_max_f32_e32 v86, v127, v86
	v_max_f32_e64 v87, |v235|, |v235|
	v_max_f32_e64 v127, |v236|, |v236|
	v_max_f32_e32 v88, v89, v88
	v_max_f32_e32 v87, v127, v87
	v_max3_f32 v88, |v234|, |v233|, v88
	v_lshlrev_b32_e32 v230, 16, v82
	v_and_b32_e32 v229, 0xffff0000, v82
	v_lshlrev_b32_e32 v211, 16, v85
	v_and_b32_e32 v210, 0xffff0000, v85
	v_max3_f32 v86, v86, v87, v88
	v_max_f32_e64 v82, |v229|, |v229|
	v_max_f32_e64 v87, |v230|, |v230|
	v_lshlrev_b32_e32 v228, 16, v83
	v_and_b32_e32 v227, 0xffff0000, v83
	v_lshlrev_b32_e32 v226, 16, v84
	v_and_b32_e32 v225, 0xffff0000, v84
	v_max_f32_e64 v84, |v210|, |v210|
	v_max_f32_e64 v85, |v211|, |v211|
	v_max_f32_e32 v82, v87, v82
	v_max_f32_e64 v83, |v227|, |v227|
	v_max_f32_e64 v87, |v228|, |v228|
	v_max_f32_e32 v84, v85, v84
	v_max_f32_e32 v83, v87, v83
	v_max3_f32 v84, |v226|, |v225|, v84
	v_lshlrev_b32_e32 v209, 16, v78
	v_and_b32_e32 v208, 0xffff0000, v78
	v_lshlrev_b32_e32 v203, 16, v81
	v_and_b32_e32 v202, 0xffff0000, v81
	v_max3_f32 v82, v82, v83, v84
	v_max_f32_e64 v78, |v208|, |v208|
	v_max_f32_e64 v83, |v209|, |v209|
	v_lshlrev_b32_e32 v207, 16, v79
	v_and_b32_e32 v206, 0xffff0000, v79
	v_lshlrev_b32_e32 v205, 16, v80
	v_and_b32_e32 v204, 0xffff0000, v80
	v_max_f32_e64 v80, |v202|, |v202|
	v_max_f32_e64 v81, |v203|, |v203|
	v_max_f32_e32 v78, v83, v78
	v_max_f32_e64 v79, |v206|, |v206|
	v_max_f32_e64 v83, |v207|, |v207|
	v_max_f32_e32 v80, v81, v80
	v_max_f32_e32 v79, v83, v79
	v_max3_f32 v80, |v205|, |v204|, v80
	v_lshlrev_b32_e32 v201, 16, v74
	v_and_b32_e32 v200, 0xffff0000, v74
	v_lshlrev_b32_e32 v189, 16, v77
	v_and_b32_e32 v186, 0xffff0000, v77
	v_max3_f32 v78, v78, v79, v80
	v_max_f32_e64 v74, |v200|, |v200|
	v_max_f32_e64 v79, |v201|, |v201|
	v_lshlrev_b32_e32 v199, 16, v75
	v_and_b32_e32 v198, 0xffff0000, v75
	v_lshlrev_b32_e32 v192, 16, v76
	v_and_b32_e32 v190, 0xffff0000, v76
	v_max_f32_e64 v76, |v186|, |v186|
	v_max_f32_e64 v77, |v189|, |v189|
	v_max_f32_e32 v74, v79, v74
	v_max_f32_e64 v75, |v198|, |v198|
	v_max_f32_e64 v79, |v199|, |v199|
	v_max_f32_e32 v76, v77, v76
	v_max_f32_e32 v75, v79, v75
	v_max3_f32 v76, |v192|, |v190|, v76
	v_lshlrev_b32_e32 v185, 16, v70
	v_and_b32_e32 v182, 0xffff0000, v70
	v_lshlrev_b32_e32 v177, 16, v73
	v_and_b32_e32 v176, 0xffff0000, v73
	v_max3_f32 v74, v74, v75, v76
	v_max_f32_e64 v70, |v182|, |v182|
	v_max_f32_e64 v75, |v185|, |v185|
	v_lshlrev_b32_e32 v181, 16, v71
	v_and_b32_e32 v180, 0xffff0000, v71
	v_lshlrev_b32_e32 v179, 16, v72
	v_and_b32_e32 v178, 0xffff0000, v72
	v_max_f32_e64 v72, |v176|, |v176|
	v_max_f32_e64 v73, |v177|, |v177|
	v_max_f32_e32 v70, v75, v70
	v_max_f32_e64 v71, |v180|, |v180|
	v_max_f32_e64 v75, |v181|, |v181|
	v_max_f32_e32 v72, v73, v72
	v_max_f32_e32 v71, v75, v71
	v_max3_f32 v72, |v179|, |v178|, v72
	v_lshlrev_b32_e32 v175, 16, v66
	v_and_b32_e32 v174, 0xffff0000, v66
	v_lshlrev_b32_e32 v169, 16, v69
	v_and_b32_e32 v168, 0xffff0000, v69
	v_max3_f32 v70, v70, v71, v72
	v_max_f32_e64 v66, |v174|, |v174|
	v_max_f32_e64 v71, |v175|, |v175|
	v_lshlrev_b32_e32 v173, 16, v67
	v_and_b32_e32 v172, 0xffff0000, v67
	v_lshlrev_b32_e32 v171, 16, v68
	v_and_b32_e32 v170, 0xffff0000, v68
	v_max_f32_e64 v68, |v168|, |v168|
	v_max_f32_e64 v69, |v169|, |v169|
	v_max_f32_e32 v66, v71, v66
	v_max_f32_e64 v67, |v172|, |v172|
	v_max_f32_e64 v71, |v173|, |v173|
	v_max_f32_e32 v68, v69, v68
	v_max_f32_e32 v67, v71, v67
	v_max3_f32 v68, |v171|, |v170|, v68
	v_lshlrev_b32_e32 v167, 16, v62
	v_and_b32_e32 v166, 0xffff0000, v62
	v_lshlrev_b32_e32 v161, 16, v65
	v_and_b32_e32 v160, 0xffff0000, v65
	v_max3_f32 v66, v66, v67, v68
	v_max_f32_e64 v62, |v166|, |v166|
	v_max_f32_e64 v67, |v167|, |v167|
	v_lshlrev_b32_e32 v165, 16, v63
	v_and_b32_e32 v164, 0xffff0000, v63
	v_lshlrev_b32_e32 v163, 16, v64
	v_and_b32_e32 v162, 0xffff0000, v64
	v_max_f32_e64 v64, |v160|, |v160|
	v_max_f32_e64 v65, |v161|, |v161|
	v_max_f32_e32 v62, v67, v62
	v_max_f32_e64 v63, |v164|, |v164|
	v_max_f32_e64 v67, |v165|, |v165|
	v_max_f32_e32 v64, v65, v64
	v_max_f32_e32 v63, v67, v63
	v_max3_f32 v64, |v163|, |v162|, v64
	v_lshlrev_b32_e32 v159, 16, v58
	v_and_b32_e32 v158, 0xffff0000, v58
	v_lshlrev_b32_e32 v153, 16, v61
	v_and_b32_e32 v152, 0xffff0000, v61
	v_max3_f32 v62, v62, v63, v64
	v_max_f32_e64 v58, |v158|, |v158|
	v_max_f32_e64 v63, |v159|, |v159|
	v_lshlrev_b32_e32 v157, 16, v59
	v_and_b32_e32 v156, 0xffff0000, v59
	v_lshlrev_b32_e32 v155, 16, v60
	v_and_b32_e32 v154, 0xffff0000, v60
	v_max_f32_e64 v60, |v152|, |v152|
	v_max_f32_e64 v61, |v153|, |v153|
	v_max_f32_e32 v58, v63, v58
	v_max_f32_e64 v59, |v156|, |v156|
	v_max_f32_e64 v63, |v157|, |v157|
	v_max_f32_e32 v60, v61, v60
	v_max_f32_e32 v59, v63, v59
	v_max3_f32 v60, |v155|, |v154|, v60
	v_lshlrev_b32_e32 v151, 16, v54
	v_and_b32_e32 v150, 0xffff0000, v54
	v_lshlrev_b32_e32 v145, 16, v57
	v_and_b32_e32 v144, 0xffff0000, v57
	v_max3_f32 v58, v58, v59, v60
	v_max_f32_e64 v54, |v150|, |v150|
	v_max_f32_e64 v59, |v151|, |v151|
	v_lshlrev_b32_e32 v149, 16, v55
	v_and_b32_e32 v148, 0xffff0000, v55
	v_lshlrev_b32_e32 v147, 16, v56
	v_and_b32_e32 v146, 0xffff0000, v56
	v_max_f32_e64 v56, |v144|, |v144|
	v_max_f32_e64 v57, |v145|, |v145|
; __device__ __forceinline__ void quant_row_h(const bf16* src, signed char* dst, float* rowinv, int lane) {
;     v4u x[22]; float mx = 0.f;
; #pragma unroll
;     for (int i = 0; i < 22; ++i) { const int id = lane + 64 * i; x[i] = id < 1376 ? __builtin_nontemporal_load((const v4u*)src + id) : (v4u){0u, 0u, 0u, 0u};
;         mx = fmaxf(mx, fmaxf(fmaxf(fmaxf(fabsf(bflo(x[i].x)), fabsf(bfhi(x[i].x))), fmaxf(fabsf(bflo(x[i].y)), fabsf(bfhi(x[i].y)))), fmaxf(fmaxf(fabsf(bflo(x[i].z)), fabsf(bfhi(x[i].z))), fmaxf(fabsf(bflo(x[i].w)), fabsf(bfhi(x[i].w)))))); }
	v_max_f32_e32 v54, v59, v54
	v_max_f32_e64 v55, |v148|, |v148|
	v_max_f32_e64 v59, |v149|, |v149|
	v_max_f32_e32 v56, v57, v56
	v_max_f32_e32 v55, v59, v55
	v_max3_f32 v56, |v147|, |v146|, v56
	v_lshlrev_b32_e32 v143, 16, v50
	v_and_b32_e32 v142, 0xffff0000, v50
	v_lshlrev_b32_e32 v137, 16, v53
	v_and_b32_e32 v136, 0xffff0000, v53
	v_max3_f32 v54, v54, v55, v56
	v_max_f32_e64 v50, |v142|, |v142|
	v_max_f32_e64 v55, |v143|, |v143|
	v_lshlrev_b32_e32 v141, 16, v51
	v_and_b32_e32 v140, 0xffff0000, v51
	v_lshlrev_b32_e32 v139, 16, v52
	v_and_b32_e32 v138, 0xffff0000, v52
	v_max_f32_e64 v52, |v136|, |v136|
	v_max_f32_e64 v53, |v137|, |v137|
	v_max_f32_e32 v50, v55, v50
	v_max_f32_e64 v51, |v140|, |v140|
	v_max_f32_e64 v55, |v141|, |v141|
	v_max_f32_e32 v52, v53, v52
	v_max_f32_e32 v51, v55, v51
	v_max3_f32 v52, |v139|, |v138|, v52
	v_lshlrev_b32_e32 v135, 16, v46
	v_and_b32_e32 v134, 0xffff0000, v46
	v_lshlrev_b32_e32 v129, 16, v49
	v_and_b32_e32 v128, 0xffff0000, v49
	v_max3_f32 v50, v50, v51, v52
	v_max_f32_e64 v46, |v134|, |v134|
	v_max_f32_e64 v51, |v135|, |v135|
	v_lshlrev_b32_e32 v133, 16, v47
	v_and_b32_e32 v132, 0xffff0000, v47
	v_lshlrev_b32_e32 v131, 16, v48
	v_and_b32_e32 v130, 0xffff0000, v48
	v_max_f32_e64 v48, |v128|, |v128|
	v_max_f32_e64 v49, |v129|, |v129|
	v_max_f32_e32 v46, v51, v46
	v_max_f32_e64 v47, |v132|, |v132|
	v_max_f32_e64 v51, |v133|, |v133|
	v_max_f32_e32 v48, v49, v48
	v_max_f32_e32 v47, v51, v47
	v_max3_f32 v48, |v131|, |v130|, v48
	v_lshlrev_b32_e32 v127, 16, v42
	v_and_b32_e32 v89, 0xffff0000, v42
	v_lshlrev_b32_e32 v84, 16, v45
	v_and_b32_e32 v83, 0xffff0000, v45
	v_max3_f32 v82, v86, 0, v82
	v_max3_f32 v46, v46, v47, v48
	v_max_f32_e64 v42, |v89|, |v89|
	v_max_f32_e64 v47, |v127|, |v127|
	v_lshlrev_b32_e32 v88, 16, v43
	v_and_b32_e32 v87, 0xffff0000, v43
	v_lshlrev_b32_e32 v86, 16, v44
	v_and_b32_e32 v85, 0xffff0000, v44
	v_max_f32_e64 v44, |v83|, |v83|
	v_max_f32_e64 v45, |v84|, |v84|
	v_max_f32_e32 v42, v47, v42
	v_max_f32_e64 v43, |v87|, |v87|
	v_max_f32_e64 v47, |v88|, |v88|
	v_max_f32_e32 v44, v45, v44
	v_max3_f32 v74, v82, v78, v74
	v_max_f32_e32 v43, v47, v43
	v_max3_f32 v44, |v86|, |v85|, v44
	v_lshlrev_b32_e32 v82, 16, v38
	v_and_b32_e32 v81, 0xffff0000, v38
	v_lshlrev_b32_e32 v76, 16, v41
	v_and_b32_e32 v75, 0xffff0000, v41
	v_max3_f32 v42, v42, v43, v44
	v_max_f32_e64 v38, |v81|, |v81|
	v_max_f32_e64 v43, |v82|, |v82|
	v_lshlrev_b32_e32 v80, 16, v39
	v_and_b32_e32 v79, 0xffff0000, v39
	v_lshlrev_b32_e32 v78, 16, v40
	v_and_b32_e32 v77, 0xffff0000, v40
	v_max_f32_e64 v40, |v75|, |v75|
	v_max_f32_e64 v41, |v76|, |v76|
	v_max_f32_e32 v38, v43, v38
	v_max_f32_e64 v39, |v79|, |v79|
	v_max_f32_e64 v43, |v80|, |v80|
	v_max_f32_e32 v40, v41, v40
	v_max3_f32 v66, v74, v70, v66
	v_max_f32_e32 v39, v43, v39
	v_max3_f32 v40, |v78|, |v77|, v40
	v_lshlrev_b32_e32 v74, 16, v34
	v_and_b32_e32 v73, 0xffff0000, v34
	v_lshlrev_b32_e32 v68, 16, v37
	v_and_b32_e32 v67, 0xffff0000, v37
	v_max3_f32 v38, v38, v39, v40
	v_max_f32_e64 v34, |v73|, |v73|
	v_max_f32_e64 v39, |v74|, |v74|
	v_lshlrev_b32_e32 v72, 16, v35
	v_and_b32_e32 v71, 0xffff0000, v35
	v_lshlrev_b32_e32 v70, 16, v36
	v_and_b32_e32 v69, 0xffff0000, v36
	v_max_f32_e64 v36, |v67|, |v67|
	v_max_f32_e64 v37, |v68|, |v68|
	v_max_f32_e32 v34, v39, v34
	v_max_f32_e64 v35, |v71|, |v71|
	v_max_f32_e64 v39, |v72|, |v72|
	v_max_f32_e32 v36, v37, v36
	v_max3_f32 v58, v66, v62, v58
	v_max_f32_e32 v35, v39, v35
	v_max3_f32 v36, |v70|, |v69|, v36
	v_lshlrev_b32_e32 v66, 16, v30
	v_and_b32_e32 v65, 0xffff0000, v30
	v_lshlrev_b32_e32 v60, 16, v33
	v_and_b32_e32 v59, 0xffff0000, v33
	v_max3_f32 v34, v34, v35, v36
	v_max_f32_e64 v30, |v65|, |v65|
	v_max_f32_e64 v35, |v66|, |v66|
	v_lshlrev_b32_e32 v64, 16, v31
	v_and_b32_e32 v63, 0xffff0000, v31
	v_lshlrev_b32_e32 v62, 16, v32
	v_and_b32_e32 v61, 0xffff0000, v32
	v_max_f32_e64 v32, |v59|, |v59|
	v_max_f32_e64 v33, |v60|, |v60|
	v_max_f32_e32 v30, v35, v30
	v_max_f32_e64 v31, |v63|, |v63|
	v_max_f32_e64 v35, |v64|, |v64|
	v_max_f32_e32 v32, v33, v32
	v_max3_f32 v50, v58, v54, v50
	v_max_f32_e32 v31, v35, v31
	v_max3_f32 v32, |v62|, |v61|, v32
	v_lshlrev_b32_e32 v58, 16, v26
	v_and_b32_e32 v57, 0xffff0000, v26
	v_lshlrev_b32_e32 v52, 16, v29
	v_and_b32_e32 v51, 0xffff0000, v29
	v_max3_f32 v30, v30, v31, v32
	v_max_f32_e64 v26, |v57|, |v57|
	v_max_f32_e64 v31, |v58|, |v58|
	v_lshlrev_b32_e32 v56, 16, v27
	v_and_b32_e32 v55, 0xffff0000, v27
	v_lshlrev_b32_e32 v54, 16, v28
	v_and_b32_e32 v53, 0xffff0000, v28
	v_max_f32_e64 v28, |v51|, |v51|
	v_max_f32_e64 v29, |v52|, |v52|
	v_max_f32_e32 v26, v31, v26
	v_max_f32_e64 v27, |v55|, |v55|
	v_max_f32_e64 v31, |v56|, |v56|
	v_max_f32_e32 v28, v29, v28
	v_max3_f32 v42, v50, v46, v42
	v_max_f32_e32 v27, v31, v27
	v_max3_f32 v28, |v54|, |v53|, v28
	v_lshlrev_b32_e32 v50, 16, v22
	v_and_b32_e32 v49, 0xffff0000, v22
	v_lshlrev_b32_e32 v44, 16, v25
	v_and_b32_e32 v43, 0xffff0000, v25
; __device__ __forceinline__ void quant_row_h(const bf16* src, signed char* dst, float* rowinv, int lane) {
;     ...
;     for (int i = 0; i < 22; ++i) { const int id = lane + 64 * i; x[i] = id < 1376 ? __builtin_nontemporal_load((const v4u*)src + id) : (v4u){0u, 0u, 0u, 0u};
;         mx = fmaxf(mx, fmaxf(fmaxf(fmaxf(fabsf(bflo(x[i].x)), fabsf(bfhi(x[i].x))), fmaxf(fabsf(bflo(x[i].y)), fabsf(bfhi(x[i].y)))), fmaxf(fmaxf(fabsf(bflo(x[i].z)), fabsf(bfhi(x[i].z))), fmaxf(fabsf(bflo(x[i].w)), fabsf(bfhi(x[i].w)))))); }
; #pragma unroll
;     for (int o = 1; o < 64; o <<= 1) mx = fmaxf(mx, __shfl_xor(mx, o));
;     mx = fmaxf(mx, 1e-20f);
;     const float sc = 127.0f / mx;
;     if (lane == 0) *rowinv = mx * (1.0f / 127.0f);
	v_max3_f32 v26, v26, v27, v28
	v_max_f32_e64 v22, |v49|, |v49|
	v_max_f32_e64 v27, |v50|, |v50|
	v_lshlrev_b32_e32 v48, 16, v23
	v_and_b32_e32 v47, 0xffff0000, v23
	v_lshlrev_b32_e32 v46, 16, v24
	v_and_b32_e32 v45, 0xffff0000, v24
	v_max_f32_e64 v24, |v43|, |v43|
	v_max_f32_e64 v25, |v44|, |v44|
	v_max_f32_e32 v22, v27, v22
	v_max_f32_e64 v23, |v47|, |v47|
	v_max_f32_e64 v27, |v48|, |v48|
	v_max_f32_e32 v24, v25, v24
	v_max3_f32 v34, v42, v38, v34
	v_max_f32_e32 v23, v27, v23
	v_max3_f32 v24, |v46|, |v45|, v24
	v_lshlrev_b32_e32 v42, 16, v18
	v_and_b32_e32 v41, 0xffff0000, v18
	v_lshlrev_b32_e32 v36, 16, v21
	v_and_b32_e32 v35, 0xffff0000, v21
	v_max3_f32 v22, v22, v23, v24
	v_max_f32_e64 v18, |v41|, |v41|
	v_max_f32_e64 v23, |v42|, |v42|
	v_lshlrev_b32_e32 v40, 16, v19
	v_and_b32_e32 v39, 0xffff0000, v19
	v_lshlrev_b32_e32 v38, 16, v20
	v_and_b32_e32 v37, 0xffff0000, v20
	v_max_f32_e64 v20, |v35|, |v35|
	v_max_f32_e64 v21, |v36|, |v36|
	v_max_f32_e32 v18, v23, v18
	v_max_f32_e64 v19, |v39|, |v39|
	v_max_f32_e64 v23, |v40|, |v40|
	v_max_f32_e32 v20, v21, v20
	v_max3_f32 v26, v34, v30, v26
	v_max_f32_e32 v19, v23, v19
	v_max3_f32 v20, |v38|, |v37|, v20
	v_lshlrev_b32_e32 v34, 16, v14
	v_and_b32_e32 v33, 0xffff0000, v14
	v_lshlrev_b32_e32 v28, 16, v17
	v_and_b32_e32 v27, 0xffff0000, v17
	v_max3_f32 v18, v18, v19, v20
	v_max_f32_e64 v14, |v33|, |v33|
	v_max_f32_e64 v19, |v34|, |v34|
	v_lshlrev_b32_e32 v32, 16, v15
	v_and_b32_e32 v31, 0xffff0000, v15
	v_lshlrev_b32_e32 v30, 16, v16
	v_and_b32_e32 v29, 0xffff0000, v16
	v_max_f32_e64 v16, |v27|, |v27|
	v_max_f32_e64 v17, |v28|, |v28|
	v_max_f32_e32 v14, v19, v14
	v_max_f32_e64 v15, |v31|, |v31|
	v_max_f32_e64 v19, |v32|, |v32|
	v_max_f32_e32 v16, v17, v16
	v_max3_f32 v18, v26, v22, v18
	v_max_f32_e32 v15, v19, v15
	v_max3_f32 v16, |v30|, |v29|, v16
	v_lshlrev_b32_e32 v26, 16, v10
	v_and_b32_e32 v25, 0xffff0000, v10
	v_lshlrev_b32_e32 v20, 16, v13
	v_and_b32_e32 v19, 0xffff0000, v13
	v_max3_f32 v14, v14, v15, v16
	v_max_f32_e64 v10, |v25|, |v25|
	v_max_f32_e64 v15, |v26|, |v26|
	v_lshlrev_b32_e32 v24, 16, v11
	v_and_b32_e32 v23, 0xffff0000, v11
	v_lshlrev_b32_e32 v22, 16, v12
	v_and_b32_e32 v21, 0xffff0000, v12
	v_max_f32_e64 v12, |v19|, |v19|
	v_max_f32_e64 v13, |v20|, |v20|
	v_max_f32_e32 v10, v15, v10
	v_max_f32_e64 v11, |v23|, |v23|
	v_max_f32_e64 v15, |v24|, |v24|
	v_max_f32_e32 v12, v13, v12
	v_max_f32_e32 v11, v15, v11
	v_max3_f32 v12, |v22|, |v21|, v12
	v_max3_f32 v10, v10, v11, v12
	v_max3_f32 v239, v18, v14, v10
	v_lshlrev_b32_e32 v18, 16, v6
	v_and_b32_e32 v17, 0xffff0000, v6
	v_lshlrev_b32_e32 v12, 16, v9
	v_and_b32_e32 v11, 0xffff0000, v9
	v_max_f32_e64 v6, |v17|, |v17|
	v_max_f32_e64 v10, |v18|, |v18|
	v_lshlrev_b32_e32 v16, 16, v7
	v_and_b32_e32 v15, 0xffff0000, v7
	v_lshlrev_b32_e32 v14, 16, v8
	v_and_b32_e32 v13, 0xffff0000, v8
	v_max_f32_e64 v8, |v11|, |v11|
	v_max_f32_e64 v9, |v12|, |v12|
	v_max_f32_e32 v6, v10, v6
	v_max_f32_e64 v7, |v15|, |v15|
	v_max_f32_e64 v10, |v16|, |v16|
	v_max_f32_e32 v8, v9, v8
	v_max_f32_e32 v7, v10, v7
	v_max3_f32 v8, |v14|, |v13|, v8
	v_lshlrev_b32_e32 v10, 16, v2
	v_and_b32_e32 v9, 0xffff0000, v2
	v_max3_f32 v240, v6, v7, v8
	v_max_f32_e64 v2, |v9|, |v9|
	v_max_f32_e64 v6, |v10|, |v10|
	v_lshlrev_b32_e32 v8, 16, v3
	v_and_b32_e32 v7, 0xffff0000, v3
	v_max_f32_e32 v241, v6, v2
	v_max_f32_e64 v2, |v7|, |v7|
	v_max_f32_e64 v3, |v8|, |v8|
	v_max_f32_e32 v242, v3, v2
	v_lshlrev_b32_e32 v3, 16, v5
	v_and_b32_e32 v2, 0xffff0000, v5
	v_max_f32_e64 v5, |v2|, |v2|
	v_max_f32_e64 v243, |v3|, |v3|
	v_lshlrev_b32_e32 v6, 16, v4
	v_and_b32_e32 v4, 0xffff0000, v4
	v_max_f32_e32 v5, v243, v5
	v_max3_f32 v5, |v6|, |v4|, v5
	v_max3_f32 v5, v241, v242, v5
	v_max3_f32 v5, v239, v240, v5
	s_nop 1
	v_mov_b32_dpp v239, v5 quad_perm:[1,0,3,2] row_mask:0xf bank_mask:0xf
	s_waitcnt lgkmcnt(0)
	v_max_f32_e32 v239, v239, v239
	v_max_f32_e32 v5, v5, v239
	s_nop 1
	v_mov_b32_dpp v239, v5 quad_perm:[2,3,0,1] row_mask:0xf bank_mask:0xf
	s_waitcnt lgkmcnt(0)
	v_max_f32_e32 v239, v239, v239
	v_max_f32_e32 v5, v5, v239
	s_nop 1
	v_mov_b32_dpp v239, v5 row_half_mirror row_mask:0xf bank_mask:0xf
	s_waitcnt lgkmcnt(0)
	v_max_f32_e32 v239, v239, v239
	v_max_f32_e32 v5, v5, v239
	s_nop 1
	v_mov_b32_dpp v239, v5 row_mirror row_mask:0xf bank_mask:0xf
	s_waitcnt lgkmcnt(0)
	v_max_f32_e32 v239, v239, v239
	v_max_f32_e32 v5, v5, v239
	v_mov_b32_e32 v239, v5
	s_nop 1
	v_permlane16_swap_b32_e32 v239, v5
	s_waitcnt lgkmcnt(0)
	v_max_f32_e32 v239, v239, v239
	v_max_f32_e32 v5, v5, v239
	v_mov_b32_e32 v239, v5
	s_nop 1
	v_permlane32_swap_b32_e32 v239, v5
	s_waitcnt lgkmcnt(0)
	v_max3_f32 v5, v5, v239, s50
	s_and_saveexec_b64 s[16:17], s[8:9]
	s_cbranch_execz .LBB0_1128
	s_ashr_i32 s15, s14, 31
	s_lshl_b64 s[14:15], s[14:15], 2
	s_add_u32 s14, s43, s14
	s_addc_u32 s15, s44, s15
	v_mul_f32_e32 v239, 0x3c010204, v5
	global_store_dword v183, v239, s[14:15]

; __device__ __forceinline__ f32x4 h4lo(const u32x4 w) { return (f32x4){hlo(w.x), hhi(w.x), hlo(w.y), hhi(w.y)}; }
; __device__ __forceinline__ f32x4 h4hi(const u32x4 w) { return (f32x4){hlo(w.z), hhi(w.z), hlo(w.w), hhi(w.w)}; }
; __device__ __forceinline__ int row_perm(int m) { const int j = m >> 11, r = m & 2047; return (11 - 3 * (j & 3) - (j >> 2)) * 2048 + r; }
; __device__ __forceinline__ void ln_fetch_b(const bf16* src, v4u (&raw)[8], int lane) {
;     const v4u* xr = (const v4u*)src + lane;
; #pragma unroll
;     for (int j = 0; j < 8; ++j) raw[j] = xr[64 * j];
; }
; __device__ __forceinline__ void ln_load_b(const v4u (&raw)[8], f32x4 (&v)[16], float& mean, float& rstd, int lane) {
;     float s = 0.f;
; #pragma unroll
;     for (int j = 0; j < 8; ++j) { const v4u w = raw[j]; v[2 * j] = pg8::h4lo(w); v[2 * j + 1] = pg8::h4hi(w);
;         s += ((v[2 * j].x + v[2 * j].y) + (v[2 * j].z + v[2 * j].w)) + ((v[2 * j + 1].x + v[2 * j + 1].y) + (v[2 * j + 1].z + v[2 * j + 1].w)); }
;     mean = wave_sum(s) * (1.f / 4096.f); float s2 = 0.f;
; __global__ void __launch_bounds__(NT, 2) fwd_kernel(Args args_unused) {
;     ...
;             for (int m0 = gw; m0 < MTOK; m0 += 2 * ngw) { const int mA = row_perm(m0), mB = row_perm(m0 + ngw < MTOK ? m0 + ngw : m0); const bool hasB = m0 + ngw < MTOK;
;                 v4u rawA[8], rawB[8]; ln_fetch_b(WSP(const bf16, WS_XR) + (size_t)mA * DM, rawA, lane); ln_fetch_b(WSP(const bf16, WS_XR) + (size_t)mB * DM, rawB, lane);
.LBB0_1266:
	s_bfe_u32 s7, s27, 0x2000b
	s_mul_i32 s7, s7, 0x1ffffd
	s_ashr_i32 s16, s27, 13
	s_sub_i32 s7, s7, s16
	s_and_b32 s6, s27, 0x7ff
	s_lshl_b32 s7, s7, 11
	s_or_b32 s6, s7, s6
	s_addk_i32 s6, 0x5800
	s_add_i32 s34, s3, s27
	s_cmpk_lt_i32 s34, 0x6000
	s_cselect_b32 s7, s34, s27
	s_bfe_u32 s17, s7, 0x2000b
	s_and_b32 s16, s7, 0x7ff
	s_mul_i32 s17, s17, 0x1ffffd
	s_ashr_i32 s7, s7, 13
	s_sub_i32 s7, s17, s7
	s_lshl_b32 s7, s7, 11
	s_or_b32 s7, s7, s16
	s_add_i32 s16, s7, 0x5800
	s_ashr_i32 s7, s6, 31
	s_lshl_b64 s[28:29], s[6:7], 13
	v_lshl_add_u64 v[2:3], v[68:69], 0, s[28:29]
	global_load_dwordx4 v[62:65], v[2:3], off
	global_load_dwordx4 v[58:61], v[2:3], off offset:1024
	global_load_dwordx4 v[54:57], v[2:3], off offset:2048
	global_load_dwordx4 v[50:53], v[2:3], off offset:3072
	v_add_co_u32_e32 v2, vcc, s25, v2
	v_mov_b32_e32 v118, v183
	s_nop 0
	v_addc_co_u32_e32 v3, vcc, 0, v3, vcc
	global_load_dwordx4 v[46:49], v[2:3], off
	global_load_dwordx4 v[42:45], v[2:3], off offset:1024
	global_load_dwordx4 v[38:41], v[2:3], off offset:2048
	global_load_dwordx4 v[34:37], v[2:3], off offset:3072
	s_ashr_i32 s17, s16, 31
	s_lshl_b64 s[30:31], s[16:17], 13
	v_lshl_add_u64 v[2:3], v[68:69], 0, s[30:31]
	global_load_dwordx4 v[30:33], v[2:3], off
	global_load_dwordx4 v[26:29], v[2:3], off offset:1024
	global_load_dwordx4 v[22:25], v[2:3], off offset:2048
	global_load_dwordx4 v[18:21], v[2:3], off offset:3072
	v_add_co_u32_e32 v2, vcc, s25, v2
	s_lshl_b64 s[6:7], s[6:7], 14
	s_nop 0
	v_addc_co_u32_e32 v3, vcc, 0, v3, vcc
	s_add_u32 s36, s8, s6
	s_addc_u32 s37, s9, s7
	global_load_dwordx4 v[14:17], v[2:3], off
	global_load_dwordx4 v[10:13], v[2:3], off offset:1024
	global_load_dwordx4 v[6:9], v[2:3], off offset:2048
	s_nop 0
	global_load_dwordx4 v[2:5], v[2:3], off offset:3072
	s_cmpk_gt_i32 s34, 0x5fff
	s_waitcnt vmcnt(0)
	v_cvt_f32_f16_e32 v104, v62
	v_cvt_f32_f16_sdwa v106, v62 dst_sel:DWORD dst_unused:UNUSED_PAD src0_sel:WORD_1
	v_cvt_f32_f16_e32 v108, v63
	v_cvt_f32_f16_sdwa v110, v63 dst_sel:DWORD dst_unused:UNUSED_PAD src0_sel:WORD_1
	v_cvt_f32_f16_e32 v105, v64
	v_cvt_f32_f16_sdwa v107, v64 dst_sel:DWORD dst_unused:UNUSED_PAD src0_sel:WORD_1
	v_cvt_f32_f16_e32 v109, v65
	v_cvt_f32_f16_sdwa v111, v65 dst_sel:DWORD dst_unused:UNUSED_PAD src0_sel:WORD_1
	v_cvt_f32_f16_sdwa v112, v60 dst_sel:DWORD dst_unused:UNUSED_PAD src0_sel:WORD_1
	v_pk_add_f32 v[104:105], v[104:105], v[106:107]
	v_cvt_f32_f16_sdwa v113, v61 dst_sel:DWORD dst_unused:UNUSED_PAD src0_sel:WORD_1
	v_pk_add_f32 v[106:107], v[108:109], v[110:111]
	v_cvt_f32_f16_sdwa v108, v58 dst_sel:DWORD dst_unused:UNUSED_PAD src0_sel:WORD_1
	v_pk_add_f32 v[104:105], v[104:105], v[106:107]
	v_cvt_f32_f16_e32 v106, v58
	v_cvt_f32_f16_e32 v107, v59
	v_cvt_f32_f16_sdwa v109, v59 dst_sel:DWORD dst_unused:UNUSED_PAD src0_sel:WORD_1
	v_cvt_f32_f16_e32 v110, v60
	v_cvt_f32_f16_e32 v111, v61
	v_pk_add_f32 v[104:105], v[104:105], v[104:105] op_sel:[0,1] op_sel_hi:[1,0]
	v_pk_add_f32 v[106:107], v[106:107], v[108:109]
	v_cvt_f32_f16_e32 v105, v54
	v_pk_add_f32 v[108:109], v[110:111], v[112:113]
	v_pk_add_f32 v[106:107], v[106:107], v[106:107] op_sel:[0,1] op_sel_hi:[1,0]
	v_pk_add_f32 v[108:109], v[108:109], v[108:109] op_sel:[0,1] op_sel_hi:[1,0]
	v_cvt_f32_f16_sdwa v107, v54 dst_sel:DWORD dst_unused:UNUSED_PAD src0_sel:WORD_1
	v_cvt_f32_f16_e32 v109, v55
	v_cvt_f32_f16_sdwa v111, v55 dst_sel:DWORD dst_unused:UNUSED_PAD src0_sel:WORD_1
	v_cvt_f32_f16_e32 v112, v56
	v_cvt_f32_f16_sdwa v113, v56 dst_sel:DWORD dst_unused:UNUSED_PAD src0_sel:WORD_1
	v_cvt_f32_f16_e32 v115, v57
	v_cvt_f32_f16_sdwa v116, v57 dst_sel:DWORD dst_unused:UNUSED_PAD src0_sel:WORD_1
	v_add_f32_e32 v110, v107, v105
	v_add_f32_e32 v114, v111, v109
	v_cvt_f32_f16_e32 v105, v50
	v_cvt_f32_f16_sdwa v119, v50 dst_sel:DWORD dst_unused:UNUSED_PAD src0_sel:WORD_1
	v_cvt_f32_f16_e32 v107, v51
	v_cvt_f32_f16_sdwa v109, v51 dst_sel:DWORD dst_unused:UNUSED_PAD src0_sel:WORD_1
	v_add_f32_e32 v112, v113, v112
	v_add_f32_e32 v116, v116, v115
	v_cvt_f32_f16_e32 v111, v52
	v_cvt_f32_f16_sdwa v115, v52 dst_sel:DWORD dst_unused:UNUSED_PAD src0_sel:WORD_1
	v_cvt_f32_f16_e32 v113, v53
	v_cvt_f32_f16_sdwa v117, v53 dst_sel:DWORD dst_unused:UNUSED_PAD src0_sel:WORD_1
	v_pk_add_f32 v[104:105], v[104:105], v[118:119]
	v_pk_add_f32 v[106:107], v[106:107], v[108:109]
	v_cvt_f32_f16_sdwa v118, v41 dst_sel:DWORD dst_unused:UNUSED_PAD src0_sel:WORD_1
	v_pk_add_f32 v[104:105], v[104:105], v[106:107]
	v_pk_add_f32 v[106:107], v[110:111], v[114:115]
	v_pk_add_f32 v[108:109], v[112:113], v[116:117]
	v_cvt_f32_f16_e32 v110, v47
	v_pk_add_f32 v[106:107], v[106:107], v[108:109]
	v_cvt_f32_f16_sdwa v108, v46 dst_sel:DWORD dst_unused:UNUSED_PAD src0_sel:WORD_1
	v_pk_add_f32 v[104:105], v[104:105], v[106:107]
	v_cvt_f32_f16_e32 v106, v46
	v_cvt_f32_f16_sdwa v112, v47 dst_sel:DWORD dst_unused:UNUSED_PAD src0_sel:WORD_1
	v_cvt_f32_f16_e32 v107, v48
	v_cvt_f32_f16_sdwa v109, v48 dst_sel:DWORD dst_unused:UNUSED_PAD src0_sel:WORD_1
	v_cvt_f32_f16_e32 v111, v49
	v_cvt_f32_f16_sdwa v113, v49 dst_sel:DWORD dst_unused:UNUSED_PAD src0_sel:WORD_1
	v_cvt_f32_f16_sdwa v114, v44 dst_sel:DWORD dst_unused:UNUSED_PAD src0_sel:WORD_1
	v_pk_add_f32 v[106:107], v[106:107], v[108:109]
	v_cvt_f32_f16_sdwa v115, v45 dst_sel:DWORD dst_unused:UNUSED_PAD src0_sel:WORD_1
	v_pk_add_f32 v[108:109], v[110:111], v[112:113]
	v_cvt_f32_f16_sdwa v110, v42 dst_sel:DWORD dst_unused:UNUSED_PAD src0_sel:WORD_1
	v_pk_add_f32 v[106:107], v[106:107], v[108:109]
	v_cvt_f32_f16_e32 v108, v42
	v_cvt_f32_f16_e32 v109, v43
	v_cvt_f32_f16_sdwa v111, v43 dst_sel:DWORD dst_unused:UNUSED_PAD src0_sel:WORD_1
; __device__ __forceinline__ f32x4 h4lo(const u32x4 w) { return (f32x4){hlo(w.x), hhi(w.x), hlo(w.y), hhi(w.y)}; }
; __device__ __forceinline__ f32x4 h4hi(const u32x4 w) { return (f32x4){hlo(w.z), hhi(w.z), hlo(w.w), hhi(w.w)}; }
; __device__ __forceinline__ void ln_load_b(const v4u (&raw)[8], f32x4 (&v)[16], float& mean, float& rstd, int lane) {
;     float s = 0.f;
; #pragma unroll
;     for (int j = 0; j < 8; ++j) { const v4u w = raw[j]; v[2 * j] = pg8::h4lo(w); v[2 * j + 1] = pg8::h4hi(w);
;         s += ((v[2 * j].x + v[2 * j].y) + (v[2 * j].z + v[2 * j].w)) + ((v[2 * j + 1].x + v[2 * j + 1].y) + (v[2 * j + 1].z + v[2 * j + 1].w)); }
;     mean = wave_sum(s) * (1.f / 4096.f); float s2 = 0.f;
; #pragma unroll
;     for (int j = 0; j < 16; ++j) { v[j] = v[j] - mean; s2 += (v[j].x * v[j].x + v[j].y * v[j].y) + (v[j].z * v[j].z + v[j].w * v[j].w); }
;     rstd = 1.f / sqrtf(wave_sum(s2) * (1.f / 4096.f) + 1e-5f);
	v_cvt_f32_f16_e32 v112, v44
	v_cvt_f32_f16_e32 v113, v45
	v_pk_add_f32 v[104:105], v[104:105], v[104:105] op_sel:[0,1] op_sel_hi:[1,0]
	v_pk_add_f32 v[108:109], v[108:109], v[110:111]
	v_pk_add_f32 v[106:107], v[106:107], v[106:107] op_sel:[0,1] op_sel_hi:[1,0]
	v_pk_add_f32 v[110:111], v[112:113], v[114:115]
	v_pk_add_f32 v[108:109], v[108:109], v[108:109] op_sel:[0,1] op_sel_hi:[1,0]
	v_pk_add_f32 v[110:111], v[110:111], v[110:111] op_sel:[0,1] op_sel_hi:[1,0]
	v_cvt_f32_f16_e32 v105, v38
	v_cvt_f32_f16_sdwa v107, v38 dst_sel:DWORD dst_unused:UNUSED_PAD src0_sel:WORD_1
	v_cvt_f32_f16_e32 v109, v39
	v_cvt_f32_f16_sdwa v111, v39 dst_sel:DWORD dst_unused:UNUSED_PAD src0_sel:WORD_1
	v_cvt_f32_f16_e32 v113, v40
	v_cvt_f32_f16_sdwa v115, v40 dst_sel:DWORD dst_unused:UNUSED_PAD src0_sel:WORD_1
	v_cvt_f32_f16_e32 v117, v41
	v_add_f32_e32 v112, v107, v105
	v_add_f32_e32 v114, v111, v109
	v_cvt_f32_f16_e32 v105, v34
	v_cvt_f32_f16_sdwa v107, v34 dst_sel:DWORD dst_unused:UNUSED_PAD src0_sel:WORD_1
	v_cvt_f32_f16_e32 v109, v35
	v_cvt_f32_f16_sdwa v111, v35 dst_sel:DWORD dst_unused:UNUSED_PAD src0_sel:WORD_1
	v_add_f32_e32 v116, v115, v113
	v_add_f32_e32 v118, v118, v117
	v_cvt_f32_f16_e32 v113, v36
	v_cvt_f32_f16_sdwa v115, v36 dst_sel:DWORD dst_unused:UNUSED_PAD src0_sel:WORD_1
	v_cvt_f32_f16_e32 v117, v37
	v_cvt_f32_f16_sdwa v119, v37 dst_sel:DWORD dst_unused:UNUSED_PAD src0_sel:WORD_1
	v_pk_add_f32 v[104:105], v[104:105], v[106:107]
	v_pk_add_f32 v[106:107], v[108:109], v[110:111]
	v_pk_add_f32 v[108:109], v[116:117], v[118:119]
	v_pk_add_f32 v[104:105], v[104:105], v[106:107]
	v_pk_add_f32 v[106:107], v[112:113], v[114:115]
	s_nop 0
	v_pk_add_f32 v[106:107], v[106:107], v[108:109]
	s_nop 0
	v_pk_add_f32 v[104:105], v[104:105], v[106:107]
	s_nop 0
	v_add_f32_e32 v104, v104, v105
	s_nop 1
	v_mov_b32_dpp v105, v104 quad_perm:[1,0,3,2] row_mask:0xf bank_mask:0xf
	s_waitcnt lgkmcnt(0)
	v_add_f32_e32 v104, v104, v105
	s_nop 1
	v_mov_b32_dpp v105, v104 quad_perm:[2,3,0,1] row_mask:0xf bank_mask:0xf
	s_waitcnt lgkmcnt(0)
	v_add_f32_e32 v104, v104, v105
	s_nop 1
	v_mov_b32_dpp v105, v104 row_half_mirror row_mask:0xf bank_mask:0xf
	s_waitcnt lgkmcnt(0)
	v_add_f32_e32 v104, v104, v105
	s_nop 1
	v_mov_b32_dpp v105, v104 row_mirror row_mask:0xf bank_mask:0xf
	s_waitcnt lgkmcnt(0)
	v_add_f32_e32 v104, v104, v105
	v_mov_b32_e32 v105, v104
	s_nop 1
	v_permlane16_swap_b32_e32 v105, v104
	s_waitcnt lgkmcnt(0)
	v_add_f32_e32 v104, v104, v105
	v_mov_b32_e32 v105, v104
	s_nop 1
	v_permlane32_swap_b32_e32 v105, v104
	s_waitcnt lgkmcnt(0)
	v_add_f32_e32 v170, v104, v105
	v_fma_mix_f32 v151, v170, s87, v62 op_sel:[0,0,1] op_sel_hi:[0,0,1]
	v_fma_mix_f32 v150, v170, s87, v62 op_sel_hi:[0,0,1]
	v_fma_mix_f32 v153, v170, s87, v63 op_sel:[0,0,1] op_sel_hi:[0,0,1]
	v_fma_mix_f32 v152, v170, s87, v63 op_sel_hi:[0,0,1]
	v_pk_mul_f32 v[62:63], v[152:153], v[152:153]
	v_pk_mul_f32 v[104:105], v[150:151], v[150:151]
	v_fma_mix_f32 v143, v170, s87, v64 op_sel:[0,0,1] op_sel_hi:[0,0,1]
	v_pk_mov_b32 v[106:107], v[104:105], v[62:63] op_sel:[1,0]
	v_mov_b32_e32 v105, v63
	v_fma_mix_f32 v142, v170, s87, v64 op_sel_hi:[0,0,1]
	v_fma_mix_f32 v149, v170, s87, v65 op_sel:[0,0,1] op_sel_hi:[0,0,1]
	v_fma_mix_f32 v148, v170, s87, v65 op_sel_hi:[0,0,1]
	v_fma_mix_f32 v144, v170, s87, v58 op_sel_hi:[0,0,1]
	v_pk_add_f32 v[62:63], v[106:107], v[104:105]
	v_pk_mul_f32 v[64:65], v[148:149], v[148:149]
	v_pk_mul_f32 v[104:105], v[142:143], v[142:143]
	v_fma_mix_f32 v145, v170, s87, v58 op_sel:[0,0,1] op_sel_hi:[0,0,1]
	v_mul_f32_e32 v58, v144, v144
	v_pk_mov_b32 v[106:107], v[104:105], v[64:65] op_sel:[1,0]
	v_mov_b32_e32 v105, v65
	v_fma_mix_f32 v147, v170, s87, v59 op_sel:[0,0,1] op_sel_hi:[0,0,1]
	v_fma_mix_f32 v146, v170, s87, v59 op_sel_hi:[0,0,1]
	v_pk_fma_f32 v[58:59], v[144:145], v[144:145], v[58:59] op_sel_hi:[1,1,0]
	v_pk_add_f32 v[64:65], v[106:107], v[104:105]
	v_mul_f32_e32 v58, v146, v146
	v_pk_add_f32 v[62:63], v[62:63], v[62:63] op_sel_hi:[0,1]
	v_pk_add_f32 v[64:65], v[64:65], v[64:65] op_sel_hi:[0,1]
	v_pk_fma_f32 v[104:105], v[146:147], v[146:147], v[58:59] op_sel_hi:[1,1,0]
	v_fma_mix_f32 v139, v170, s87, v61 op_sel:[0,0,1] op_sel_hi:[0,0,1]
	v_fma_mix_f32 v138, v170, s87, v61 op_sel_hi:[0,0,1]
	v_fma_mix_f32 v135, v170, s87, v60 op_sel:[0,0,1] op_sel_hi:[0,0,1]
	v_fma_mix_f32 v134, v170, s87, v60 op_sel_hi:[0,0,1]
	v_mul_f32_e32 v58, v134, v134
	v_mul_f32_e32 v104, v135, v135
	v_mul_f32_e32 v62, v138, v138
	v_mul_f32_e32 v64, v139, v139
	v_pk_add_f32 v[58:59], v[58:59], v[104:105]
	v_pk_add_f32 v[60:61], v[62:63], v[64:65]
	v_fma_mix_f32 v137, v170, s87, v54 op_sel:[0,0,1] op_sel_hi:[0,0,1]
	v_fma_mix_f32 v136, v170, s87, v54 op_sel_hi:[0,0,1]
	v_fma_mix_f32 v141, v170, s87, v55 op_sel:[0,0,1] op_sel_hi:[0,0,1]
	v_fma_mix_f32 v140, v170, s87, v55 op_sel_hi:[0,0,1]
	v_pk_add_f32 v[58:59], v[58:59], v[60:61]
	v_pk_mul_f32 v[54:55], v[140:141], v[140:141]
	v_pk_mul_f32 v[60:61], v[136:137], v[136:137]
	v_fma_mix_f32 v130, v170, s87, v56 op_sel_hi:[0,0,1]
	v_pk_mov_b32 v[62:63], v[60:61], v[54:55] op_sel:[1,0]
	v_mov_b32_e32 v61, v55
	v_pk_add_f32 v[54:55], v[62:63], v[60:61]
	v_fma_mix_f32 v131, v170, s87, v56 op_sel:[0,0,1] op_sel_hi:[0,0,1]
	v_pk_add_f32 v[54:55], v[54:55], v[54:55] op_sel_hi:[0,1]
	v_fma_mix_f32 v132, v170, s87, v57 op_sel_hi:[0,0,1]
	v_mul_f32_e32 v54, v130, v130
	v_fma_mix_f32 v133, v170, s87, v57 op_sel:[0,0,1] op_sel_hi:[0,0,1]
	v_pk_fma_f32 v[56:57], v[130:131], v[130:131], v[54:55] op_sel_hi:[1,1,0]
	v_mul_f32_e32 v54, v132, v132
	v_pk_add_f32 v[58:59], v[58:59], v[58:59] op_sel_hi:[0,1]
	v_pk_fma_f32 v[60:61], v[132:133], v[132:133], v[54:55] op_sel_hi:[1,1,0]
; __device__ __forceinline__ void ln_load_b(const v4u (&raw)[8], f32x4 (&v)[16], float& mean, float& rstd, int lane) {
;     ...
;     mean = wave_sum(s) * (1.f / 4096.f); float s2 = 0.f;
; #pragma unroll
;     for (int j = 0; j < 16; ++j) { v[j] = v[j] - mean; s2 += (v[j].x * v[j].x + v[j].y * v[j].y) + (v[j].z * v[j].z + v[j].w * v[j].w); }
;     rstd = 1.f / sqrtf(wave_sum(s2) * (1.f / 4096.f) + 1e-5f);
	v_fma_mix_f32 v127, v170, s87, v51 op_sel:[0,0,1] op_sel_hi:[0,0,1]
	v_fma_mix_f32 v126, v170, s87, v51 op_sel_hi:[0,0,1]
	v_fma_mix_f32 v129, v170, s87, v50 op_sel:[0,0,1] op_sel_hi:[0,0,1]
	v_fma_mix_f32 v128, v170, s87, v50 op_sel_hi:[0,0,1]
	v_mul_f32_e32 v56, v128, v128
	v_mul_f32_e32 v60, v129, v129
	v_mul_f32_e32 v54, v126, v126
	v_mul_f32_e32 v58, v127, v127
	v_pk_add_f32 v[50:51], v[56:57], v[60:61]
	v_pk_add_f32 v[54:55], v[54:55], v[58:59]
	v_fma_mix_f32 v123, v170, s87, v52 op_sel:[0,0,1] op_sel_hi:[0,0,1]
	v_fma_mix_f32 v122, v170, s87, v52 op_sel_hi:[0,0,1]
	v_fma_mix_f32 v125, v170, s87, v53 op_sel:[0,0,1] op_sel_hi:[0,0,1]
	v_fma_mix_f32 v124, v170, s87, v53 op_sel_hi:[0,0,1]
	v_fma_mix_f32 v118, v170, s87, v46 op_sel_hi:[0,0,1]
	v_pk_add_f32 v[50:51], v[50:51], v[54:55]
	v_pk_mul_f32 v[52:53], v[124:125], v[124:125]
	v_pk_mul_f32 v[54:55], v[122:123], v[122:123]
	v_fma_mix_f32 v119, v170, s87, v46 op_sel:[0,0,1] op_sel_hi:[0,0,1]
	v_mul_f32_e32 v46, v118, v118
	v_pk_mov_b32 v[56:57], v[54:55], v[52:53] op_sel:[1,0]
	v_mov_b32_e32 v55, v53
	v_fma_mix_f32 v121, v170, s87, v47 op_sel:[0,0,1] op_sel_hi:[0,0,1]
	v_fma_mix_f32 v120, v170, s87, v47 op_sel_hi:[0,0,1]
	v_pk_fma_f32 v[46:47], v[118:119], v[118:119], v[46:47] op_sel_hi:[1,1,0]
	v_pk_add_f32 v[52:53], v[56:57], v[54:55]
	v_mul_f32_e32 v46, v120, v120
	v_pk_add_f32 v[50:51], v[50:51], v[50:51] op_sel_hi:[0,1]
	v_pk_add_f32 v[52:53], v[52:53], v[52:53] op_sel_hi:[0,1]
	v_pk_fma_f32 v[54:55], v[120:121], v[120:121], v[46:47] op_sel_hi:[1,1,0]
	v_fma_mix_f32 v117, v170, s87, v49 op_sel:[0,0,1] op_sel_hi:[0,0,1]
	v_fma_mix_f32 v116, v170, s87, v49 op_sel_hi:[0,0,1]
	v_fma_mix_f32 v115, v170, s87, v48 op_sel:[0,0,1] op_sel_hi:[0,0,1]
	v_fma_mix_f32 v114, v170, s87, v48 op_sel_hi:[0,0,1]
	v_mul_f32_e32 v46, v114, v114
	v_mul_f32_e32 v54, v115, v115
	v_mul_f32_e32 v52, v116, v116
	v_mul_f32_e32 v50, v117, v117
	v_pk_add_f32 v[46:47], v[46:47], v[54:55]
	v_pk_add_f32 v[48:49], v[52:53], v[50:51]
	v_fma_mix_f32 v111, v170, s87, v42 op_sel:[0,0,1] op_sel_hi:[0,0,1]
	v_fma_mix_f32 v110, v170, s87, v42 op_sel_hi:[0,0,1]
	v_fma_mix_f32 v113, v170, s87, v43 op_sel:[0,0,1] op_sel_hi:[0,0,1]
	v_fma_mix_f32 v112, v170, s87, v43 op_sel_hi:[0,0,1]
	v_pk_add_f32 v[46:47], v[46:47], v[48:49]
	v_pk_mul_f32 v[42:43], v[112:113], v[112:113]
	v_pk_mul_f32 v[48:49], v[110:111], v[110:111]
	v_fma_mix_f32 v106, v170, s87, v44 op_sel_hi:[0,0,1]
	v_pk_mov_b32 v[50:51], v[48:49], v[42:43] op_sel:[1,0]
	v_mov_b32_e32 v49, v43
	v_pk_add_f32 v[42:43], v[50:51], v[48:49]
	v_fma_mix_f32 v107, v170, s87, v44 op_sel:[0,0,1] op_sel_hi:[0,0,1]
	v_pk_add_f32 v[42:43], v[42:43], v[42:43] op_sel_hi:[0,1]
	v_fma_mix_f32 v108, v170, s87, v45 op_sel_hi:[0,0,1]
	v_mul_f32_e32 v42, v106, v106
	v_fma_mix_f32 v109, v170, s87, v45 op_sel:[0,0,1] op_sel_hi:[0,0,1]
	v_pk_fma_f32 v[44:45], v[106:107], v[106:107], v[42:43] op_sel_hi:[1,1,0]
	v_mul_f32_e32 v42, v108, v108
	v_pk_add_f32 v[46:47], v[46:47], v[46:47] op_sel_hi:[0,1]
	v_pk_fma_f32 v[48:49], v[108:109], v[108:109], v[42:43] op_sel_hi:[1,1,0]
	v_fma_mix_f32 v65, v170, s87, v39 op_sel:[0,0,1] op_sel_hi:[0,0,1]
	v_fma_mix_f32 v64, v170, s87, v39 op_sel_hi:[0,0,1]
	v_fma_mix_f32 v105, v170, s87, v38 op_sel:[0,0,1] op_sel_hi:[0,0,1]
	v_fma_mix_f32 v104, v170, s87, v38 op_sel_hi:[0,0,1]
	v_mul_f32_e32 v44, v104, v104
	v_mul_f32_e32 v48, v105, v105
	v_mul_f32_e32 v42, v64, v64
	v_mul_f32_e32 v46, v65, v65
	v_pk_add_f32 v[38:39], v[44:45], v[48:49]
	v_pk_add_f32 v[42:43], v[42:43], v[46:47]
	v_fma_mix_f32 v61, v170, s87, v40 op_sel:[0,0,1] op_sel_hi:[0,0,1]
	v_fma_mix_f32 v60, v170, s87, v40 op_sel_hi:[0,0,1]
	v_fma_mix_f32 v63, v170, s87, v41 op_sel:[0,0,1] op_sel_hi:[0,0,1]
	v_fma_mix_f32 v62, v170, s87, v41 op_sel_hi:[0,0,1]
	v_fma_mix_f32 v54, v170, s87, v34 op_sel_hi:[0,0,1]
	v_pk_add_f32 v[38:39], v[38:39], v[42:43]
	v_pk_mul_f32 v[40:41], v[62:63], v[62:63]
	v_pk_mul_f32 v[42:43], v[60:61], v[60:61]
	v_fma_mix_f32 v55, v170, s87, v34 op_sel:[0,0,1] op_sel_hi:[0,0,1]
	v_mul_f32_e32 v34, v54, v54
	v_pk_mov_b32 v[44:45], v[42:43], v[40:41] op_sel:[1,0]
	v_mov_b32_e32 v43, v41
	v_fma_mix_f32 v57, v170, s87, v35 op_sel:[0,0,1] op_sel_hi:[0,0,1]
	v_fma_mix_f32 v56, v170, s87, v35 op_sel_hi:[0,0,1]
	v_pk_fma_f32 v[34:35], v[54:55], v[54:55], v[34:35] op_sel_hi:[1,1,0]
	v_pk_add_f32 v[40:41], v[44:45], v[42:43]
	v_mul_f32_e32 v34, v56, v56
	v_pk_add_f32 v[38:39], v[38:39], v[38:39] op_sel_hi:[0,1]
	v_pk_add_f32 v[40:41], v[40:41], v[40:41] op_sel_hi:[0,1]
	v_pk_fma_f32 v[42:43], v[56:57], v[56:57], v[34:35] op_sel_hi:[1,1,0]
	v_fma_mix_f32 v53, v170, s87, v37 op_sel:[0,0,1] op_sel_hi:[0,0,1]
	v_fma_mix_f32 v52, v170, s87, v37 op_sel_hi:[0,0,1]
	v_fma_mix_f32 v51, v170, s87, v36 op_sel:[0,0,1] op_sel_hi:[0,0,1]
	v_fma_mix_f32 v50, v170, s87, v36 op_sel_hi:[0,0,1]
	v_mul_f32_e32 v34, v50, v50
	v_mul_f32_e32 v42, v51, v51
	v_mul_f32_e32 v40, v52, v52
	v_mul_f32_e32 v38, v53, v53
	v_pk_add_f32 v[34:35], v[34:35], v[42:43]
	v_pk_add_f32 v[36:37], v[40:41], v[38:39]
	s_nop 0
	v_pk_add_f32 v[34:35], v[34:35], v[36:37]
	s_nop 0
	v_add_f32_e32 v34, v34, v35
	s_nop 1
	v_mov_b32_dpp v35, v34 quad_perm:[1,0,3,2] row_mask:0xf bank_mask:0xf
	s_waitcnt lgkmcnt(0)
	v_add_f32_e32 v34, v34, v35
	s_nop 1
	v_mov_b32_dpp v35, v34 quad_perm:[2,3,0,1] row_mask:0xf bank_mask:0xf
	s_waitcnt lgkmcnt(0)
	v_add_f32_e32 v34, v34, v35
	s_nop 1
	v_mov_b32_dpp v35, v34 row_half_mirror row_mask:0xf bank_mask:0xf
	s_waitcnt lgkmcnt(0)
	v_add_f32_e32 v34, v34, v35
	s_nop 1
	v_mov_b32_dpp v35, v34 row_mirror row_mask:0xf bank_mask:0xf
	s_waitcnt lgkmcnt(0)
; __device__ __forceinline__ unsigned pk2(float lo, float hi) { const f32x2 v = {lo, hi}; return __builtin_bit_cast(unsigned, __builtin_convertvector(v, bf16x2_t)); }
; __device__ __forceinline__ float wave_sum(float v) {
; #pragma unroll
;     for (int o = 1; o < 64; o <<= 1) v += __shfl_xor(v, o);
;     return v;
; }
; __device__ __forceinline__ void ln_load_b(const v4u (&raw)[8], f32x4 (&v)[16], float& mean, float& rstd, int lane) {
;     ...
;     mean = wave_sum(s) * (1.f / 4096.f); float s2 = 0.f;
; #pragma unroll
;     for (int j = 0; j < 16; ++j) { v[j] = v[j] - mean; s2 += (v[j].x * v[j].x + v[j].y * v[j].y) + (v[j].z * v[j].z + v[j].w * v[j].w); }
;     rstd = 1.f / sqrtf(wave_sum(s2) * (1.f / 4096.f) + 1e-5f);
; template <bool WF> __device__ __forceinline__ void ln_row_b(const v4u (&src)[8], const float* g, const float* b, float* dstf, bf16* dstb, int lane) {
;     f32x4 v[16]; float mean, rstd; ln_load_b(src, v, mean, rstd, lane);
; #pragma unroll
;     for (int j = 0; j < 8; ++j) { const int q = 2 * (64 * j + lane);
;         const f32x4 o0 = v[2 * j] * rstd * ((const f32x4*)g)[q] + ((const f32x4*)b)[q], o1 = v[2 * j + 1] * rstd * ((const f32x4*)g)[q + 1] + ((const f32x4*)b)[q + 1];
;         if (WF) { ((f32x4*)dstf)[q] = o0; ((f32x4*)dstf)[q + 1] = o1; }
;         else { v4u w; w.x = pk2(o0.x, o0.y); w.y = pk2(o0.z, o0.w); w.z = pk2(o1.x, o1.y); w.w = pk2(o1.z, o1.w); ((v4u*)dstb)[64 * j + lane] = w; } }
	v_add_f32_e32 v34, v34, v35
	v_mov_b32_e32 v35, v34
	s_nop 1
	v_permlane16_swap_b32_e32 v35, v34
	s_waitcnt lgkmcnt(0)
	v_add_f32_e32 v34, v34, v35
	v_mov_b32_e32 v35, v34
	s_nop 1
	v_permlane32_swap_b32_e32 v35, v34
	s_waitcnt lgkmcnt(0)
	v_add_f32_e32 v34, v34, v35
	v_fmamk_f32 v34, v34, 0x39800000, v216
	v_cmp_gt_f32_e32 vcc, s95, v34
	v_mul_f32_e32 v35, 0x4f800000, v34
	s_nop 0
	v_cndmask_b32_e32 v34, v34, v35, vcc
	v_sqrt_f32_e32 v35, v34
	s_nop 0
	v_add_u32_e32 v36, -1, v35
	v_fma_f32 v37, -v36, v35, v34
	v_cmp_ge_f32_e64 s[6:7], 0, v37
	v_add_u32_e32 v37, 1, v35
	s_nop 0
	v_cndmask_b32_e64 v36, v35, v36, s[6:7]
	v_fma_f32 v35, -v37, v35, v34
	v_cmp_lt_f32_e64 s[6:7], 0, v35
	s_nop 1
	v_cndmask_b32_e64 v35, v36, v37, s[6:7]
	v_mul_f32_e32 v36, 0x37800000, v35
	v_cndmask_b32_e32 v35, v35, v36, vcc
	v_cmp_class_f32_e32 vcc, v34, v215
	s_nop 1
	v_cndmask_b32_e32 v34, v35, v34, vcc
	v_div_scale_f32 v35, s[6:7], v34, v34, 1.0
	v_rcp_f32_e32 v36, v35
	s_nop 0
	v_fma_f32 v37, -v35, v36, 1.0
	v_fmac_f32_e32 v36, v37, v36
	v_div_scale_f32 v37, vcc, 1.0, v34, 1.0
	v_mul_f32_e32 v38, v37, v36
	v_fma_f32 v39, -v35, v38, v37
	v_fmac_f32_e32 v38, v39, v36
	v_fma_f32 v35, -v35, v38, v37
	v_div_fmas_f32 v35, v35, v36, v38
	v_div_fixup_f32 v58, v35, v34, 1.0
	global_load_dwordx4 v[34:37], v[72:73], off offset:16
	global_load_dwordx4 v[42:45], v[72:73], off
	global_load_dwordx4 v[38:41], v[74:75], off offset:16
	global_load_dwordx4 v[46:49], v[74:75], off
	v_pk_mul_f32 v[150:151], v[150:151], v[58:59] op_sel_hi:[1,0]
	v_pk_mul_f32 v[152:153], v[152:153], v[58:59] op_sel_hi:[1,0]
	v_pk_mul_f32 v[146:147], v[146:147], v[58:59] op_sel_hi:[1,0]
	v_pk_mul_f32 v[144:145], v[144:145], v[58:59] op_sel_hi:[1,0]
	v_pk_mul_f32 v[136:137], v[136:137], v[58:59] op_sel_hi:[1,0]
	v_pk_mul_f32 v[126:127], v[126:127], v[58:59] op_sel_hi:[1,0]
	v_pk_mul_f32 v[128:129], v[128:129], v[58:59] op_sel_hi:[1,0]
	v_pk_mul_f32 v[120:121], v[120:121], v[58:59] op_sel_hi:[1,0]
	v_pk_mul_f32 v[118:119], v[118:119], v[58:59] op_sel_hi:[1,0]
	v_pk_mul_f32 v[112:113], v[112:113], v[58:59] op_sel_hi:[1,0]
	v_pk_mul_f32 v[110:111], v[110:111], v[58:59] op_sel_hi:[1,0]
	v_pk_mul_f32 v[64:65], v[64:65], v[58:59] op_sel_hi:[1,0]
	v_pk_mul_f32 v[104:105], v[104:105], v[58:59] op_sel_hi:[1,0]
	v_pk_mul_f32 v[56:57], v[56:57], v[58:59] op_sel_hi:[1,0]
	v_pk_mul_f32 v[54:55], v[54:55], v[58:59] op_sel_hi:[1,0]
	s_waitcnt vmcnt(0)
	v_pk_fma_f32 v[44:45], v[44:45], v[152:153], v[48:49]
	v_pk_fma_f32 v[42:43], v[42:43], v[150:151], v[46:47]
	v_pk_mul_f32 v[46:47], v[142:143], v[58:59] op_sel_hi:[1,0]
	v_pk_mul_f32 v[48:49], v[148:149], v[58:59] op_sel_hi:[1,0]
	v_lshlrev_b32_e32 v142, 4, v70
	v_pk_fma_f32 v[36:37], v[36:37], v[48:49], v[40:41]
	v_pk_fma_f32 v[34:35], v[34:35], v[46:47], v[38:39]
	global_store_dwordx4 v142, v[42:45], s[36:37]
	global_store_dwordx4 v142, v[34:37], s[36:37] offset:16
	global_load_dwordx4 v[34:37], v[76:77], off offset:16
	s_nop 0
	global_load_dwordx4 v[38:41], v[76:77], off
	global_load_dwordx4 v[42:45], v[78:79], off offset:16
	global_load_dwordx4 v[46:49], v[78:79], off
	s_waitcnt vmcnt(0)
	v_pk_fma_f32 v[38:39], v[38:39], v[144:145], v[46:47]
	v_pk_fma_f32 v[40:41], v[40:41], v[146:147], v[48:49]
	v_pk_mul_f32 v[46:47], v[138:139], v[58:59] op_sel_hi:[1,0]
	v_pk_mul_f32 v[48:49], v[134:135], v[58:59] op_sel_hi:[1,0]
	v_pk_fma_f32 v[36:37], v[36:37], v[46:47], v[44:45]
	v_pk_fma_f32 v[34:35], v[34:35], v[48:49], v[42:43]
	global_store_dwordx4 v142, v[38:41], s[36:37] offset:2048
	global_store_dwordx4 v142, v[34:37], s[36:37] offset:2064
	global_load_dwordx4 v[34:37], v[80:81], off offset:16
	s_nop 0
	global_load_dwordx4 v[38:41], v[80:81], off
	global_load_dwordx4 v[42:45], v[82:83], off offset:16
	global_load_dwordx4 v[46:49], v[82:83], off
	v_pk_mul_f32 v[134:135], v[140:141], v[58:59] op_sel_hi:[1,0]
	s_waitcnt vmcnt(0)
	v_pk_fma_f32 v[38:39], v[38:39], v[136:137], v[46:47]
	v_pk_fma_f32 v[40:41], v[40:41], v[134:135], v[48:49]
	v_pk_mul_f32 v[46:47], v[132:133], v[58:59] op_sel_hi:[1,0]
	v_pk_mul_f32 v[48:49], v[130:131], v[58:59] op_sel_hi:[1,0]
	v_pk_fma_f32 v[36:37], v[36:37], v[46:47], v[44:45]
	v_pk_fma_f32 v[34:35], v[34:35], v[48:49], v[42:43]
	global_store_dwordx4 v158, v[38:41], s[36:37]
	global_store_dwordx4 v159, v[34:37], s[36:37]
	global_load_dwordx4 v[34:37], v[84:85], off offset:16
	s_nop 0
	global_load_dwordx4 v[38:41], v[84:85], off
	global_load_dwordx4 v[42:45], v[86:87], off offset:16
	global_load_dwordx4 v[46:49], v[86:87], off
	s_waitcnt vmcnt(0)
	v_pk_fma_f32 v[38:39], v[38:39], v[128:129], v[46:47]
	v_pk_fma_f32 v[40:41], v[40:41], v[126:127], v[48:49]
	v_pk_mul_f32 v[46:47], v[124:125], v[58:59] op_sel_hi:[1,0]
	v_pk_mul_f32 v[48:49], v[122:123], v[58:59] op_sel_hi:[1,0]
	v_pk_fma_f32 v[36:37], v[36:37], v[46:47], v[44:45]
	v_pk_fma_f32 v[34:35], v[34:35], v[48:49], v[42:43]
	global_store_dwordx4 v160, v[38:41], s[36:37]
	global_store_dwordx4 v161, v[34:37], s[36:37]
	global_load_dwordx4 v[34:37], v[88:89], off offset:16
	s_nop 0
	global_load_dwordx4 v[38:41], v[88:89], off
	global_load_dwordx4 v[42:45], v[90:91], off offset:16
	global_load_dwordx4 v[46:49], v[90:91], off
	s_waitcnt vmcnt(0)
	v_pk_fma_f32 v[38:39], v[38:39], v[118:119], v[46:47]
	v_pk_fma_f32 v[40:41], v[40:41], v[120:121], v[48:49]
	v_pk_mul_f32 v[46:47], v[116:117], v[58:59] op_sel_hi:[1,0]
	v_pk_mul_f32 v[48:49], v[114:115], v[58:59] op_sel_hi:[1,0]
	v_pk_fma_f32 v[36:37], v[36:37], v[46:47], v[44:45]
	v_pk_fma_f32 v[34:35], v[34:35], v[48:49], v[42:43]
	global_store_dwordx4 v162, v[38:41], s[36:37]
	global_store_dwordx4 v163, v[34:37], s[36:37]
	global_load_dwordx4 v[34:37], v[92:93], off offset:16
	s_nop 0
	global_load_dwordx4 v[38:41], v[92:93], off
	global_load_dwordx4 v[42:45], v[94:95], off offset:16
	global_load_dwordx4 v[46:49], v[94:95], off
	s_waitcnt vmcnt(0)
; __device__ __forceinline__ f32x4 h4lo(const u32x4 w) { return (f32x4){hlo(w.x), hhi(w.x), hlo(w.y), hhi(w.y)}; }
; __device__ __forceinline__ f32x4 h4hi(const u32x4 w) { return (f32x4){hlo(w.z), hhi(w.z), hlo(w.w), hhi(w.w)}; }
; __device__ __forceinline__ int row_perm(int m) { const int j = m >> 11, r = m & 2047; return (11 - 3 * (j & 3) - (j >> 2)) * 2048 + r; }
; __device__ __forceinline__ unsigned pk2(float lo, float hi) { const f32x2 v = {lo, hi}; return __builtin_bit_cast(unsigned, __builtin_convertvector(v, bf16x2_t)); }
; __device__ __forceinline__ void ln_load_b(const v4u (&raw)[8], f32x4 (&v)[16], float& mean, float& rstd, int lane) {
;     float s = 0.f;
; #pragma unroll
;     for (int j = 0; j < 8; ++j) { const v4u w = raw[j]; v[2 * j] = pg8::h4lo(w); v[2 * j + 1] = pg8::h4hi(w);
;         s += ((v[2 * j].x + v[2 * j].y) + (v[2 * j].z + v[2 * j].w)) + ((v[2 * j + 1].x + v[2 * j + 1].y) + (v[2 * j + 1].z + v[2 * j + 1].w)); }
; template <bool WF> __device__ __forceinline__ void ln_row_b(const v4u (&src)[8], const float* g, const float* b, float* dstf, bf16* dstb, int lane) {
;     f32x4 v[16]; float mean, rstd; ln_load_b(src, v, mean, rstd, lane);
; #pragma unroll
;     for (int j = 0; j < 8; ++j) { const int q = 2 * (64 * j + lane);
;         const f32x4 o0 = v[2 * j] * rstd * ((const f32x4*)g)[q] + ((const f32x4*)b)[q], o1 = v[2 * j + 1] * rstd * ((const f32x4*)g)[q + 1] + ((const f32x4*)b)[q + 1];
;         if (WF) { ((f32x4*)dstf)[q] = o0; ((f32x4*)dstf)[q + 1] = o1; }
;         else { v4u w; w.x = pk2(o0.x, o0.y); w.y = pk2(o0.z, o0.w); w.z = pk2(o1.x, o1.y); w.w = pk2(o1.z, o1.w); ((v4u*)dstb)[64 * j + lane] = w; } }
; __global__ void __launch_bounds__(NT, 2) fwd_kernel(Args args_unused) {
;     ...
;             for (int m0 = gw; m0 < MTOK; m0 += 2 * ngw) { const int mA = row_perm(m0), mB = row_perm(m0 + ngw < MTOK ? m0 + ngw : m0); const bool hasB = m0 + ngw < MTOK;
;                 v4u rawA[8], rawB[8]; ln_fetch_b(WSP(const bf16, WS_XR) + (size_t)mA * DM, rawA, lane); ln_fetch_b(WSP(const bf16, WS_XR) + (size_t)mB * DM, rawB, lane);
;                 { const int m = mA; ln_row_b<true>(rawA, KA_IN(ka, 24) + DM, KA_IN(ka, 25) + DM, xres + (size_t)m * DM, (bf16*)nullptr, lane); }
;                 if (hasB) { const int m = mB; ln_row_b<true>(rawB, KA_IN(ka, 24) + DM, KA_IN(ka, 25) + DM, xres + (size_t)m * DM, (bf16*)nullptr, lane); } }
	v_pk_fma_f32 v[38:39], v[38:39], v[110:111], v[46:47]
	v_pk_fma_f32 v[40:41], v[40:41], v[112:113], v[48:49]
	v_pk_mul_f32 v[46:47], v[108:109], v[58:59] op_sel_hi:[1,0]
	v_pk_mul_f32 v[48:49], v[106:107], v[58:59] op_sel_hi:[1,0]
	v_pk_fma_f32 v[36:37], v[46:47], v[36:37], v[44:45]
	v_pk_fma_f32 v[34:35], v[48:49], v[34:35], v[42:43]
	global_store_dwordx4 v164, v[38:41], s[36:37]
	global_store_dwordx4 v165, v[34:37], s[36:37]
	global_load_dwordx4 v[34:37], v[96:97], off offset:16
	s_nop 0
	global_load_dwordx4 v[38:41], v[96:97], off
	global_load_dwordx4 v[42:45], v[98:99], off offset:16
	global_load_dwordx4 v[46:49], v[98:99], off
	s_waitcnt vmcnt(0)
	v_pk_fma_f32 v[38:39], v[104:105], v[38:39], v[46:47]
	v_pk_fma_f32 v[40:41], v[64:65], v[40:41], v[48:49]
	v_pk_mul_f32 v[46:47], v[62:63], v[58:59] op_sel_hi:[1,0]
	v_pk_mul_f32 v[48:49], v[60:61], v[58:59] op_sel_hi:[1,0]
	v_pk_fma_f32 v[36:37], v[46:47], v[36:37], v[44:45]
	v_pk_fma_f32 v[34:35], v[48:49], v[34:35], v[42:43]
	global_store_dwordx4 v166, v[38:41], s[36:37]
	global_store_dwordx4 v167, v[34:37], s[36:37]
	global_load_dwordx4 v[34:37], v[100:101], off offset:16
	s_nop 0
	global_load_dwordx4 v[38:41], v[100:101], off
	global_load_dwordx4 v[42:45], v[102:103], off offset:16
	global_load_dwordx4 v[46:49], v[102:103], off
	s_waitcnt vmcnt(0)
	v_pk_fma_f32 v[38:39], v[54:55], v[38:39], v[46:47]
	v_pk_fma_f32 v[40:41], v[56:57], v[40:41], v[48:49]
	v_pk_mul_f32 v[46:47], v[52:53], v[58:59] op_sel_hi:[1,0]
	v_pk_mul_f32 v[48:49], v[50:51], v[58:59] op_sel_hi:[1,0]
	v_pk_fma_f32 v[36:37], v[46:47], v[36:37], v[44:45]
	v_pk_fma_f32 v[34:35], v[48:49], v[34:35], v[42:43]
	global_store_dwordx4 v168, v[38:41], s[36:37]
	global_store_dwordx4 v169, v[34:37], s[36:37]
	s_cbranch_scc1 .LBB0_1265
	s_nop 0
	v_cvt_f32_f16_sdwa v34, v30 dst_sel:DWORD dst_unused:UNUSED_PAD src0_sel:WORD_1
	v_cvt_f32_f16_e32 v36, v30
	v_cvt_f32_f16_sdwa v38, v31 dst_sel:DWORD dst_unused:UNUSED_PAD src0_sel:WORD_1
	v_cvt_f32_f16_e32 v40, v31
	v_cvt_f32_f16_sdwa v35, v32 dst_sel:DWORD dst_unused:UNUSED_PAD src0_sel:WORD_1
	v_cvt_f32_f16_e32 v37, v32
	v_cvt_f32_f16_sdwa v39, v33 dst_sel:DWORD dst_unused:UNUSED_PAD src0_sel:WORD_1
	v_cvt_f32_f16_e32 v41, v33
	v_cvt_f32_f16_e32 v42, v28
	v_pk_add_f32 v[34:35], v[36:37], v[34:35]
	v_cvt_f32_f16_e32 v43, v29
	v_pk_add_f32 v[36:37], v[40:41], v[38:39]
	v_cvt_f32_f16_e32 v38, v26
	v_pk_add_f32 v[34:35], v[34:35], v[36:37]
	v_cvt_f32_f16_sdwa v36, v26 dst_sel:DWORD dst_unused:UNUSED_PAD src0_sel:WORD_1
	v_cvt_f32_f16_sdwa v37, v27 dst_sel:DWORD dst_unused:UNUSED_PAD src0_sel:WORD_1
	v_cvt_f32_f16_e32 v39, v27
	v_cvt_f32_f16_sdwa v40, v28 dst_sel:DWORD dst_unused:UNUSED_PAD src0_sel:WORD_1
	v_cvt_f32_f16_sdwa v41, v29 dst_sel:DWORD dst_unused:UNUSED_PAD src0_sel:WORD_1
	v_pk_add_f32 v[34:35], v[34:35], v[34:35] op_sel:[0,1] op_sel_hi:[1,0]
	v_pk_add_f32 v[36:37], v[38:39], v[36:37]
	v_cvt_f32_f16_sdwa v35, v22 dst_sel:DWORD dst_unused:UNUSED_PAD src0_sel:WORD_1
	v_pk_add_f32 v[38:39], v[42:43], v[40:41]
	v_pk_add_f32 v[36:37], v[36:37], v[36:37] op_sel:[0,1] op_sel_hi:[1,0]
	v_pk_add_f32 v[38:39], v[38:39], v[38:39] op_sel:[0,1] op_sel_hi:[1,0]
	v_cvt_f32_f16_e32 v37, v22
	v_cvt_f32_f16_sdwa v39, v23 dst_sel:DWORD dst_unused:UNUSED_PAD src0_sel:WORD_1
	v_cvt_f32_f16_e32 v41, v23
	v_cvt_f32_f16_sdwa v43, v24 dst_sel:DWORD dst_unused:UNUSED_PAD src0_sel:WORD_1
	v_cvt_f32_f16_e32 v44, v24
	v_cvt_f32_f16_sdwa v45, v25 dst_sel:DWORD dst_unused:UNUSED_PAD src0_sel:WORD_1
	v_cvt_f32_f16_e32 v46, v25
	v_add_f32_e32 v40, v35, v37
	v_add_f32_e32 v42, v39, v41
	v_cvt_f32_f16_sdwa v49, v18 dst_sel:DWORD dst_unused:UNUSED_PAD src0_sel:WORD_1
	v_cvt_f32_f16_e32 v35, v18
	v_cvt_f32_f16_sdwa v39, v19 dst_sel:DWORD dst_unused:UNUSED_PAD src0_sel:WORD_1
	v_cvt_f32_f16_e32 v37, v19
	v_add_f32_e32 v44, v43, v44
	v_add_f32_e32 v46, v45, v46
	v_cvt_f32_f16_sdwa v43, v20 dst_sel:DWORD dst_unused:UNUSED_PAD src0_sel:WORD_1
	v_cvt_f32_f16_e32 v41, v20
	v_cvt_f32_f16_sdwa v47, v21 dst_sel:DWORD dst_unused:UNUSED_PAD src0_sel:WORD_1
	v_cvt_f32_f16_e32 v45, v21
	v_mov_b32_e32 v48, v183
	v_pk_add_f32 v[34:35], v[34:35], v[48:49]
	v_pk_add_f32 v[36:37], v[36:37], v[38:39]
	v_pk_add_f32 v[38:39], v[44:45], v[46:47]
	v_pk_add_f32 v[34:35], v[34:35], v[36:37]
	v_pk_add_f32 v[36:37], v[40:41], v[42:43]
	v_cvt_f32_f16_sdwa v40, v15 dst_sel:DWORD dst_unused:UNUSED_PAD src0_sel:WORD_1
	v_pk_add_f32 v[36:37], v[36:37], v[38:39]
	v_cvt_f32_f16_e32 v38, v14
	v_pk_add_f32 v[34:35], v[34:35], v[36:37]
	v_cvt_f32_f16_sdwa v36, v14 dst_sel:DWORD dst_unused:UNUSED_PAD src0_sel:WORD_1
	v_cvt_f32_f16_e32 v42, v15
	v_cvt_f32_f16_sdwa v37, v16 dst_sel:DWORD dst_unused:UNUSED_PAD src0_sel:WORD_1
	v_cvt_f32_f16_e32 v39, v16
	v_cvt_f32_f16_sdwa v41, v17 dst_sel:DWORD dst_unused:UNUSED_PAD src0_sel:WORD_1
	v_cvt_f32_f16_e32 v43, v17
	v_cvt_f32_f16_e32 v44, v12
	v_pk_add_f32 v[36:37], v[38:39], v[36:37]
	v_cvt_f32_f16_e32 v45, v13
	v_pk_add_f32 v[38:39], v[42:43], v[40:41]
	v_cvt_f32_f16_e32 v40, v10
	v_pk_add_f32 v[36:37], v[36:37], v[38:39]
	v_cvt_f32_f16_sdwa v38, v10 dst_sel:DWORD dst_unused:UNUSED_PAD src0_sel:WORD_1
	v_cvt_f32_f16_sdwa v39, v11 dst_sel:DWORD dst_unused:UNUSED_PAD src0_sel:WORD_1
	v_cvt_f32_f16_e32 v41, v11
	v_cvt_f32_f16_sdwa v42, v12 dst_sel:DWORD dst_unused:UNUSED_PAD src0_sel:WORD_1
	v_cvt_f32_f16_sdwa v43, v13 dst_sel:DWORD dst_unused:UNUSED_PAD src0_sel:WORD_1
	v_pk_add_f32 v[34:35], v[34:35], v[34:35] op_sel:[0,1] op_sel_hi:[1,0]
	v_pk_add_f32 v[38:39], v[40:41], v[38:39]
	v_pk_add_f32 v[36:37], v[36:37], v[36:37] op_sel:[0,1] op_sel_hi:[1,0]
	v_pk_add_f32 v[40:41], v[44:45], v[42:43]
; __device__ __forceinline__ f32x4 h4lo(const u32x4 w) { return (f32x4){hlo(w.x), hhi(w.x), hlo(w.y), hhi(w.y)}; }
; __device__ __forceinline__ f32x4 h4hi(const u32x4 w) { return (f32x4){hlo(w.z), hhi(w.z), hlo(w.w), hhi(w.w)}; }
; __device__ __forceinline__ float wave_sum(float v) {
; #pragma unroll
;     for (int o = 1; o < 64; o <<= 1) v += __shfl_xor(v, o);
;     return v;
; }
; __device__ __forceinline__ void ln_load_b(const v4u (&raw)[8], f32x4 (&v)[16], float& mean, float& rstd, int lane) {
;     float s = 0.f;
; #pragma unroll
;     for (int j = 0; j < 8; ++j) { const v4u w = raw[j]; v[2 * j] = pg8::h4lo(w); v[2 * j + 1] = pg8::h4hi(w);
;         s += ((v[2 * j].x + v[2 * j].y) + (v[2 * j].z + v[2 * j].w)) + ((v[2 * j + 1].x + v[2 * j + 1].y) + (v[2 * j + 1].z + v[2 * j + 1].w)); }
;     mean = wave_sum(s) * (1.f / 4096.f); float s2 = 0.f;
; #pragma unroll
;     for (int j = 0; j < 16; ++j) { v[j] = v[j] - mean; s2 += (v[j].x * v[j].x + v[j].y * v[j].y) + (v[j].z * v[j].z + v[j].w * v[j].w); }
	v_pk_add_f32 v[38:39], v[38:39], v[38:39] op_sel:[0,1] op_sel_hi:[1,0]
	v_pk_add_f32 v[40:41], v[40:41], v[40:41] op_sel:[0,1] op_sel_hi:[1,0]
	v_cvt_f32_f16_sdwa v35, v6 dst_sel:DWORD dst_unused:UNUSED_PAD src0_sel:WORD_1
	v_cvt_f32_f16_e32 v37, v6
	v_cvt_f32_f16_sdwa v39, v7 dst_sel:DWORD dst_unused:UNUSED_PAD src0_sel:WORD_1
	v_cvt_f32_f16_e32 v41, v7
	v_cvt_f32_f16_sdwa v43, v8 dst_sel:DWORD dst_unused:UNUSED_PAD src0_sel:WORD_1
	v_cvt_f32_f16_e32 v45, v8
	v_cvt_f32_f16_sdwa v47, v9 dst_sel:DWORD dst_unused:UNUSED_PAD src0_sel:WORD_1
	v_cvt_f32_f16_e32 v48, v9
	v_add_f32_e32 v42, v35, v37
	v_add_f32_e32 v44, v39, v41
	v_cvt_f32_f16_sdwa v37, v2 dst_sel:DWORD dst_unused:UNUSED_PAD src0_sel:WORD_1
	v_cvt_f32_f16_e32 v35, v2
	v_cvt_f32_f16_sdwa v41, v3 dst_sel:DWORD dst_unused:UNUSED_PAD src0_sel:WORD_1
	v_cvt_f32_f16_e32 v39, v3
	v_add_f32_e32 v46, v43, v45
	v_add_f32_e32 v48, v47, v48
	v_cvt_f32_f16_sdwa v45, v4 dst_sel:DWORD dst_unused:UNUSED_PAD src0_sel:WORD_1
	v_cvt_f32_f16_e32 v43, v4
	v_cvt_f32_f16_sdwa v49, v5 dst_sel:DWORD dst_unused:UNUSED_PAD src0_sel:WORD_1
	v_cvt_f32_f16_e32 v47, v5
	v_pk_add_f32 v[34:35], v[34:35], v[36:37]
	v_pk_add_f32 v[36:37], v[38:39], v[40:41]
	s_lshl_b64 s[6:7], s[16:17], 12
	v_pk_add_f32 v[34:35], v[34:35], v[36:37]
	v_pk_add_f32 v[36:37], v[42:43], v[44:45]
	v_pk_add_f32 v[38:39], v[46:47], v[48:49]
	s_lshl_b64 s[6:7], s[6:7], 2
	v_pk_add_f32 v[36:37], v[36:37], v[38:39]
	s_add_u32 s16, s8, s6
	v_pk_add_f32 v[34:35], v[34:35], v[36:37]
	s_addc_u32 s17, s9, s7
	v_add_f32_e32 v34, v34, v35
	s_nop 1
	v_mov_b32_dpp v35, v34 quad_perm:[1,0,3,2] row_mask:0xf bank_mask:0xf
	s_waitcnt lgkmcnt(0)
	v_add_f32_e32 v34, v34, v35
	s_nop 1
	v_mov_b32_dpp v35, v34 quad_perm:[2,3,0,1] row_mask:0xf bank_mask:0xf
	s_waitcnt lgkmcnt(0)
	v_add_f32_e32 v34, v34, v35
	s_nop 1
	v_mov_b32_dpp v35, v34 row_half_mirror row_mask:0xf bank_mask:0xf
	s_waitcnt lgkmcnt(0)
	v_add_f32_e32 v34, v34, v35
	s_nop 1
	v_mov_b32_dpp v35, v34 row_mirror row_mask:0xf bank_mask:0xf
	s_waitcnt lgkmcnt(0)
	v_add_f32_e32 v34, v34, v35
	v_mov_b32_e32 v35, v34
	s_nop 1
	v_permlane16_swap_b32_e32 v35, v34
	s_waitcnt lgkmcnt(0)
	v_add_f32_e32 v34, v34, v35
	v_mov_b32_e32 v35, v34
	s_nop 1
	v_permlane32_swap_b32_e32 v35, v34
	s_waitcnt lgkmcnt(0)
	v_add_f32_e32 v114, v34, v35
	v_fma_mix_f32 v107, v114, s87, v30 op_sel:[0,0,1] op_sel_hi:[0,0,1]
	v_fma_mix_f32 v106, v114, s87, v30 op_sel_hi:[0,0,1]
	v_fma_mix_f32 v109, v114, s87, v31 op_sel:[0,0,1] op_sel_hi:[0,0,1]
	v_fma_mix_f32 v108, v114, s87, v31 op_sel_hi:[0,0,1]
	v_pk_mul_f32 v[30:31], v[108:109], v[108:109]
	v_pk_mul_f32 v[34:35], v[106:107], v[106:107]
	v_fma_mix_f32 v65, v114, s87, v32 op_sel:[0,0,1] op_sel_hi:[0,0,1]
	v_pk_mov_b32 v[36:37], v[34:35], v[30:31] op_sel:[1,0]
	v_mov_b32_e32 v35, v31
	v_fma_mix_f32 v64, v114, s87, v32 op_sel_hi:[0,0,1]
	v_fma_mix_f32 v105, v114, s87, v33 op_sel:[0,0,1] op_sel_hi:[0,0,1]
	v_fma_mix_f32 v104, v114, s87, v33 op_sel_hi:[0,0,1]
	v_fma_mix_f32 v60, v114, s87, v26 op_sel_hi:[0,0,1]
	v_pk_add_f32 v[30:31], v[36:37], v[34:35]
	v_pk_mul_f32 v[32:33], v[104:105], v[104:105]
	v_pk_mul_f32 v[34:35], v[64:65], v[64:65]
	v_fma_mix_f32 v61, v114, s87, v26 op_sel:[0,0,1] op_sel_hi:[0,0,1]
	v_mul_f32_e32 v26, v60, v60
	v_pk_mov_b32 v[36:37], v[34:35], v[32:33] op_sel:[1,0]
	v_mov_b32_e32 v35, v33
	v_fma_mix_f32 v63, v114, s87, v27 op_sel:[0,0,1] op_sel_hi:[0,0,1]
	v_fma_mix_f32 v62, v114, s87, v27 op_sel_hi:[0,0,1]
	v_pk_fma_f32 v[26:27], v[60:61], v[60:61], v[26:27] op_sel_hi:[1,1,0]
	v_pk_add_f32 v[32:33], v[36:37], v[34:35]
	v_mul_f32_e32 v26, v62, v62
	v_pk_add_f32 v[30:31], v[30:31], v[30:31] op_sel_hi:[0,1]
	v_pk_add_f32 v[32:33], v[32:33], v[32:33] op_sel_hi:[0,1]
	v_pk_fma_f32 v[34:35], v[62:63], v[62:63], v[26:27] op_sel_hi:[1,1,0]
	v_fma_mix_f32 v57, v114, s87, v29 op_sel:[0,0,1] op_sel_hi:[0,0,1]
	v_fma_mix_f32 v56, v114, s87, v29 op_sel_hi:[0,0,1]
	v_fma_mix_f32 v53, v114, s87, v28 op_sel:[0,0,1] op_sel_hi:[0,0,1]
	v_fma_mix_f32 v52, v114, s87, v28 op_sel_hi:[0,0,1]
	v_mul_f32_e32 v26, v52, v52
	v_mul_f32_e32 v34, v53, v53
	v_mul_f32_e32 v30, v56, v56
	v_mul_f32_e32 v32, v57, v57
	v_pk_add_f32 v[26:27], v[26:27], v[34:35]
	v_pk_add_f32 v[28:29], v[30:31], v[32:33]
	v_fma_mix_f32 v55, v114, s87, v22 op_sel:[0,0,1] op_sel_hi:[0,0,1]
	v_fma_mix_f32 v54, v114, s87, v22 op_sel_hi:[0,0,1]
	v_fma_mix_f32 v59, v114, s87, v23 op_sel:[0,0,1] op_sel_hi:[0,0,1]
	v_fma_mix_f32 v58, v114, s87, v23 op_sel_hi:[0,0,1]
	v_pk_add_f32 v[26:27], v[26:27], v[28:29]
	v_pk_mul_f32 v[22:23], v[58:59], v[58:59]
	v_pk_mul_f32 v[28:29], v[54:55], v[54:55]
	v_fma_mix_f32 v48, v114, s87, v24 op_sel_hi:[0,0,1]
	v_pk_mov_b32 v[30:31], v[28:29], v[22:23] op_sel:[1,0]
	v_mov_b32_e32 v29, v23
	v_pk_add_f32 v[22:23], v[30:31], v[28:29]
	v_fma_mix_f32 v49, v114, s87, v24 op_sel:[0,0,1] op_sel_hi:[0,0,1]
	v_pk_add_f32 v[22:23], v[22:23], v[22:23] op_sel_hi:[0,1]
	v_fma_mix_f32 v50, v114, s87, v25 op_sel_hi:[0,0,1]
	v_mul_f32_e32 v22, v48, v48
	v_fma_mix_f32 v51, v114, s87, v25 op_sel:[0,0,1] op_sel_hi:[0,0,1]
	v_pk_fma_f32 v[24:25], v[48:49], v[48:49], v[22:23] op_sel_hi:[1,1,0]
	v_mul_f32_e32 v22, v50, v50
	v_pk_add_f32 v[26:27], v[26:27], v[26:27] op_sel_hi:[0,1]
	v_pk_fma_f32 v[28:29], v[50:51], v[50:51], v[22:23] op_sel_hi:[1,1,0]
	v_fma_mix_f32 v45, v114, s87, v19 op_sel:[0,0,1] op_sel_hi:[0,0,1]
	v_fma_mix_f32 v44, v114, s87, v19 op_sel_hi:[0,0,1]
	v_fma_mix_f32 v47, v114, s87, v18 op_sel:[0,0,1] op_sel_hi:[0,0,1]
	v_fma_mix_f32 v46, v114, s87, v18 op_sel_hi:[0,0,1]
	v_mul_f32_e32 v24, v46, v46
	v_mul_f32_e32 v28, v47, v47
	v_mul_f32_e32 v22, v44, v44
	v_mul_f32_e32 v26, v45, v45
; __device__ __forceinline__ float wave_sum(float v) {
; #pragma unroll
;     for (int o = 1; o < 64; o <<= 1) v += __shfl_xor(v, o);
;     return v;
; }
; __device__ __forceinline__ void ln_load_b(const v4u (&raw)[8], f32x4 (&v)[16], float& mean, float& rstd, int lane) {
;     ...
;     mean = wave_sum(s) * (1.f / 4096.f); float s2 = 0.f;
; #pragma unroll
;     for (int j = 0; j < 16; ++j) { v[j] = v[j] - mean; s2 += (v[j].x * v[j].x + v[j].y * v[j].y) + (v[j].z * v[j].z + v[j].w * v[j].w); }
;     rstd = 1.f / sqrtf(wave_sum(s2) * (1.f / 4096.f) + 1e-5f);
	v_pk_add_f32 v[18:19], v[24:25], v[28:29]
	v_pk_add_f32 v[22:23], v[22:23], v[26:27]
	v_fma_mix_f32 v41, v114, s87, v20 op_sel:[0,0,1] op_sel_hi:[0,0,1]
	v_fma_mix_f32 v40, v114, s87, v20 op_sel_hi:[0,0,1]
	v_fma_mix_f32 v43, v114, s87, v21 op_sel:[0,0,1] op_sel_hi:[0,0,1]
	v_fma_mix_f32 v42, v114, s87, v21 op_sel_hi:[0,0,1]
	v_fma_mix_f32 v36, v114, s87, v14 op_sel_hi:[0,0,1]
	v_pk_add_f32 v[18:19], v[18:19], v[22:23]
	v_pk_mul_f32 v[20:21], v[42:43], v[42:43]
	v_pk_mul_f32 v[22:23], v[40:41], v[40:41]
	v_fma_mix_f32 v37, v114, s87, v14 op_sel:[0,0,1] op_sel_hi:[0,0,1]
	v_mul_f32_e32 v14, v36, v36
	v_pk_mov_b32 v[24:25], v[22:23], v[20:21] op_sel:[1,0]
	v_mov_b32_e32 v23, v21
	v_fma_mix_f32 v39, v114, s87, v15 op_sel:[0,0,1] op_sel_hi:[0,0,1]
	v_fma_mix_f32 v38, v114, s87, v15 op_sel_hi:[0,0,1]
	v_pk_fma_f32 v[14:15], v[36:37], v[36:37], v[14:15] op_sel_hi:[1,1,0]
	v_pk_add_f32 v[20:21], v[24:25], v[22:23]
	v_mul_f32_e32 v14, v38, v38
	v_pk_add_f32 v[18:19], v[18:19], v[18:19] op_sel_hi:[0,1]
	v_pk_add_f32 v[20:21], v[20:21], v[20:21] op_sel_hi:[0,1]
	v_pk_fma_f32 v[22:23], v[38:39], v[38:39], v[14:15] op_sel_hi:[1,1,0]
	v_fma_mix_f32 v35, v114, s87, v17 op_sel:[0,0,1] op_sel_hi:[0,0,1]
	v_fma_mix_f32 v34, v114, s87, v17 op_sel_hi:[0,0,1]
	v_fma_mix_f32 v33, v114, s87, v16 op_sel:[0,0,1] op_sel_hi:[0,0,1]
	v_fma_mix_f32 v32, v114, s87, v16 op_sel_hi:[0,0,1]
	v_mul_f32_e32 v14, v32, v32
	v_mul_f32_e32 v22, v33, v33
	v_mul_f32_e32 v20, v34, v34
	v_mul_f32_e32 v18, v35, v35
	v_pk_add_f32 v[14:15], v[14:15], v[22:23]
	v_pk_add_f32 v[16:17], v[20:21], v[18:19]
	v_fma_mix_f32 v29, v114, s87, v10 op_sel:[0,0,1] op_sel_hi:[0,0,1]
	v_fma_mix_f32 v28, v114, s87, v10 op_sel_hi:[0,0,1]
	v_fma_mix_f32 v31, v114, s87, v11 op_sel:[0,0,1] op_sel_hi:[0,0,1]
	v_fma_mix_f32 v30, v114, s87, v11 op_sel_hi:[0,0,1]
	v_pk_add_f32 v[14:15], v[14:15], v[16:17]
	v_pk_mul_f32 v[10:11], v[30:31], v[30:31]
	v_pk_mul_f32 v[16:17], v[28:29], v[28:29]
	v_fma_mix_f32 v24, v114, s87, v12 op_sel_hi:[0,0,1]
	v_pk_mov_b32 v[18:19], v[16:17], v[10:11] op_sel:[1,0]
	v_mov_b32_e32 v17, v11
	v_pk_add_f32 v[10:11], v[18:19], v[16:17]
	v_fma_mix_f32 v25, v114, s87, v12 op_sel:[0,0,1] op_sel_hi:[0,0,1]
	v_pk_add_f32 v[10:11], v[10:11], v[10:11] op_sel_hi:[0,1]
	v_fma_mix_f32 v26, v114, s87, v13 op_sel_hi:[0,0,1]
	v_mul_f32_e32 v10, v24, v24
	v_fma_mix_f32 v27, v114, s87, v13 op_sel:[0,0,1] op_sel_hi:[0,0,1]
	v_pk_fma_f32 v[12:13], v[24:25], v[24:25], v[10:11] op_sel_hi:[1,1,0]
	v_mul_f32_e32 v10, v26, v26
	v_pk_add_f32 v[14:15], v[14:15], v[14:15] op_sel_hi:[0,1]
	v_pk_fma_f32 v[16:17], v[26:27], v[26:27], v[10:11] op_sel_hi:[1,1,0]
	v_fma_mix_f32 v21, v114, s87, v7 op_sel:[0,0,1] op_sel_hi:[0,0,1]
	v_fma_mix_f32 v20, v114, s87, v7 op_sel_hi:[0,0,1]
	v_fma_mix_f32 v23, v114, s87, v6 op_sel:[0,0,1] op_sel_hi:[0,0,1]
	v_fma_mix_f32 v22, v114, s87, v6 op_sel_hi:[0,0,1]
	v_mul_f32_e32 v12, v22, v22
	v_mul_f32_e32 v16, v23, v23
	v_mul_f32_e32 v10, v20, v20
	v_mul_f32_e32 v14, v21, v21
	v_pk_add_f32 v[6:7], v[12:13], v[16:17]
	v_pk_add_f32 v[10:11], v[10:11], v[14:15]
	v_fma_mix_f32 v17, v114, s87, v8 op_sel:[0,0,1] op_sel_hi:[0,0,1]
	v_pk_add_f32 v[6:7], v[6:7], v[10:11]
	v_fma_mix_f32 v16, v114, s87, v8 op_sel_hi:[0,0,1]
	v_fma_mix_f32 v19, v114, s87, v9 op_sel:[0,0,1] op_sel_hi:[0,0,1]
	v_fma_mix_f32 v18, v114, s87, v9 op_sel_hi:[0,0,1]
	v_pk_add_f32 v[14:15], v[6:7], v[6:7] op_sel_hi:[0,1]
	v_pk_mul_f32 v[6:7], v[18:19], v[18:19]
	v_pk_mul_f32 v[8:9], v[16:17], v[16:17]
	v_fma_mix_f32 v13, v114, s87, v3 op_sel:[0,0,1] op_sel_hi:[0,0,1]
	v_pk_mov_b32 v[10:11], v[8:9], v[6:7] op_sel:[1,0]
	v_mov_b32_e32 v9, v7
	v_pk_add_f32 v[6:7], v[10:11], v[8:9]
	v_fma_mix_f32 v10, v114, s87, v2 op_sel_hi:[0,0,1]
	v_fma_mix_f32 v11, v114, s87, v2 op_sel:[0,0,1] op_sel_hi:[0,0,1]
	v_mul_f32_e32 v2, v10, v10
	v_fma_mix_f32 v12, v114, s87, v3 op_sel_hi:[0,0,1]
	v_pk_fma_f32 v[2:3], v[10:11], v[10:11], v[2:3] op_sel_hi:[1,1,0]
	v_pk_add_f32 v[110:111], v[6:7], v[6:7] op_sel_hi:[0,1]
	v_mul_f32_e32 v2, v12, v12
	v_pk_fma_f32 v[112:113], v[12:13], v[12:13], v[2:3] op_sel_hi:[1,1,0]
	v_fma_mix_f32 v9, v114, s87, v5 op_sel:[0,0,1] op_sel_hi:[0,0,1]
	v_fma_mix_f32 v8, v114, s87, v5 op_sel_hi:[0,0,1]
	v_fma_mix_f32 v7, v114, s87, v4 op_sel:[0,0,1] op_sel_hi:[0,0,1]
	v_fma_mix_f32 v6, v114, s87, v4 op_sel_hi:[0,0,1]
	v_mul_f32_e32 v2, v6, v6
	v_mul_f32_e32 v112, v7, v7
	v_mul_f32_e32 v110, v8, v8
	v_mul_f32_e32 v14, v9, v9
	v_pk_add_f32 v[2:3], v[2:3], v[112:113]
	v_pk_add_f32 v[4:5], v[110:111], v[14:15]
	s_nop 0
	v_pk_add_f32 v[2:3], v[2:3], v[4:5]
	s_nop 0
	v_add_f32_e32 v2, v2, v3
	s_nop 1
	v_mov_b32_dpp v3, v2 quad_perm:[1,0,3,2] row_mask:0xf bank_mask:0xf
	s_waitcnt lgkmcnt(0)
	v_add_f32_e32 v2, v2, v3
	s_nop 1
	v_mov_b32_dpp v3, v2 quad_perm:[2,3,0,1] row_mask:0xf bank_mask:0xf
	s_waitcnt lgkmcnt(0)
	v_add_f32_e32 v2, v2, v3
	s_nop 1
	v_mov_b32_dpp v3, v2 row_half_mirror row_mask:0xf bank_mask:0xf
	s_waitcnt lgkmcnt(0)
	v_add_f32_e32 v2, v2, v3
	s_nop 1
	v_mov_b32_dpp v3, v2 row_mirror row_mask:0xf bank_mask:0xf
	s_waitcnt lgkmcnt(0)
	v_add_f32_e32 v2, v2, v3
	v_mov_b32_e32 v3, v2
	s_nop 1
	v_permlane16_swap_b32_e32 v3, v2
	s_waitcnt lgkmcnt(0)
	v_add_f32_e32 v2, v2, v3
	v_mov_b32_e32 v3, v2
	s_nop 1
	v_permlane32_swap_b32_e32 v3, v2
	s_waitcnt lgkmcnt(0)
; __device__ __forceinline__ unsigned pk2(float lo, float hi) { const f32x2 v = {lo, hi}; return __builtin_bit_cast(unsigned, __builtin_convertvector(v, bf16x2_t)); }
; __device__ __forceinline__ void ln_load_b(const v4u (&raw)[8], f32x4 (&v)[16], float& mean, float& rstd, int lane) {
;     ...
;     rstd = 1.f / sqrtf(wave_sum(s2) * (1.f / 4096.f) + 1e-5f);
; template <bool WF> __device__ __forceinline__ void ln_row_b(const v4u (&src)[8], const float* g, const float* b, float* dstf, bf16* dstb, int lane) {
;     f32x4 v[16]; float mean, rstd; ln_load_b(src, v, mean, rstd, lane);
; #pragma unroll
;     for (int j = 0; j < 8; ++j) { const int q = 2 * (64 * j + lane);
;         const f32x4 o0 = v[2 * j] * rstd * ((const f32x4*)g)[q] + ((const f32x4*)b)[q], o1 = v[2 * j + 1] * rstd * ((const f32x4*)g)[q + 1] + ((const f32x4*)b)[q + 1];
;         if (WF) { ((f32x4*)dstf)[q] = o0; ((f32x4*)dstf)[q + 1] = o1; }
;         else { v4u w; w.x = pk2(o0.x, o0.y); w.y = pk2(o0.z, o0.w); w.z = pk2(o1.x, o1.y); w.w = pk2(o1.z, o1.w); ((v4u*)dstb)[64 * j + lane] = w; } }
	v_add_f32_e32 v2, v2, v3
	v_fmamk_f32 v2, v2, 0x39800000, v216
	v_cmp_gt_f32_e32 vcc, s95, v2
	v_mul_f32_e32 v3, 0x4f800000, v2
	s_nop 0
	v_cndmask_b32_e32 v2, v2, v3, vcc
	v_sqrt_f32_e32 v3, v2
	s_nop 0
	v_add_u32_e32 v4, -1, v3
	v_fma_f32 v5, -v4, v3, v2
	v_cmp_ge_f32_e64 s[6:7], 0, v5
	v_add_u32_e32 v5, 1, v3
	s_nop 0
	v_cndmask_b32_e64 v4, v3, v4, s[6:7]
	v_fma_f32 v3, -v5, v3, v2
	v_cmp_lt_f32_e64 s[6:7], 0, v3
	s_nop 1
	v_cndmask_b32_e64 v3, v4, v5, s[6:7]
	v_mul_f32_e32 v4, 0x37800000, v3
	v_cndmask_b32_e32 v3, v3, v4, vcc
	v_cmp_class_f32_e32 vcc, v2, v215
	s_nop 1
	v_cndmask_b32_e32 v2, v3, v2, vcc
	v_div_scale_f32 v3, s[6:7], v2, v2, 1.0
	v_rcp_f32_e32 v4, v3
	s_nop 0
	v_fma_f32 v5, -v3, v4, 1.0
	v_fmac_f32_e32 v4, v5, v4
	v_div_scale_f32 v5, vcc, 1.0, v2, 1.0
	v_mul_f32_e32 v14, v5, v4
	v_fma_f32 v15, -v3, v14, v5
	v_fmac_f32_e32 v14, v15, v4
	v_fma_f32 v3, -v3, v14, v5
	v_div_fmas_f32 v3, v3, v4, v14
	v_div_fixup_f32 v14, v3, v2, 1.0
	global_load_dwordx4 v[2:5], v[72:73], off offset:16
	global_load_dwordx4 v[110:113], v[72:73], off
	global_load_dwordx4 v[114:117], v[74:75], off offset:16
	global_load_dwordx4 v[118:121], v[74:75], off
	v_pk_mul_f32 v[106:107], v[106:107], v[14:15] op_sel_hi:[1,0]
	v_pk_mul_f32 v[108:109], v[108:109], v[14:15] op_sel_hi:[1,0]
	v_pk_mul_f32 v[64:65], v[64:65], v[14:15] op_sel_hi:[1,0]
	v_pk_mul_f32 v[104:105], v[104:105], v[14:15] op_sel_hi:[1,0]
	v_pk_mul_f32 v[56:57], v[56:57], v[14:15] op_sel_hi:[1,0]
	v_pk_mul_f32 v[52:53], v[52:53], v[14:15] op_sel_hi:[1,0]
	v_pk_mul_f32 v[50:51], v[50:51], v[14:15] op_sel_hi:[1,0]
	v_pk_mul_f32 v[48:49], v[48:49], v[14:15] op_sel_hi:[1,0]
	v_pk_mul_f32 v[42:43], v[42:43], v[14:15] op_sel_hi:[1,0]
	v_pk_mul_f32 v[40:41], v[40:41], v[14:15] op_sel_hi:[1,0]
	v_pk_mul_f32 v[34:35], v[34:35], v[14:15] op_sel_hi:[1,0]
	v_pk_mul_f32 v[32:33], v[32:33], v[14:15] op_sel_hi:[1,0]
	v_pk_mul_f32 v[26:27], v[26:27], v[14:15] op_sel_hi:[1,0]
	v_pk_mul_f32 v[24:25], v[24:25], v[14:15] op_sel_hi:[1,0]
	v_pk_mul_f32 v[18:19], v[18:19], v[14:15] op_sel_hi:[1,0]
	v_pk_mul_f32 v[16:17], v[16:17], v[14:15] op_sel_hi:[1,0]
	v_pk_mul_f32 v[8:9], v[8:9], v[14:15] op_sel_hi:[1,0]
	v_pk_mul_f32 v[6:7], v[6:7], v[14:15] op_sel_hi:[1,0]
	s_waitcnt vmcnt(1)
	v_pk_fma_f32 v[4:5], v[4:5], v[104:105], v[116:117]
	s_waitcnt vmcnt(0)
	v_pk_fma_f32 v[108:109], v[112:113], v[108:109], v[120:121]
	v_pk_fma_f32 v[106:107], v[110:111], v[106:107], v[118:119]
	v_pk_fma_f32 v[2:3], v[2:3], v[64:65], v[114:115]
	global_store_dwordx4 v142, v[106:109], s[16:17]
	global_store_dwordx4 v142, v[2:5], s[16:17] offset:16
	v_pk_mul_f32 v[64:65], v[62:63], v[14:15] op_sel_hi:[1,0]
	v_pk_mul_f32 v[112:113], v[60:61], v[14:15] op_sel_hi:[1,0]
	global_load_dwordx4 v[2:5], v[76:77], off offset:16
	global_load_dwordx4 v[60:63], v[76:77], off
	global_load_dwordx4 v[104:107], v[78:79], off offset:16
	global_load_dwordx4 v[108:111], v[78:79], off
	s_waitcnt vmcnt(1)
	v_pk_fma_f32 v[2:3], v[2:3], v[52:53], v[104:105]
	s_waitcnt vmcnt(0)
	v_pk_fma_f32 v[60:61], v[60:61], v[112:113], v[108:109]
	v_pk_fma_f32 v[62:63], v[62:63], v[64:65], v[110:111]
	v_pk_fma_f32 v[4:5], v[4:5], v[56:57], v[106:107]
	global_store_dwordx4 v142, v[60:63], s[16:17] offset:2048
	global_store_dwordx4 v142, v[2:5], s[16:17] offset:2064
	v_pk_mul_f32 v[64:65], v[58:59], v[14:15] op_sel_hi:[1,0]
	v_pk_mul_f32 v[104:105], v[54:55], v[14:15] op_sel_hi:[1,0]
	global_load_dwordx4 v[2:5], v[80:81], off offset:16
	global_load_dwordx4 v[52:55], v[80:81], off
	global_load_dwordx4 v[56:59], v[82:83], off offset:16
	global_load_dwordx4 v[60:63], v[82:83], off
	s_waitcnt vmcnt(1)
; __device__ __forceinline__ int row_perm(int m) { const int j = m >> 11, r = m & 2047; return (11 - 3 * (j & 3) - (j >> 2)) * 2048 + r; }
; __device__ __forceinline__ unsigned pk2(float lo, float hi) { const f32x2 v = {lo, hi}; return __builtin_bit_cast(unsigned, __builtin_convertvector(v, bf16x2_t)); }
; #define KA_IN(ka, i) (*(const float* const __attribute__((address_space(4)))*)((ka) + 8 * (i)))
; template <bool WF> __device__ __forceinline__ void ln_row_b(const v4u (&src)[8], const float* g, const float* b, float* dstf, bf16* dstb, int lane) {
;     ...
;     for (int j = 0; j < 8; ++j) { const int q = 2 * (64 * j + lane);
;         const f32x4 o0 = v[2 * j] * rstd * ((const f32x4*)g)[q] + ((const f32x4*)b)[q], o1 = v[2 * j + 1] * rstd * ((const f32x4*)g)[q + 1] + ((const f32x4*)b)[q + 1];
;         if (WF) { ((f32x4*)dstf)[q] = o0; ((f32x4*)dstf)[q + 1] = o1; }
;         else { v4u w; w.x = pk2(o0.x, o0.y); w.y = pk2(o0.z, o0.w); w.z = pk2(o1.x, o1.y); w.w = pk2(o1.z, o1.w); ((v4u*)dstb)[64 * j + lane] = w; } }
; __global__ void __launch_bounds__(NT, 2) fwd_kernel(Args args_unused) {
;     ...
;             for (int m0 = gw; m0 < MTOK; m0 += 2 * ngw) { const int mA = row_perm(m0), mB = row_perm(m0 + ngw < MTOK ? m0 + ngw : m0); const bool hasB = m0 + ngw < MTOK;
;                 v4u rawA[8], rawB[8]; ln_fetch_b(WSP(const bf16, WS_XR) + (size_t)mA * DM, rawA, lane); ln_fetch_b(WSP(const bf16, WS_XR) + (size_t)mB * DM, rawB, lane);
;                 { const int m = mA; ln_row_b<true>(rawA, KA_IN(ka, 24) + DM, KA_IN(ka, 25) + DM, xres + (size_t)m * DM, (bf16*)nullptr, lane); }
;                 if (hasB) { const int m = mB; ln_row_b<true>(rawB, KA_IN(ka, 24) + DM, KA_IN(ka, 25) + DM, xres + (size_t)m * DM, (bf16*)nullptr, lane); } }
	v_pk_fma_f32 v[2:3], v[2:3], v[48:49], v[56:57]
	s_waitcnt vmcnt(0)
	v_pk_fma_f32 v[52:53], v[52:53], v[104:105], v[60:61]
	v_pk_fma_f32 v[54:55], v[54:55], v[64:65], v[62:63]
	v_pk_fma_f32 v[4:5], v[4:5], v[50:51], v[58:59]
	global_store_dwordx4 v158, v[52:55], s[16:17]
	global_store_dwordx4 v159, v[2:5], s[16:17]
	v_pk_mul_f32 v[56:57], v[44:45], v[14:15] op_sel_hi:[1,0]
	v_pk_mul_f32 v[58:59], v[46:47], v[14:15] op_sel_hi:[1,0]
	global_load_dwordx4 v[2:5], v[84:85], off offset:16
	global_load_dwordx4 v[44:47], v[84:85], off
	global_load_dwordx4 v[48:51], v[86:87], off offset:16
	global_load_dwordx4 v[52:55], v[86:87], off
	s_waitcnt vmcnt(1)
	v_pk_fma_f32 v[2:3], v[2:3], v[40:41], v[48:49]
	s_waitcnt vmcnt(0)
	v_pk_fma_f32 v[44:45], v[44:45], v[58:59], v[52:53]
	v_pk_fma_f32 v[46:47], v[46:47], v[56:57], v[54:55]
	v_pk_fma_f32 v[4:5], v[4:5], v[42:43], v[50:51]
	global_store_dwordx4 v160, v[44:47], s[16:17]
	global_store_dwordx4 v161, v[2:5], s[16:17]
	v_pk_mul_f32 v[48:49], v[38:39], v[14:15] op_sel_hi:[1,0]
	v_pk_mul_f32 v[50:51], v[36:37], v[14:15] op_sel_hi:[1,0]
	global_load_dwordx4 v[2:5], v[88:89], off offset:16
	global_load_dwordx4 v[36:39], v[88:89], off
	global_load_dwordx4 v[40:43], v[90:91], off offset:16
	global_load_dwordx4 v[44:47], v[90:91], off
	s_waitcnt vmcnt(1)
	v_pk_fma_f32 v[2:3], v[2:3], v[32:33], v[40:41]
	s_waitcnt vmcnt(0)
	v_pk_fma_f32 v[36:37], v[36:37], v[50:51], v[44:45]
	v_pk_fma_f32 v[38:39], v[38:39], v[48:49], v[46:47]
	v_pk_fma_f32 v[4:5], v[4:5], v[34:35], v[42:43]
	global_store_dwordx4 v162, v[36:39], s[16:17]
	global_store_dwordx4 v163, v[2:5], s[16:17]
	v_pk_mul_f32 v[40:41], v[30:31], v[14:15] op_sel_hi:[1,0]
	v_pk_mul_f32 v[42:43], v[28:29], v[14:15] op_sel_hi:[1,0]
	global_load_dwordx4 v[2:5], v[92:93], off offset:16
	global_load_dwordx4 v[28:31], v[92:93], off
	global_load_dwordx4 v[32:35], v[94:95], off offset:16
	global_load_dwordx4 v[36:39], v[94:95], off
	s_waitcnt vmcnt(1)
	v_pk_fma_f32 v[2:3], v[24:25], v[2:3], v[32:33]
	s_waitcnt vmcnt(0)
	v_pk_fma_f32 v[28:29], v[28:29], v[42:43], v[36:37]
	v_pk_fma_f32 v[30:31], v[30:31], v[40:41], v[38:39]
	v_pk_fma_f32 v[4:5], v[26:27], v[4:5], v[34:35]
	global_store_dwordx4 v164, v[28:31], s[16:17]
	global_store_dwordx4 v165, v[2:5], s[16:17]
	v_pk_mul_f32 v[32:33], v[20:21], v[14:15] op_sel_hi:[1,0]
	v_pk_mul_f32 v[34:35], v[22:23], v[14:15] op_sel_hi:[1,0]
	global_load_dwordx4 v[2:5], v[96:97], off offset:16
	global_load_dwordx4 v[20:23], v[96:97], off
	global_load_dwordx4 v[24:27], v[98:99], off offset:16
	global_load_dwordx4 v[28:31], v[98:99], off
	s_waitcnt vmcnt(1)
	v_pk_fma_f32 v[2:3], v[16:17], v[2:3], v[24:25]
	s_waitcnt vmcnt(0)
	v_pk_fma_f32 v[20:21], v[34:35], v[20:21], v[28:29]
	v_pk_fma_f32 v[22:23], v[32:33], v[22:23], v[30:31]
	v_pk_fma_f32 v[4:5], v[18:19], v[4:5], v[26:27]
	global_store_dwordx4 v166, v[20:23], s[16:17]
	global_store_dwordx4 v167, v[2:5], s[16:17]
	v_pk_mul_f32 v[24:25], v[12:13], v[14:15] op_sel_hi:[1,0]
	v_pk_mul_f32 v[26:27], v[10:11], v[14:15] op_sel_hi:[1,0]
	global_load_dwordx4 v[2:5], v[100:101], off offset:16
	global_load_dwordx4 v[10:13], v[100:101], off
	global_load_dwordx4 v[16:19], v[102:103], off offset:16
	global_load_dwordx4 v[20:23], v[102:103], off
	s_waitcnt vmcnt(1)
	v_pk_fma_f32 v[2:3], v[6:7], v[2:3], v[16:17]
	s_waitcnt vmcnt(0)
	v_pk_fma_f32 v[10:11], v[26:27], v[10:11], v[20:21]
	v_pk_fma_f32 v[12:13], v[24:25], v[12:13], v[22:23]
	v_pk_fma_f32 v[4:5], v[8:9], v[4:5], v[18:19]
	global_store_dwordx4 v168, v[10:13], s[16:17]
	global_store_dwordx4 v169, v[2:5], s[16:17]
	s_branch .LBB0_1265

; __device__ __forceinline__ f32x4 h4lo(const u32x4 w) { return (f32x4){hlo(w.x), hhi(w.x), hlo(w.y), hhi(w.y)}; }
; __device__ __forceinline__ f32x4 h4hi(const u32x4 w) { return (f32x4){hlo(w.z), hhi(w.z), hlo(w.w), hhi(w.w)}; }
; #define KA_IN(ka, i) (*(const float* const __attribute__((address_space(4)))*)((ka) + 8 * (i)))
; __device__ __forceinline__ int row_perm(int m) { const int j = m >> 11, r = m & 2047; return (11 - 3 * (j & 3) - (j >> 2)) * 2048 + r; }
; __device__ __forceinline__ void ln_fetch_b(const bf16* src, v4u (&raw)[8], int lane) {
;     const v4u* xr = (const v4u*)src + lane;
; #pragma unroll
;     for (int j = 0; j < 8; ++j) raw[j] = xr[64 * j];
; }
; __device__ __forceinline__ void ln_load_b(const v4u (&raw)[8], f32x4 (&v)[16], float& mean, float& rstd, int lane) {
;     float s = 0.f;
; #pragma unroll
;     for (int j = 0; j < 8; ++j) { const v4u w = raw[j]; v[2 * j] = pg8::h4lo(w); v[2 * j + 1] = pg8::h4hi(w);
;         s += ((v[2 * j].x + v[2 * j].y) + (v[2 * j].z + v[2 * j].w)) + ((v[2 * j + 1].x + v[2 * j + 1].y) + (v[2 * j + 1].z + v[2 * j + 1].w)); }
; __global__ void __launch_bounds__(NT, 2) fwd_kernel(Args args_unused) {
;     ...
;             for (int m0 = gw; m0 < MTOK; m0 += 2 * ngw) { const int mA = row_perm(m0), mB = row_perm(m0 + ngw < MTOK ? m0 + ngw : m0); const bool hasB = m0 + ngw < MTOK;
;                 v4u rawA[8], rawB[8]; ln_fetch_b(WSP(const bf16, WS_XR) + (size_t)mA * DM, rawA, lane); ln_fetch_b(WSP(const bf16, WS_XR) + (size_t)mB * DM, rawB, lane);
;                 { const int m = mA; ln_row_b_in(rawA, KA_IN(ka, 24), KA_IN(ka, 25), WSP(bf16, WS_XB) + (size_t)m * DM, WSP(signed char, WS_XQ) + (size_t)m * DM, WSP(float, WS_ROWINV3) + m, lane); }
.LBB0_1274:
	s_bfe_u32 s7, s47, 0x2000b
	s_mul_i32 s7, s7, 0x1ffffd
	s_ashr_i32 s8, s47, 13
	s_sub_i32 s7, s7, s8
	s_and_b32 s6, s47, 0x7ff
	s_lshl_b32 s7, s7, 11
	s_or_b32 s6, s7, s6
	s_add_i32 s36, s6, 0x5800
	s_add_i32 s8, s3, s47
	s_cmpk_lt_i32 s8, 0x6000
	s_cselect_b64 s[16:17], -1, 0
	s_and_b64 s[6:7], s[16:17], exec
	s_cselect_b32 s6, s8, s47
	s_bfe_u32 s8, s6, 0x2000b
	s_and_b32 s7, s6, 0x7ff
	s_mul_i32 s8, s8, 0x1ffffd
	s_ashr_i32 s6, s6, 13
	s_sub_i32 s6, s8, s6
	s_lshl_b32 s6, s6, 11
	s_or_b32 s6, s6, s7
	s_ashr_i32 s37, s36, 31
	s_add_i32 s8, s6, 0x5800
	s_lshl_b64 s[6:7], s[36:37], 13
	v_lshl_add_u64 v[2:3], v[68:69], 0, s[6:7]
	global_load_dwordx4 v[62:65], v[2:3], off
	global_load_dwordx4 v[58:61], v[2:3], off offset:1024
	global_load_dwordx4 v[54:57], v[2:3], off offset:2048
	global_load_dwordx4 v[50:53], v[2:3], off offset:3072
	v_add_co_u32_e32 v2, vcc, s25, v2
	v_mov_b32_e32 v126, v183
	s_nop 0
	v_addc_co_u32_e32 v3, vcc, 0, v3, vcc
	global_load_dwordx4 v[46:49], v[2:3], off
	global_load_dwordx4 v[42:45], v[2:3], off offset:1024
	global_load_dwordx4 v[38:41], v[2:3], off offset:2048
	global_load_dwordx4 v[34:37], v[2:3], off offset:3072
	s_ashr_i32 s9, s8, 31
	s_lshl_b64 s[30:31], s[8:9], 13
	v_lshl_add_u64 v[2:3], v[68:69], 0, s[30:31]
	global_load_dwordx4 v[30:33], v[2:3], off
	global_load_dwordx4 v[26:29], v[2:3], off offset:1024
	global_load_dwordx4 v[22:25], v[2:3], off offset:2048
	global_load_dwordx4 v[18:21], v[2:3], off offset:3072
	v_add_co_u32_e32 v2, vcc, s25, v2
	s_add_u32 s42, s26, s6
	s_nop 0
	v_addc_co_u32_e32 v3, vcc, 0, v3, vcc
	s_addc_u32 s43, s27, s7
	global_load_dwordx4 v[14:17], v[2:3], off
	global_load_dwordx4 v[10:13], v[2:3], off offset:1024
	global_load_dwordx4 v[6:9], v[2:3], off offset:2048
	s_nop 0
	global_load_dwordx4 v[2:5], v[2:3], off offset:3072
	s_waitcnt vmcnt(0)
	v_cvt_f32_f16_e32 v112, v62
	v_cvt_f32_f16_sdwa v114, v62 dst_sel:DWORD dst_unused:UNUSED_PAD src0_sel:WORD_1
	v_cvt_f32_f16_e32 v116, v63
	v_cvt_f32_f16_sdwa v118, v63 dst_sel:DWORD dst_unused:UNUSED_PAD src0_sel:WORD_1
	v_cvt_f32_f16_e32 v113, v64
	v_cvt_f32_f16_sdwa v115, v64 dst_sel:DWORD dst_unused:UNUSED_PAD src0_sel:WORD_1
	v_cvt_f32_f16_e32 v117, v65
	v_cvt_f32_f16_sdwa v119, v65 dst_sel:DWORD dst_unused:UNUSED_PAD src0_sel:WORD_1
	v_cvt_f32_f16_sdwa v120, v60 dst_sel:DWORD dst_unused:UNUSED_PAD src0_sel:WORD_1
	v_pk_add_f32 v[112:113], v[112:113], v[114:115]
	v_cvt_f32_f16_sdwa v121, v61 dst_sel:DWORD dst_unused:UNUSED_PAD src0_sel:WORD_1
	v_pk_add_f32 v[114:115], v[116:117], v[118:119]
	v_cvt_f32_f16_sdwa v116, v58 dst_sel:DWORD dst_unused:UNUSED_PAD src0_sel:WORD_1
	v_pk_add_f32 v[112:113], v[112:113], v[114:115]
	v_cvt_f32_f16_e32 v114, v58
	v_cvt_f32_f16_e32 v115, v59
	v_cvt_f32_f16_sdwa v117, v59 dst_sel:DWORD dst_unused:UNUSED_PAD src0_sel:WORD_1
	v_cvt_f32_f16_e32 v118, v60
	v_cvt_f32_f16_e32 v119, v61
	v_pk_add_f32 v[112:113], v[112:113], v[112:113] op_sel:[0,1] op_sel_hi:[1,0]
	v_pk_add_f32 v[114:115], v[114:115], v[116:117]
	v_cvt_f32_f16_e32 v113, v54
	v_pk_add_f32 v[116:117], v[118:119], v[120:121]
	v_pk_add_f32 v[114:115], v[114:115], v[114:115] op_sel:[0,1] op_sel_hi:[1,0]
	v_pk_add_f32 v[116:117], v[116:117], v[116:117] op_sel:[0,1] op_sel_hi:[1,0]
	v_cvt_f32_f16_sdwa v115, v54 dst_sel:DWORD dst_unused:UNUSED_PAD src0_sel:WORD_1
	v_cvt_f32_f16_e32 v117, v55
	v_cvt_f32_f16_sdwa v119, v55 dst_sel:DWORD dst_unused:UNUSED_PAD src0_sel:WORD_1
	v_cvt_f32_f16_e32 v120, v56
	v_cvt_f32_f16_sdwa v121, v56 dst_sel:DWORD dst_unused:UNUSED_PAD src0_sel:WORD_1
	v_cvt_f32_f16_e32 v123, v57
	v_cvt_f32_f16_sdwa v124, v57 dst_sel:DWORD dst_unused:UNUSED_PAD src0_sel:WORD_1
	v_add_f32_e32 v118, v115, v113
	v_add_f32_e32 v122, v119, v117
	v_cvt_f32_f16_e32 v113, v50
	v_cvt_f32_f16_sdwa v127, v50 dst_sel:DWORD dst_unused:UNUSED_PAD src0_sel:WORD_1
	v_cvt_f32_f16_e32 v115, v51
	v_cvt_f32_f16_sdwa v117, v51 dst_sel:DWORD dst_unused:UNUSED_PAD src0_sel:WORD_1
	v_add_f32_e32 v120, v121, v120
	v_add_f32_e32 v124, v124, v123
	v_cvt_f32_f16_e32 v119, v52
	v_cvt_f32_f16_sdwa v123, v52 dst_sel:DWORD dst_unused:UNUSED_PAD src0_sel:WORD_1
	v_cvt_f32_f16_e32 v121, v53
	v_cvt_f32_f16_sdwa v125, v53 dst_sel:DWORD dst_unused:UNUSED_PAD src0_sel:WORD_1
	v_pk_add_f32 v[112:113], v[112:113], v[126:127]
	v_pk_add_f32 v[114:115], v[114:115], v[116:117]
	v_cvt_f32_f16_sdwa v126, v41 dst_sel:DWORD dst_unused:UNUSED_PAD src0_sel:WORD_1
	v_pk_add_f32 v[112:113], v[112:113], v[114:115]
	v_pk_add_f32 v[114:115], v[118:119], v[122:123]
	v_pk_add_f32 v[116:117], v[120:121], v[124:125]
	v_cvt_f32_f16_e32 v118, v47
	v_pk_add_f32 v[114:115], v[114:115], v[116:117]
	v_cvt_f32_f16_sdwa v116, v46 dst_sel:DWORD dst_unused:UNUSED_PAD src0_sel:WORD_1
	v_pk_add_f32 v[112:113], v[112:113], v[114:115]
	v_cvt_f32_f16_e32 v114, v46
	v_cvt_f32_f16_sdwa v120, v47 dst_sel:DWORD dst_unused:UNUSED_PAD src0_sel:WORD_1
	v_cvt_f32_f16_e32 v115, v48
	v_cvt_f32_f16_sdwa v117, v48 dst_sel:DWORD dst_unused:UNUSED_PAD src0_sel:WORD_1
	v_cvt_f32_f16_e32 v119, v49
	v_cvt_f32_f16_sdwa v121, v49 dst_sel:DWORD dst_unused:UNUSED_PAD src0_sel:WORD_1
	v_cvt_f32_f16_sdwa v122, v44 dst_sel:DWORD dst_unused:UNUSED_PAD src0_sel:WORD_1
	v_pk_add_f32 v[114:115], v[114:115], v[116:117]
	v_cvt_f32_f16_sdwa v123, v45 dst_sel:DWORD dst_unused:UNUSED_PAD src0_sel:WORD_1
	v_pk_add_f32 v[116:117], v[118:119], v[120:121]
	v_cvt_f32_f16_sdwa v118, v42 dst_sel:DWORD dst_unused:UNUSED_PAD src0_sel:WORD_1
	v_pk_add_f32 v[114:115], v[114:115], v[116:117]
	v_cvt_f32_f16_e32 v116, v42
	v_cvt_f32_f16_e32 v117, v43
	v_cvt_f32_f16_sdwa v119, v43 dst_sel:DWORD dst_unused:UNUSED_PAD src0_sel:WORD_1
; __device__ __forceinline__ f32x4 h4lo(const u32x4 w) { return (f32x4){hlo(w.x), hhi(w.x), hlo(w.y), hhi(w.y)}; }
; __device__ __forceinline__ f32x4 h4hi(const u32x4 w) { return (f32x4){hlo(w.z), hhi(w.z), hlo(w.w), hhi(w.w)}; }
; __device__ __forceinline__ float wave_sum(float v) {
; #pragma unroll
;     for (int o = 1; o < 64; o <<= 1) v += __shfl_xor(v, o);
;     return v;
; }
; __device__ __forceinline__ void ln_load_b(const v4u (&raw)[8], f32x4 (&v)[16], float& mean, float& rstd, int lane) {
;     float s = 0.f;
; #pragma unroll
;     for (int j = 0; j < 8; ++j) { const v4u w = raw[j]; v[2 * j] = pg8::h4lo(w); v[2 * j + 1] = pg8::h4hi(w);
;         s += ((v[2 * j].x + v[2 * j].y) + (v[2 * j].z + v[2 * j].w)) + ((v[2 * j + 1].x + v[2 * j + 1].y) + (v[2 * j + 1].z + v[2 * j + 1].w)); }
;     mean = wave_sum(s) * (1.f / 4096.f); float s2 = 0.f;
; #pragma unroll
;     for (int j = 0; j < 16; ++j) { v[j] = v[j] - mean; s2 += (v[j].x * v[j].x + v[j].y * v[j].y) + (v[j].z * v[j].z + v[j].w * v[j].w); }
	v_cvt_f32_f16_e32 v120, v44
	v_cvt_f32_f16_e32 v121, v45
	v_pk_add_f32 v[112:113], v[112:113], v[112:113] op_sel:[0,1] op_sel_hi:[1,0]
	v_pk_add_f32 v[116:117], v[116:117], v[118:119]
	v_pk_add_f32 v[114:115], v[114:115], v[114:115] op_sel:[0,1] op_sel_hi:[1,0]
	v_pk_add_f32 v[118:119], v[120:121], v[122:123]
	v_pk_add_f32 v[116:117], v[116:117], v[116:117] op_sel:[0,1] op_sel_hi:[1,0]
	v_pk_add_f32 v[118:119], v[118:119], v[118:119] op_sel:[0,1] op_sel_hi:[1,0]
	v_cvt_f32_f16_e32 v113, v38
	v_cvt_f32_f16_sdwa v115, v38 dst_sel:DWORD dst_unused:UNUSED_PAD src0_sel:WORD_1
	v_cvt_f32_f16_e32 v117, v39
	v_cvt_f32_f16_sdwa v119, v39 dst_sel:DWORD dst_unused:UNUSED_PAD src0_sel:WORD_1
	v_cvt_f32_f16_e32 v121, v40
	v_cvt_f32_f16_sdwa v123, v40 dst_sel:DWORD dst_unused:UNUSED_PAD src0_sel:WORD_1
	v_cvt_f32_f16_e32 v125, v41
	v_add_f32_e32 v120, v115, v113
	v_add_f32_e32 v122, v119, v117
	v_cvt_f32_f16_e32 v113, v34
	v_cvt_f32_f16_sdwa v115, v34 dst_sel:DWORD dst_unused:UNUSED_PAD src0_sel:WORD_1
	v_cvt_f32_f16_e32 v117, v35
	v_cvt_f32_f16_sdwa v119, v35 dst_sel:DWORD dst_unused:UNUSED_PAD src0_sel:WORD_1
	v_add_f32_e32 v124, v123, v121
	v_add_f32_e32 v126, v126, v125
	v_cvt_f32_f16_e32 v121, v36
	v_cvt_f32_f16_sdwa v123, v36 dst_sel:DWORD dst_unused:UNUSED_PAD src0_sel:WORD_1
	v_cvt_f32_f16_e32 v125, v37
	v_cvt_f32_f16_sdwa v127, v37 dst_sel:DWORD dst_unused:UNUSED_PAD src0_sel:WORD_1
	v_pk_add_f32 v[112:113], v[112:113], v[114:115]
	v_pk_add_f32 v[114:115], v[116:117], v[118:119]
	v_pk_add_f32 v[116:117], v[124:125], v[126:127]
	v_pk_add_f32 v[112:113], v[112:113], v[114:115]
	v_pk_add_f32 v[114:115], v[120:121], v[122:123]
	s_nop 0
	v_pk_add_f32 v[114:115], v[114:115], v[116:117]
	s_nop 0
	v_pk_add_f32 v[112:113], v[112:113], v[114:115]
	s_nop 0
	v_add_f32_e32 v112, v112, v113
	s_nop 1
	v_mov_b32_dpp v113, v112 quad_perm:[1,0,3,2] row_mask:0xf bank_mask:0xf
	s_waitcnt lgkmcnt(0)
	v_add_f32_e32 v112, v112, v113
	s_nop 1
	v_mov_b32_dpp v113, v112 quad_perm:[2,3,0,1] row_mask:0xf bank_mask:0xf
	s_waitcnt lgkmcnt(0)
	v_add_f32_e32 v112, v112, v113
	s_nop 1
	v_mov_b32_dpp v113, v112 row_half_mirror row_mask:0xf bank_mask:0xf
	s_waitcnt lgkmcnt(0)
	v_add_f32_e32 v112, v112, v113
	s_nop 1
	v_mov_b32_dpp v113, v112 row_mirror row_mask:0xf bank_mask:0xf
	s_waitcnt lgkmcnt(0)
	v_add_f32_e32 v112, v112, v113
	v_mov_b32_e32 v113, v112
	s_nop 1
	v_permlane16_swap_b32_e32 v113, v112
	s_waitcnt lgkmcnt(0)
	v_add_f32_e32 v112, v112, v113
	v_mov_b32_e32 v113, v112
	s_nop 1
	v_permlane32_swap_b32_e32 v113, v112
	s_waitcnt lgkmcnt(0)
	v_add_f32_e32 v159, v112, v113
	v_fma_mix_f32 v155, v159, s87, v62 op_sel:[0,0,1] op_sel_hi:[0,0,1]
	v_fma_mix_f32 v154, v159, s87, v62 op_sel_hi:[0,0,1]
	v_fma_mix_f32 v157, v159, s87, v63 op_sel:[0,0,1] op_sel_hi:[0,0,1]
	v_fma_mix_f32 v156, v159, s87, v63 op_sel_hi:[0,0,1]
	v_pk_mul_f32 v[62:63], v[156:157], v[156:157]
	v_pk_mul_f32 v[112:113], v[154:155], v[154:155]
	v_fma_mix_f32 v153, v159, s87, v65 op_sel:[0,0,1] op_sel_hi:[0,0,1]
	v_pk_mov_b32 v[114:115], v[112:113], v[62:63] op_sel:[1,0]
	v_mov_b32_e32 v113, v63
	v_pk_add_f32 v[62:63], v[114:115], v[112:113]
	v_fma_mix_f32 v113, v159, s87, v64 op_sel:[0,0,1] op_sel_hi:[0,0,1]
	v_fma_mix_f32 v112, v159, s87, v64 op_sel_hi:[0,0,1]
	v_fma_mix_f32 v152, v159, s87, v65 op_sel_hi:[0,0,1]
	v_fma_mix_f32 v148, v159, s87, v58 op_sel_hi:[0,0,1]
	v_pk_mul_f32 v[64:65], v[152:153], v[152:153]
	v_pk_mul_f32 v[114:115], v[112:113], v[112:113]
	v_fma_mix_f32 v149, v159, s87, v58 op_sel:[0,0,1] op_sel_hi:[0,0,1]
	v_mul_f32_e32 v58, v148, v148
	v_pk_mov_b32 v[116:117], v[114:115], v[64:65] op_sel:[1,0]
	v_mov_b32_e32 v115, v65
	v_fma_mix_f32 v151, v159, s87, v59 op_sel:[0,0,1] op_sel_hi:[0,0,1]
	v_fma_mix_f32 v150, v159, s87, v59 op_sel_hi:[0,0,1]
	v_pk_fma_f32 v[58:59], v[148:149], v[148:149], v[58:59] op_sel_hi:[1,1,0]
	v_pk_add_f32 v[64:65], v[116:117], v[114:115]
	v_mul_f32_e32 v58, v150, v150
	v_pk_add_f32 v[62:63], v[62:63], v[62:63] op_sel_hi:[0,1]
	v_pk_add_f32 v[114:115], v[64:65], v[64:65] op_sel_hi:[0,1]
	v_pk_fma_f32 v[116:117], v[150:151], v[150:151], v[58:59] op_sel_hi:[1,1,0]
	v_fma_mix_f32 v65, v159, s87, v61 op_sel:[0,0,1] op_sel_hi:[0,0,1]
	v_fma_mix_f32 v64, v159, s87, v61 op_sel_hi:[0,0,1]
	v_fma_mix_f32 v127, v159, s87, v60 op_sel:[0,0,1] op_sel_hi:[0,0,1]
	v_fma_mix_f32 v126, v159, s87, v60 op_sel_hi:[0,0,1]
	v_mul_f32_e32 v58, v126, v126
	v_mul_f32_e32 v116, v127, v127
	v_mul_f32_e32 v62, v64, v64
	v_mul_f32_e32 v114, v65, v65
	v_pk_add_f32 v[58:59], v[58:59], v[116:117]
	v_pk_add_f32 v[60:61], v[62:63], v[114:115]
	v_fma_mix_f32 v119, v159, s87, v54 op_sel:[0,0,1] op_sel_hi:[0,0,1]
	v_fma_mix_f32 v118, v159, s87, v54 op_sel_hi:[0,0,1]
	v_fma_mix_f32 v147, v159, s87, v55 op_sel:[0,0,1] op_sel_hi:[0,0,1]
	v_fma_mix_f32 v146, v159, s87, v55 op_sel_hi:[0,0,1]
	v_pk_add_f32 v[58:59], v[58:59], v[60:61]
	v_pk_mul_f32 v[54:55], v[146:147], v[146:147]
	v_pk_mul_f32 v[60:61], v[118:119], v[118:119]
	v_fma_mix_f32 v128, v159, s87, v56 op_sel_hi:[0,0,1]
	v_pk_mov_b32 v[62:63], v[60:61], v[54:55] op_sel:[1,0]
	v_mov_b32_e32 v61, v55
	v_pk_add_f32 v[54:55], v[62:63], v[60:61]
	v_fma_mix_f32 v129, v159, s87, v56 op_sel:[0,0,1] op_sel_hi:[0,0,1]
	v_pk_add_f32 v[54:55], v[54:55], v[54:55] op_sel_hi:[0,1]
	v_fma_mix_f32 v124, v159, s87, v57 op_sel_hi:[0,0,1]
	v_mul_f32_e32 v54, v128, v128
	v_fma_mix_f32 v125, v159, s87, v57 op_sel:[0,0,1] op_sel_hi:[0,0,1]
	v_pk_fma_f32 v[56:57], v[128:129], v[128:129], v[54:55] op_sel_hi:[1,1,0]
	v_mul_f32_e32 v54, v124, v124
	v_pk_add_f32 v[58:59], v[58:59], v[58:59] op_sel_hi:[0,1]
	v_pk_fma_f32 v[60:61], v[124:125], v[124:125], v[54:55] op_sel_hi:[1,1,0]
; __device__ __forceinline__ float wave_sum(float v) {
; #pragma unroll
;     for (int o = 1; o < 64; o <<= 1) v += __shfl_xor(v, o);
;     return v;
; }
; __device__ __forceinline__ void ln_load_b(const v4u (&raw)[8], f32x4 (&v)[16], float& mean, float& rstd, int lane) {
;     ...
;     mean = wave_sum(s) * (1.f / 4096.f); float s2 = 0.f;
; #pragma unroll
;     for (int j = 0; j < 16; ++j) { v[j] = v[j] - mean; s2 += (v[j].x * v[j].x + v[j].y * v[j].y) + (v[j].z * v[j].z + v[j].w * v[j].w); }
;     rstd = 1.f / sqrtf(wave_sum(s2) * (1.f / 4096.f) + 1e-5f);
	v_fma_mix_f32 v131, v159, s87, v51 op_sel:[0,0,1] op_sel_hi:[0,0,1]
	v_fma_mix_f32 v130, v159, s87, v51 op_sel_hi:[0,0,1]
	v_fma_mix_f32 v133, v159, s87, v50 op_sel:[0,0,1] op_sel_hi:[0,0,1]
	v_fma_mix_f32 v132, v159, s87, v50 op_sel_hi:[0,0,1]
	v_mul_f32_e32 v56, v132, v132
	v_mul_f32_e32 v60, v133, v133
	v_mul_f32_e32 v54, v130, v130
	v_mul_f32_e32 v58, v131, v131
	v_pk_add_f32 v[50:51], v[56:57], v[60:61]
	v_pk_add_f32 v[54:55], v[54:55], v[58:59]
	v_fma_mix_f32 v135, v159, s87, v52 op_sel:[0,0,1] op_sel_hi:[0,0,1]
	v_fma_mix_f32 v134, v159, s87, v52 op_sel_hi:[0,0,1]
	v_fma_mix_f32 v139, v159, s87, v53 op_sel:[0,0,1] op_sel_hi:[0,0,1]
	v_fma_mix_f32 v138, v159, s87, v53 op_sel_hi:[0,0,1]
	v_fma_mix_f32 v142, v159, s87, v46 op_sel_hi:[0,0,1]
	v_pk_add_f32 v[50:51], v[50:51], v[54:55]
	v_pk_mul_f32 v[52:53], v[138:139], v[138:139]
	v_pk_mul_f32 v[54:55], v[134:135], v[134:135]
	v_fma_mix_f32 v143, v159, s87, v46 op_sel:[0,0,1] op_sel_hi:[0,0,1]
	v_mul_f32_e32 v46, v142, v142
	v_pk_mov_b32 v[56:57], v[54:55], v[52:53] op_sel:[1,0]
	v_mov_b32_e32 v55, v53
	v_fma_mix_f32 v145, v159, s87, v47 op_sel:[0,0,1] op_sel_hi:[0,0,1]
	v_fma_mix_f32 v144, v159, s87, v47 op_sel_hi:[0,0,1]
	v_pk_fma_f32 v[46:47], v[142:143], v[142:143], v[46:47] op_sel_hi:[1,1,0]
	v_pk_add_f32 v[52:53], v[56:57], v[54:55]
	v_mul_f32_e32 v46, v144, v144
	v_pk_add_f32 v[50:51], v[50:51], v[50:51] op_sel_hi:[0,1]
	v_pk_add_f32 v[52:53], v[52:53], v[52:53] op_sel_hi:[0,1]
	v_pk_fma_f32 v[54:55], v[144:145], v[144:145], v[46:47] op_sel_hi:[1,1,0]
	v_fma_mix_f32 v137, v159, s87, v49 op_sel:[0,0,1] op_sel_hi:[0,0,1]
	v_fma_mix_f32 v136, v159, s87, v49 op_sel_hi:[0,0,1]
	v_fma_mix_f32 v141, v159, s87, v48 op_sel:[0,0,1] op_sel_hi:[0,0,1]
	v_fma_mix_f32 v140, v159, s87, v48 op_sel_hi:[0,0,1]
	v_mul_f32_e32 v46, v140, v140
	v_mul_f32_e32 v54, v141, v141
	v_mul_f32_e32 v52, v136, v136
	v_mul_f32_e32 v50, v137, v137
	v_pk_add_f32 v[46:47], v[46:47], v[54:55]
	v_pk_add_f32 v[48:49], v[52:53], v[50:51]
	v_fma_mix_f32 v121, v159, s87, v42 op_sel:[0,0,1] op_sel_hi:[0,0,1]
	v_fma_mix_f32 v120, v159, s87, v42 op_sel_hi:[0,0,1]
	v_fma_mix_f32 v123, v159, s87, v43 op_sel:[0,0,1] op_sel_hi:[0,0,1]
	v_fma_mix_f32 v122, v159, s87, v43 op_sel_hi:[0,0,1]
	v_pk_add_f32 v[46:47], v[46:47], v[48:49]
	v_pk_mul_f32 v[42:43], v[122:123], v[122:123]
	v_pk_mul_f32 v[48:49], v[120:121], v[120:121]
	v_fma_mix_f32 v114, v159, s87, v44 op_sel_hi:[0,0,1]
	v_pk_mov_b32 v[50:51], v[48:49], v[42:43] op_sel:[1,0]
	v_mov_b32_e32 v49, v43
	v_pk_add_f32 v[42:43], v[50:51], v[48:49]
	v_fma_mix_f32 v115, v159, s87, v44 op_sel:[0,0,1] op_sel_hi:[0,0,1]
	v_pk_add_f32 v[42:43], v[42:43], v[42:43] op_sel_hi:[0,1]
	v_fma_mix_f32 v116, v159, s87, v45 op_sel_hi:[0,0,1]
	v_mul_f32_e32 v42, v114, v114
	v_fma_mix_f32 v117, v159, s87, v45 op_sel:[0,0,1] op_sel_hi:[0,0,1]
	v_pk_fma_f32 v[44:45], v[114:115], v[114:115], v[42:43] op_sel_hi:[1,1,0]
	v_mul_f32_e32 v42, v116, v116
	v_pk_add_f32 v[46:47], v[46:47], v[46:47] op_sel_hi:[0,1]
	v_pk_fma_f32 v[48:49], v[116:117], v[116:117], v[42:43] op_sel_hi:[1,1,0]
	v_fma_mix_f32 v61, v159, s87, v39 op_sel:[0,0,1] op_sel_hi:[0,0,1]
	v_fma_mix_f32 v60, v159, s87, v39 op_sel_hi:[0,0,1]
	v_fma_mix_f32 v63, v159, s87, v38 op_sel:[0,0,1] op_sel_hi:[0,0,1]
	v_fma_mix_f32 v62, v159, s87, v38 op_sel_hi:[0,0,1]
	v_mul_f32_e32 v44, v62, v62
	v_mul_f32_e32 v48, v63, v63
	v_mul_f32_e32 v42, v60, v60
	v_mul_f32_e32 v46, v61, v61
	v_pk_add_f32 v[38:39], v[44:45], v[48:49]
	v_pk_add_f32 v[42:43], v[42:43], v[46:47]
	v_fma_mix_f32 v57, v159, s87, v40 op_sel:[0,0,1] op_sel_hi:[0,0,1]
	v_fma_mix_f32 v56, v159, s87, v40 op_sel_hi:[0,0,1]
	v_fma_mix_f32 v59, v159, s87, v41 op_sel:[0,0,1] op_sel_hi:[0,0,1]
	v_fma_mix_f32 v58, v159, s87, v41 op_sel_hi:[0,0,1]
	v_fma_mix_f32 v50, v159, s87, v34 op_sel_hi:[0,0,1]
	v_pk_add_f32 v[38:39], v[38:39], v[42:43]
	v_pk_mul_f32 v[40:41], v[58:59], v[58:59]
	v_pk_mul_f32 v[42:43], v[56:57], v[56:57]
	v_fma_mix_f32 v51, v159, s87, v34 op_sel:[0,0,1] op_sel_hi:[0,0,1]
	v_mul_f32_e32 v34, v50, v50
	v_pk_mov_b32 v[44:45], v[42:43], v[40:41] op_sel:[1,0]
	v_mov_b32_e32 v43, v41
	v_fma_mix_f32 v53, v159, s87, v35 op_sel:[0,0,1] op_sel_hi:[0,0,1]
	v_fma_mix_f32 v52, v159, s87, v35 op_sel_hi:[0,0,1]
	v_pk_fma_f32 v[34:35], v[50:51], v[50:51], v[34:35] op_sel_hi:[1,1,0]
	v_pk_add_f32 v[40:41], v[44:45], v[42:43]
	v_mul_f32_e32 v34, v52, v52
	v_pk_add_f32 v[38:39], v[38:39], v[38:39] op_sel_hi:[0,1]
	v_pk_add_f32 v[40:41], v[40:41], v[40:41] op_sel_hi:[0,1]
	v_pk_fma_f32 v[42:43], v[52:53], v[52:53], v[34:35] op_sel_hi:[1,1,0]
	v_fma_mix_f32 v47, v159, s87, v37 op_sel:[0,0,1] op_sel_hi:[0,0,1]
	v_fma_mix_f32 v46, v159, s87, v37 op_sel_hi:[0,0,1]
	v_fma_mix_f32 v49, v159, s87, v36 op_sel:[0,0,1] op_sel_hi:[0,0,1]
	v_fma_mix_f32 v48, v159, s87, v36 op_sel_hi:[0,0,1]
	v_mul_f32_e32 v34, v48, v48
	v_mul_f32_e32 v42, v49, v49
	v_mul_f32_e32 v40, v46, v46
	v_mul_f32_e32 v38, v47, v47
	v_pk_add_f32 v[34:35], v[34:35], v[42:43]
	v_pk_add_f32 v[36:37], v[40:41], v[38:39]
	s_nop 0
	v_pk_add_f32 v[34:35], v[34:35], v[36:37]
	s_nop 0
	v_add_f32_e32 v34, v34, v35
	s_nop 1
	v_mov_b32_dpp v35, v34 quad_perm:[1,0,3,2] row_mask:0xf bank_mask:0xf
	s_waitcnt lgkmcnt(0)
	v_add_f32_e32 v34, v34, v35
	s_nop 1
	v_mov_b32_dpp v35, v34 quad_perm:[2,3,0,1] row_mask:0xf bank_mask:0xf
	s_waitcnt lgkmcnt(0)
	v_add_f32_e32 v34, v34, v35
	s_nop 1
	v_mov_b32_dpp v35, v34 row_half_mirror row_mask:0xf bank_mask:0xf
	s_waitcnt lgkmcnt(0)
	v_add_f32_e32 v34, v34, v35
	s_nop 1
	v_mov_b32_dpp v35, v34 row_mirror row_mask:0xf bank_mask:0xf
	s_waitcnt lgkmcnt(0)
; __device__ __forceinline__ unsigned pkh(float a, float b) { const f2v_t f = {a, b}; const h2v_t h = __builtin_convertvector(f, h2v_t); return __builtin_bit_cast(unsigned, h); }
; __device__ __forceinline__ float wave_sum(float v) {
; #pragma unroll
;     for (int o = 1; o < 64; o <<= 1) v += __shfl_xor(v, o);
;     return v;
; }
; __device__ __forceinline__ void ln_load_b(const v4u (&raw)[8], f32x4 (&v)[16], float& mean, float& rstd, int lane) {
;     ...
;     rstd = 1.f / sqrtf(wave_sum(s2) * (1.f / 4096.f) + 1e-5f);
; __device__ __forceinline__ void ln_row_b_in(const v4u (&src)[8], const float* g, const float* b, bf16* dstb, signed char* dstq, float* rowinv, int lane) {
;     f32x4 v[16]; float mean, rstd; ln_load_b(src, v, mean, rstd, lane);
; #pragma unroll
;     for (int j = 0; j < 8; ++j) { const int q = 2 * (64 * j + lane);
;         v[2 * j] = v[2 * j] * rstd * ((const f32x4*)g)[q] + ((const f32x4*)b)[q]; v[2 * j + 1] = v[2 * j + 1] * rstd * ((const f32x4*)g)[q + 1] + ((const f32x4*)b)[q + 1];
;         v4u w; w.x = pg8::pkh(v[2 * j].x, v[2 * j].y); w.y = pg8::pkh(v[2 * j].z, v[2 * j].w); w.z = pg8::pkh(v[2 * j + 1].x, v[2 * j + 1].y); w.w = pg8::pkh(v[2 * j + 1].z, v[2 * j + 1].w); ((v4u*)dstb)[64 * j + lane] = w; }
	v_add_f32_e32 v34, v34, v35
	v_mov_b32_e32 v35, v34
	s_nop 1
	v_permlane16_swap_b32_e32 v35, v34
	s_waitcnt lgkmcnt(0)
	v_add_f32_e32 v34, v34, v35
	v_mov_b32_e32 v35, v34
	s_nop 1
	v_permlane32_swap_b32_e32 v35, v34
	s_waitcnt lgkmcnt(0)
	v_add_f32_e32 v34, v34, v35
	v_fmamk_f32 v34, v34, 0x39800000, v216
	v_cmp_gt_f32_e32 vcc, s95, v34
	v_mul_f32_e32 v35, 0x4f800000, v34
	s_nop 0
	v_cndmask_b32_e32 v34, v34, v35, vcc
	v_sqrt_f32_e32 v35, v34
	s_nop 0
	v_add_u32_e32 v36, -1, v35
	v_fma_f32 v37, -v36, v35, v34
	v_cmp_ge_f32_e64 s[6:7], 0, v37
	v_add_u32_e32 v37, 1, v35
	s_nop 0
	v_cndmask_b32_e64 v36, v35, v36, s[6:7]
	v_fma_f32 v35, -v37, v35, v34
	v_cmp_lt_f32_e64 s[6:7], 0, v35
	s_nop 1
	v_cndmask_b32_e64 v35, v36, v37, s[6:7]
	v_mul_f32_e32 v36, 0x37800000, v35
	v_cndmask_b32_e32 v35, v35, v36, vcc
	v_cmp_class_f32_e32 vcc, v34, v215
	s_nop 1
	v_cndmask_b32_e32 v34, v35, v34, vcc
	v_div_scale_f32 v35, s[6:7], v34, v34, 1.0
	v_rcp_f32_e32 v36, v35
	s_nop 0
	v_fma_f32 v37, -v35, v36, 1.0
	v_fmac_f32_e32 v36, v37, v36
	v_div_scale_f32 v37, vcc, 1.0, v34, 1.0
	v_mul_f32_e32 v38, v37, v36
	v_fma_f32 v39, -v35, v38, v37
	v_fmac_f32_e32 v38, v39, v36
	v_fma_f32 v35, -v35, v38, v37
	v_div_fmas_f32 v35, v35, v36, v38
	v_div_fixup_f32 v54, v35, v34, 1.0
	global_load_dwordx4 v[34:37], v[70:71], off offset:16
	global_load_dwordx4 v[42:45], v[70:71], off
	global_load_dwordx4 v[38:41], v[72:73], off offset:16
	global_load_dwordx4 v[160:163], v[72:73], off
	v_pk_mul_f32 v[154:155], v[154:155], v[54:55] op_sel_hi:[1,0]
	v_pk_mul_f32 v[156:157], v[156:157], v[54:55] op_sel_hi:[1,0]
	v_pk_mul_f32 v[112:113], v[112:113], v[54:55] op_sel_hi:[1,0]
	v_pk_mul_f32 v[152:153], v[152:153], v[54:55] op_sel_hi:[1,0]
	v_pk_mul_f32 v[164:165], v[150:151], v[54:55] op_sel_hi:[1,0]
	v_pk_mul_f32 v[126:127], v[126:127], v[54:55] op_sel_hi:[1,0]
	v_pk_mul_f32 v[128:129], v[128:129], v[54:55] op_sel_hi:[1,0]
	v_pk_mul_f32 v[124:125], v[124:125], v[54:55] op_sel_hi:[1,0]
	v_pk_mul_f32 v[132:133], v[132:133], v[54:55] op_sel_hi:[1,0]
	v_pk_mul_f32 v[130:131], v[130:131], v[54:55] op_sel_hi:[1,0]
	v_pk_mul_f32 v[140:141], v[140:141], v[54:55] op_sel_hi:[1,0]
	v_pk_mul_f32 v[136:137], v[136:137], v[54:55] op_sel_hi:[1,0]
	v_pk_mul_f32 v[168:169], v[120:121], v[54:55] op_sel_hi:[1,0]
	v_pk_mul_f32 v[120:121], v[122:123], v[54:55] op_sel_hi:[1,0]
	v_pk_mul_f32 v[62:63], v[62:63], v[54:55] op_sel_hi:[1,0]
	v_pk_mul_f32 v[60:61], v[60:61], v[54:55] op_sel_hi:[1,0]
	v_pk_mul_f32 v[48:49], v[48:49], v[54:55] op_sel_hi:[1,0]
	v_pk_mul_f32 v[46:47], v[46:47], v[54:55] op_sel_hi:[1,0]
	s_waitcnt vmcnt(1)
	v_pk_fma_f32 v[36:37], v[36:37], v[152:153], v[40:41]
	s_waitcnt vmcnt(0)
	v_pk_fma_f32 v[44:45], v[44:45], v[156:157], v[162:163]
	v_pk_fma_f32 v[42:43], v[42:43], v[154:155], v[160:161]
	v_pk_fma_f32 v[34:35], v[34:35], v[112:113], v[38:39]
	v_cvt_pk_f16_f32 v38, v42, v43
	v_cvt_pk_f16_f32 v39, v44, v45
	v_cvt_pk_f16_f32 v40, v34, v35
	v_cvt_pk_f16_f32 v41, v36, v37
	v_lshlrev_b32_e32 v152, 4, v66
	global_store_dwordx4 v152, v[38:41], s[42:43]
	v_pk_mul_f32 v[112:113], v[148:149], v[54:55] op_sel_hi:[1,0]
	global_load_dwordx4 v[148:151], v[74:75], off offset:16
	global_load_dwordx4 v[38:41], v[74:75], off
	global_load_dwordx4 v[154:157], v[76:77], off offset:16
	global_load_dwordx4 v[160:163], v[76:77], off
	s_waitcnt vmcnt(0)
	v_pk_fma_f32 v[112:113], v[38:39], v[112:113], v[160:161]
	v_pk_mul_f32 v[38:39], v[64:65], v[54:55] op_sel_hi:[1,0]
	v_pk_fma_f32 v[40:41], v[40:41], v[164:165], v[162:163]
	v_pk_fma_f32 v[38:39], v[150:151], v[38:39], v[156:157]
	v_pk_fma_f32 v[64:65], v[148:149], v[126:127], v[154:155]
	v_cvt_pk_f16_f32 v148, v112, v113
	v_cvt_pk_f16_f32 v149, v40, v41
	v_cvt_pk_f16_f32 v150, v64, v65
	v_cvt_pk_f16_f32 v151, v38, v39
	global_store_dwordx4 v152, v[148:151], s[42:43] offset:1024
	v_pk_mul_f32 v[126:127], v[118:119], v[54:55] op_sel_hi:[1,0]
	v_pk_mul_f32 v[118:119], v[146:147], v[54:55] op_sel_hi:[1,0]
	global_load_dwordx4 v[146:149], v[78:79], off offset:16
	global_load_dwordx4 v[154:157], v[78:79], off
	global_load_dwordx4 v[160:163], v[80:81], off offset:16
	global_load_dwordx4 v[164:167], v[80:81], off
	v_pk_mul_f32 v[150:151], v[134:135], v[54:55] op_sel_hi:[1,0]
	v_pk_mul_f32 v[134:135], v[138:139], v[54:55] op_sel_hi:[1,0]
	s_waitcnt vmcnt(1)
	v_pk_fma_f32 v[124:125], v[148:149], v[124:125], v[162:163]
	s_waitcnt vmcnt(0)
	v_pk_fma_f32 v[118:119], v[156:157], v[118:119], v[166:167]
	v_pk_fma_f32 v[126:127], v[154:155], v[126:127], v[164:165]
	v_pk_fma_f32 v[128:129], v[146:147], v[128:129], v[160:161]
	v_cvt_pk_f16_f32 v146, v126, v127
	v_cvt_pk_f16_f32 v147, v118, v119
	v_cvt_pk_f16_f32 v148, v128, v129
	v_cvt_pk_f16_f32 v149, v124, v125
	global_store_dwordx4 v152, v[146:149], s[42:43] offset:2048
	global_load_dwordx4 v[146:149], v[82:83], off offset:16
	s_nop 0
	global_load_dwordx4 v[154:157], v[82:83], off
	global_load_dwordx4 v[160:163], v[84:85], off offset:16
	global_load_dwordx4 v[164:167], v[84:85], off
	s_waitcnt vmcnt(1)
	v_pk_fma_f32 v[134:135], v[148:149], v[134:135], v[162:163]
	s_waitcnt vmcnt(0)
	v_pk_fma_f32 v[130:131], v[156:157], v[130:131], v[166:167]
	v_pk_fma_f32 v[132:133], v[154:155], v[132:133], v[164:165]
	v_pk_fma_f32 v[138:139], v[146:147], v[150:151], v[160:161]
	v_cvt_pk_f16_f32 v146, v132, v133
	v_cvt_pk_f16_f32 v147, v130, v131
	v_cvt_pk_f16_f32 v148, v138, v139
	v_cvt_pk_f16_f32 v149, v134, v135
	global_store_dwordx4 v152, v[146:149], s[42:43] offset:3072
	global_load_dwordx4 v[146:149], v[88:89], off offset:16
	s_nop 0
	global_load_dwordx4 v[154:157], v[88:89], off
	global_load_dwordx4 v[160:163], v[90:91], off offset:16
	global_load_dwordx4 v[164:167], v[90:91], off
	v_pk_mul_f32 v[150:151], v[142:143], v[54:55] op_sel_hi:[1,0]
	v_pk_mul_f32 v[142:143], v[144:145], v[54:55] op_sel_hi:[1,0]
	s_waitcnt vmcnt(1)
; __device__ __forceinline__ unsigned pkh(float a, float b) { const f2v_t f = {a, b}; const h2v_t h = __builtin_convertvector(f, h2v_t); return __builtin_bit_cast(unsigned, h); }
; template <bool PAIR> __device__ __forceinline__ void row_quant(const f32x4 (&v)[16], signed char* dstq, float* rowinv, int lane) {
;     float mx = 0.f;
; #pragma unroll
;     for (int j = 0; j < 16; ++j) mx = fmaxf(fmaxf(mx, fmaxf(fabsf(v[j].x), fabsf(v[j].y))), fmaxf(fabsf(v[j].z), fabsf(v[j].w)));
; #pragma unroll
;     for (int o = 1; o < 64; o <<= 1) mx = fmaxf(mx, __shfl_xor(mx, o));
;     mx = fmaxf(mx, 1e-20f);
;     const float sc = 127.0f / mx;
;     if (lane == 0) *rowinv = mx * (1.0f / 127.0f);
; __device__ __forceinline__ void ln_row_b_in(const v4u (&src)[8], const float* g, const float* b, bf16* dstb, signed char* dstq, float* rowinv, int lane) {
;     ...
;     for (int j = 0; j < 8; ++j) { const int q = 2 * (64 * j + lane);
;         v[2 * j] = v[2 * j] * rstd * ((const f32x4*)g)[q] + ((const f32x4*)b)[q]; v[2 * j + 1] = v[2 * j + 1] * rstd * ((const f32x4*)g)[q + 1] + ((const f32x4*)b)[q + 1];
;         v4u w; w.x = pg8::pkh(v[2 * j].x, v[2 * j].y); w.y = pg8::pkh(v[2 * j].z, v[2 * j].w); w.z = pg8::pkh(v[2 * j + 1].x, v[2 * j + 1].y); w.w = pg8::pkh(v[2 * j + 1].z, v[2 * j + 1].w); ((v4u*)dstb)[64 * j + lane] = w; }
	v_pk_fma_f32 v[136:137], v[148:149], v[136:137], v[162:163]
	s_waitcnt vmcnt(0)
	v_pk_fma_f32 v[142:143], v[156:157], v[142:143], v[166:167]
	v_pk_fma_f32 v[144:145], v[154:155], v[150:151], v[164:165]
	v_pk_fma_f32 v[140:141], v[146:147], v[140:141], v[160:161]
	v_cvt_pk_f16_f32 v148, v144, v145
	v_cvt_pk_f16_f32 v149, v142, v143
	v_cvt_pk_f16_f32 v150, v140, v141
	v_cvt_pk_f16_f32 v151, v136, v137
	v_lshlrev_b32_e32 v146, 4, v86
	global_store_dwordx4 v146, v[148:151], s[42:43]
	global_load_dwordx4 v[148:151], v[94:95], off offset:16
	s_nop 0
	global_load_dwordx4 v[154:157], v[94:95], off
	global_load_dwordx4 v[160:163], v[96:97], off offset:16
	global_load_dwordx4 v[164:167], v[96:97], off
	v_lshlrev_b32_e32 v147, 4, v92
	s_waitcnt vmcnt(0)
	v_pk_fma_f32 v[122:123], v[154:155], v[168:169], v[164:165]
	v_pk_mul_f32 v[154:155], v[114:115], v[54:55] op_sel_hi:[1,0]
	v_pk_mul_f32 v[114:115], v[116:117], v[54:55] op_sel_hi:[1,0]
	v_pk_fma_f32 v[120:121], v[156:157], v[120:121], v[166:167]
	v_pk_fma_f32 v[114:115], v[150:151], v[114:115], v[162:163]
	v_pk_fma_f32 v[116:117], v[148:149], v[154:155], v[160:161]
	v_cvt_pk_f16_f32 v148, v122, v123
	v_cvt_pk_f16_f32 v149, v120, v121
	v_cvt_pk_f16_f32 v150, v116, v117
	v_cvt_pk_f16_f32 v151, v114, v115
	global_store_dwordx4 v147, v[148:151], s[42:43]
	global_load_dwordx4 v[148:151], v[100:101], off offset:16
	s_nop 0
	global_load_dwordx4 v[154:157], v[100:101], off
	global_load_dwordx4 v[160:163], v[102:103], off offset:16
	global_load_dwordx4 v[164:167], v[102:103], off
	s_waitcnt vmcnt(0)
	v_pk_fma_f32 v[62:63], v[154:155], v[62:63], v[164:165]
	v_pk_mul_f32 v[154:155], v[56:57], v[54:55] op_sel_hi:[1,0]
	v_pk_mul_f32 v[56:57], v[58:59], v[54:55] op_sel_hi:[1,0]
	v_pk_fma_f32 v[60:61], v[156:157], v[60:61], v[166:167]
	v_pk_fma_f32 v[56:57], v[56:57], v[150:151], v[162:163]
	v_pk_fma_f32 v[58:59], v[154:155], v[148:149], v[160:161]
	v_cvt_pk_f16_f32 v154, v62, v63
	v_cvt_pk_f16_f32 v155, v60, v61
	v_cvt_pk_f16_f32 v156, v58, v59
	v_cvt_pk_f16_f32 v157, v56, v57
	v_lshlrev_b32_e32 v148, 4, v98
	global_store_dwordx4 v148, v[154:157], s[42:43]
	global_load_dwordx4 v[154:157], v[106:107], off offset:16
	s_nop 0
	global_load_dwordx4 v[160:163], v[106:107], off
	global_load_dwordx4 v[164:167], v[108:109], off offset:16
	global_load_dwordx4 v[168:171], v[108:109], off
	v_pk_mul_f32 v[150:151], v[50:51], v[54:55] op_sel_hi:[1,0]
	v_pk_mul_f32 v[50:51], v[52:53], v[54:55] op_sel_hi:[1,0]
	v_max_f32_e64 v54, |v42|, |v43|
	v_max_f32_e64 v55, |v44|, |v45|
	v_max3_f32 v54, v54, 0, v55
	v_max_f32_e64 v55, |v34|, |v35|
	v_lshlrev_b32_e32 v149, 4, v104
	s_waitcnt vmcnt(1)
	v_pk_fma_f32 v[46:47], v[46:47], v[156:157], v[166:167]
	s_waitcnt vmcnt(0)
	v_pk_fma_f32 v[52:53], v[150:151], v[160:161], v[168:169]
	v_max_f32_e64 v150, |v36|, |v37|
	v_max3_f32 v54, v54, v55, v150
	v_max_f32_e64 v55, |v112|, |v113|
	v_max_f32_e64 v150, |v40|, |v41|
	v_max3_f32 v54, v54, v55, v150
	v_max_f32_e64 v55, |v64|, |v65|
	v_max_f32_e64 v150, |v38|, |v39|
	v_max3_f32 v54, v54, v55, v150
	v_max_f32_e64 v55, |v126|, |v127|
	v_max_f32_e64 v150, |v118|, |v119|
	v_max3_f32 v54, v54, v55, v150
	v_max_f32_e64 v55, |v128|, |v129|
	v_max_f32_e64 v150, |v124|, |v125|
	v_max3_f32 v54, v54, v55, v150
	v_max_f32_e64 v55, |v132|, |v133|
	v_max_f32_e64 v150, |v130|, |v131|
	v_max3_f32 v54, v54, v55, v150
	v_max_f32_e64 v55, |v138|, |v139|
	v_max_f32_e64 v150, |v134|, |v135|
	v_max3_f32 v54, v54, v55, v150
	v_max_f32_e64 v55, |v144|, |v145|
	v_max_f32_e64 v150, |v142|, |v143|
	v_max3_f32 v54, v54, v55, v150
	v_max_f32_e64 v55, |v140|, |v141|
	v_max_f32_e64 v150, |v136|, |v137|
	v_max3_f32 v54, v54, v55, v150
	v_max_f32_e64 v55, |v122|, |v123|
	v_max_f32_e64 v150, |v120|, |v121|
	v_max3_f32 v54, v54, v55, v150
	v_max_f32_e64 v55, |v116|, |v117|
	v_max_f32_e64 v150, |v114|, |v115|
	v_max3_f32 v54, v54, v55, v150
	v_max_f32_e64 v55, |v62|, |v63|
	v_max_f32_e64 v150, |v60|, |v61|
	v_pk_fma_f32 v[50:51], v[50:51], v[162:163], v[170:171]
	v_max3_f32 v54, v54, v55, v150
	v_max_f32_e64 v55, |v58|, |v59|
	v_max_f32_e64 v150, |v56|, |v57|
	v_pk_fma_f32 v[48:49], v[48:49], v[154:155], v[164:165]
	v_max3_f32 v54, v54, v55, v150
	v_max_f32_e64 v55, |v52|, |v53|
	v_max_f32_e64 v150, |v50|, |v51|
	v_max3_f32 v54, v54, v55, v150
	v_max_f32_e64 v55, |v48|, |v49|
	v_max_f32_e64 v150, |v46|, |v47|
	v_max3_f32 v54, v54, v55, v150
	s_nop 1
	v_mov_b32_dpp v55, v54 quad_perm:[1,0,3,2] row_mask:0xf bank_mask:0xf
	v_cvt_pk_f16_f32 v154, v52, v53
	v_cvt_pk_f16_f32 v155, v50, v51
	v_cvt_pk_f16_f32 v156, v48, v49
	v_cvt_pk_f16_f32 v157, v46, v47
	s_waitcnt lgkmcnt(0)
	v_max_f32_e32 v55, v55, v55
	v_max_f32_e32 v54, v54, v55
	s_nop 1
	v_mov_b32_dpp v55, v54 quad_perm:[2,3,0,1] row_mask:0xf bank_mask:0xf
	global_store_dwordx4 v149, v[154:157], s[42:43]
	s_waitcnt lgkmcnt(0)
	v_max_f32_e32 v55, v55, v55
	v_max_f32_e32 v54, v54, v55
	s_nop 1
	v_mov_b32_dpp v55, v54 row_half_mirror row_mask:0xf bank_mask:0xf
	s_waitcnt lgkmcnt(0)
	v_max_f32_e32 v55, v55, v55
	v_max_f32_e32 v54, v54, v55
	s_nop 1
	v_mov_b32_dpp v55, v54 row_mirror row_mask:0xf bank_mask:0xf
	s_waitcnt lgkmcnt(0)
	v_max_f32_e32 v55, v55, v55
	v_max_f32_e32 v54, v54, v55
	v_mov_b32_e32 v55, v54
	s_nop 1
	v_permlane16_swap_b32_e32 v55, v54
	s_waitcnt lgkmcnt(0)
	v_max_f32_e32 v55, v55, v55
	v_max_f32_e32 v54, v54, v55
	v_mov_b32_e32 v55, v54
	s_nop 1
	v_permlane32_swap_b32_e32 v55, v54
	s_waitcnt lgkmcnt(0)
	v_max3_f32 v54, v54, v55, s50
	s_and_saveexec_b64 s[6:7], s[4:5]
	s_cbranch_execz .LBB0_1276
	s_lshl_b64 s[30:31], s[36:37], 2
	s_add_u32 s30, s28, s30
	v_mul_f32_e32 v55, 0x3c010204, v54
	s_addc_u32 s31, s29, s31
	global_store_dword v183, v55, s[30:31]
; template <bool PAIR> __device__ __forceinline__ void row_quant(const f32x4 (&v)[16], signed char* dstq, float* rowinv, int lane) {
;     ...
;     const float sc = 127.0f / mx;
;     if (lane == 0) *rowinv = mx * (1.0f / 127.0f);
;     unsigned w[16];
; #pragma unroll
;     for (int j = 0; j < 16; ++j) w[j] = ((unsigned)(int)rintf(v[j].x * sc) & 0xffu) | (((unsigned)(int)rintf(v[j].y * sc) & 0xffu) << 8) | (((unsigned)(int)rintf(v[j].z * sc) & 0xffu) << 16) | (((unsigned)(int)rintf(v[j].w * sc) & 0xffu) << 24);
.LBB0_1276:
	s_or_b64 exec, exec, s[6:7]
	v_div_scale_f32 v55, s[6:7], v54, v54, s41
	v_rcp_f32_e32 v150, v55
	s_lshl_b64 s[6:7], s[36:37], 12
	v_fma_f32 v151, -v55, v150, 1.0
	v_fmac_f32_e32 v150, v151, v150
	v_div_scale_f32 v151, vcc, s41, v54, s41
	v_mul_f32_e32 v153, v151, v150
	v_fma_f32 v154, -v55, v153, v151
	v_fmac_f32_e32 v153, v154, v150
	v_fma_f32 v55, -v55, v153, v151
	v_div_fmas_f32 v55, v55, v150, v153
	v_div_fixup_f32 v150, v55, v54, s41
	v_mul_f32_e32 v43, v43, v150
	v_mul_f32_e32 v35, v35, v150
	v_mul_f32_e32 v42, v42, v150
	v_rndne_f32_e32 v43, v43
	v_mul_f32_e32 v44, v44, v150
	v_mul_f32_e32 v45, v45, v150
	v_mul_f32_e32 v34, v34, v150
	v_rndne_f32_e32 v35, v35
	v_mul_f32_e32 v36, v36, v150
	v_mul_f32_e32 v37, v37, v150
	v_rndne_f32_e32 v42, v42
	v_cvt_i32_f32_e32 v43, v43
	v_rndne_f32_e32 v44, v44
	v_rndne_f32_e32 v45, v45
	v_rndne_f32_e32 v34, v34
	v_cvt_i32_f32_e32 v35, v35
	v_rndne_f32_e32 v36, v36
	v_rndne_f32_e32 v37, v37
	v_cvt_i32_f32_e32 v42, v42
	v_cvt_i32_f32_sdwa v44, v44 dst_sel:WORD_1 dst_unused:UNUSED_PAD src0_sel:DWORD
	v_cvt_i32_f32_e32 v45, v45
	v_cvt_i32_f32_e32 v34, v34
	v_cvt_i32_f32_sdwa v36, v36 dst_sel:WORD_1 dst_unused:UNUSED_PAD src0_sel:DWORD
	v_cvt_i32_f32_e32 v37, v37
	v_lshlrev_b32_e32 v43, 8, v43
	v_lshlrev_b32_e32 v35, 8, v35
	v_and_b32_e32 v43, 0xff00, v43
	v_and_b32_e32 v44, 0xff0000, v44
	v_perm_b32 v42, v45, v42, s88
	v_and_b32_e32 v35, 0xff00, v35
	v_and_b32_e32 v36, 0xff0000, v36
	v_perm_b32 v34, v37, v34, s88
	v_or3_b32 v42, v42, v43, v44
	v_or3_b32 v43, v34, v35, v36
	v_mul_f32_e32 v35, v113, v150
	v_mul_f32_e32 v34, v112, v150
	v_rndne_f32_e32 v35, v35
	v_mul_f32_e32 v36, v40, v150
	v_mul_f32_e32 v37, v41, v150
	v_rndne_f32_e32 v34, v34
	v_cvt_i32_f32_e32 v35, v35
	v_rndne_f32_e32 v36, v36
	v_rndne_f32_e32 v37, v37
	v_cvt_i32_f32_e32 v34, v34
	v_cvt_i32_f32_sdwa v36, v36 dst_sel:WORD_1 dst_unused:UNUSED_PAD src0_sel:DWORD
	v_cvt_i32_f32_e32 v37, v37
	v_lshlrev_b32_e32 v35, 8, v35
	v_and_b32_e32 v35, 0xff00, v35
	v_and_b32_e32 v36, 0xff0000, v36
	v_perm_b32 v34, v37, v34, s88
	v_or3_b32 v34, v34, v35, v36
	v_mul_f32_e32 v36, v65, v150
	v_mul_f32_e32 v35, v64, v150
	v_rndne_f32_e32 v36, v36
	v_mul_f32_e32 v37, v38, v150
	v_mul_f32_e32 v38, v39, v150
	v_rndne_f32_e32 v35, v35
	v_cvt_i32_f32_e32 v36, v36
	v_rndne_f32_e32 v37, v37
	v_rndne_f32_e32 v38, v38
	v_cvt_i32_f32_e32 v35, v35
	v_cvt_i32_f32_sdwa v37, v37 dst_sel:WORD_1 dst_unused:UNUSED_PAD src0_sel:DWORD
	v_cvt_i32_f32_e32 v38, v38
	v_lshlrev_b32_e32 v36, 8, v36
	v_and_b32_e32 v36, 0xff00, v36
	v_and_b32_e32 v37, 0xff0000, v37
	v_perm_b32 v35, v38, v35, s88
	v_or3_b32 v35, v35, v36, v37
	v_mul_f32_e32 v37, v127, v150
	v_mul_f32_e32 v36, v126, v150
	v_rndne_f32_e32 v37, v37
	v_mul_f32_e32 v38, v118, v150
	v_mul_f32_e32 v39, v119, v150
	v_rndne_f32_e32 v36, v36
	v_cvt_i32_f32_e32 v37, v37
	v_rndne_f32_e32 v38, v38
	v_rndne_f32_e32 v39, v39
	v_cvt_i32_f32_e32 v36, v36
	v_cvt_i32_f32_sdwa v38, v38 dst_sel:WORD_1 dst_unused:UNUSED_PAD src0_sel:DWORD
	v_cvt_i32_f32_e32 v39, v39
	v_lshlrev_b32_e32 v37, 8, v37
	v_and_b32_e32 v37, 0xff00, v37
	v_and_b32_e32 v38, 0xff0000, v38
	v_perm_b32 v36, v39, v36, s88
	v_or3_b32 v36, v36, v37, v38
	v_mul_f32_e32 v38, v129, v150
	v_mul_f32_e32 v37, v128, v150
	v_rndne_f32_e32 v38, v38
	v_mul_f32_e32 v39, v124, v150
	v_mul_f32_e32 v40, v125, v150
	v_rndne_f32_e32 v37, v37
	v_cvt_i32_f32_e32 v38, v38
	v_rndne_f32_e32 v39, v39
	v_rndne_f32_e32 v40, v40
	v_cvt_i32_f32_e32 v37, v37
	v_cvt_i32_f32_sdwa v39, v39 dst_sel:WORD_1 dst_unused:UNUSED_PAD src0_sel:DWORD
	v_cvt_i32_f32_e32 v40, v40
	v_lshlrev_b32_e32 v38, 8, v38
	v_and_b32_e32 v38, 0xff00, v38
	v_and_b32_e32 v39, 0xff0000, v39
	v_perm_b32 v37, v40, v37, s88
	v_or3_b32 v37, v37, v38, v39
	v_mul_f32_e32 v39, v133, v150
	v_mul_f32_e32 v38, v132, v150
	v_rndne_f32_e32 v39, v39
	v_mul_f32_e32 v40, v130, v150
	v_mul_f32_e32 v41, v131, v150
	v_rndne_f32_e32 v38, v38
	v_cvt_i32_f32_e32 v39, v39
	v_rndne_f32_e32 v40, v40
	v_rndne_f32_e32 v41, v41
	v_cvt_i32_f32_e32 v38, v38
	v_cvt_i32_f32_sdwa v40, v40 dst_sel:WORD_1 dst_unused:UNUSED_PAD src0_sel:DWORD
	v_cvt_i32_f32_e32 v41, v41
	v_lshlrev_b32_e32 v39, 8, v39
	v_and_b32_e32 v39, 0xff00, v39
	v_and_b32_e32 v40, 0xff0000, v40
	v_perm_b32 v38, v41, v38, s88
	v_or3_b32 v38, v38, v39, v40
	v_mul_f32_e32 v40, v139, v150
	v_mul_f32_e32 v39, v138, v150
	v_rndne_f32_e32 v40, v40
	v_mul_f32_e32 v41, v134, v150
	v_mul_f32_e32 v44, v135, v150
	v_rndne_f32_e32 v39, v39
	v_cvt_i32_f32_e32 v40, v40
	v_rndne_f32_e32 v41, v41
	v_rndne_f32_e32 v44, v44
	v_cvt_i32_f32_e32 v39, v39
	v_cvt_i32_f32_sdwa v41, v41 dst_sel:WORD_1 dst_unused:UNUSED_PAD src0_sel:DWORD
	v_cvt_i32_f32_e32 v44, v44
	v_lshlrev_b32_e32 v40, 8, v40
	v_and_b32_e32 v40, 0xff00, v40
	v_and_b32_e32 v41, 0xff0000, v41
	v_perm_b32 v39, v44, v39, s88
	v_or3_b32 v39, v39, v40, v41
	v_mul_f32_e32 v41, v145, v150
	v_mul_f32_e32 v40, v144, v150
	v_rndne_f32_e32 v41, v41
	v_mul_f32_e32 v44, v142, v150
	v_mul_f32_e32 v45, v143, v150
	v_rndne_f32_e32 v40, v40
	v_cvt_i32_f32_e32 v41, v41
	v_rndne_f32_e32 v44, v44
	v_rndne_f32_e32 v45, v45
	v_cvt_i32_f32_e32 v40, v40
	v_cvt_i32_f32_sdwa v44, v44 dst_sel:WORD_1 dst_unused:UNUSED_PAD src0_sel:DWORD
	v_cvt_i32_f32_e32 v45, v45
	v_lshlrev_b32_e32 v41, 8, v41
	v_and_b32_e32 v41, 0xff00, v41
	v_and_b32_e32 v44, 0xff0000, v44
	v_perm_b32 v40, v45, v40, s88
	v_or3_b32 v40, v40, v41, v44
	v_mul_f32_e32 v44, v141, v150
	v_mul_f32_e32 v41, v140, v150
	v_rndne_f32_e32 v44, v44
	v_mul_f32_e32 v45, v136, v150
	v_mul_f32_e32 v54, v137, v150
	v_rndne_f32_e32 v41, v41
	v_cvt_i32_f32_e32 v44, v44
	v_rndne_f32_e32 v45, v45
; __device__ __forceinline__ f32x4 h4lo(const u32x4 w) { return (f32x4){hlo(w.x), hhi(w.x), hlo(w.y), hhi(w.y)}; }
; __device__ __forceinline__ f32x4 h4hi(const u32x4 w) { return (f32x4){hlo(w.z), hhi(w.z), hlo(w.w), hhi(w.w)}; }
; __device__ __forceinline__ void ln_load_b(const v4u (&raw)[8], f32x4 (&v)[16], float& mean, float& rstd, int lane) {
;     float s = 0.f;
; #pragma unroll
;     for (int j = 0; j < 8; ++j) { const v4u w = raw[j]; v[2 * j] = pg8::h4lo(w); v[2 * j + 1] = pg8::h4hi(w);
;         s += ((v[2 * j].x + v[2 * j].y) + (v[2 * j].z + v[2 * j].w)) + ((v[2 * j + 1].x + v[2 * j + 1].y) + (v[2 * j + 1].z + v[2 * j + 1].w)); }
; template <bool PAIR> __device__ __forceinline__ void row_quant(const f32x4 (&v)[16], signed char* dstq, float* rowinv, int lane) {
;     ...
;     unsigned w[16];
; #pragma unroll
;     for (int j = 0; j < 16; ++j) w[j] = ((unsigned)(int)rintf(v[j].x * sc) & 0xffu) | (((unsigned)(int)rintf(v[j].y * sc) & 0xffu) << 8) | (((unsigned)(int)rintf(v[j].z * sc) & 0xffu) << 16) | (((unsigned)(int)rintf(v[j].w * sc) & 0xffu) << 24);
;     if (PAIR) {
; #pragma unroll
;         for (int j = 0; j < 8; ++j) ((v2u*)dstq)[64 * j + lane] = (v2u){w[2 * j], w[2 * j + 1]};
	v_rndne_f32_e32 v54, v54
	v_cvt_i32_f32_e32 v41, v41
	v_cvt_i32_f32_sdwa v45, v45 dst_sel:WORD_1 dst_unused:UNUSED_PAD src0_sel:DWORD
	v_cvt_i32_f32_e32 v54, v54
	v_lshlrev_b32_e32 v44, 8, v44
	v_and_b32_e32 v44, 0xff00, v44
	v_and_b32_e32 v45, 0xff0000, v45
	v_perm_b32 v41, v54, v41, s88
	v_or3_b32 v41, v41, v44, v45
	v_mul_f32_e32 v45, v123, v150
	v_mul_f32_e32 v44, v122, v150
	v_rndne_f32_e32 v45, v45
	v_mul_f32_e32 v54, v120, v150
	v_mul_f32_e32 v55, v121, v150
	v_rndne_f32_e32 v44, v44
	v_cvt_i32_f32_e32 v45, v45
	v_rndne_f32_e32 v54, v54
	v_rndne_f32_e32 v55, v55
	v_cvt_i32_f32_e32 v44, v44
	v_cvt_i32_f32_sdwa v54, v54 dst_sel:WORD_1 dst_unused:UNUSED_PAD src0_sel:DWORD
	v_cvt_i32_f32_e32 v55, v55
	v_lshlrev_b32_e32 v45, 8, v45
	v_and_b32_e32 v45, 0xff00, v45
	v_and_b32_e32 v54, 0xff0000, v54
	v_perm_b32 v44, v55, v44, s88
	v_or3_b32 v44, v44, v45, v54
	v_mul_f32_e32 v54, v117, v150
	v_mul_f32_e32 v45, v116, v150
	v_rndne_f32_e32 v54, v54
	v_mul_f32_e32 v55, v114, v150
	v_mul_f32_e32 v64, v115, v150
	v_rndne_f32_e32 v45, v45
	v_cvt_i32_f32_e32 v54, v54
	v_rndne_f32_e32 v55, v55
	v_rndne_f32_e32 v64, v64
	v_cvt_i32_f32_e32 v45, v45
	v_cvt_i32_f32_sdwa v55, v55 dst_sel:WORD_1 dst_unused:UNUSED_PAD src0_sel:DWORD
	v_cvt_i32_f32_e32 v64, v64
	v_lshlrev_b32_e32 v54, 8, v54
	v_and_b32_e32 v54, 0xff00, v54
	v_and_b32_e32 v55, 0xff0000, v55
	v_perm_b32 v45, v64, v45, s88
	v_or3_b32 v45, v45, v54, v55
	v_mul_f32_e32 v55, v63, v150
	v_mul_f32_e32 v54, v62, v150
	v_rndne_f32_e32 v55, v55
	v_mul_f32_e32 v60, v60, v150
	v_mul_f32_e32 v61, v61, v150
	v_rndne_f32_e32 v54, v54
	v_cvt_i32_f32_e32 v55, v55
	v_rndne_f32_e32 v60, v60
	v_rndne_f32_e32 v61, v61
	v_cvt_i32_f32_e32 v54, v54
	v_cvt_i32_f32_sdwa v60, v60 dst_sel:WORD_1 dst_unused:UNUSED_PAD src0_sel:DWORD
	v_cvt_i32_f32_e32 v61, v61
	v_lshlrev_b32_e32 v55, 8, v55
	v_and_b32_e32 v55, 0xff00, v55
	v_and_b32_e32 v60, 0xff0000, v60
	v_perm_b32 v54, v61, v54, s88
	v_mul_f32_e32 v53, v53, v150
	v_mul_f32_e32 v49, v49, v150
	v_or3_b32 v54, v54, v55, v60
	v_mul_f32_e32 v55, v58, v150
	v_mul_f32_e32 v58, v59, v150
	v_mul_f32_e32 v52, v52, v150
	v_rndne_f32_e32 v53, v53
	v_mul_f32_e32 v50, v50, v150
	v_mul_f32_e32 v51, v51, v150
	v_mul_f32_e32 v48, v48, v150
	v_rndne_f32_e32 v49, v49
	v_mul_f32_e32 v46, v46, v150
	v_mul_f32_e32 v47, v47, v150
	v_rndne_f32_e32 v58, v58
	v_mul_f32_e32 v56, v56, v150
	v_mul_f32_e32 v57, v57, v150
	v_rndne_f32_e32 v52, v52
	v_cvt_i32_f32_e32 v53, v53
	v_rndne_f32_e32 v50, v50
	v_rndne_f32_e32 v51, v51
	v_rndne_f32_e32 v48, v48
	v_cvt_i32_f32_e32 v49, v49
	v_rndne_f32_e32 v46, v46
	v_rndne_f32_e32 v47, v47
	v_rndne_f32_e32 v55, v55
	v_cvt_i32_f32_e32 v58, v58
	v_rndne_f32_e32 v56, v56
	v_rndne_f32_e32 v57, v57
	v_cvt_i32_f32_e32 v52, v52
	v_cvt_i32_f32_sdwa v50, v50 dst_sel:WORD_1 dst_unused:UNUSED_PAD src0_sel:DWORD
	v_cvt_i32_f32_e32 v51, v51
	v_cvt_i32_f32_e32 v48, v48
	v_cvt_i32_f32_sdwa v46, v46 dst_sel:WORD_1 dst_unused:UNUSED_PAD src0_sel:DWORD
	v_cvt_i32_f32_e32 v47, v47
	v_cvt_i32_f32_e32 v55, v55
	v_cvt_i32_f32_sdwa v56, v56 dst_sel:WORD_1 dst_unused:UNUSED_PAD src0_sel:DWORD
	v_cvt_i32_f32_e32 v57, v57
	v_lshlrev_b32_e32 v53, 8, v53
	v_lshlrev_b32_e32 v49, 8, v49
	v_lshlrev_b32_e32 v58, 8, v58
	v_and_b32_e32 v53, 0xff00, v53
	v_and_b32_e32 v50, 0xff0000, v50
	v_perm_b32 v51, v51, v52, s88
	v_and_b32_e32 v49, 0xff00, v49
	v_and_b32_e32 v46, 0xff0000, v46
	v_perm_b32 v47, v47, v48, s88
	v_and_b32_e32 v58, 0xff00, v58
	v_and_b32_e32 v56, 0xff0000, v56
	v_perm_b32 v55, v57, v55, s88
	v_or3_b32 v50, v51, v53, v50
	v_or3_b32 v51, v47, v49, v46
	v_lshl_add_u64 v[46:47], v[110:111], 0, s[6:7]
	s_andn2_b64 vcc, exec, s[16:17]
	v_or3_b32 v55, v55, v58, v56
	global_store_dwordx2 v[46:47], v[42:43], off
	global_store_dwordx2 v[46:47], v[34:35], off offset:512
	global_store_dwordx2 v[46:47], v[36:37], off offset:1024
	global_store_dwordx2 v[46:47], v[38:39], off offset:1536
	global_store_dwordx2 v[46:47], v[40:41], off offset:2048
	global_store_dwordx2 v[46:47], v[44:45], off offset:2560
	global_store_dwordx2 v[46:47], v[54:55], off offset:3072
	global_store_dwordx2 v[46:47], v[50:51], off offset:3584
	s_cbranch_vccnz .LBB0_1273
	v_cvt_f32_f16_sdwa v34, v30 dst_sel:DWORD dst_unused:UNUSED_PAD src0_sel:WORD_1
	v_cvt_f32_f16_e32 v36, v30
	v_cvt_f32_f16_sdwa v38, v31 dst_sel:DWORD dst_unused:UNUSED_PAD src0_sel:WORD_1
	v_cvt_f32_f16_e32 v40, v31
	v_cvt_f32_f16_sdwa v35, v32 dst_sel:DWORD dst_unused:UNUSED_PAD src0_sel:WORD_1
	v_cvt_f32_f16_e32 v37, v32
	v_cvt_f32_f16_sdwa v39, v33 dst_sel:DWORD dst_unused:UNUSED_PAD src0_sel:WORD_1
	v_cvt_f32_f16_e32 v41, v33
	v_cvt_f32_f16_e32 v42, v28
	v_pk_add_f32 v[34:35], v[36:37], v[34:35]
	v_cvt_f32_f16_e32 v43, v29
	v_pk_add_f32 v[36:37], v[40:41], v[38:39]
	v_cvt_f32_f16_e32 v38, v26
	v_pk_add_f32 v[34:35], v[34:35], v[36:37]
	v_cvt_f32_f16_sdwa v36, v26 dst_sel:DWORD dst_unused:UNUSED_PAD src0_sel:WORD_1
	v_cvt_f32_f16_sdwa v37, v27 dst_sel:DWORD dst_unused:UNUSED_PAD src0_sel:WORD_1
	v_cvt_f32_f16_e32 v39, v27
	v_cvt_f32_f16_sdwa v40, v28 dst_sel:DWORD dst_unused:UNUSED_PAD src0_sel:WORD_1
	v_cvt_f32_f16_sdwa v41, v29 dst_sel:DWORD dst_unused:UNUSED_PAD src0_sel:WORD_1
	v_pk_add_f32 v[34:35], v[34:35], v[34:35] op_sel:[0,1] op_sel_hi:[1,0]
	v_pk_add_f32 v[36:37], v[38:39], v[36:37]
	v_cvt_f32_f16_sdwa v35, v22 dst_sel:DWORD dst_unused:UNUSED_PAD src0_sel:WORD_1
	v_pk_add_f32 v[38:39], v[42:43], v[40:41]
	v_pk_add_f32 v[36:37], v[36:37], v[36:37] op_sel:[0,1] op_sel_hi:[1,0]
	v_pk_add_f32 v[38:39], v[38:39], v[38:39] op_sel:[0,1] op_sel_hi:[1,0]
	v_cvt_f32_f16_e32 v37, v22
	v_cvt_f32_f16_sdwa v39, v23 dst_sel:DWORD dst_unused:UNUSED_PAD src0_sel:WORD_1
; __device__ __forceinline__ f32x4 h4lo(const u32x4 w) { return (f32x4){hlo(w.x), hhi(w.x), hlo(w.y), hhi(w.y)}; }
; __device__ __forceinline__ f32x4 h4hi(const u32x4 w) { return (f32x4){hlo(w.z), hhi(w.z), hlo(w.w), hhi(w.w)}; }
; __device__ __forceinline__ float wave_sum(float v) {
; #pragma unroll
;     for (int o = 1; o < 64; o <<= 1) v += __shfl_xor(v, o);
;     return v;
; }
; __device__ __forceinline__ void ln_load_b(const v4u (&raw)[8], f32x4 (&v)[16], float& mean, float& rstd, int lane) {
;     float s = 0.f;
; #pragma unroll
;     for (int j = 0; j < 8; ++j) { const v4u w = raw[j]; v[2 * j] = pg8::h4lo(w); v[2 * j + 1] = pg8::h4hi(w);
;         s += ((v[2 * j].x + v[2 * j].y) + (v[2 * j].z + v[2 * j].w)) + ((v[2 * j + 1].x + v[2 * j + 1].y) + (v[2 * j + 1].z + v[2 * j + 1].w)); }
;     mean = wave_sum(s) * (1.f / 4096.f); float s2 = 0.f;
	v_cvt_f32_f16_e32 v41, v23
	v_cvt_f32_f16_sdwa v43, v24 dst_sel:DWORD dst_unused:UNUSED_PAD src0_sel:WORD_1
	v_cvt_f32_f16_e32 v44, v24
	v_cvt_f32_f16_sdwa v45, v25 dst_sel:DWORD dst_unused:UNUSED_PAD src0_sel:WORD_1
	v_cvt_f32_f16_e32 v46, v25
	v_add_f32_e32 v40, v35, v37
	v_add_f32_e32 v42, v39, v41
	v_cvt_f32_f16_sdwa v49, v18 dst_sel:DWORD dst_unused:UNUSED_PAD src0_sel:WORD_1
	v_cvt_f32_f16_e32 v35, v18
	v_cvt_f32_f16_sdwa v39, v19 dst_sel:DWORD dst_unused:UNUSED_PAD src0_sel:WORD_1
	v_cvt_f32_f16_e32 v37, v19
	v_add_f32_e32 v44, v43, v44
	v_add_f32_e32 v46, v45, v46
	v_cvt_f32_f16_sdwa v43, v20 dst_sel:DWORD dst_unused:UNUSED_PAD src0_sel:WORD_1
	v_cvt_f32_f16_e32 v41, v20
	v_cvt_f32_f16_sdwa v47, v21 dst_sel:DWORD dst_unused:UNUSED_PAD src0_sel:WORD_1
	v_cvt_f32_f16_e32 v45, v21
	v_mov_b32_e32 v48, v183
	v_pk_add_f32 v[34:35], v[34:35], v[48:49]
	v_pk_add_f32 v[36:37], v[36:37], v[38:39]
	v_pk_add_f32 v[38:39], v[44:45], v[46:47]
	v_pk_add_f32 v[34:35], v[34:35], v[36:37]
	v_pk_add_f32 v[36:37], v[40:41], v[42:43]
	v_cvt_f32_f16_e32 v40, v14
	v_pk_add_f32 v[36:37], v[36:37], v[38:39]
	v_cvt_f32_f16_sdwa v38, v14 dst_sel:DWORD dst_unused:UNUSED_PAD src0_sel:WORD_1
	v_cvt_f32_f16_sdwa v42, v15 dst_sel:DWORD dst_unused:UNUSED_PAD src0_sel:WORD_1
	v_cvt_f32_f16_e32 v44, v15
	v_cvt_f32_f16_sdwa v39, v16 dst_sel:DWORD dst_unused:UNUSED_PAD src0_sel:WORD_1
	v_cvt_f32_f16_e32 v41, v16
	v_cvt_f32_f16_sdwa v43, v17 dst_sel:DWORD dst_unused:UNUSED_PAD src0_sel:WORD_1
	v_cvt_f32_f16_e32 v45, v17
	v_pk_add_f32 v[34:35], v[34:35], v[36:37]
	v_pk_add_f32 v[36:37], v[40:41], v[38:39]
	v_cvt_f32_f16_e32 v40, v10
	v_pk_add_f32 v[38:39], v[44:45], v[42:43]
	v_cvt_f32_f16_e32 v41, v11
	v_pk_add_f32 v[36:37], v[36:37], v[38:39]
	v_cvt_f32_f16_sdwa v38, v10 dst_sel:DWORD dst_unused:UNUSED_PAD src0_sel:WORD_1
	v_cvt_f32_f16_sdwa v39, v11 dst_sel:DWORD dst_unused:UNUSED_PAD src0_sel:WORD_1
	v_cvt_f32_f16_sdwa v42, v12 dst_sel:DWORD dst_unused:UNUSED_PAD src0_sel:WORD_1
	v_cvt_f32_f16_e32 v44, v12
	v_cvt_f32_f16_sdwa v43, v13 dst_sel:DWORD dst_unused:UNUSED_PAD src0_sel:WORD_1
	v_cvt_f32_f16_e32 v45, v13
	v_pk_add_f32 v[38:39], v[40:41], v[38:39]
	v_pk_add_f32 v[34:35], v[34:35], v[34:35] op_sel:[0,1] op_sel_hi:[1,0]
	v_pk_add_f32 v[36:37], v[36:37], v[36:37] op_sel:[0,1] op_sel_hi:[1,0]
	v_pk_add_f32 v[40:41], v[44:45], v[42:43]
	v_pk_add_f32 v[38:39], v[38:39], v[38:39] op_sel:[0,1] op_sel_hi:[1,0]
	v_pk_add_f32 v[40:41], v[40:41], v[40:41] op_sel:[0,1] op_sel_hi:[1,0]
	v_cvt_f32_f16_sdwa v35, v6 dst_sel:DWORD dst_unused:UNUSED_PAD src0_sel:WORD_1
	v_cvt_f32_f16_e32 v37, v6
	v_cvt_f32_f16_sdwa v39, v7 dst_sel:DWORD dst_unused:UNUSED_PAD src0_sel:WORD_1
	v_cvt_f32_f16_e32 v41, v7
	v_cvt_f32_f16_sdwa v43, v8 dst_sel:DWORD dst_unused:UNUSED_PAD src0_sel:WORD_1
	v_cvt_f32_f16_e32 v45, v8
	v_cvt_f32_f16_sdwa v47, v9 dst_sel:DWORD dst_unused:UNUSED_PAD src0_sel:WORD_1
	v_cvt_f32_f16_e32 v48, v9
	v_add_f32_e32 v42, v35, v37
	v_add_f32_e32 v44, v39, v41
	v_cvt_f32_f16_sdwa v37, v2 dst_sel:DWORD dst_unused:UNUSED_PAD src0_sel:WORD_1
	v_cvt_f32_f16_e32 v35, v2
	v_cvt_f32_f16_sdwa v41, v3 dst_sel:DWORD dst_unused:UNUSED_PAD src0_sel:WORD_1
	v_cvt_f32_f16_e32 v39, v3
	v_add_f32_e32 v46, v43, v45
	v_add_f32_e32 v48, v47, v48
	v_cvt_f32_f16_sdwa v45, v4 dst_sel:DWORD dst_unused:UNUSED_PAD src0_sel:WORD_1
	v_cvt_f32_f16_e32 v43, v4
	v_cvt_f32_f16_sdwa v49, v5 dst_sel:DWORD dst_unused:UNUSED_PAD src0_sel:WORD_1
	v_cvt_f32_f16_e32 v47, v5
	v_pk_add_f32 v[34:35], v[34:35], v[36:37]
	v_pk_add_f32 v[36:37], v[38:39], v[40:41]
	s_lshl_b64 s[16:17], s[8:9], 12
	v_pk_add_f32 v[34:35], v[34:35], v[36:37]
	v_pk_add_f32 v[36:37], v[42:43], v[44:45]
	v_pk_add_f32 v[38:39], v[46:47], v[48:49]
	s_nop 0
	v_pk_add_f32 v[36:37], v[36:37], v[38:39]
	s_nop 0
	v_pk_add_f32 v[34:35], v[34:35], v[36:37]
	s_nop 0
	v_add_f32_e32 v34, v34, v35
	s_nop 1
	v_mov_b32_dpp v35, v34 quad_perm:[1,0,3,2] row_mask:0xf bank_mask:0xf
	s_waitcnt lgkmcnt(0)
	v_add_f32_e32 v34, v34, v35
	s_nop 1
	v_mov_b32_dpp v35, v34 quad_perm:[2,3,0,1] row_mask:0xf bank_mask:0xf
	s_waitcnt lgkmcnt(0)
	v_add_f32_e32 v34, v34, v35
	s_nop 1
	v_mov_b32_dpp v35, v34 row_half_mirror row_mask:0xf bank_mask:0xf
	s_waitcnt lgkmcnt(0)
	v_add_f32_e32 v34, v34, v35
	s_nop 1
	v_mov_b32_dpp v35, v34 row_mirror row_mask:0xf bank_mask:0xf
	s_waitcnt lgkmcnt(0)
	v_add_f32_e32 v34, v34, v35
	v_mov_b32_e32 v35, v34
	s_nop 1
	v_permlane16_swap_b32_e32 v35, v34
	s_waitcnt lgkmcnt(0)
	v_add_f32_e32 v34, v34, v35
	v_mov_b32_e32 v35, v34
	s_nop 1
	v_permlane32_swap_b32_e32 v35, v34
	s_waitcnt lgkmcnt(0)
; __device__ __forceinline__ void ln_load_b(const v4u (&raw)[8], f32x4 (&v)[16], float& mean, float& rstd, int lane) {
;     ...
; #pragma unroll
;     for (int j = 0; j < 16; ++j) { v[j] = v[j] - mean; s2 += (v[j].x * v[j].x + v[j].y * v[j].y) + (v[j].z * v[j].z + v[j].w * v[j].w); }
	v_add_f32_e32 v64, v34, v35
	v_fma_mix_f32 v41, v64, s87, v30 op_sel:[0,0,1] op_sel_hi:[0,0,1]
	v_fma_mix_f32 v40, v64, s87, v30 op_sel_hi:[0,0,1]
	v_fma_mix_f32 v43, v64, s87, v31 op_sel:[0,0,1] op_sel_hi:[0,0,1]
	v_fma_mix_f32 v42, v64, s87, v31 op_sel_hi:[0,0,1]
	v_pk_mul_f32 v[30:31], v[42:43], v[42:43]
	v_pk_mul_f32 v[34:35], v[40:41], v[40:41]
	v_fma_mix_f32 v127, v64, s87, v32 op_sel:[0,0,1] op_sel_hi:[0,0,1]
	v_pk_mov_b32 v[36:37], v[34:35], v[30:31] op_sel:[1,0]
	v_mov_b32_e32 v35, v31
	v_fma_mix_f32 v126, v64, s87, v32 op_sel_hi:[0,0,1]
	v_fma_mix_f32 v129, v64, s87, v33 op_sel:[0,0,1] op_sel_hi:[0,0,1]
	v_fma_mix_f32 v128, v64, s87, v33 op_sel_hi:[0,0,1]
	v_pk_add_f32 v[30:31], v[36:37], v[34:35]
	v_pk_mul_f32 v[32:33], v[128:129], v[128:129]
	v_pk_mul_f32 v[34:35], v[126:127], v[126:127]
	v_fma_mix_f32 v51, v64, s87, v27 op_sel:[0,0,1] op_sel_hi:[0,0,1]
	v_pk_mov_b32 v[36:37], v[34:35], v[32:33] op_sel:[1,0]
	v_mov_b32_e32 v35, v33
	v_pk_add_f32 v[32:33], v[36:37], v[34:35]
	v_fma_mix_f32 v50, v64, s87, v27 op_sel_hi:[0,0,1]
	v_pk_add_f32 v[34:35], v[32:33], v[32:33] op_sel_hi:[0,1]
	v_fma_mix_f32 v32, v64, s87, v26 op_sel_hi:[0,0,1]
	v_fma_mix_f32 v33, v64, s87, v26 op_sel:[0,0,1] op_sel_hi:[0,0,1]
	v_mul_f32_e32 v26, v32, v32
	v_pk_fma_f32 v[26:27], v[32:33], v[32:33], v[26:27] op_sel_hi:[1,1,0]
	v_pk_add_f32 v[30:31], v[30:31], v[30:31] op_sel_hi:[0,1]
	v_mul_f32_e32 v26, v50, v50
	v_pk_fma_f32 v[36:37], v[50:51], v[50:51], v[26:27] op_sel_hi:[1,1,0]
	v_fma_mix_f32 v39, v64, s87, v29 op_sel:[0,0,1] op_sel_hi:[0,0,1]
	v_fma_mix_f32 v38, v64, s87, v29 op_sel_hi:[0,0,1]
	v_fma_mix_f32 v125, v64, s87, v28 op_sel:[0,0,1] op_sel_hi:[0,0,1]
	v_fma_mix_f32 v124, v64, s87, v28 op_sel_hi:[0,0,1]
	v_mul_f32_e32 v26, v124, v124
	v_mul_f32_e32 v36, v125, v125
	v_mul_f32_e32 v30, v38, v38
	v_mul_f32_e32 v34, v39, v39
	v_pk_add_f32 v[26:27], v[26:27], v[36:37]
	v_pk_add_f32 v[28:29], v[30:31], v[34:35]
	v_fma_mix_f32 v31, v64, s87, v22 op_sel:[0,0,1] op_sel_hi:[0,0,1]
	v_fma_mix_f32 v30, v64, s87, v22 op_sel_hi:[0,0,1]
	v_fma_mix_f32 v49, v64, s87, v23 op_sel:[0,0,1] op_sel_hi:[0,0,1]
	v_fma_mix_f32 v48, v64, s87, v23 op_sel_hi:[0,0,1]
	v_pk_add_f32 v[26:27], v[26:27], v[28:29]
	v_pk_mul_f32 v[22:23], v[48:49], v[48:49]
	v_pk_mul_f32 v[28:29], v[30:31], v[30:31]
	v_fma_mix_f32 v120, v64, s87, v24 op_sel_hi:[0,0,1]
	v_pk_mov_b32 v[34:35], v[28:29], v[22:23] op_sel:[1,0]
	v_mov_b32_e32 v29, v23
	v_pk_add_f32 v[22:23], v[34:35], v[28:29]
	v_fma_mix_f32 v121, v64, s87, v24 op_sel:[0,0,1] op_sel_hi:[0,0,1]
	v_pk_add_f32 v[28:29], v[22:23], v[22:23] op_sel_hi:[0,1]
	v_fma_mix_f32 v122, v64, s87, v25 op_sel_hi:[0,0,1]
	v_mul_f32_e32 v22, v120, v120
	v_fma_mix_f32 v123, v64, s87, v25 op_sel:[0,0,1] op_sel_hi:[0,0,1]
	v_pk_fma_f32 v[24:25], v[120:121], v[120:121], v[22:23] op_sel_hi:[1,1,0]
	v_mul_f32_e32 v22, v122, v122
	v_pk_add_f32 v[26:27], v[26:27], v[26:27] op_sel_hi:[0,1]
	v_pk_fma_f32 v[36:37], v[122:123], v[122:123], v[22:23] op_sel_hi:[1,1,0]
	v_fma_mix_f32 v23, v64, s87, v19 op_sel:[0,0,1] op_sel_hi:[0,0,1]
	v_fma_mix_f32 v22, v64, s87, v19 op_sel_hi:[0,0,1]
	v_fma_mix_f32 v35, v64, s87, v18 op_sel:[0,0,1] op_sel_hi:[0,0,1]
	v_fma_mix_f32 v34, v64, s87, v18 op_sel_hi:[0,0,1]
	v_mul_f32_e32 v24, v34, v34
	v_mul_f32_e32 v36, v35, v35
	v_mul_f32_e32 v28, v22, v22
	v_mul_f32_e32 v26, v23, v23
	v_pk_add_f32 v[18:19], v[24:25], v[36:37]
	v_pk_add_f32 v[24:25], v[28:29], v[26:27]
	v_fma_mix_f32 v53, v64, s87, v20 op_sel:[0,0,1] op_sel_hi:[0,0,1]
	v_fma_mix_f32 v52, v64, s87, v20 op_sel_hi:[0,0,1]
	v_fma_mix_f32 v119, v64, s87, v21 op_sel:[0,0,1] op_sel_hi:[0,0,1]
	v_fma_mix_f32 v118, v64, s87, v21 op_sel_hi:[0,0,1]
	v_pk_add_f32 v[18:19], v[18:19], v[24:25]
	v_pk_mul_f32 v[20:21], v[118:119], v[118:119]
	v_pk_mul_f32 v[24:25], v[52:53], v[52:53]
	v_fma_mix_f32 v55, v64, s87, v15 op_sel:[0,0,1] op_sel_hi:[0,0,1]
	v_pk_mov_b32 v[26:27], v[24:25], v[20:21] op_sel:[1,0]
	v_mov_b32_e32 v25, v21
	v_pk_add_f32 v[20:21], v[26:27], v[24:25]
	v_fma_mix_f32 v24, v64, s87, v14 op_sel_hi:[0,0,1]
	v_fma_mix_f32 v25, v64, s87, v14 op_sel:[0,0,1] op_sel_hi:[0,0,1]
	v_mul_f32_e32 v14, v24, v24
	v_fma_mix_f32 v54, v64, s87, v15 op_sel_hi:[0,0,1]
	v_pk_fma_f32 v[14:15], v[24:25], v[24:25], v[14:15] op_sel_hi:[1,1,0]
	v_pk_add_f32 v[18:19], v[18:19], v[18:19] op_sel_hi:[0,1]
	v_mul_f32_e32 v14, v54, v54
	v_pk_add_f32 v[20:21], v[20:21], v[20:21] op_sel_hi:[0,1]
	v_pk_fma_f32 v[26:27], v[54:55], v[54:55], v[14:15] op_sel_hi:[1,1,0]
	v_fma_mix_f32 v37, v64, s87, v17 op_sel:[0,0,1] op_sel_hi:[0,0,1]
	v_fma_mix_f32 v36, v64, s87, v17 op_sel_hi:[0,0,1]
	v_fma_mix_f32 v117, v64, s87, v16 op_sel:[0,0,1] op_sel_hi:[0,0,1]
	v_fma_mix_f32 v116, v64, s87, v16 op_sel_hi:[0,0,1]
	v_mul_f32_e32 v14, v116, v116
	v_mul_f32_e32 v26, v117, v117
	v_mul_f32_e32 v20, v36, v36
	v_mul_f32_e32 v18, v37, v37
	v_pk_add_f32 v[14:15], v[14:15], v[26:27]
	v_pk_add_f32 v[16:17], v[20:21], v[18:19]
	v_fma_mix_f32 v27, v64, s87, v11 op_sel:[0,0,1] op_sel_hi:[0,0,1]
	v_pk_add_f32 v[14:15], v[14:15], v[16:17]
	v_fma_mix_f32 v26, v64, s87, v11 op_sel_hi:[0,0,1]
	v_pk_add_f32 v[18:19], v[14:15], v[14:15] op_sel_hi:[0,1]
	v_fma_mix_f32 v15, v64, s87, v10 op_sel:[0,0,1] op_sel_hi:[0,0,1]
	v_fma_mix_f32 v14, v64, s87, v10 op_sel_hi:[0,0,1]
	v_pk_mul_f32 v[10:11], v[26:27], v[26:27]
	v_pk_mul_f32 v[16:17], v[14:15], v[14:15]
	v_fma_mix_f32 v44, v64, s87, v12 op_sel_hi:[0,0,1]
	v_pk_mov_b32 v[20:21], v[16:17], v[10:11] op_sel:[1,0]
	v_mov_b32_e32 v17, v11
	v_pk_add_f32 v[10:11], v[20:21], v[16:17]
	v_fma_mix_f32 v45, v64, s87, v12 op_sel:[0,0,1] op_sel_hi:[0,0,1]
	v_pk_add_f32 v[10:11], v[10:11], v[10:11] op_sel_hi:[0,1]
; __device__ __forceinline__ unsigned pkh(float a, float b) { const f2v_t f = {a, b}; const h2v_t h = __builtin_convertvector(f, h2v_t); return __builtin_bit_cast(unsigned, h); }
; __device__ __forceinline__ float wave_sum(float v) {
; #pragma unroll
;     for (int o = 1; o < 64; o <<= 1) v += __shfl_xor(v, o);
;     return v;
; }
; __device__ __forceinline__ void ln_load_b(const v4u (&raw)[8], f32x4 (&v)[16], float& mean, float& rstd, int lane) {
;     ...
;     rstd = 1.f / sqrtf(wave_sum(s2) * (1.f / 4096.f) + 1e-5f);
; __device__ __forceinline__ void ln_row_b_in(const v4u (&src)[8], const float* g, const float* b, bf16* dstb, signed char* dstq, float* rowinv, int lane) {
;     f32x4 v[16]; float mean, rstd; ln_load_b(src, v, mean, rstd, lane);
; #pragma unroll
;     for (int j = 0; j < 8; ++j) { const int q = 2 * (64 * j + lane);
;         v[2 * j] = v[2 * j] * rstd * ((const f32x4*)g)[q] + ((const f32x4*)b)[q]; v[2 * j + 1] = v[2 * j + 1] * rstd * ((const f32x4*)g)[q + 1] + ((const f32x4*)b)[q + 1];
;         v4u w; w.x = pg8::pkh(v[2 * j].x, v[2 * j].y); w.y = pg8::pkh(v[2 * j].z, v[2 * j].w); w.z = pg8::pkh(v[2 * j + 1].x, v[2 * j + 1].y); w.w = pg8::pkh(v[2 * j + 1].z, v[2 * j + 1].w); ((v4u*)dstb)[64 * j + lane] = w; }
	v_fma_mix_f32 v114, v64, s87, v13 op_sel_hi:[0,0,1]
	v_mul_f32_e32 v10, v44, v44
	v_fma_mix_f32 v115, v64, s87, v13 op_sel:[0,0,1] op_sel_hi:[0,0,1]
	v_pk_fma_f32 v[12:13], v[44:45], v[44:45], v[10:11] op_sel_hi:[1,1,0]
	v_mul_f32_e32 v10, v114, v114
	v_pk_fma_f32 v[20:21], v[114:115], v[114:115], v[10:11] op_sel_hi:[1,1,0]
	v_fma_mix_f32 v17, v64, s87, v7 op_sel:[0,0,1] op_sel_hi:[0,0,1]
	v_fma_mix_f32 v16, v64, s87, v7 op_sel_hi:[0,0,1]
	v_fma_mix_f32 v29, v64, s87, v6 op_sel:[0,0,1] op_sel_hi:[0,0,1]
	v_fma_mix_f32 v28, v64, s87, v6 op_sel_hi:[0,0,1]
	v_mul_f32_e32 v12, v28, v28
	v_mul_f32_e32 v20, v29, v29
	v_mul_f32_e32 v10, v16, v16
	v_mul_f32_e32 v18, v17, v17
	v_pk_add_f32 v[6:7], v[12:13], v[20:21]
	v_pk_add_f32 v[10:11], v[10:11], v[18:19]
	v_fma_mix_f32 v47, v64, s87, v8 op_sel:[0,0,1] op_sel_hi:[0,0,1]
	v_pk_add_f32 v[6:7], v[6:7], v[10:11]
	v_fma_mix_f32 v46, v64, s87, v8 op_sel_hi:[0,0,1]
	v_fma_mix_f32 v113, v64, s87, v9 op_sel:[0,0,1] op_sel_hi:[0,0,1]
	v_fma_mix_f32 v112, v64, s87, v9 op_sel_hi:[0,0,1]
	v_pk_add_f32 v[56:57], v[6:7], v[6:7] op_sel_hi:[0,1]
	v_pk_mul_f32 v[6:7], v[112:113], v[112:113]
	v_pk_mul_f32 v[8:9], v[46:47], v[46:47]
	v_fma_mix_f32 v58, v64, s87, v2 op_sel_hi:[0,0,1]
	v_pk_mov_b32 v[10:11], v[8:9], v[6:7] op_sel:[1,0]
	v_mov_b32_e32 v9, v7
	v_fma_mix_f32 v59, v64, s87, v2 op_sel:[0,0,1] op_sel_hi:[0,0,1]
	v_fma_mix_f32 v62, v64, s87, v3 op_sel_hi:[0,0,1]
	v_mul_f32_e32 v2, v58, v58
	v_pk_add_f32 v[6:7], v[10:11], v[8:9]
	v_fma_mix_f32 v63, v64, s87, v3 op_sel:[0,0,1] op_sel_hi:[0,0,1]
	v_pk_fma_f32 v[132:133], v[58:59], v[58:59], v[2:3] op_sel_hi:[1,1,0]
	v_mul_f32_e32 v2, v62, v62
	v_pk_add_f32 v[130:131], v[6:7], v[6:7] op_sel_hi:[0,1]
	v_pk_fma_f32 v[134:135], v[62:63], v[62:63], v[2:3] op_sel_hi:[1,1,0]
	v_fma_mix_f32 v61, v64, s87, v5 op_sel:[0,0,1] op_sel_hi:[0,0,1]
	v_fma_mix_f32 v60, v64, s87, v5 op_sel_hi:[0,0,1]
	v_fma_mix_f32 v65, v64, s87, v4 op_sel:[0,0,1] op_sel_hi:[0,0,1]
	v_fma_mix_f32 v64, v64, s87, v4 op_sel_hi:[0,0,1]
	global_load_dwordx4 v[2:5], v[70:71], off offset:16
	global_load_dwordx4 v[6:9], v[70:71], off
	global_load_dwordx4 v[10:13], v[72:73], off offset:16
	global_load_dwordx4 v[18:21], v[72:73], off
	v_mul_f32_e32 v132, v64, v64
	v_mul_f32_e32 v134, v65, v65
	v_mul_f32_e32 v130, v60, v60
	v_mul_f32_e32 v56, v61, v61
	v_pk_add_f32 v[132:133], v[132:133], v[134:135]
	v_pk_add_f32 v[56:57], v[130:131], v[56:57]
	s_nop 0
	v_pk_add_f32 v[56:57], v[132:133], v[56:57]
	s_nop 0
	v_add_f32_e32 v56, v56, v57
	s_nop 1
	v_mov_b32_dpp v57, v56 quad_perm:[1,0,3,2] row_mask:0xf bank_mask:0xf
	s_waitcnt lgkmcnt(0)
	v_add_f32_e32 v56, v56, v57
	s_nop 1
	v_mov_b32_dpp v57, v56 quad_perm:[2,3,0,1] row_mask:0xf bank_mask:0xf
	s_waitcnt lgkmcnt(0)
	v_add_f32_e32 v56, v56, v57
	s_nop 1
	v_mov_b32_dpp v57, v56 row_half_mirror row_mask:0xf bank_mask:0xf
	s_waitcnt lgkmcnt(0)
	v_add_f32_e32 v56, v56, v57
	s_nop 1
	v_mov_b32_dpp v57, v56 row_mirror row_mask:0xf bank_mask:0xf
	s_waitcnt lgkmcnt(0)
	v_add_f32_e32 v56, v56, v57
	v_mov_b32_e32 v57, v56
	s_nop 1
	v_permlane16_swap_b32_e32 v57, v56
	s_waitcnt lgkmcnt(0)
	v_add_f32_e32 v56, v56, v57
	v_mov_b32_e32 v57, v56
	s_nop 1
	v_permlane32_swap_b32_e32 v57, v56
	s_waitcnt lgkmcnt(0)
	v_add_f32_e32 v56, v56, v57
	v_fmamk_f32 v56, v56, 0x39800000, v216
	v_mul_f32_e32 v57, 0x4f800000, v56
	v_cmp_gt_f32_e32 vcc, s95, v56
	s_nop 1
	v_cndmask_b32_e32 v56, v56, v57, vcc
	v_sqrt_f32_e32 v57, v56
	s_nop 0
	v_add_u32_e32 v130, -1, v57
	v_fma_f32 v131, -v130, v57, v56
	v_cmp_ge_f32_e64 s[6:7], 0, v131
	v_add_u32_e32 v131, 1, v57
	s_nop 0
	v_cndmask_b32_e64 v130, v57, v130, s[6:7]
	v_fma_f32 v57, -v131, v57, v56
	v_cmp_lt_f32_e64 s[6:7], 0, v57
	s_nop 1
	v_cndmask_b32_e64 v57, v130, v131, s[6:7]
	v_mul_f32_e32 v130, 0x37800000, v57
	v_cndmask_b32_e32 v57, v57, v130, vcc
	v_cmp_class_f32_e32 vcc, v56, v215
	s_nop 1
	v_cndmask_b32_e32 v56, v57, v56, vcc
	v_div_scale_f32 v57, s[6:7], v56, v56, 1.0
	v_rcp_f32_e32 v130, v57
	s_lshl_b64 s[6:7], s[16:17], 1
	s_add_u32 s6, s26, s6
	s_addc_u32 s7, s27, s7
	v_fma_f32 v131, -v57, v130, 1.0
	v_fmac_f32_e32 v130, v131, v130
	v_div_scale_f32 v131, vcc, 1.0, v56, 1.0
	v_mul_f32_e32 v132, v131, v130
	v_fma_f32 v133, -v57, v132, v131
	v_fmac_f32_e32 v132, v133, v130
	v_fma_f32 v57, -v57, v132, v131
	v_div_fmas_f32 v57, v57, v130, v132
	v_div_fixup_f32 v130, v57, v56, 1.0
	v_pk_mul_f32 v[40:41], v[40:41], v[130:131] op_sel_hi:[1,0]
	v_pk_mul_f32 v[42:43], v[42:43], v[130:131] op_sel_hi:[1,0]
	s_waitcnt vmcnt(0)
	v_pk_fma_f32 v[56:57], v[6:7], v[40:41], v[18:19]
	v_pk_fma_f32 v[42:43], v[8:9], v[42:43], v[20:21]
	v_pk_mul_f32 v[6:7], v[126:127], v[130:131] op_sel_hi:[1,0]
	v_pk_mul_f32 v[8:9], v[128:129], v[130:131] op_sel_hi:[1,0]
	v_pk_fma_f32 v[40:41], v[2:3], v[6:7], v[10:11]
	v_pk_fma_f32 v[18:19], v[4:5], v[8:9], v[12:13]
	v_cvt_pk_f16_f32 v2, v56, v57
	v_cvt_pk_f16_f32 v3, v42, v43
	v_cvt_pk_f16_f32 v4, v40, v41
	v_cvt_pk_f16_f32 v5, v18, v19
	global_store_dwordx4 v152, v[2:5], s[6:7]
	global_load_dwordx4 v[2:5], v[76:77], off
	s_nop 0
	global_load_dwordx4 v[6:9], v[74:75], off
	global_load_dwordx4 v[10:13], v[74:75], off offset:16
	global_load_dwordx4 v[126:129], v[76:77], off offset:16
	v_pk_mul_f32 v[20:21], v[32:33], v[130:131] op_sel_hi:[1,0]
	v_pk_mul_f32 v[32:33], v[50:51], v[130:131] op_sel_hi:[1,0]
	v_pk_mul_f32 v[22:23], v[22:23], v[130:131] op_sel_hi:[1,0]
	v_pk_mul_f32 v[118:119], v[118:119], v[130:131] op_sel_hi:[1,0]
	v_pk_mul_f32 v[116:117], v[116:117], v[130:131] op_sel_hi:[1,0]
	v_pk_mul_f32 v[14:15], v[14:15], v[130:131] op_sel_hi:[1,0]
	v_pk_mul_f32 v[26:27], v[26:27], v[130:131] op_sel_hi:[1,0]
	v_pk_mul_f32 v[114:115], v[114:115], v[130:131] op_sel_hi:[1,0]
	v_pk_mul_f32 v[16:17], v[16:17], v[130:131] op_sel_hi:[1,0]
	v_pk_mul_f32 v[112:113], v[112:113], v[130:131] op_sel_hi:[1,0]
	v_pk_mul_f32 v[58:59], v[58:59], v[130:131] op_sel_hi:[1,0]
	v_pk_mul_f32 v[62:63], v[62:63], v[130:131] op_sel_hi:[1,0]
	v_pk_mul_f32 v[60:61], v[60:61], v[130:131] op_sel_hi:[1,0]
	s_waitcnt vmcnt(2)
; __device__ __forceinline__ unsigned pkh(float a, float b) { const f2v_t f = {a, b}; const h2v_t h = __builtin_convertvector(f, h2v_t); return __builtin_bit_cast(unsigned, h); }
; __device__ __forceinline__ void ln_row_b_in(const v4u (&src)[8], const float* g, const float* b, bf16* dstb, signed char* dstq, float* rowinv, int lane) {
;     ...
;     for (int j = 0; j < 8; ++j) { const int q = 2 * (64 * j + lane);
;         v[2 * j] = v[2 * j] * rstd * ((const f32x4*)g)[q] + ((const f32x4*)b)[q]; v[2 * j + 1] = v[2 * j + 1] * rstd * ((const f32x4*)g)[q + 1] + ((const f32x4*)b)[q + 1];
;         v4u w; w.x = pg8::pkh(v[2 * j].x, v[2 * j].y); w.y = pg8::pkh(v[2 * j].z, v[2 * j].w); w.z = pg8::pkh(v[2 * j + 1].x, v[2 * j + 1].y); w.w = pg8::pkh(v[2 * j + 1].z, v[2 * j + 1].w); ((v4u*)dstb)[64 * j + lane] = w; }
	v_pk_fma_f32 v[32:33], v[8:9], v[32:33], v[4:5]
	v_pk_fma_f32 v[50:51], v[6:7], v[20:21], v[2:3]
	v_pk_mul_f32 v[2:3], v[124:125], v[130:131] op_sel_hi:[1,0]
	v_pk_mul_f32 v[4:5], v[38:39], v[130:131] op_sel_hi:[1,0]
	s_waitcnt vmcnt(0)
	v_pk_fma_f32 v[38:39], v[10:11], v[2:3], v[126:127]
	v_pk_fma_f32 v[12:13], v[12:13], v[4:5], v[128:129]
	v_cvt_pk_f16_f32 v2, v50, v51
	v_cvt_pk_f16_f32 v3, v32, v33
	v_cvt_pk_f16_f32 v4, v38, v39
	v_cvt_pk_f16_f32 v5, v12, v13
	global_store_dwordx4 v152, v[2:5], s[6:7] offset:1024
	global_load_dwordx4 v[2:5], v[80:81], off
	s_nop 0
	global_load_dwordx4 v[6:9], v[78:79], off
	global_load_dwordx4 v[124:127], v[78:79], off offset:16
	global_load_dwordx4 v[132:135], v[80:81], off offset:16
	v_pk_mul_f32 v[10:11], v[30:31], v[130:131] op_sel_hi:[1,0]
	v_pk_mul_f32 v[20:21], v[48:49], v[130:131] op_sel_hi:[1,0]
	v_pk_mul_f32 v[128:129], v[34:35], v[130:131] op_sel_hi:[1,0]
	s_waitcnt vmcnt(2)
	v_pk_fma_f32 v[30:31], v[8:9], v[20:21], v[4:5]
	v_pk_fma_f32 v[48:49], v[6:7], v[10:11], v[2:3]
	v_pk_mul_f32 v[2:3], v[120:121], v[130:131] op_sel_hi:[1,0]
	v_pk_mul_f32 v[4:5], v[122:123], v[130:131] op_sel_hi:[1,0]
	s_waitcnt vmcnt(0)
	v_pk_fma_f32 v[20:21], v[124:125], v[2:3], v[132:133]
	v_pk_fma_f32 v[6:7], v[126:127], v[4:5], v[134:135]
	v_cvt_pk_f16_f32 v2, v48, v49
	v_cvt_pk_f16_f32 v3, v30, v31
	v_cvt_pk_f16_f32 v4, v20, v21
	v_cvt_pk_f16_f32 v5, v6, v7
	global_store_dwordx4 v152, v[2:5], s[6:7] offset:2048
	global_load_dwordx4 v[2:5], v[84:85], off
	s_nop 0
	global_load_dwordx4 v[8:11], v[82:83], off
	global_load_dwordx4 v[120:123], v[82:83], off offset:16
	global_load_dwordx4 v[124:127], v[84:85], off offset:16
	v_pk_mul_f32 v[132:133], v[52:53], v[130:131] op_sel_hi:[1,0]
	s_waitcnt vmcnt(2)
	v_pk_fma_f32 v[34:35], v[10:11], v[22:23], v[4:5]
	v_pk_fma_f32 v[52:53], v[8:9], v[128:129], v[2:3]
	s_waitcnt vmcnt(0)
	v_pk_fma_f32 v[8:9], v[122:123], v[118:119], v[126:127]
	v_pk_fma_f32 v[22:23], v[120:121], v[132:133], v[124:125]
	v_cvt_pk_f16_f32 v2, v52, v53
	v_cvt_pk_f16_f32 v3, v34, v35
	v_cvt_pk_f16_f32 v4, v22, v23
	v_cvt_pk_f16_f32 v5, v8, v9
	global_store_dwordx4 v152, v[2:5], s[6:7] offset:3072
	global_load_dwordx4 v[2:5], v[90:91], off
	s_nop 0
	global_load_dwordx4 v[118:121], v[88:89], off
	global_load_dwordx4 v[122:125], v[88:89], off offset:16
	global_load_dwordx4 v[126:129], v[90:91], off offset:16
	v_pk_mul_f32 v[10:11], v[24:25], v[130:131] op_sel_hi:[1,0]
	v_pk_mul_f32 v[24:25], v[54:55], v[130:131] op_sel_hi:[1,0]
	v_pk_mul_f32 v[132:133], v[36:37], v[130:131] op_sel_hi:[1,0]
	s_waitcnt vmcnt(2)
	v_pk_fma_f32 v[36:37], v[120:121], v[24:25], v[4:5]
	v_pk_fma_f32 v[54:55], v[118:119], v[10:11], v[2:3]
	s_waitcnt vmcnt(0)
	v_pk_fma_f32 v[10:11], v[124:125], v[132:133], v[128:129]
	v_pk_fma_f32 v[24:25], v[122:123], v[116:117], v[126:127]
	v_cvt_pk_f16_f32 v2, v54, v55
	v_cvt_pk_f16_f32 v3, v36, v37
	v_cvt_pk_f16_f32 v4, v24, v25
	v_cvt_pk_f16_f32 v5, v10, v11
	global_store_dwordx4 v146, v[2:5], s[6:7]
	global_load_dwordx4 v[2:5], v[96:97], off
	s_nop 0
	global_load_dwordx4 v[116:119], v[94:95], off
	global_load_dwordx4 v[120:123], v[94:95], off offset:16
	global_load_dwordx4 v[124:127], v[96:97], off offset:16
	v_pk_mul_f32 v[128:129], v[44:45], v[130:131] op_sel_hi:[1,0]
	v_pk_mul_f32 v[132:133], v[46:47], v[130:131] op_sel_hi:[1,0]
	s_waitcnt vmcnt(2)
	v_pk_fma_f32 v[26:27], v[118:119], v[26:27], v[4:5]
	v_pk_fma_f32 v[44:45], v[116:117], v[14:15], v[2:3]
	s_waitcnt vmcnt(0)
	v_pk_fma_f32 v[2:3], v[122:123], v[114:115], v[126:127]
	v_pk_fma_f32 v[14:15], v[120:121], v[128:129], v[124:125]
	v_cvt_pk_f16_f32 v114, v44, v45
	v_cvt_pk_f16_f32 v115, v26, v27
	v_cvt_pk_f16_f32 v116, v14, v15
	v_cvt_pk_f16_f32 v117, v2, v3
	global_store_dwordx4 v147, v[114:117], s[6:7]
	global_load_dwordx4 v[114:117], v[102:103], off
	s_nop 0
	global_load_dwordx4 v[118:121], v[100:101], off
	global_load_dwordx4 v[122:125], v[100:101], off offset:16
	global_load_dwordx4 v[126:129], v[102:103], off offset:16
	v_pk_mul_f32 v[4:5], v[28:29], v[130:131] op_sel_hi:[1,0]
	s_waitcnt vmcnt(2)
; __device__ __forceinline__ unsigned pkh(float a, float b) { const f2v_t f = {a, b}; const h2v_t h = __builtin_convertvector(f, h2v_t); return __builtin_bit_cast(unsigned, h); }
; template <bool PAIR> __device__ __forceinline__ void row_quant(const f32x4 (&v)[16], signed char* dstq, float* rowinv, int lane) {
;     float mx = 0.f;
; #pragma unroll
;     for (int j = 0; j < 16; ++j) mx = fmaxf(fmaxf(mx, fmaxf(fabsf(v[j].x), fabsf(v[j].y))), fmaxf(fabsf(v[j].z), fabsf(v[j].w)));
; #pragma unroll
;     for (int o = 1; o < 64; o <<= 1) mx = fmaxf(mx, __shfl_xor(mx, o));
;     mx = fmaxf(mx, 1e-20f);
;     const float sc = 127.0f / mx;
;     if (lane == 0) *rowinv = mx * (1.0f / 127.0f);
; __device__ __forceinline__ void ln_row_b_in(const v4u (&src)[8], const float* g, const float* b, bf16* dstb, signed char* dstq, float* rowinv, int lane) {
;     ...
;     for (int j = 0; j < 8; ++j) { const int q = 2 * (64 * j + lane);
;         v[2 * j] = v[2 * j] * rstd * ((const f32x4*)g)[q] + ((const f32x4*)b)[q]; v[2 * j + 1] = v[2 * j + 1] * rstd * ((const f32x4*)g)[q + 1] + ((const f32x4*)b)[q + 1];
;         v4u w; w.x = pg8::pkh(v[2 * j].x, v[2 * j].y); w.y = pg8::pkh(v[2 * j].z, v[2 * j].w); w.z = pg8::pkh(v[2 * j + 1].x, v[2 * j + 1].y); w.w = pg8::pkh(v[2 * j + 1].z, v[2 * j + 1].w); ((v4u*)dstb)[64 * j + lane] = w; }
	v_pk_fma_f32 v[28:29], v[120:121], v[16:17], v[116:117]
	v_pk_fma_f32 v[46:47], v[118:119], v[4:5], v[114:115]
	s_waitcnt vmcnt(0)
	v_pk_fma_f32 v[4:5], v[112:113], v[124:125], v[128:129]
	v_pk_fma_f32 v[16:17], v[132:133], v[122:123], v[126:127]
	v_cvt_pk_f16_f32 v112, v46, v47
	v_cvt_pk_f16_f32 v113, v28, v29
	v_cvt_pk_f16_f32 v114, v16, v17
	v_cvt_pk_f16_f32 v115, v4, v5
	global_store_dwordx4 v148, v[112:115], s[6:7]
	global_load_dwordx4 v[112:115], v[108:109], off
	s_nop 0
	global_load_dwordx4 v[116:119], v[106:107], off
	global_load_dwordx4 v[120:123], v[106:107], off offset:16
	global_load_dwordx4 v[124:127], v[108:109], off offset:16
	v_pk_mul_f32 v[128:129], v[64:65], v[130:131] op_sel_hi:[1,0]
	v_max_f32_e64 v64, |v56|, |v57|
	v_max_f32_e64 v65, |v42|, |v43|
	v_max_f32_e64 v130, |v40|, |v41|
	v_max_f32_e64 v131, |v18|, |v19|
	v_max3_f32 v64, v64, 0, v65
	v_max3_f32 v64, v64, v130, v131
	v_max_f32_e64 v65, |v50|, |v51|
	v_max_f32_e64 v130, |v32|, |v33|
	v_max_f32_e64 v131, |v38|, |v39|
	v_max_f32_e64 v132, |v12|, |v13|
	v_max3_f32 v64, v64, v65, v130
	v_max3_f32 v64, v64, v131, v132
	v_max_f32_e64 v65, |v48|, |v49|
	v_max_f32_e64 v130, |v30|, |v31|
	v_max_f32_e64 v131, |v20|, |v21|
	v_max_f32_e64 v132, |v6|, |v7|
	v_max3_f32 v64, v64, v65, v130
	v_max3_f32 v64, v64, v131, v132
	v_max_f32_e64 v65, |v52|, |v53|
	v_max_f32_e64 v130, |v34|, |v35|
	v_max_f32_e64 v131, |v22|, |v23|
	v_max_f32_e64 v132, |v8|, |v9|
	v_max3_f32 v64, v64, v65, v130
	v_max3_f32 v64, v64, v131, v132
	v_max_f32_e64 v65, |v54|, |v55|
	v_max_f32_e64 v130, |v36|, |v37|
	v_max_f32_e64 v131, |v24|, |v25|
	v_max_f32_e64 v132, |v10|, |v11|
	v_max3_f32 v64, v64, v65, v130
	v_max3_f32 v64, v64, v131, v132
	v_max_f32_e64 v65, |v44|, |v45|
	v_max_f32_e64 v130, |v26|, |v27|
	v_max_f32_e64 v131, |v14|, |v15|
	v_max_f32_e64 v132, |v2|, |v3|
	v_max3_f32 v64, v64, v65, v130
	v_max3_f32 v64, v64, v131, v132
	v_max_f32_e64 v65, |v46|, |v47|
	v_max_f32_e64 v130, |v28|, |v29|
	v_max_f32_e64 v131, |v16|, |v17|
	v_max_f32_e64 v132, |v4|, |v5|
	v_max3_f32 v64, v64, v65, v130
	v_max3_f32 v130, v64, v131, v132
	s_waitcnt vmcnt(2)
	v_pk_fma_f32 v[62:63], v[62:63], v[118:119], v[114:115]
	v_pk_fma_f32 v[64:65], v[58:59], v[116:117], v[112:113]
	s_waitcnt vmcnt(0)
	v_pk_fma_f32 v[58:59], v[60:61], v[122:123], v[126:127]
	v_pk_fma_f32 v[60:61], v[128:129], v[120:121], v[124:125]
	v_max_f32_e64 v112, |v64|, |v65|
	v_max_f32_e64 v113, |v62|, |v63|
	v_max_f32_e64 v114, |v60|, |v61|
	v_max3_f32 v112, v130, v112, v113
	v_max_f32_e64 v113, |v58|, |v59|
	v_max3_f32 v112, v112, v114, v113
	s_nop 1
	v_mov_b32_dpp v113, v112 quad_perm:[1,0,3,2] row_mask:0xf bank_mask:0xf
	v_cvt_pk_f16_f32 v115, v58, v59
	s_waitcnt lgkmcnt(0)
	v_max_f32_e32 v113, v113, v113
	v_max_f32_e32 v112, v112, v113
	s_nop 1
	v_mov_b32_dpp v113, v112 quad_perm:[2,3,0,1] row_mask:0xf bank_mask:0xf
	s_waitcnt lgkmcnt(0)
	v_max_f32_e32 v113, v113, v113
	v_max_f32_e32 v112, v112, v113
	s_nop 1
	v_mov_b32_dpp v113, v112 row_half_mirror row_mask:0xf bank_mask:0xf
	s_waitcnt lgkmcnt(0)
	v_max_f32_e32 v113, v113, v113
	v_max_f32_e32 v112, v112, v113
	s_nop 1
	v_mov_b32_dpp v113, v112 row_mirror row_mask:0xf bank_mask:0xf
	s_waitcnt lgkmcnt(0)
	v_max_f32_e32 v113, v113, v113
	v_max_f32_e32 v113, v112, v113
	v_mov_b32_e32 v114, v113
	s_nop 1
	v_permlane16_swap_b32_e32 v114, v113
	v_cvt_pk_f16_f32 v112, v64, v65
	s_waitcnt lgkmcnt(0)
	v_max_f32_e32 v114, v114, v114
	v_max_f32_e32 v116, v113, v114
	v_mov_b32_e32 v117, v116
	v_mov_b32_e32 v250, v116
	s_nop 1
	v_permlane32_swap_b32_e32 v117, v250
	v_cvt_pk_f16_f32 v113, v62, v63
	v_cvt_pk_f16_f32 v114, v60, v61
	global_store_dwordx4 v149, v[112:115], s[6:7]
	s_waitcnt lgkmcnt(0)
	s_nop 0
	v_max3_f32 v112, v250, v117, s50
	s_and_saveexec_b64 s[6:7], s[4:5]
	s_cbranch_execz .LBB0_1272
	s_lshl_b64 s[8:9], s[8:9], 2
	s_add_u32 s8, s28, s8
	v_mul_f32_e32 v113, 0x3c010204, v112
	s_addc_u32 s9, s29, s9
	global_store_dword v183, v113, s[8:9]
	s_branch .LBB0_1272
